# residual-stream reads that are overwritten in place right after (gather v side, attention w_o epilogue) streamed (nt)
# baseline (speedup 1.0000x reference)
.LpgL0_vloopv0:
	s_lshl_b32 s64, s0, 9
	s_add_u32 s64, s64, 0x0
	s_add_u32 s70, s28, s64
	s_addc_u32 s71, s29, 0
	global_load_dwordx2 v[228:229], v239, s[70:71] nt
	s_waitcnt lgkmcnt(0)
	v_lshl_or_b32 v128, v128, 7, v232
	v_lshl_or_b32 v129, v129, 7, v232
	v_lshl_or_b32 v130, v130, 7, v232
	v_lshl_or_b32 v131, v131, 7, v232
	v_lshl_or_b32 v132, v132, 7, v232
	v_lshl_or_b32 v133, v133, 7, v232
	v_lshl_or_b32 v134, v134, 7, v232
	v_lshl_or_b32 v135, v135, 7, v232
	buffer_load_dwordx4 v[96:99], v128, s[20:23], s1 offen
	buffer_load_dwordx4 v[100:103], v129, s[20:23], s1 offen
	buffer_load_dwordx4 v[104:107], v130, s[20:23], s1 offen
	buffer_load_dwordx4 v[108:111], v131, s[20:23], s1 offen
	buffer_load_dwordx4 v[112:115], v132, s[20:23], s1 offen
	buffer_load_dwordx4 v[116:119], v133, s[20:23], s1 offen
	buffer_load_dwordx4 v[120:123], v134, s[20:23], s1 offen
	buffer_load_dwordx4 v[124:127], v135, s[20:23], s1 offen
	ds_read_b32 v128, v243 offset:1024
	ds_read_b32 v129, v243 offset:1056
	ds_read_b32 v130, v243 offset:1088
	ds_read_b32 v131, v243 offset:1120
	ds_read_b32 v132, v243 offset:1152
	ds_read_b32 v133, v243 offset:1184
	ds_read_b32 v134, v243 offset:1216
	ds_read_b32 v135, v243 offset:1248
	ds_read_b64 v[176:177], v234 offset:256
	ds_read_b64 v[178:179], v234 offset:288
	ds_read_b64 v[180:181], v234 offset:320
	ds_read_b64 v[182:183], v234 offset:352
	ds_read_b64 v[184:185], v234 offset:384
	ds_read_b64 v[186:187], v234 offset:416
	ds_read_b64 v[188:189], v234 offset:448
	ds_read_b64 v[190:191], v234 offset:480
	s_waitcnt vmcnt(28)
	v_and_b32_e32 v144, v160, v235
	v_and_b32_e32 v145, v160, v236
	v_and_b32_e32 v146, v160, v237
	v_and_b32_e32 v147, v160, v238
	v_and_b32_e32 v148, v161, v235
	v_and_b32_e32 v149, v161, v236
	v_and_b32_e32 v150, v161, v237
	v_and_b32_e32 v151, v161, v238
	s_mov_b64 vcc, s[4:5]
	v_cndmask_b32_dpp v138, v0, v2, vcc row_shl:4 row_mask:0xf bank_mask:0xf bound_ctrl:1
	v_cndmask_b32_dpp v139, v1, v3, vcc row_shl:4 row_mask:0xf bank_mask:0xf bound_ctrl:1
	s_mov_b64 vcc, s[6:7]
	v_cndmask_b32_dpp v136, v2, v0, vcc row_shr:4 row_mask:0xf bank_mask:0xf bound_ctrl:1
	v_cndmask_b32_dpp v137, v3, v1, vcc row_shr:4 row_mask:0xf bank_mask:0xf bound_ctrl:1
	v_and_b32_e32 v204, v162, v235
	v_and_b32_e32 v205, v162, v236
	v_and_b32_e32 v206, v162, v237
	v_and_b32_e32 v207, v162, v238
	v_and_b32_e32 v208, v163, v235
	v_and_b32_e32 v209, v163, v236
	v_and_b32_e32 v210, v163, v237
	v_and_b32_e32 v211, v163, v238
	s_mov_b64 vcc, s[6:7]
	v_cndmask_b32_dpp v140, v6, v4, vcc row_shr:4 row_mask:0xf bank_mask:0xf bound_ctrl:1
	v_cndmask_b32_dpp v141, v7, v5, vcc row_shr:4 row_mask:0xf bank_mask:0xf bound_ctrl:1
	s_mov_b64 vcc, s[4:5]
	v_cndmask_b32_dpp v142, v4, v6, vcc row_shl:4 row_mask:0xf bank_mask:0xf bound_ctrl:1
	v_cndmask_b32_dpp v143, v5, v7, vcc row_shl:4 row_mask:0xf bank_mask:0xf bound_ctrl:1
	v_mfma_scale_f32_16x16x128_f8f6f4 v[212:215], v[136:139], v[144:151], 0, v240, v241 op_sel_hi:[0,0,0] cbsz:4
	v_and_b32_e32 v144, v164, v235
	v_and_b32_e32 v145, v164, v236
	v_and_b32_e32 v146, v164, v237
	v_and_b32_e32 v147, v164, v238
	v_and_b32_e32 v148, v165, v235
	v_and_b32_e32 v149, v165, v236
	v_and_b32_e32 v150, v165, v237
	v_and_b32_e32 v151, v165, v238
	s_mov_b64 vcc, s[4:5]
	v_cndmask_b32_dpp v138, v8, v10, vcc row_shl:4 row_mask:0xf bank_mask:0xf bound_ctrl:1
	v_cndmask_b32_dpp v139, v9, v11, vcc row_shl:4 row_mask:0xf bank_mask:0xf bound_ctrl:1
	s_mov_b64 vcc, s[6:7]
	v_cndmask_b32_dpp v136, v10, v8, vcc row_shr:4 row_mask:0xf bank_mask:0xf bound_ctrl:1
	v_cndmask_b32_dpp v137, v11, v9, vcc row_shr:4 row_mask:0xf bank_mask:0xf bound_ctrl:1
	v_mfma_scale_f32_16x16x128_f8f6f4 v[212:215], v[140:143], v[204:211], v[212:215], v240, v241 op_sel_hi:[0,0,0] cbsz:4
	v_and_b32_e32 v204, v166, v235
	v_and_b32_e32 v205, v166, v236
	v_and_b32_e32 v206, v166, v237
	v_and_b32_e32 v207, v166, v238
	v_and_b32_e32 v208, v167, v235
	v_and_b32_e32 v209, v167, v236
	v_and_b32_e32 v210, v167, v237
	v_and_b32_e32 v211, v167, v238
	s_mov_b64 vcc, s[6:7]
	v_cndmask_b32_dpp v140, v14, v12, vcc row_shr:4 row_mask:0xf bank_mask:0xf bound_ctrl:1
	v_cndmask_b32_dpp v141, v15, v13, vcc row_shr:4 row_mask:0xf bank_mask:0xf bound_ctrl:1
	s_mov_b64 vcc, s[4:5]
	v_cndmask_b32_dpp v142, v12, v14, vcc row_shl:4 row_mask:0xf bank_mask:0xf bound_ctrl:1
	v_cndmask_b32_dpp v143, v13, v15, vcc row_shl:4 row_mask:0xf bank_mask:0xf bound_ctrl:1
	v_mfma_scale_f32_16x16x128_f8f6f4 v[212:215], v[136:139], v[144:151], v[212:215], v240, v241 op_sel_hi:[0,0,0] cbsz:4
	v_and_b32_e32 v144, v168, v235
	v_and_b32_e32 v145, v168, v236
	v_and_b32_e32 v146, v168, v237
	v_and_b32_e32 v147, v168, v238
	v_and_b32_e32 v148, v169, v235
	v_and_b32_e32 v149, v169, v236
	v_and_b32_e32 v150, v169, v237
	v_and_b32_e32 v151, v169, v238
	s_mov_b64 vcc, s[4:5]
	v_cndmask_b32_dpp v138, v16, v18, vcc row_shl:4 row_mask:0xf bank_mask:0xf bound_ctrl:1
	v_cndmask_b32_dpp v139, v17, v19, vcc row_shl:4 row_mask:0xf bank_mask:0xf bound_ctrl:1
	s_mov_b64 vcc, s[6:7]
	v_cndmask_b32_dpp v136, v18, v16, vcc row_shr:4 row_mask:0xf bank_mask:0xf bound_ctrl:1
	v_cndmask_b32_dpp v137, v19, v17, vcc row_shr:4 row_mask:0xf bank_mask:0xf bound_ctrl:1
	v_mfma_scale_f32_16x16x128_f8f6f4 v[212:215], v[140:143], v[204:211], v[212:215], v240, v241 op_sel_hi:[0,0,0] cbsz:4
	v_and_b32_e32 v204, v170, v235
	v_and_b32_e32 v205, v170, v236
	v_and_b32_e32 v206, v170, v237
	v_and_b32_e32 v207, v170, v238
	v_and_b32_e32 v208, v171, v235
	v_and_b32_e32 v209, v171, v236
	v_and_b32_e32 v210, v171, v237
	v_and_b32_e32 v211, v171, v238
	s_mov_b64 vcc, s[6:7]
	v_cndmask_b32_dpp v140, v22, v20, vcc row_shr:4 row_mask:0xf bank_mask:0xf bound_ctrl:1
	v_cndmask_b32_dpp v141, v23, v21, vcc row_shr:4 row_mask:0xf bank_mask:0xf bound_ctrl:1
	s_mov_b64 vcc, s[4:5]
	v_cndmask_b32_dpp v142, v20, v22, vcc row_shl:4 row_mask:0xf bank_mask:0xf bound_ctrl:1
	v_cndmask_b32_dpp v143, v21, v23, vcc row_shl:4 row_mask:0xf bank_mask:0xf bound_ctrl:1
	v_mfma_scale_f32_16x16x128_f8f6f4 v[212:215], v[136:139], v[144:151], v[212:215], v240, v241 op_sel_hi:[0,0,0] cbsz:4
	v_and_b32_e32 v144, v172, v235
	v_and_b32_e32 v145, v172, v236
	v_and_b32_e32 v146, v172, v237
	v_and_b32_e32 v147, v172, v238
	v_and_b32_e32 v148, v173, v235
	v_and_b32_e32 v149, v173, v236
	v_and_b32_e32 v150, v173, v237
	v_and_b32_e32 v151, v173, v238
	s_mov_b64 vcc, s[4:5]
	v_cndmask_b32_dpp v138, v24, v26, vcc row_shl:4 row_mask:0xf bank_mask:0xf bound_ctrl:1
	v_cndmask_b32_dpp v139, v25, v27, vcc row_shl:4 row_mask:0xf bank_mask:0xf bound_ctrl:1
	s_mov_b64 vcc, s[6:7]
	v_cndmask_b32_dpp v136, v26, v24, vcc row_shr:4 row_mask:0xf bank_mask:0xf bound_ctrl:1
	v_cndmask_b32_dpp v137, v27, v25, vcc row_shr:4 row_mask:0xf bank_mask:0xf bound_ctrl:1
	v_mfma_scale_f32_16x16x128_f8f6f4 v[212:215], v[140:143], v[204:211], v[212:215], v240, v241 op_sel_hi:[0,0,0] cbsz:4
	v_and_b32_e32 v204, v174, v235
	v_and_b32_e32 v205, v174, v236
	v_and_b32_e32 v206, v174, v237
	v_and_b32_e32 v207, v174, v238
	v_and_b32_e32 v208, v175, v235
	v_and_b32_e32 v209, v175, v236
	v_and_b32_e32 v210, v175, v237
	v_and_b32_e32 v211, v175, v238
	s_mov_b64 vcc, s[6:7]
	v_cndmask_b32_dpp v140, v30, v28, vcc row_shr:4 row_mask:0xf bank_mask:0xf bound_ctrl:1
	v_cndmask_b32_dpp v141, v31, v29, vcc row_shr:4 row_mask:0xf bank_mask:0xf bound_ctrl:1
	s_mov_b64 vcc, s[4:5]
	v_cndmask_b32_dpp v142, v28, v30, vcc row_shl:4 row_mask:0xf bank_mask:0xf bound_ctrl:1
	v_cndmask_b32_dpp v143, v29, v31, vcc row_shl:4 row_mask:0xf bank_mask:0xf bound_ctrl:1
	v_mfma_scale_f32_16x16x128_f8f6f4 v[212:215], v[136:139], v[144:151], v[212:215], v240, v241 op_sel_hi:[0,0,0] cbsz:4
	s_nop 0
	v_mfma_scale_f32_16x16x128_f8f6f4 v[212:215], v[140:143], v[204:211], v[212:215], v240, v241 op_sel_hi:[0,0,0] cbsz:4
	s_waitcnt lgkmcnt(0)
	v_lshl_or_b32 v128, v128, 7, v232
	v_lshl_or_b32 v129, v129, 7, v232
	v_lshl_or_b32 v130, v130, 7, v232
	v_lshl_or_b32 v131, v131, 7, v232
	v_lshl_or_b32 v132, v132, 7, v232
	v_lshl_or_b32 v133, v133, 7, v232
	v_lshl_or_b32 v134, v134, 7, v232
	v_lshl_or_b32 v135, v135, 7, v232
	buffer_load_dwordx4 v[0:3], v128, s[20:23], s1 offen
	buffer_load_dwordx4 v[4:7], v129, s[20:23], s1 offen
	buffer_load_dwordx4 v[8:11], v130, s[20:23], s1 offen
	buffer_load_dwordx4 v[12:15], v131, s[20:23], s1 offen
	buffer_load_dwordx4 v[16:19], v132, s[20:23], s1 offen
	buffer_load_dwordx4 v[20:23], v133, s[20:23], s1 offen
	buffer_load_dwordx4 v[24:27], v134, s[20:23], s1 offen
	buffer_load_dwordx4 v[28:31], v135, s[20:23], s1 offen
	ds_read_b32 v128, v243 offset:1280
	ds_read_b32 v129, v243 offset:1312
	ds_read_b32 v130, v243 offset:1344
	ds_read_b32 v131, v243 offset:1376
	ds_read_b32 v132, v243 offset:1408
	ds_read_b32 v133, v243 offset:1440
	ds_read_b32 v134, v243 offset:1472
	ds_read_b32 v135, v243 offset:1504
	ds_read_b64 v[160:161], v234 offset:512
	ds_read_b64 v[162:163], v234 offset:544
	ds_read_b64 v[164:165], v234 offset:576
	ds_read_b64 v[166:167], v234 offset:608
	ds_read_b64 v[168:169], v234 offset:640
	ds_read_b64 v[170:171], v234 offset:672
	ds_read_b64 v[172:173], v234 offset:704
	ds_read_b64 v[174:175], v234 offset:736
	s_waitcnt vmcnt(26)
	s_cmp_eq_u32 s0, 0
	s_cbranch_scc1 .LpgL0_vdummyv0
	v_and_b32_e32 v144, v176, v235
	v_and_b32_e32 v145, v176, v236
	v_and_b32_e32 v146, v176, v237
	v_and_b32_e32 v147, v176, v238
	v_and_b32_e32 v148, v177, v235
	v_and_b32_e32 v149, v177, v236
	v_and_b32_e32 v150, v177, v237
	v_and_b32_e32 v151, v177, v238
	s_mov_b64 vcc, s[4:5]
	v_cndmask_b32_dpp v138, v32, v34, vcc row_shl:4 row_mask:0xf bank_mask:0xf bound_ctrl:1
	v_cndmask_b32_dpp v139, v33, v35, vcc row_shl:4 row_mask:0xf bank_mask:0xf bound_ctrl:1
	s_mov_b64 vcc, s[6:7]
	v_cndmask_b32_dpp v136, v34, v32, vcc row_shr:4 row_mask:0xf bank_mask:0xf bound_ctrl:1
	v_cndmask_b32_dpp v137, v35, v33, vcc row_shr:4 row_mask:0xf bank_mask:0xf bound_ctrl:1
	v_and_b32_e32 v204, v178, v235
	v_and_b32_e32 v205, v178, v236
	v_and_b32_e32 v206, v178, v237
	v_and_b32_e32 v207, v178, v238
	v_and_b32_e32 v208, v179, v235
	v_and_b32_e32 v209, v179, v236
	v_and_b32_e32 v210, v179, v237
	v_and_b32_e32 v211, v179, v238
	s_mov_b64 vcc, s[6:7]
	v_cndmask_b32_dpp v140, v38, v36, vcc row_shr:4 row_mask:0xf bank_mask:0xf bound_ctrl:1
	v_cndmask_b32_dpp v141, v39, v37, vcc row_shr:4 row_mask:0xf bank_mask:0xf bound_ctrl:1
	s_mov_b64 vcc, s[4:5]
	v_cndmask_b32_dpp v142, v36, v38, vcc row_shl:4 row_mask:0xf bank_mask:0xf bound_ctrl:1
	v_cndmask_b32_dpp v143, v37, v39, vcc row_shl:4 row_mask:0xf bank_mask:0xf bound_ctrl:1
	v_mfma_scale_f32_16x16x128_f8f6f4 v[212:215], v[136:139], v[144:151], v[212:215], v240, v241 op_sel_hi:[0,0,0] cbsz:4
	v_permlane16_swap_b32_e32 v216, v218
	v_permlane16_swap_b32_e32 v217, v219
	v_lshlrev_b32_e32 v252, 16, v230
	v_and_b32_e32 v144, v180, v235
	v_and_b32_e32 v145, v180, v236
	v_and_b32_e32 v146, v180, v237
	v_and_b32_e32 v147, v180, v238
	v_and_b32_e32 v148, v181, v235
	v_and_b32_e32 v149, v181, v236
	v_and_b32_e32 v150, v181, v237
	v_and_b32_e32 v151, v181, v238
	s_mov_b64 vcc, s[4:5]
	v_cndmask_b32_dpp v138, v40, v42, vcc row_shl:4 row_mask:0xf bank_mask:0xf bound_ctrl:1
	v_cndmask_b32_dpp v139, v41, v43, vcc row_shl:4 row_mask:0xf bank_mask:0xf bound_ctrl:1
	s_mov_b64 vcc, s[6:7]
	v_cndmask_b32_dpp v136, v42, v40, vcc row_shr:4 row_mask:0xf bank_mask:0xf bound_ctrl:1
	v_cndmask_b32_dpp v137, v43, v41, vcc row_shr:4 row_mask:0xf bank_mask:0xf bound_ctrl:1
	v_mfma_scale_f32_16x16x128_f8f6f4 v[212:215], v[140:143], v[204:211], v[212:215], v240, v241 op_sel_hi:[0,0,0] cbsz:4
	v_and_b32_e32 v253, 0xffff0000, v230
	v_lshlrev_b32_e32 v254, 16, v231
	v_and_b32_e32 v255, 0xffff0000, v231
	v_and_b32_e32 v204, v182, v235
	v_and_b32_e32 v205, v182, v236
	v_and_b32_e32 v206, v182, v237
	v_and_b32_e32 v207, v182, v238
	v_and_b32_e32 v208, v183, v235
	v_and_b32_e32 v209, v183, v236
	v_and_b32_e32 v210, v183, v237
	v_and_b32_e32 v211, v183, v238
	s_mov_b64 vcc, s[6:7]
	v_cndmask_b32_dpp v140, v46, v44, vcc row_shr:4 row_mask:0xf bank_mask:0xf bound_ctrl:1
	v_cndmask_b32_dpp v141, v47, v45, vcc row_shr:4 row_mask:0xf bank_mask:0xf bound_ctrl:1
	s_mov_b64 vcc, s[4:5]
	v_cndmask_b32_dpp v142, v44, v46, vcc row_shl:4 row_mask:0xf bank_mask:0xf bound_ctrl:1
	v_cndmask_b32_dpp v143, v45, v47, vcc row_shl:4 row_mask:0xf bank_mask:0xf bound_ctrl:1
	v_mfma_scale_f32_16x16x128_f8f6f4 v[212:215], v[136:139], v[144:151], v[212:215], v240, v241 op_sel_hi:[0,0,0] cbsz:4
	v_add_f32_e32 v252, v216, v252
	v_add_f32_e32 v253, v218, v253
	v_add_f32_e32 v254, v217, v254
	v_and_b32_e32 v144, v184, v235
	v_and_b32_e32 v145, v184, v236
	v_and_b32_e32 v146, v184, v237
	v_and_b32_e32 v147, v184, v238
	v_and_b32_e32 v148, v185, v235
	v_and_b32_e32 v149, v185, v236
	v_and_b32_e32 v150, v185, v237
	v_and_b32_e32 v151, v185, v238
	s_mov_b64 vcc, s[4:5]
	v_cndmask_b32_dpp v138, v48, v50, vcc row_shl:4 row_mask:0xf bank_mask:0xf bound_ctrl:1
	v_cndmask_b32_dpp v139, v49, v51, vcc row_shl:4 row_mask:0xf bank_mask:0xf bound_ctrl:1
	s_mov_b64 vcc, s[6:7]
	v_cndmask_b32_dpp v136, v50, v48, vcc row_shr:4 row_mask:0xf bank_mask:0xf bound_ctrl:1
	v_cndmask_b32_dpp v137, v51, v49, vcc row_shr:4 row_mask:0xf bank_mask:0xf bound_ctrl:1
	v_mfma_scale_f32_16x16x128_f8f6f4 v[212:215], v[140:143], v[204:211], v[212:215], v240, v241 op_sel_hi:[0,0,0] cbsz:4
	v_add_f32_e32 v255, v219, v255
	v_mul_f32_e32 v192, v252, v252
	v_mul_f32_e32 v193, v254, v254
	v_and_b32_e32 v204, v186, v235
	v_and_b32_e32 v205, v186, v236
	v_and_b32_e32 v206, v186, v237
	v_and_b32_e32 v207, v186, v238
	v_and_b32_e32 v208, v187, v235
	v_and_b32_e32 v209, v187, v236
	v_and_b32_e32 v210, v187, v237
	v_and_b32_e32 v211, v187, v238
	s_mov_b64 vcc, s[6:7]
	v_cndmask_b32_dpp v140, v54, v52, vcc row_shr:4 row_mask:0xf bank_mask:0xf bound_ctrl:1
	v_cndmask_b32_dpp v141, v55, v53, vcc row_shr:4 row_mask:0xf bank_mask:0xf bound_ctrl:1
	s_mov_b64 vcc, s[4:5]
	v_cndmask_b32_dpp v142, v52, v54, vcc row_shl:4 row_mask:0xf bank_mask:0xf bound_ctrl:1
	v_cndmask_b32_dpp v143, v53, v55, vcc row_shl:4 row_mask:0xf bank_mask:0xf bound_ctrl:1
	v_mfma_scale_f32_16x16x128_f8f6f4 v[212:215], v[136:139], v[144:151], v[212:215], v240, v241 op_sel_hi:[0,0,0] cbsz:4
	v_fmac_f32_e32 v192, v253, v253
	v_fmac_f32_e32 v193, v255, v255
	v_cvt_pk_bf16_f32 v250, v252, v253
	v_and_b32_e32 v144, v188, v235
	v_and_b32_e32 v145, v188, v236
	v_and_b32_e32 v146, v188, v237
	v_and_b32_e32 v147, v188, v238
	v_and_b32_e32 v148, v189, v235
	v_and_b32_e32 v149, v189, v236
	v_and_b32_e32 v150, v189, v237
	v_and_b32_e32 v151, v189, v238
	s_mov_b64 vcc, s[4:5]
	v_cndmask_b32_dpp v138, v56, v58, vcc row_shl:4 row_mask:0xf bank_mask:0xf bound_ctrl:1
	v_cndmask_b32_dpp v139, v57, v59, vcc row_shl:4 row_mask:0xf bank_mask:0xf bound_ctrl:1
	s_mov_b64 vcc, s[6:7]
	v_cndmask_b32_dpp v136, v58, v56, vcc row_shr:4 row_mask:0xf bank_mask:0xf bound_ctrl:1
	v_cndmask_b32_dpp v137, v59, v57, vcc row_shr:4 row_mask:0xf bank_mask:0xf bound_ctrl:1
	v_mfma_scale_f32_16x16x128_f8f6f4 v[212:215], v[140:143], v[204:211], v[212:215], v240, v241 op_sel_hi:[0,0,0] cbsz:4
	v_cvt_pk_bf16_f32 v251, v254, v255
	v_add_f32_e32 v192, v192, v193
	v_add_f32_e32 v227, v227, v192
	v_and_b32_e32 v204, v190, v235
	v_and_b32_e32 v205, v190, v236
	v_and_b32_e32 v206, v190, v237
	v_and_b32_e32 v207, v190, v238
	v_and_b32_e32 v208, v191, v235
	v_and_b32_e32 v209, v191, v236
	v_and_b32_e32 v210, v191, v237
	v_and_b32_e32 v211, v191, v238
	s_mov_b64 vcc, s[6:7]
	v_cndmask_b32_dpp v140, v62, v60, vcc row_shr:4 row_mask:0xf bank_mask:0xf bound_ctrl:1
	v_cndmask_b32_dpp v141, v63, v61, vcc row_shr:4 row_mask:0xf bank_mask:0xf bound_ctrl:1
	s_mov_b64 vcc, s[4:5]
	v_cndmask_b32_dpp v142, v60, v62, vcc row_shl:4 row_mask:0xf bank_mask:0xf bound_ctrl:1
	v_cndmask_b32_dpp v143, v61, v63, vcc row_shl:4 row_mask:0xf bank_mask:0xf bound_ctrl:1
	v_mfma_scale_f32_16x16x128_f8f6f4 v[212:215], v[136:139], v[144:151], v[212:215], v240, v241 op_sel_hi:[0,0,0] cbsz:4
	s_nop 0
	v_mfma_scale_f32_16x16x128_f8f6f4 v[212:215], v[140:143], v[204:211], v[212:215], v240, v241 op_sel_hi:[0,0,0] cbsz:4
	s_lshl_b32 s64, s0, 9
	s_add_u32 s64, s64, 0x6e00
	s_add_u32 s76, s28, s64
	s_addc_u32 s77, s29, 0
	global_store_dwordx2 v239, v[250:251], s[76:77]
	s_branch .LpgL0_vjoinv0

.LpgL0_vjoinv0:
	s_lshl_b32 s64, s0, 9
	s_add_u32 s64, s64, 0x1000
	s_add_u32 s70, s28, s64
	s_addc_u32 s71, s29, 0
	global_load_dwordx2 v[230:231], v239, s[70:71] nt
	s_waitcnt lgkmcnt(0)
	v_lshl_or_b32 v128, v128, 7, v232
	v_lshl_or_b32 v129, v129, 7, v232
	v_lshl_or_b32 v130, v130, 7, v232
	v_lshl_or_b32 v131, v131, 7, v232
	v_lshl_or_b32 v132, v132, 7, v232
	v_lshl_or_b32 v133, v133, 7, v232
	v_lshl_or_b32 v134, v134, 7, v232
	v_lshl_or_b32 v135, v135, 7, v232
	buffer_load_dwordx4 v[32:35], v128, s[20:23], s1 offen
	buffer_load_dwordx4 v[36:39], v129, s[20:23], s1 offen
	buffer_load_dwordx4 v[40:43], v130, s[20:23], s1 offen
	buffer_load_dwordx4 v[44:47], v131, s[20:23], s1 offen
	buffer_load_dwordx4 v[48:51], v132, s[20:23], s1 offen
	buffer_load_dwordx4 v[52:55], v133, s[20:23], s1 offen
	buffer_load_dwordx4 v[56:59], v134, s[20:23], s1 offen
	buffer_load_dwordx4 v[60:63], v135, s[20:23], s1 offen
	ds_read_b32 v128, v243 offset:1536
	ds_read_b32 v129, v243 offset:1568
	ds_read_b32 v130, v243 offset:1600
	ds_read_b32 v131, v243 offset:1632
	ds_read_b32 v132, v243 offset:1664
	ds_read_b32 v133, v243 offset:1696
	ds_read_b32 v134, v243 offset:1728
	ds_read_b32 v135, v243 offset:1760
	ds_read_b64 v[176:177], v234 offset:768
	ds_read_b64 v[178:179], v234 offset:800
	ds_read_b64 v[180:181], v234 offset:832
	ds_read_b64 v[182:183], v234 offset:864
	ds_read_b64 v[184:185], v234 offset:896
	ds_read_b64 v[186:187], v234 offset:928
	ds_read_b64 v[188:189], v234 offset:960
	ds_read_b64 v[190:191], v234 offset:992
	s_waitcnt vmcnt(28)
	v_and_b32_e32 v144, v160, v235
	v_and_b32_e32 v145, v160, v236
	v_and_b32_e32 v146, v160, v237
	v_and_b32_e32 v147, v160, v238
	v_and_b32_e32 v148, v161, v235
	v_and_b32_e32 v149, v161, v236
	v_and_b32_e32 v150, v161, v237
	v_and_b32_e32 v151, v161, v238
	s_mov_b64 vcc, s[4:5]
	v_cndmask_b32_dpp v138, v64, v66, vcc row_shl:4 row_mask:0xf bank_mask:0xf bound_ctrl:1
	v_cndmask_b32_dpp v139, v65, v67, vcc row_shl:4 row_mask:0xf bank_mask:0xf bound_ctrl:1
	s_mov_b64 vcc, s[6:7]
	v_cndmask_b32_dpp v136, v66, v64, vcc row_shr:4 row_mask:0xf bank_mask:0xf bound_ctrl:1
	v_cndmask_b32_dpp v137, v67, v65, vcc row_shr:4 row_mask:0xf bank_mask:0xf bound_ctrl:1
	v_and_b32_e32 v204, v162, v235
	v_and_b32_e32 v205, v162, v236
	v_and_b32_e32 v206, v162, v237
	v_and_b32_e32 v207, v162, v238
	v_and_b32_e32 v208, v163, v235
	v_and_b32_e32 v209, v163, v236
	v_and_b32_e32 v210, v163, v237
	v_and_b32_e32 v211, v163, v238
	s_mov_b64 vcc, s[6:7]
	v_cndmask_b32_dpp v140, v70, v68, vcc row_shr:4 row_mask:0xf bank_mask:0xf bound_ctrl:1
	v_cndmask_b32_dpp v141, v71, v69, vcc row_shr:4 row_mask:0xf bank_mask:0xf bound_ctrl:1
	s_mov_b64 vcc, s[4:5]
	v_cndmask_b32_dpp v142, v68, v70, vcc row_shl:4 row_mask:0xf bank_mask:0xf bound_ctrl:1
	v_cndmask_b32_dpp v143, v69, v71, vcc row_shl:4 row_mask:0xf bank_mask:0xf bound_ctrl:1
	v_mfma_scale_f32_16x16x128_f8f6f4 v[216:219], v[136:139], v[144:151], 0, v240, v241 op_sel_hi:[0,0,0] cbsz:4
	v_and_b32_e32 v144, v164, v235
	v_and_b32_e32 v145, v164, v236
	v_and_b32_e32 v146, v164, v237
	v_and_b32_e32 v147, v164, v238
	v_and_b32_e32 v148, v165, v235
	v_and_b32_e32 v149, v165, v236
	v_and_b32_e32 v150, v165, v237
	v_and_b32_e32 v151, v165, v238
	s_mov_b64 vcc, s[4:5]
	v_cndmask_b32_dpp v138, v72, v74, vcc row_shl:4 row_mask:0xf bank_mask:0xf bound_ctrl:1
	v_cndmask_b32_dpp v139, v73, v75, vcc row_shl:4 row_mask:0xf bank_mask:0xf bound_ctrl:1
	s_mov_b64 vcc, s[6:7]
	v_cndmask_b32_dpp v136, v74, v72, vcc row_shr:4 row_mask:0xf bank_mask:0xf bound_ctrl:1
	v_cndmask_b32_dpp v137, v75, v73, vcc row_shr:4 row_mask:0xf bank_mask:0xf bound_ctrl:1
	v_mfma_scale_f32_16x16x128_f8f6f4 v[216:219], v[140:143], v[204:211], v[216:219], v240, v241 op_sel_hi:[0,0,0] cbsz:4
	v_and_b32_e32 v204, v166, v235
	v_and_b32_e32 v205, v166, v236
	v_and_b32_e32 v206, v166, v237
	v_and_b32_e32 v207, v166, v238
	v_and_b32_e32 v208, v167, v235
	v_and_b32_e32 v209, v167, v236
	v_and_b32_e32 v210, v167, v237
	v_and_b32_e32 v211, v167, v238
	s_mov_b64 vcc, s[6:7]
	v_cndmask_b32_dpp v140, v78, v76, vcc row_shr:4 row_mask:0xf bank_mask:0xf bound_ctrl:1
	v_cndmask_b32_dpp v141, v79, v77, vcc row_shr:4 row_mask:0xf bank_mask:0xf bound_ctrl:1
	s_mov_b64 vcc, s[4:5]
	v_cndmask_b32_dpp v142, v76, v78, vcc row_shl:4 row_mask:0xf bank_mask:0xf bound_ctrl:1
	v_cndmask_b32_dpp v143, v77, v79, vcc row_shl:4 row_mask:0xf bank_mask:0xf bound_ctrl:1
	v_mfma_scale_f32_16x16x128_f8f6f4 v[216:219], v[136:139], v[144:151], v[216:219], v240, v241 op_sel_hi:[0,0,0] cbsz:4
	v_and_b32_e32 v144, v168, v235
	v_and_b32_e32 v145, v168, v236
	v_and_b32_e32 v146, v168, v237
	v_and_b32_e32 v147, v168, v238
	v_and_b32_e32 v148, v169, v235
	v_and_b32_e32 v149, v169, v236
	v_and_b32_e32 v150, v169, v237
	v_and_b32_e32 v151, v169, v238
	s_mov_b64 vcc, s[4:5]
	v_cndmask_b32_dpp v138, v80, v82, vcc row_shl:4 row_mask:0xf bank_mask:0xf bound_ctrl:1
	v_cndmask_b32_dpp v139, v81, v83, vcc row_shl:4 row_mask:0xf bank_mask:0xf bound_ctrl:1
	s_mov_b64 vcc, s[6:7]
	v_cndmask_b32_dpp v136, v82, v80, vcc row_shr:4 row_mask:0xf bank_mask:0xf bound_ctrl:1
	v_cndmask_b32_dpp v137, v83, v81, vcc row_shr:4 row_mask:0xf bank_mask:0xf bound_ctrl:1
	v_mfma_scale_f32_16x16x128_f8f6f4 v[216:219], v[140:143], v[204:211], v[216:219], v240, v241 op_sel_hi:[0,0,0] cbsz:4
	v_and_b32_e32 v204, v170, v235
	v_and_b32_e32 v205, v170, v236
	v_and_b32_e32 v206, v170, v237
	v_and_b32_e32 v207, v170, v238
	v_and_b32_e32 v208, v171, v235
	v_and_b32_e32 v209, v171, v236
	v_and_b32_e32 v210, v171, v237
	v_and_b32_e32 v211, v171, v238
	s_mov_b64 vcc, s[6:7]
	v_cndmask_b32_dpp v140, v86, v84, vcc row_shr:4 row_mask:0xf bank_mask:0xf bound_ctrl:1
	v_cndmask_b32_dpp v141, v87, v85, vcc row_shr:4 row_mask:0xf bank_mask:0xf bound_ctrl:1
	s_mov_b64 vcc, s[4:5]
	v_cndmask_b32_dpp v142, v84, v86, vcc row_shl:4 row_mask:0xf bank_mask:0xf bound_ctrl:1
	v_cndmask_b32_dpp v143, v85, v87, vcc row_shl:4 row_mask:0xf bank_mask:0xf bound_ctrl:1
	v_mfma_scale_f32_16x16x128_f8f6f4 v[216:219], v[136:139], v[144:151], v[216:219], v240, v241 op_sel_hi:[0,0,0] cbsz:4
	v_and_b32_e32 v144, v172, v235
	v_and_b32_e32 v145, v172, v236
	v_and_b32_e32 v146, v172, v237
	v_and_b32_e32 v147, v172, v238
	v_and_b32_e32 v148, v173, v235
	v_and_b32_e32 v149, v173, v236
	v_and_b32_e32 v150, v173, v237
	v_and_b32_e32 v151, v173, v238
	s_mov_b64 vcc, s[4:5]
	v_cndmask_b32_dpp v138, v88, v90, vcc row_shl:4 row_mask:0xf bank_mask:0xf bound_ctrl:1
	v_cndmask_b32_dpp v139, v89, v91, vcc row_shl:4 row_mask:0xf bank_mask:0xf bound_ctrl:1
	s_mov_b64 vcc, s[6:7]
	v_cndmask_b32_dpp v136, v90, v88, vcc row_shr:4 row_mask:0xf bank_mask:0xf bound_ctrl:1
	v_cndmask_b32_dpp v137, v91, v89, vcc row_shr:4 row_mask:0xf bank_mask:0xf bound_ctrl:1
	v_mfma_scale_f32_16x16x128_f8f6f4 v[216:219], v[140:143], v[204:211], v[216:219], v240, v241 op_sel_hi:[0,0,0] cbsz:4
	v_and_b32_e32 v204, v174, v235
	v_and_b32_e32 v205, v174, v236
	v_and_b32_e32 v206, v174, v237
	v_and_b32_e32 v207, v174, v238
	v_and_b32_e32 v208, v175, v235
	v_and_b32_e32 v209, v175, v236
	v_and_b32_e32 v210, v175, v237
	v_and_b32_e32 v211, v175, v238
	s_mov_b64 vcc, s[6:7]
	v_cndmask_b32_dpp v140, v94, v92, vcc row_shr:4 row_mask:0xf bank_mask:0xf bound_ctrl:1
	v_cndmask_b32_dpp v141, v95, v93, vcc row_shr:4 row_mask:0xf bank_mask:0xf bound_ctrl:1
	s_mov_b64 vcc, s[4:5]
	v_cndmask_b32_dpp v142, v92, v94, vcc row_shl:4 row_mask:0xf bank_mask:0xf bound_ctrl:1
	v_cndmask_b32_dpp v143, v93, v95, vcc row_shl:4 row_mask:0xf bank_mask:0xf bound_ctrl:1
	v_mfma_scale_f32_16x16x128_f8f6f4 v[216:219], v[136:139], v[144:151], v[216:219], v240, v241 op_sel_hi:[0,0,0] cbsz:4
	s_nop 0
	v_mfma_scale_f32_16x16x128_f8f6f4 v[216:219], v[140:143], v[204:211], v[216:219], v240, v241 op_sel_hi:[0,0,0] cbsz:4
	s_waitcnt lgkmcnt(0)
	v_lshl_or_b32 v128, v128, 7, v232
	v_lshl_or_b32 v129, v129, 7, v232
	v_lshl_or_b32 v130, v130, 7, v232
	v_lshl_or_b32 v131, v131, 7, v232
	v_lshl_or_b32 v132, v132, 7, v232
	v_lshl_or_b32 v133, v133, 7, v232
	v_lshl_or_b32 v134, v134, 7, v232
	v_lshl_or_b32 v135, v135, 7, v232
	buffer_load_dwordx4 v[64:67], v128, s[20:23], s1 offen
	buffer_load_dwordx4 v[68:71], v129, s[20:23], s1 offen
	buffer_load_dwordx4 v[72:75], v130, s[20:23], s1 offen
	buffer_load_dwordx4 v[76:79], v131, s[20:23], s1 offen
	buffer_load_dwordx4 v[80:83], v132, s[20:23], s1 offen
	buffer_load_dwordx4 v[84:87], v133, s[20:23], s1 offen
	buffer_load_dwordx4 v[88:91], v134, s[20:23], s1 offen
	buffer_load_dwordx4 v[92:95], v135, s[20:23], s1 offen
	ds_read_b32 v128, v243 offset:1792
	ds_read_b32 v129, v243 offset:1824
	ds_read_b32 v130, v243 offset:1856
	ds_read_b32 v131, v243 offset:1888
	ds_read_b32 v132, v243 offset:1920
	ds_read_b32 v133, v243 offset:1952
	ds_read_b32 v134, v243 offset:1984
	ds_read_b32 v135, v243 offset:2016
	ds_read_b64 v[160:161], v234 offset:1024
	ds_read_b64 v[162:163], v234 offset:1056
	ds_read_b64 v[164:165], v234 offset:1088
	ds_read_b64 v[166:167], v234 offset:1120
	ds_read_b64 v[168:169], v234 offset:1152
	ds_read_b64 v[170:171], v234 offset:1184
	ds_read_b64 v[172:173], v234 offset:1216
	ds_read_b64 v[174:175], v234 offset:1248
	s_waitcnt vmcnt(26)
	v_and_b32_e32 v144, v176, v235
	v_and_b32_e32 v145, v176, v236
	v_and_b32_e32 v146, v176, v237
	v_and_b32_e32 v147, v176, v238
	v_and_b32_e32 v148, v177, v235
	v_and_b32_e32 v149, v177, v236
	v_and_b32_e32 v150, v177, v237
	v_and_b32_e32 v151, v177, v238
	s_mov_b64 vcc, s[4:5]
	v_cndmask_b32_dpp v138, v96, v98, vcc row_shl:4 row_mask:0xf bank_mask:0xf bound_ctrl:1
	v_cndmask_b32_dpp v139, v97, v99, vcc row_shl:4 row_mask:0xf bank_mask:0xf bound_ctrl:1
	s_mov_b64 vcc, s[6:7]
	v_cndmask_b32_dpp v136, v98, v96, vcc row_shr:4 row_mask:0xf bank_mask:0xf bound_ctrl:1
	v_cndmask_b32_dpp v137, v99, v97, vcc row_shr:4 row_mask:0xf bank_mask:0xf bound_ctrl:1
	v_and_b32_e32 v204, v178, v235
	v_and_b32_e32 v205, v178, v236
	v_and_b32_e32 v206, v178, v237
	v_and_b32_e32 v207, v178, v238
	v_and_b32_e32 v208, v179, v235
	v_and_b32_e32 v209, v179, v236
	v_and_b32_e32 v210, v179, v237
	v_and_b32_e32 v211, v179, v238
	s_mov_b64 vcc, s[6:7]
	v_cndmask_b32_dpp v140, v102, v100, vcc row_shr:4 row_mask:0xf bank_mask:0xf bound_ctrl:1
	v_cndmask_b32_dpp v141, v103, v101, vcc row_shr:4 row_mask:0xf bank_mask:0xf bound_ctrl:1
	s_mov_b64 vcc, s[4:5]
	v_cndmask_b32_dpp v142, v100, v102, vcc row_shl:4 row_mask:0xf bank_mask:0xf bound_ctrl:1
	v_cndmask_b32_dpp v143, v101, v103, vcc row_shl:4 row_mask:0xf bank_mask:0xf bound_ctrl:1
	v_mfma_scale_f32_16x16x128_f8f6f4 v[216:219], v[136:139], v[144:151], v[216:219], v240, v241 op_sel_hi:[0,0,0] cbsz:4
	v_permlane16_swap_b32_e32 v212, v214
	v_permlane16_swap_b32_e32 v213, v215
	v_lshlrev_b32_e32 v252, 16, v228
	v_and_b32_e32 v144, v180, v235
	v_and_b32_e32 v145, v180, v236
	v_and_b32_e32 v146, v180, v237
	v_and_b32_e32 v147, v180, v238
	v_and_b32_e32 v148, v181, v235
	v_and_b32_e32 v149, v181, v236
	v_and_b32_e32 v150, v181, v237
	v_and_b32_e32 v151, v181, v238
	s_mov_b64 vcc, s[4:5]
	v_cndmask_b32_dpp v138, v104, v106, vcc row_shl:4 row_mask:0xf bank_mask:0xf bound_ctrl:1
	v_cndmask_b32_dpp v139, v105, v107, vcc row_shl:4 row_mask:0xf bank_mask:0xf bound_ctrl:1
	s_mov_b64 vcc, s[6:7]
	v_cndmask_b32_dpp v136, v106, v104, vcc row_shr:4 row_mask:0xf bank_mask:0xf bound_ctrl:1
	v_cndmask_b32_dpp v137, v107, v105, vcc row_shr:4 row_mask:0xf bank_mask:0xf bound_ctrl:1
	v_mfma_scale_f32_16x16x128_f8f6f4 v[216:219], v[140:143], v[204:211], v[216:219], v240, v241 op_sel_hi:[0,0,0] cbsz:4
	v_and_b32_e32 v253, 0xffff0000, v228
	v_lshlrev_b32_e32 v254, 16, v229
	v_and_b32_e32 v255, 0xffff0000, v229
	v_and_b32_e32 v204, v182, v235
	v_and_b32_e32 v205, v182, v236
	v_and_b32_e32 v206, v182, v237
	v_and_b32_e32 v207, v182, v238
	v_and_b32_e32 v208, v183, v235
	v_and_b32_e32 v209, v183, v236
	v_and_b32_e32 v210, v183, v237
	v_and_b32_e32 v211, v183, v238
	s_mov_b64 vcc, s[6:7]
	v_cndmask_b32_dpp v140, v110, v108, vcc row_shr:4 row_mask:0xf bank_mask:0xf bound_ctrl:1
	v_cndmask_b32_dpp v141, v111, v109, vcc row_shr:4 row_mask:0xf bank_mask:0xf bound_ctrl:1
	s_mov_b64 vcc, s[4:5]
	v_cndmask_b32_dpp v142, v108, v110, vcc row_shl:4 row_mask:0xf bank_mask:0xf bound_ctrl:1
	v_cndmask_b32_dpp v143, v109, v111, vcc row_shl:4 row_mask:0xf bank_mask:0xf bound_ctrl:1
	v_mfma_scale_f32_16x16x128_f8f6f4 v[216:219], v[136:139], v[144:151], v[216:219], v240, v241 op_sel_hi:[0,0,0] cbsz:4
	v_add_f32_e32 v252, v212, v252
	v_add_f32_e32 v253, v214, v253
	v_add_f32_e32 v254, v213, v254
	v_and_b32_e32 v144, v184, v235
	v_and_b32_e32 v145, v184, v236
	v_and_b32_e32 v146, v184, v237
	v_and_b32_e32 v147, v184, v238
	v_and_b32_e32 v148, v185, v235
	v_and_b32_e32 v149, v185, v236
	v_and_b32_e32 v150, v185, v237
	v_and_b32_e32 v151, v185, v238
	s_mov_b64 vcc, s[4:5]
	v_cndmask_b32_dpp v138, v112, v114, vcc row_shl:4 row_mask:0xf bank_mask:0xf bound_ctrl:1
	v_cndmask_b32_dpp v139, v113, v115, vcc row_shl:4 row_mask:0xf bank_mask:0xf bound_ctrl:1
	s_mov_b64 vcc, s[6:7]
	v_cndmask_b32_dpp v136, v114, v112, vcc row_shr:4 row_mask:0xf bank_mask:0xf bound_ctrl:1
	v_cndmask_b32_dpp v137, v115, v113, vcc row_shr:4 row_mask:0xf bank_mask:0xf bound_ctrl:1
	v_mfma_scale_f32_16x16x128_f8f6f4 v[216:219], v[140:143], v[204:211], v[216:219], v240, v241 op_sel_hi:[0,0,0] cbsz:4
	v_add_f32_e32 v255, v215, v255
	v_mul_f32_e32 v192, v252, v252
	v_mul_f32_e32 v193, v254, v254
	v_and_b32_e32 v204, v186, v235
	v_and_b32_e32 v205, v186, v236
	v_and_b32_e32 v206, v186, v237
	v_and_b32_e32 v207, v186, v238
	v_and_b32_e32 v208, v187, v235
	v_and_b32_e32 v209, v187, v236
	v_and_b32_e32 v210, v187, v237
	v_and_b32_e32 v211, v187, v238
	s_mov_b64 vcc, s[6:7]
	v_cndmask_b32_dpp v140, v118, v116, vcc row_shr:4 row_mask:0xf bank_mask:0xf bound_ctrl:1
	v_cndmask_b32_dpp v141, v119, v117, vcc row_shr:4 row_mask:0xf bank_mask:0xf bound_ctrl:1
	s_mov_b64 vcc, s[4:5]
	v_cndmask_b32_dpp v142, v116, v118, vcc row_shl:4 row_mask:0xf bank_mask:0xf bound_ctrl:1
	v_cndmask_b32_dpp v143, v117, v119, vcc row_shl:4 row_mask:0xf bank_mask:0xf bound_ctrl:1
	v_mfma_scale_f32_16x16x128_f8f6f4 v[216:219], v[136:139], v[144:151], v[216:219], v240, v241 op_sel_hi:[0,0,0] cbsz:4
	v_fmac_f32_e32 v192, v253, v253
	v_fmac_f32_e32 v193, v255, v255
	v_cvt_pk_bf16_f32 v250, v252, v253
	v_and_b32_e32 v144, v188, v235
	v_and_b32_e32 v145, v188, v236
	v_and_b32_e32 v146, v188, v237
	v_and_b32_e32 v147, v188, v238
	v_and_b32_e32 v148, v189, v235
	v_and_b32_e32 v149, v189, v236
	v_and_b32_e32 v150, v189, v237
	v_and_b32_e32 v151, v189, v238
	s_mov_b64 vcc, s[4:5]
	v_cndmask_b32_dpp v138, v120, v122, vcc row_shl:4 row_mask:0xf bank_mask:0xf bound_ctrl:1
	v_cndmask_b32_dpp v139, v121, v123, vcc row_shl:4 row_mask:0xf bank_mask:0xf bound_ctrl:1
	s_mov_b64 vcc, s[6:7]
	v_cndmask_b32_dpp v136, v122, v120, vcc row_shr:4 row_mask:0xf bank_mask:0xf bound_ctrl:1
	v_cndmask_b32_dpp v137, v123, v121, vcc row_shr:4 row_mask:0xf bank_mask:0xf bound_ctrl:1
	v_mfma_scale_f32_16x16x128_f8f6f4 v[216:219], v[140:143], v[204:211], v[216:219], v240, v241 op_sel_hi:[0,0,0] cbsz:4
	v_cvt_pk_bf16_f32 v251, v254, v255
	v_add_f32_e32 v192, v192, v193
	v_add_f32_e32 v220, v220, v192
	v_and_b32_e32 v204, v190, v235
	v_and_b32_e32 v205, v190, v236
	v_and_b32_e32 v206, v190, v237
	v_and_b32_e32 v207, v190, v238
	v_and_b32_e32 v208, v191, v235
	v_and_b32_e32 v209, v191, v236
	v_and_b32_e32 v210, v191, v237
	v_and_b32_e32 v211, v191, v238
	s_mov_b64 vcc, s[6:7]
	v_cndmask_b32_dpp v140, v126, v124, vcc row_shr:4 row_mask:0xf bank_mask:0xf bound_ctrl:1
	v_cndmask_b32_dpp v141, v127, v125, vcc row_shr:4 row_mask:0xf bank_mask:0xf bound_ctrl:1
	s_mov_b64 vcc, s[4:5]
	v_cndmask_b32_dpp v142, v124, v126, vcc row_shl:4 row_mask:0xf bank_mask:0xf bound_ctrl:1
	v_cndmask_b32_dpp v143, v125, v127, vcc row_shl:4 row_mask:0xf bank_mask:0xf bound_ctrl:1
	v_mfma_scale_f32_16x16x128_f8f6f4 v[216:219], v[136:139], v[144:151], v[216:219], v240, v241 op_sel_hi:[0,0,0] cbsz:4
	s_nop 0
	v_mfma_scale_f32_16x16x128_f8f6f4 v[216:219], v[140:143], v[204:211], v[216:219], v240, v241 op_sel_hi:[0,0,0] cbsz:4
	s_lshl_b32 s64, s0, 9
	s_add_u32 s64, s64, 0x0
	s_add_u32 s76, s28, s64
	s_addc_u32 s77, s29, 0
	global_store_dwordx2 v239, v[250:251], s[76:77]
	s_lshl_b32 s64, s0, 9
	s_add_u32 s64, s64, 0x2000
	s_add_u32 s70, s28, s64
	s_addc_u32 s71, s29, 0
	global_load_dwordx2 v[228:229], v239, s[70:71] nt
	s_waitcnt lgkmcnt(0)
	v_lshl_or_b32 v128, v128, 7, v232
	v_lshl_or_b32 v129, v129, 7, v232
	v_lshl_or_b32 v130, v130, 7, v232
	v_lshl_or_b32 v131, v131, 7, v232
	v_lshl_or_b32 v132, v132, 7, v232
	v_lshl_or_b32 v133, v133, 7, v232
	v_lshl_or_b32 v134, v134, 7, v232
	v_lshl_or_b32 v135, v135, 7, v232
	buffer_load_dwordx4 v[96:99], v128, s[20:23], s1 offen
	buffer_load_dwordx4 v[100:103], v129, s[20:23], s1 offen
	buffer_load_dwordx4 v[104:107], v130, s[20:23], s1 offen
	buffer_load_dwordx4 v[108:111], v131, s[20:23], s1 offen
	buffer_load_dwordx4 v[112:115], v132, s[20:23], s1 offen
	buffer_load_dwordx4 v[116:119], v133, s[20:23], s1 offen
	buffer_load_dwordx4 v[120:123], v134, s[20:23], s1 offen
	buffer_load_dwordx4 v[124:127], v135, s[20:23], s1 offen
	ds_read_b32 v128, v243 offset:2048
	ds_read_b32 v129, v243 offset:2080
	ds_read_b32 v130, v243 offset:2112
	ds_read_b32 v131, v243 offset:2144
	ds_read_b32 v132, v243 offset:2176
	ds_read_b32 v133, v243 offset:2208
	ds_read_b32 v134, v243 offset:2240
	ds_read_b32 v135, v243 offset:2272
	ds_read_b64 v[176:177], v234 offset:1280
	ds_read_b64 v[178:179], v234 offset:1312
	ds_read_b64 v[180:181], v234 offset:1344
	ds_read_b64 v[182:183], v234 offset:1376
	ds_read_b64 v[184:185], v234 offset:1408
	ds_read_b64 v[186:187], v234 offset:1440
	ds_read_b64 v[188:189], v234 offset:1472
	ds_read_b64 v[190:191], v234 offset:1504
	s_waitcnt vmcnt(28)
	v_and_b32_e32 v144, v160, v235
	v_and_b32_e32 v145, v160, v236
	v_and_b32_e32 v146, v160, v237
	v_and_b32_e32 v147, v160, v238
	v_and_b32_e32 v148, v161, v235
	v_and_b32_e32 v149, v161, v236
	v_and_b32_e32 v150, v161, v237
	v_and_b32_e32 v151, v161, v238
	s_mov_b64 vcc, s[4:5]
	v_cndmask_b32_dpp v138, v0, v2, vcc row_shl:4 row_mask:0xf bank_mask:0xf bound_ctrl:1
	v_cndmask_b32_dpp v139, v1, v3, vcc row_shl:4 row_mask:0xf bank_mask:0xf bound_ctrl:1
	s_mov_b64 vcc, s[6:7]
	v_cndmask_b32_dpp v136, v2, v0, vcc row_shr:4 row_mask:0xf bank_mask:0xf bound_ctrl:1
	v_cndmask_b32_dpp v137, v3, v1, vcc row_shr:4 row_mask:0xf bank_mask:0xf bound_ctrl:1
	v_and_b32_e32 v204, v162, v235
	v_and_b32_e32 v205, v162, v236
	v_and_b32_e32 v206, v162, v237
	v_and_b32_e32 v207, v162, v238
	v_and_b32_e32 v208, v163, v235
	v_and_b32_e32 v209, v163, v236
	v_and_b32_e32 v210, v163, v237
	v_and_b32_e32 v211, v163, v238
	s_mov_b64 vcc, s[6:7]
	v_cndmask_b32_dpp v140, v6, v4, vcc row_shr:4 row_mask:0xf bank_mask:0xf bound_ctrl:1
	v_cndmask_b32_dpp v141, v7, v5, vcc row_shr:4 row_mask:0xf bank_mask:0xf bound_ctrl:1
	s_mov_b64 vcc, s[4:5]
	v_cndmask_b32_dpp v142, v4, v6, vcc row_shl:4 row_mask:0xf bank_mask:0xf bound_ctrl:1
	v_cndmask_b32_dpp v143, v5, v7, vcc row_shl:4 row_mask:0xf bank_mask:0xf bound_ctrl:1
	v_mfma_scale_f32_16x16x128_f8f6f4 v[212:215], v[136:139], v[144:151], 0, v240, v241 op_sel_hi:[0,0,0] cbsz:4
	v_and_b32_e32 v144, v164, v235
	v_and_b32_e32 v145, v164, v236
	v_and_b32_e32 v146, v164, v237
	v_and_b32_e32 v147, v164, v238
	v_and_b32_e32 v148, v165, v235
	v_and_b32_e32 v149, v165, v236
	v_and_b32_e32 v150, v165, v237
	v_and_b32_e32 v151, v165, v238
	s_mov_b64 vcc, s[4:5]
	v_cndmask_b32_dpp v138, v8, v10, vcc row_shl:4 row_mask:0xf bank_mask:0xf bound_ctrl:1
	v_cndmask_b32_dpp v139, v9, v11, vcc row_shl:4 row_mask:0xf bank_mask:0xf bound_ctrl:1
	s_mov_b64 vcc, s[6:7]
	v_cndmask_b32_dpp v136, v10, v8, vcc row_shr:4 row_mask:0xf bank_mask:0xf bound_ctrl:1
	v_cndmask_b32_dpp v137, v11, v9, vcc row_shr:4 row_mask:0xf bank_mask:0xf bound_ctrl:1
	v_mfma_scale_f32_16x16x128_f8f6f4 v[212:215], v[140:143], v[204:211], v[212:215], v240, v241 op_sel_hi:[0,0,0] cbsz:4
	v_and_b32_e32 v204, v166, v235
	v_and_b32_e32 v205, v166, v236
	v_and_b32_e32 v206, v166, v237
	v_and_b32_e32 v207, v166, v238
	v_and_b32_e32 v208, v167, v235
	v_and_b32_e32 v209, v167, v236
	v_and_b32_e32 v210, v167, v237
	v_and_b32_e32 v211, v167, v238
	s_mov_b64 vcc, s[6:7]
	v_cndmask_b32_dpp v140, v14, v12, vcc row_shr:4 row_mask:0xf bank_mask:0xf bound_ctrl:1
	v_cndmask_b32_dpp v141, v15, v13, vcc row_shr:4 row_mask:0xf bank_mask:0xf bound_ctrl:1
	s_mov_b64 vcc, s[4:5]
	v_cndmask_b32_dpp v142, v12, v14, vcc row_shl:4 row_mask:0xf bank_mask:0xf bound_ctrl:1
	v_cndmask_b32_dpp v143, v13, v15, vcc row_shl:4 row_mask:0xf bank_mask:0xf bound_ctrl:1
	v_mfma_scale_f32_16x16x128_f8f6f4 v[212:215], v[136:139], v[144:151], v[212:215], v240, v241 op_sel_hi:[0,0,0] cbsz:4
	v_and_b32_e32 v144, v168, v235
	v_and_b32_e32 v145, v168, v236
	v_and_b32_e32 v146, v168, v237
	v_and_b32_e32 v147, v168, v238
	v_and_b32_e32 v148, v169, v235
	v_and_b32_e32 v149, v169, v236
	v_and_b32_e32 v150, v169, v237
	v_and_b32_e32 v151, v169, v238
	s_mov_b64 vcc, s[4:5]
	v_cndmask_b32_dpp v138, v16, v18, vcc row_shl:4 row_mask:0xf bank_mask:0xf bound_ctrl:1
	v_cndmask_b32_dpp v139, v17, v19, vcc row_shl:4 row_mask:0xf bank_mask:0xf bound_ctrl:1
	s_mov_b64 vcc, s[6:7]
	v_cndmask_b32_dpp v136, v18, v16, vcc row_shr:4 row_mask:0xf bank_mask:0xf bound_ctrl:1
	v_cndmask_b32_dpp v137, v19, v17, vcc row_shr:4 row_mask:0xf bank_mask:0xf bound_ctrl:1
	v_mfma_scale_f32_16x16x128_f8f6f4 v[212:215], v[140:143], v[204:211], v[212:215], v240, v241 op_sel_hi:[0,0,0] cbsz:4
	v_and_b32_e32 v204, v170, v235
	v_and_b32_e32 v205, v170, v236
	v_and_b32_e32 v206, v170, v237
	v_and_b32_e32 v207, v170, v238
	v_and_b32_e32 v208, v171, v235
	v_and_b32_e32 v209, v171, v236
	v_and_b32_e32 v210, v171, v237
	v_and_b32_e32 v211, v171, v238
	s_mov_b64 vcc, s[6:7]
	v_cndmask_b32_dpp v140, v22, v20, vcc row_shr:4 row_mask:0xf bank_mask:0xf bound_ctrl:1
	v_cndmask_b32_dpp v141, v23, v21, vcc row_shr:4 row_mask:0xf bank_mask:0xf bound_ctrl:1
	s_mov_b64 vcc, s[4:5]
	v_cndmask_b32_dpp v142, v20, v22, vcc row_shl:4 row_mask:0xf bank_mask:0xf bound_ctrl:1
	v_cndmask_b32_dpp v143, v21, v23, vcc row_shl:4 row_mask:0xf bank_mask:0xf bound_ctrl:1
	v_mfma_scale_f32_16x16x128_f8f6f4 v[212:215], v[136:139], v[144:151], v[212:215], v240, v241 op_sel_hi:[0,0,0] cbsz:4
	v_and_b32_e32 v144, v172, v235
	v_and_b32_e32 v145, v172, v236
	v_and_b32_e32 v146, v172, v237
	v_and_b32_e32 v147, v172, v238
	v_and_b32_e32 v148, v173, v235
	v_and_b32_e32 v149, v173, v236
	v_and_b32_e32 v150, v173, v237
	v_and_b32_e32 v151, v173, v238
	s_mov_b64 vcc, s[4:5]
	v_cndmask_b32_dpp v138, v24, v26, vcc row_shl:4 row_mask:0xf bank_mask:0xf bound_ctrl:1
	v_cndmask_b32_dpp v139, v25, v27, vcc row_shl:4 row_mask:0xf bank_mask:0xf bound_ctrl:1
	s_mov_b64 vcc, s[6:7]
	v_cndmask_b32_dpp v136, v26, v24, vcc row_shr:4 row_mask:0xf bank_mask:0xf bound_ctrl:1
	v_cndmask_b32_dpp v137, v27, v25, vcc row_shr:4 row_mask:0xf bank_mask:0xf bound_ctrl:1
	v_mfma_scale_f32_16x16x128_f8f6f4 v[212:215], v[140:143], v[204:211], v[212:215], v240, v241 op_sel_hi:[0,0,0] cbsz:4
	v_and_b32_e32 v204, v174, v235
	v_and_b32_e32 v205, v174, v236
	v_and_b32_e32 v206, v174, v237
	v_and_b32_e32 v207, v174, v238
	v_and_b32_e32 v208, v175, v235
	v_and_b32_e32 v209, v175, v236
	v_and_b32_e32 v210, v175, v237
	v_and_b32_e32 v211, v175, v238
	s_mov_b64 vcc, s[6:7]
	v_cndmask_b32_dpp v140, v30, v28, vcc row_shr:4 row_mask:0xf bank_mask:0xf bound_ctrl:1
	v_cndmask_b32_dpp v141, v31, v29, vcc row_shr:4 row_mask:0xf bank_mask:0xf bound_ctrl:1
	s_mov_b64 vcc, s[4:5]
	v_cndmask_b32_dpp v142, v28, v30, vcc row_shl:4 row_mask:0xf bank_mask:0xf bound_ctrl:1
	v_cndmask_b32_dpp v143, v29, v31, vcc row_shl:4 row_mask:0xf bank_mask:0xf bound_ctrl:1
	v_mfma_scale_f32_16x16x128_f8f6f4 v[212:215], v[136:139], v[144:151], v[212:215], v240, v241 op_sel_hi:[0,0,0] cbsz:4
	s_nop 0
	v_mfma_scale_f32_16x16x128_f8f6f4 v[212:215], v[140:143], v[204:211], v[212:215], v240, v241 op_sel_hi:[0,0,0] cbsz:4
	s_waitcnt lgkmcnt(0)
	v_lshl_or_b32 v128, v128, 7, v232
	v_lshl_or_b32 v129, v129, 7, v232
	v_lshl_or_b32 v130, v130, 7, v232
	v_lshl_or_b32 v131, v131, 7, v232
	v_lshl_or_b32 v132, v132, 7, v232
	v_lshl_or_b32 v133, v133, 7, v232
	v_lshl_or_b32 v134, v134, 7, v232
	v_lshl_or_b32 v135, v135, 7, v232
	buffer_load_dwordx4 v[0:3], v128, s[20:23], s1 offen
	buffer_load_dwordx4 v[4:7], v129, s[20:23], s1 offen
	buffer_load_dwordx4 v[8:11], v130, s[20:23], s1 offen
	buffer_load_dwordx4 v[12:15], v131, s[20:23], s1 offen
	buffer_load_dwordx4 v[16:19], v132, s[20:23], s1 offen
	buffer_load_dwordx4 v[20:23], v133, s[20:23], s1 offen
	buffer_load_dwordx4 v[24:27], v134, s[20:23], s1 offen
	buffer_load_dwordx4 v[28:31], v135, s[20:23], s1 offen
	ds_read_b32 v128, v243 offset:2304
	ds_read_b32 v129, v243 offset:2336
	ds_read_b32 v130, v243 offset:2368
	ds_read_b32 v131, v243 offset:2400
	ds_read_b32 v132, v243 offset:2432
	ds_read_b32 v133, v243 offset:2464
	ds_read_b32 v134, v243 offset:2496
	ds_read_b32 v135, v243 offset:2528
	ds_read_b64 v[160:161], v234 offset:1536
	ds_read_b64 v[162:163], v234 offset:1568
	ds_read_b64 v[164:165], v234 offset:1600
	ds_read_b64 v[166:167], v234 offset:1632
	ds_read_b64 v[168:169], v234 offset:1664
	ds_read_b64 v[170:171], v234 offset:1696
	ds_read_b64 v[172:173], v234 offset:1728
	ds_read_b64 v[174:175], v234 offset:1760
	s_waitcnt vmcnt(26)
	v_and_b32_e32 v144, v176, v235
	v_and_b32_e32 v145, v176, v236
	v_and_b32_e32 v146, v176, v237
	v_and_b32_e32 v147, v176, v238
	v_and_b32_e32 v148, v177, v235
	v_and_b32_e32 v149, v177, v236
	v_and_b32_e32 v150, v177, v237
	v_and_b32_e32 v151, v177, v238
	s_mov_b64 vcc, s[4:5]
	v_cndmask_b32_dpp v138, v32, v34, vcc row_shl:4 row_mask:0xf bank_mask:0xf bound_ctrl:1
	v_cndmask_b32_dpp v139, v33, v35, vcc row_shl:4 row_mask:0xf bank_mask:0xf bound_ctrl:1
	s_mov_b64 vcc, s[6:7]
	v_cndmask_b32_dpp v136, v34, v32, vcc row_shr:4 row_mask:0xf bank_mask:0xf bound_ctrl:1
	v_cndmask_b32_dpp v137, v35, v33, vcc row_shr:4 row_mask:0xf bank_mask:0xf bound_ctrl:1
	v_and_b32_e32 v204, v178, v235
	v_and_b32_e32 v205, v178, v236
	v_and_b32_e32 v206, v178, v237
	v_and_b32_e32 v207, v178, v238
	v_and_b32_e32 v208, v179, v235
	v_and_b32_e32 v209, v179, v236
	v_and_b32_e32 v210, v179, v237
	v_and_b32_e32 v211, v179, v238
	s_mov_b64 vcc, s[6:7]
	v_cndmask_b32_dpp v140, v38, v36, vcc row_shr:4 row_mask:0xf bank_mask:0xf bound_ctrl:1
	v_cndmask_b32_dpp v141, v39, v37, vcc row_shr:4 row_mask:0xf bank_mask:0xf bound_ctrl:1
	s_mov_b64 vcc, s[4:5]
	v_cndmask_b32_dpp v142, v36, v38, vcc row_shl:4 row_mask:0xf bank_mask:0xf bound_ctrl:1
	v_cndmask_b32_dpp v143, v37, v39, vcc row_shl:4 row_mask:0xf bank_mask:0xf bound_ctrl:1
	v_mfma_scale_f32_16x16x128_f8f6f4 v[212:215], v[136:139], v[144:151], v[212:215], v240, v241 op_sel_hi:[0,0,0] cbsz:4
	v_permlane16_swap_b32_e32 v216, v218
	v_permlane16_swap_b32_e32 v217, v219
	v_lshlrev_b32_e32 v252, 16, v230
	v_and_b32_e32 v144, v180, v235
	v_and_b32_e32 v145, v180, v236
	v_and_b32_e32 v146, v180, v237
	v_and_b32_e32 v147, v180, v238
	v_and_b32_e32 v148, v181, v235
	v_and_b32_e32 v149, v181, v236
	v_and_b32_e32 v150, v181, v237
	v_and_b32_e32 v151, v181, v238
	s_mov_b64 vcc, s[4:5]
	v_cndmask_b32_dpp v138, v40, v42, vcc row_shl:4 row_mask:0xf bank_mask:0xf bound_ctrl:1
	v_cndmask_b32_dpp v139, v41, v43, vcc row_shl:4 row_mask:0xf bank_mask:0xf bound_ctrl:1
	s_mov_b64 vcc, s[6:7]
	v_cndmask_b32_dpp v136, v42, v40, vcc row_shr:4 row_mask:0xf bank_mask:0xf bound_ctrl:1
	v_cndmask_b32_dpp v137, v43, v41, vcc row_shr:4 row_mask:0xf bank_mask:0xf bound_ctrl:1
	v_mfma_scale_f32_16x16x128_f8f6f4 v[212:215], v[140:143], v[204:211], v[212:215], v240, v241 op_sel_hi:[0,0,0] cbsz:4
	v_and_b32_e32 v253, 0xffff0000, v230
	v_lshlrev_b32_e32 v254, 16, v231
	v_and_b32_e32 v255, 0xffff0000, v231
	v_and_b32_e32 v204, v182, v235
	v_and_b32_e32 v205, v182, v236
	v_and_b32_e32 v206, v182, v237
	v_and_b32_e32 v207, v182, v238
	v_and_b32_e32 v208, v183, v235
	v_and_b32_e32 v209, v183, v236
	v_and_b32_e32 v210, v183, v237
	v_and_b32_e32 v211, v183, v238
	s_mov_b64 vcc, s[6:7]
	v_cndmask_b32_dpp v140, v46, v44, vcc row_shr:4 row_mask:0xf bank_mask:0xf bound_ctrl:1
	v_cndmask_b32_dpp v141, v47, v45, vcc row_shr:4 row_mask:0xf bank_mask:0xf bound_ctrl:1
	s_mov_b64 vcc, s[4:5]
	v_cndmask_b32_dpp v142, v44, v46, vcc row_shl:4 row_mask:0xf bank_mask:0xf bound_ctrl:1
	v_cndmask_b32_dpp v143, v45, v47, vcc row_shl:4 row_mask:0xf bank_mask:0xf bound_ctrl:1
	v_mfma_scale_f32_16x16x128_f8f6f4 v[212:215], v[136:139], v[144:151], v[212:215], v240, v241 op_sel_hi:[0,0,0] cbsz:4
	v_add_f32_e32 v252, v216, v252
	v_add_f32_e32 v253, v218, v253
	v_add_f32_e32 v254, v217, v254
	v_and_b32_e32 v144, v184, v235
	v_and_b32_e32 v145, v184, v236
	v_and_b32_e32 v146, v184, v237
	v_and_b32_e32 v147, v184, v238
	v_and_b32_e32 v148, v185, v235
	v_and_b32_e32 v149, v185, v236
	v_and_b32_e32 v150, v185, v237
	v_and_b32_e32 v151, v185, v238
	s_mov_b64 vcc, s[4:5]
	v_cndmask_b32_dpp v138, v48, v50, vcc row_shl:4 row_mask:0xf bank_mask:0xf bound_ctrl:1
	v_cndmask_b32_dpp v139, v49, v51, vcc row_shl:4 row_mask:0xf bank_mask:0xf bound_ctrl:1
	s_mov_b64 vcc, s[6:7]
	v_cndmask_b32_dpp v136, v50, v48, vcc row_shr:4 row_mask:0xf bank_mask:0xf bound_ctrl:1
	v_cndmask_b32_dpp v137, v51, v49, vcc row_shr:4 row_mask:0xf bank_mask:0xf bound_ctrl:1
	v_mfma_scale_f32_16x16x128_f8f6f4 v[212:215], v[140:143], v[204:211], v[212:215], v240, v241 op_sel_hi:[0,0,0] cbsz:4
	v_add_f32_e32 v255, v219, v255
	v_mul_f32_e32 v192, v252, v252
	v_mul_f32_e32 v193, v254, v254
	v_and_b32_e32 v204, v186, v235
	v_and_b32_e32 v205, v186, v236
	v_and_b32_e32 v206, v186, v237
	v_and_b32_e32 v207, v186, v238
	v_and_b32_e32 v208, v187, v235
	v_and_b32_e32 v209, v187, v236
	v_and_b32_e32 v210, v187, v237
	v_and_b32_e32 v211, v187, v238
	s_mov_b64 vcc, s[6:7]
	v_cndmask_b32_dpp v140, v54, v52, vcc row_shr:4 row_mask:0xf bank_mask:0xf bound_ctrl:1
	v_cndmask_b32_dpp v141, v55, v53, vcc row_shr:4 row_mask:0xf bank_mask:0xf bound_ctrl:1
	s_mov_b64 vcc, s[4:5]
	v_cndmask_b32_dpp v142, v52, v54, vcc row_shl:4 row_mask:0xf bank_mask:0xf bound_ctrl:1
	v_cndmask_b32_dpp v143, v53, v55, vcc row_shl:4 row_mask:0xf bank_mask:0xf bound_ctrl:1
	v_mfma_scale_f32_16x16x128_f8f6f4 v[212:215], v[136:139], v[144:151], v[212:215], v240, v241 op_sel_hi:[0,0,0] cbsz:4
	v_fmac_f32_e32 v192, v253, v253
	v_fmac_f32_e32 v193, v255, v255
	v_cvt_pk_bf16_f32 v250, v252, v253
	v_and_b32_e32 v144, v188, v235
	v_and_b32_e32 v145, v188, v236
	v_and_b32_e32 v146, v188, v237
	v_and_b32_e32 v147, v188, v238
	v_and_b32_e32 v148, v189, v235
	v_and_b32_e32 v149, v189, v236
	v_and_b32_e32 v150, v189, v237
	v_and_b32_e32 v151, v189, v238
	s_mov_b64 vcc, s[4:5]
	v_cndmask_b32_dpp v138, v56, v58, vcc row_shl:4 row_mask:0xf bank_mask:0xf bound_ctrl:1
	v_cndmask_b32_dpp v139, v57, v59, vcc row_shl:4 row_mask:0xf bank_mask:0xf bound_ctrl:1
	s_mov_b64 vcc, s[6:7]
	v_cndmask_b32_dpp v136, v58, v56, vcc row_shr:4 row_mask:0xf bank_mask:0xf bound_ctrl:1
	v_cndmask_b32_dpp v137, v59, v57, vcc row_shr:4 row_mask:0xf bank_mask:0xf bound_ctrl:1
	v_mfma_scale_f32_16x16x128_f8f6f4 v[212:215], v[140:143], v[204:211], v[212:215], v240, v241 op_sel_hi:[0,0,0] cbsz:4
	v_cvt_pk_bf16_f32 v251, v254, v255
	v_add_f32_e32 v192, v192, v193
	v_add_f32_e32 v221, v221, v192
	v_and_b32_e32 v204, v190, v235
	v_and_b32_e32 v205, v190, v236
	v_and_b32_e32 v206, v190, v237
	v_and_b32_e32 v207, v190, v238
	v_and_b32_e32 v208, v191, v235
	v_and_b32_e32 v209, v191, v236
	v_and_b32_e32 v210, v191, v237
	v_and_b32_e32 v211, v191, v238
	s_mov_b64 vcc, s[6:7]
	v_cndmask_b32_dpp v140, v62, v60, vcc row_shr:4 row_mask:0xf bank_mask:0xf bound_ctrl:1
	v_cndmask_b32_dpp v141, v63, v61, vcc row_shr:4 row_mask:0xf bank_mask:0xf bound_ctrl:1
	s_mov_b64 vcc, s[4:5]
	v_cndmask_b32_dpp v142, v60, v62, vcc row_shl:4 row_mask:0xf bank_mask:0xf bound_ctrl:1
	v_cndmask_b32_dpp v143, v61, v63, vcc row_shl:4 row_mask:0xf bank_mask:0xf bound_ctrl:1
	v_mfma_scale_f32_16x16x128_f8f6f4 v[212:215], v[136:139], v[144:151], v[212:215], v240, v241 op_sel_hi:[0,0,0] cbsz:4
	s_nop 0
	v_mfma_scale_f32_16x16x128_f8f6f4 v[212:215], v[140:143], v[204:211], v[212:215], v240, v241 op_sel_hi:[0,0,0] cbsz:4
	s_lshl_b32 s64, s0, 9
	s_add_u32 s64, s64, 0x1000
	s_add_u32 s76, s28, s64
	s_addc_u32 s77, s29, 0
	global_store_dwordx2 v239, v[250:251], s[76:77]
	s_lshl_b32 s64, s0, 9
	s_add_u32 s64, s64, 0x3000
	s_add_u32 s70, s28, s64
	s_addc_u32 s71, s29, 0
	global_load_dwordx2 v[230:231], v239, s[70:71] nt
	s_waitcnt lgkmcnt(0)
	v_lshl_or_b32 v128, v128, 7, v232
	v_lshl_or_b32 v129, v129, 7, v232
	v_lshl_or_b32 v130, v130, 7, v232
	v_lshl_or_b32 v131, v131, 7, v232
	v_lshl_or_b32 v132, v132, 7, v232
	v_lshl_or_b32 v133, v133, 7, v232
	v_lshl_or_b32 v134, v134, 7, v232
	v_lshl_or_b32 v135, v135, 7, v232
	buffer_load_dwordx4 v[32:35], v128, s[20:23], s1 offen
	buffer_load_dwordx4 v[36:39], v129, s[20:23], s1 offen
	buffer_load_dwordx4 v[40:43], v130, s[20:23], s1 offen
	buffer_load_dwordx4 v[44:47], v131, s[20:23], s1 offen
	buffer_load_dwordx4 v[48:51], v132, s[20:23], s1 offen
	buffer_load_dwordx4 v[52:55], v133, s[20:23], s1 offen
	buffer_load_dwordx4 v[56:59], v134, s[20:23], s1 offen
	buffer_load_dwordx4 v[60:63], v135, s[20:23], s1 offen
	ds_read_b32 v128, v243 offset:2560
	ds_read_b32 v129, v243 offset:2592
	ds_read_b32 v130, v243 offset:2624
	ds_read_b32 v131, v243 offset:2656
	ds_read_b32 v132, v243 offset:2688
	ds_read_b32 v133, v243 offset:2720
	ds_read_b32 v134, v243 offset:2752
	ds_read_b32 v135, v243 offset:2784
	ds_read_b64 v[176:177], v234 offset:1792
	ds_read_b64 v[178:179], v234 offset:1824
	ds_read_b64 v[180:181], v234 offset:1856
	ds_read_b64 v[182:183], v234 offset:1888
	ds_read_b64 v[184:185], v234 offset:1920
	ds_read_b64 v[186:187], v234 offset:1952
	ds_read_b64 v[188:189], v234 offset:1984
	ds_read_b64 v[190:191], v234 offset:2016
	s_waitcnt vmcnt(28)
	v_and_b32_e32 v144, v160, v235
	v_and_b32_e32 v145, v160, v236
	v_and_b32_e32 v146, v160, v237
	v_and_b32_e32 v147, v160, v238
	v_and_b32_e32 v148, v161, v235
	v_and_b32_e32 v149, v161, v236
	v_and_b32_e32 v150, v161, v237
	v_and_b32_e32 v151, v161, v238
	s_mov_b64 vcc, s[4:5]
	v_cndmask_b32_dpp v138, v64, v66, vcc row_shl:4 row_mask:0xf bank_mask:0xf bound_ctrl:1
	v_cndmask_b32_dpp v139, v65, v67, vcc row_shl:4 row_mask:0xf bank_mask:0xf bound_ctrl:1
	s_mov_b64 vcc, s[6:7]
	v_cndmask_b32_dpp v136, v66, v64, vcc row_shr:4 row_mask:0xf bank_mask:0xf bound_ctrl:1
	v_cndmask_b32_dpp v137, v67, v65, vcc row_shr:4 row_mask:0xf bank_mask:0xf bound_ctrl:1
	v_and_b32_e32 v204, v162, v235
	v_and_b32_e32 v205, v162, v236
	v_and_b32_e32 v206, v162, v237
	v_and_b32_e32 v207, v162, v238
	v_and_b32_e32 v208, v163, v235
	v_and_b32_e32 v209, v163, v236
	v_and_b32_e32 v210, v163, v237
	v_and_b32_e32 v211, v163, v238
	s_mov_b64 vcc, s[6:7]
	v_cndmask_b32_dpp v140, v70, v68, vcc row_shr:4 row_mask:0xf bank_mask:0xf bound_ctrl:1
	v_cndmask_b32_dpp v141, v71, v69, vcc row_shr:4 row_mask:0xf bank_mask:0xf bound_ctrl:1
	s_mov_b64 vcc, s[4:5]
	v_cndmask_b32_dpp v142, v68, v70, vcc row_shl:4 row_mask:0xf bank_mask:0xf bound_ctrl:1
	v_cndmask_b32_dpp v143, v69, v71, vcc row_shl:4 row_mask:0xf bank_mask:0xf bound_ctrl:1
	v_mfma_scale_f32_16x16x128_f8f6f4 v[216:219], v[136:139], v[144:151], 0, v240, v241 op_sel_hi:[0,0,0] cbsz:4
	v_and_b32_e32 v144, v164, v235
	v_and_b32_e32 v145, v164, v236
	v_and_b32_e32 v146, v164, v237
	v_and_b32_e32 v147, v164, v238
	v_and_b32_e32 v148, v165, v235
	v_and_b32_e32 v149, v165, v236
	v_and_b32_e32 v150, v165, v237
	v_and_b32_e32 v151, v165, v238
	s_mov_b64 vcc, s[4:5]
	v_cndmask_b32_dpp v138, v72, v74, vcc row_shl:4 row_mask:0xf bank_mask:0xf bound_ctrl:1
	v_cndmask_b32_dpp v139, v73, v75, vcc row_shl:4 row_mask:0xf bank_mask:0xf bound_ctrl:1
	s_mov_b64 vcc, s[6:7]
	v_cndmask_b32_dpp v136, v74, v72, vcc row_shr:4 row_mask:0xf bank_mask:0xf bound_ctrl:1
	v_cndmask_b32_dpp v137, v75, v73, vcc row_shr:4 row_mask:0xf bank_mask:0xf bound_ctrl:1
	v_mfma_scale_f32_16x16x128_f8f6f4 v[216:219], v[140:143], v[204:211], v[216:219], v240, v241 op_sel_hi:[0,0,0] cbsz:4
	v_and_b32_e32 v204, v166, v235
	v_and_b32_e32 v205, v166, v236
	v_and_b32_e32 v206, v166, v237
	v_and_b32_e32 v207, v166, v238
	v_and_b32_e32 v208, v167, v235
	v_and_b32_e32 v209, v167, v236
	v_and_b32_e32 v210, v167, v237
	v_and_b32_e32 v211, v167, v238
	s_mov_b64 vcc, s[6:7]
	v_cndmask_b32_dpp v140, v78, v76, vcc row_shr:4 row_mask:0xf bank_mask:0xf bound_ctrl:1
	v_cndmask_b32_dpp v141, v79, v77, vcc row_shr:4 row_mask:0xf bank_mask:0xf bound_ctrl:1
	s_mov_b64 vcc, s[4:5]
	v_cndmask_b32_dpp v142, v76, v78, vcc row_shl:4 row_mask:0xf bank_mask:0xf bound_ctrl:1
	v_cndmask_b32_dpp v143, v77, v79, vcc row_shl:4 row_mask:0xf bank_mask:0xf bound_ctrl:1
	v_mfma_scale_f32_16x16x128_f8f6f4 v[216:219], v[136:139], v[144:151], v[216:219], v240, v241 op_sel_hi:[0,0,0] cbsz:4
	v_and_b32_e32 v144, v168, v235
	v_and_b32_e32 v145, v168, v236
	v_and_b32_e32 v146, v168, v237
	v_and_b32_e32 v147, v168, v238
	v_and_b32_e32 v148, v169, v235
	v_and_b32_e32 v149, v169, v236
	v_and_b32_e32 v150, v169, v237
	v_and_b32_e32 v151, v169, v238
	s_mov_b64 vcc, s[4:5]
	v_cndmask_b32_dpp v138, v80, v82, vcc row_shl:4 row_mask:0xf bank_mask:0xf bound_ctrl:1
	v_cndmask_b32_dpp v139, v81, v83, vcc row_shl:4 row_mask:0xf bank_mask:0xf bound_ctrl:1
	s_mov_b64 vcc, s[6:7]
	v_cndmask_b32_dpp v136, v82, v80, vcc row_shr:4 row_mask:0xf bank_mask:0xf bound_ctrl:1
	v_cndmask_b32_dpp v137, v83, v81, vcc row_shr:4 row_mask:0xf bank_mask:0xf bound_ctrl:1
	v_mfma_scale_f32_16x16x128_f8f6f4 v[216:219], v[140:143], v[204:211], v[216:219], v240, v241 op_sel_hi:[0,0,0] cbsz:4
	v_and_b32_e32 v204, v170, v235
	v_and_b32_e32 v205, v170, v236
	v_and_b32_e32 v206, v170, v237
	v_and_b32_e32 v207, v170, v238
	v_and_b32_e32 v208, v171, v235
	v_and_b32_e32 v209, v171, v236
	v_and_b32_e32 v210, v171, v237
	v_and_b32_e32 v211, v171, v238
	s_mov_b64 vcc, s[6:7]
	v_cndmask_b32_dpp v140, v86, v84, vcc row_shr:4 row_mask:0xf bank_mask:0xf bound_ctrl:1
	v_cndmask_b32_dpp v141, v87, v85, vcc row_shr:4 row_mask:0xf bank_mask:0xf bound_ctrl:1
	s_mov_b64 vcc, s[4:5]
	v_cndmask_b32_dpp v142, v84, v86, vcc row_shl:4 row_mask:0xf bank_mask:0xf bound_ctrl:1
	v_cndmask_b32_dpp v143, v85, v87, vcc row_shl:4 row_mask:0xf bank_mask:0xf bound_ctrl:1
	v_mfma_scale_f32_16x16x128_f8f6f4 v[216:219], v[136:139], v[144:151], v[216:219], v240, v241 op_sel_hi:[0,0,0] cbsz:4
	v_and_b32_e32 v144, v172, v235
	v_and_b32_e32 v145, v172, v236
	v_and_b32_e32 v146, v172, v237
	v_and_b32_e32 v147, v172, v238
	v_and_b32_e32 v148, v173, v235
	v_and_b32_e32 v149, v173, v236
	v_and_b32_e32 v150, v173, v237
	v_and_b32_e32 v151, v173, v238
	s_mov_b64 vcc, s[4:5]
	v_cndmask_b32_dpp v138, v88, v90, vcc row_shl:4 row_mask:0xf bank_mask:0xf bound_ctrl:1
	v_cndmask_b32_dpp v139, v89, v91, vcc row_shl:4 row_mask:0xf bank_mask:0xf bound_ctrl:1
	s_mov_b64 vcc, s[6:7]
	v_cndmask_b32_dpp v136, v90, v88, vcc row_shr:4 row_mask:0xf bank_mask:0xf bound_ctrl:1
	v_cndmask_b32_dpp v137, v91, v89, vcc row_shr:4 row_mask:0xf bank_mask:0xf bound_ctrl:1
	v_mfma_scale_f32_16x16x128_f8f6f4 v[216:219], v[140:143], v[204:211], v[216:219], v240, v241 op_sel_hi:[0,0,0] cbsz:4
	v_and_b32_e32 v204, v174, v235
	v_and_b32_e32 v205, v174, v236
	v_and_b32_e32 v206, v174, v237
	v_and_b32_e32 v207, v174, v238
	v_and_b32_e32 v208, v175, v235
	v_and_b32_e32 v209, v175, v236
	v_and_b32_e32 v210, v175, v237
	v_and_b32_e32 v211, v175, v238
	s_mov_b64 vcc, s[6:7]
	v_cndmask_b32_dpp v140, v94, v92, vcc row_shr:4 row_mask:0xf bank_mask:0xf bound_ctrl:1
	v_cndmask_b32_dpp v141, v95, v93, vcc row_shr:4 row_mask:0xf bank_mask:0xf bound_ctrl:1
	s_mov_b64 vcc, s[4:5]
	v_cndmask_b32_dpp v142, v92, v94, vcc row_shl:4 row_mask:0xf bank_mask:0xf bound_ctrl:1
	v_cndmask_b32_dpp v143, v93, v95, vcc row_shl:4 row_mask:0xf bank_mask:0xf bound_ctrl:1
	v_mfma_scale_f32_16x16x128_f8f6f4 v[216:219], v[136:139], v[144:151], v[216:219], v240, v241 op_sel_hi:[0,0,0] cbsz:4
	s_nop 0
	v_mfma_scale_f32_16x16x128_f8f6f4 v[216:219], v[140:143], v[204:211], v[216:219], v240, v241 op_sel_hi:[0,0,0] cbsz:4
	s_waitcnt lgkmcnt(0)
	v_lshl_or_b32 v128, v128, 7, v232
	v_lshl_or_b32 v129, v129, 7, v232
	v_lshl_or_b32 v130, v130, 7, v232
	v_lshl_or_b32 v131, v131, 7, v232
	v_lshl_or_b32 v132, v132, 7, v232
	v_lshl_or_b32 v133, v133, 7, v232
	v_lshl_or_b32 v134, v134, 7, v232
	v_lshl_or_b32 v135, v135, 7, v232
	buffer_load_dwordx4 v[64:67], v128, s[20:23], s1 offen
	buffer_load_dwordx4 v[68:71], v129, s[20:23], s1 offen
	buffer_load_dwordx4 v[72:75], v130, s[20:23], s1 offen
	buffer_load_dwordx4 v[76:79], v131, s[20:23], s1 offen
	buffer_load_dwordx4 v[80:83], v132, s[20:23], s1 offen
	buffer_load_dwordx4 v[84:87], v133, s[20:23], s1 offen
	buffer_load_dwordx4 v[88:91], v134, s[20:23], s1 offen
	buffer_load_dwordx4 v[92:95], v135, s[20:23], s1 offen
	ds_read_b32 v128, v243 offset:2816
	ds_read_b32 v129, v243 offset:2848
	ds_read_b32 v130, v243 offset:2880
	ds_read_b32 v131, v243 offset:2912
	ds_read_b32 v132, v243 offset:2944
	ds_read_b32 v133, v243 offset:2976
	ds_read_b32 v134, v243 offset:3008
	ds_read_b32 v135, v243 offset:3040
	ds_read_b64 v[160:161], v234 offset:2048
	ds_read_b64 v[162:163], v234 offset:2080
	ds_read_b64 v[164:165], v234 offset:2112
	ds_read_b64 v[166:167], v234 offset:2144
	ds_read_b64 v[168:169], v234 offset:2176
	ds_read_b64 v[170:171], v234 offset:2208
	ds_read_b64 v[172:173], v234 offset:2240
	ds_read_b64 v[174:175], v234 offset:2272
	s_waitcnt vmcnt(26)
	v_and_b32_e32 v144, v176, v235
	v_and_b32_e32 v145, v176, v236
	v_and_b32_e32 v146, v176, v237
	v_and_b32_e32 v147, v176, v238
	v_and_b32_e32 v148, v177, v235
	v_and_b32_e32 v149, v177, v236
	v_and_b32_e32 v150, v177, v237
	v_and_b32_e32 v151, v177, v238
	s_mov_b64 vcc, s[4:5]
	v_cndmask_b32_dpp v138, v96, v98, vcc row_shl:4 row_mask:0xf bank_mask:0xf bound_ctrl:1
	v_cndmask_b32_dpp v139, v97, v99, vcc row_shl:4 row_mask:0xf bank_mask:0xf bound_ctrl:1
	s_mov_b64 vcc, s[6:7]
	v_cndmask_b32_dpp v136, v98, v96, vcc row_shr:4 row_mask:0xf bank_mask:0xf bound_ctrl:1
	v_cndmask_b32_dpp v137, v99, v97, vcc row_shr:4 row_mask:0xf bank_mask:0xf bound_ctrl:1
	v_and_b32_e32 v204, v178, v235
	v_and_b32_e32 v205, v178, v236
	v_and_b32_e32 v206, v178, v237
	v_and_b32_e32 v207, v178, v238
	v_and_b32_e32 v208, v179, v235
	v_and_b32_e32 v209, v179, v236
	v_and_b32_e32 v210, v179, v237
	v_and_b32_e32 v211, v179, v238
	s_mov_b64 vcc, s[6:7]
	v_cndmask_b32_dpp v140, v102, v100, vcc row_shr:4 row_mask:0xf bank_mask:0xf bound_ctrl:1
	v_cndmask_b32_dpp v141, v103, v101, vcc row_shr:4 row_mask:0xf bank_mask:0xf bound_ctrl:1
	s_mov_b64 vcc, s[4:5]
	v_cndmask_b32_dpp v142, v100, v102, vcc row_shl:4 row_mask:0xf bank_mask:0xf bound_ctrl:1
	v_cndmask_b32_dpp v143, v101, v103, vcc row_shl:4 row_mask:0xf bank_mask:0xf bound_ctrl:1
	v_mfma_scale_f32_16x16x128_f8f6f4 v[216:219], v[136:139], v[144:151], v[216:219], v240, v241 op_sel_hi:[0,0,0] cbsz:4
	v_permlane16_swap_b32_e32 v212, v214
	v_permlane16_swap_b32_e32 v213, v215
	v_lshlrev_b32_e32 v252, 16, v228
	v_and_b32_e32 v144, v180, v235
	v_and_b32_e32 v145, v180, v236
	v_and_b32_e32 v146, v180, v237
	v_and_b32_e32 v147, v180, v238
	v_and_b32_e32 v148, v181, v235
	v_and_b32_e32 v149, v181, v236
	v_and_b32_e32 v150, v181, v237
	v_and_b32_e32 v151, v181, v238
	s_mov_b64 vcc, s[4:5]
	v_cndmask_b32_dpp v138, v104, v106, vcc row_shl:4 row_mask:0xf bank_mask:0xf bound_ctrl:1
	v_cndmask_b32_dpp v139, v105, v107, vcc row_shl:4 row_mask:0xf bank_mask:0xf bound_ctrl:1
	s_mov_b64 vcc, s[6:7]
	v_cndmask_b32_dpp v136, v106, v104, vcc row_shr:4 row_mask:0xf bank_mask:0xf bound_ctrl:1
	v_cndmask_b32_dpp v137, v107, v105, vcc row_shr:4 row_mask:0xf bank_mask:0xf bound_ctrl:1
	v_mfma_scale_f32_16x16x128_f8f6f4 v[216:219], v[140:143], v[204:211], v[216:219], v240, v241 op_sel_hi:[0,0,0] cbsz:4
	v_and_b32_e32 v253, 0xffff0000, v228
	v_lshlrev_b32_e32 v254, 16, v229
	v_and_b32_e32 v255, 0xffff0000, v229
	v_and_b32_e32 v204, v182, v235
	v_and_b32_e32 v205, v182, v236
	v_and_b32_e32 v206, v182, v237
	v_and_b32_e32 v207, v182, v238
	v_and_b32_e32 v208, v183, v235
	v_and_b32_e32 v209, v183, v236
	v_and_b32_e32 v210, v183, v237
	v_and_b32_e32 v211, v183, v238
	s_mov_b64 vcc, s[6:7]
	v_cndmask_b32_dpp v140, v110, v108, vcc row_shr:4 row_mask:0xf bank_mask:0xf bound_ctrl:1
	v_cndmask_b32_dpp v141, v111, v109, vcc row_shr:4 row_mask:0xf bank_mask:0xf bound_ctrl:1
	s_mov_b64 vcc, s[4:5]
	v_cndmask_b32_dpp v142, v108, v110, vcc row_shl:4 row_mask:0xf bank_mask:0xf bound_ctrl:1
	v_cndmask_b32_dpp v143, v109, v111, vcc row_shl:4 row_mask:0xf bank_mask:0xf bound_ctrl:1
	v_mfma_scale_f32_16x16x128_f8f6f4 v[216:219], v[136:139], v[144:151], v[216:219], v240, v241 op_sel_hi:[0,0,0] cbsz:4
	v_add_f32_e32 v252, v212, v252
	v_add_f32_e32 v253, v214, v253
	v_add_f32_e32 v254, v213, v254
	v_and_b32_e32 v144, v184, v235
	v_and_b32_e32 v145, v184, v236
	v_and_b32_e32 v146, v184, v237
	v_and_b32_e32 v147, v184, v238
	v_and_b32_e32 v148, v185, v235
	v_and_b32_e32 v149, v185, v236
	v_and_b32_e32 v150, v185, v237
	v_and_b32_e32 v151, v185, v238
	s_mov_b64 vcc, s[4:5]
	v_cndmask_b32_dpp v138, v112, v114, vcc row_shl:4 row_mask:0xf bank_mask:0xf bound_ctrl:1
	v_cndmask_b32_dpp v139, v113, v115, vcc row_shl:4 row_mask:0xf bank_mask:0xf bound_ctrl:1
	s_mov_b64 vcc, s[6:7]
	v_cndmask_b32_dpp v136, v114, v112, vcc row_shr:4 row_mask:0xf bank_mask:0xf bound_ctrl:1
	v_cndmask_b32_dpp v137, v115, v113, vcc row_shr:4 row_mask:0xf bank_mask:0xf bound_ctrl:1
	v_mfma_scale_f32_16x16x128_f8f6f4 v[216:219], v[140:143], v[204:211], v[216:219], v240, v241 op_sel_hi:[0,0,0] cbsz:4
	v_add_f32_e32 v255, v215, v255
	v_mul_f32_e32 v192, v252, v252
	v_mul_f32_e32 v193, v254, v254
	v_and_b32_e32 v204, v186, v235
	v_and_b32_e32 v205, v186, v236
	v_and_b32_e32 v206, v186, v237
	v_and_b32_e32 v207, v186, v238
	v_and_b32_e32 v208, v187, v235
	v_and_b32_e32 v209, v187, v236
	v_and_b32_e32 v210, v187, v237
	v_and_b32_e32 v211, v187, v238
	s_mov_b64 vcc, s[6:7]
	v_cndmask_b32_dpp v140, v118, v116, vcc row_shr:4 row_mask:0xf bank_mask:0xf bound_ctrl:1
	v_cndmask_b32_dpp v141, v119, v117, vcc row_shr:4 row_mask:0xf bank_mask:0xf bound_ctrl:1
	s_mov_b64 vcc, s[4:5]
	v_cndmask_b32_dpp v142, v116, v118, vcc row_shl:4 row_mask:0xf bank_mask:0xf bound_ctrl:1
	v_cndmask_b32_dpp v143, v117, v119, vcc row_shl:4 row_mask:0xf bank_mask:0xf bound_ctrl:1
	v_mfma_scale_f32_16x16x128_f8f6f4 v[216:219], v[136:139], v[144:151], v[216:219], v240, v241 op_sel_hi:[0,0,0] cbsz:4
	v_fmac_f32_e32 v192, v253, v253
	v_fmac_f32_e32 v193, v255, v255
	v_cvt_pk_bf16_f32 v250, v252, v253
	v_and_b32_e32 v144, v188, v235
	v_and_b32_e32 v145, v188, v236
	v_and_b32_e32 v146, v188, v237
	v_and_b32_e32 v147, v188, v238
	v_and_b32_e32 v148, v189, v235
	v_and_b32_e32 v149, v189, v236
	v_and_b32_e32 v150, v189, v237
	v_and_b32_e32 v151, v189, v238
	s_mov_b64 vcc, s[4:5]
	v_cndmask_b32_dpp v138, v120, v122, vcc row_shl:4 row_mask:0xf bank_mask:0xf bound_ctrl:1
	v_cndmask_b32_dpp v139, v121, v123, vcc row_shl:4 row_mask:0xf bank_mask:0xf bound_ctrl:1
	s_mov_b64 vcc, s[6:7]
	v_cndmask_b32_dpp v136, v122, v120, vcc row_shr:4 row_mask:0xf bank_mask:0xf bound_ctrl:1
	v_cndmask_b32_dpp v137, v123, v121, vcc row_shr:4 row_mask:0xf bank_mask:0xf bound_ctrl:1
	v_mfma_scale_f32_16x16x128_f8f6f4 v[216:219], v[140:143], v[204:211], v[216:219], v240, v241 op_sel_hi:[0,0,0] cbsz:4
	v_cvt_pk_bf16_f32 v251, v254, v255
	v_add_f32_e32 v192, v192, v193
	v_add_f32_e32 v222, v222, v192
	v_and_b32_e32 v204, v190, v235
	v_and_b32_e32 v205, v190, v236
	v_and_b32_e32 v206, v190, v237
	v_and_b32_e32 v207, v190, v238
	v_and_b32_e32 v208, v191, v235
	v_and_b32_e32 v209, v191, v236
	v_and_b32_e32 v210, v191, v237
	v_and_b32_e32 v211, v191, v238
	s_mov_b64 vcc, s[6:7]
	v_cndmask_b32_dpp v140, v126, v124, vcc row_shr:4 row_mask:0xf bank_mask:0xf bound_ctrl:1
	v_cndmask_b32_dpp v141, v127, v125, vcc row_shr:4 row_mask:0xf bank_mask:0xf bound_ctrl:1
	s_mov_b64 vcc, s[4:5]
	v_cndmask_b32_dpp v142, v124, v126, vcc row_shl:4 row_mask:0xf bank_mask:0xf bound_ctrl:1
	v_cndmask_b32_dpp v143, v125, v127, vcc row_shl:4 row_mask:0xf bank_mask:0xf bound_ctrl:1
	v_mfma_scale_f32_16x16x128_f8f6f4 v[216:219], v[136:139], v[144:151], v[216:219], v240, v241 op_sel_hi:[0,0,0] cbsz:4
	s_nop 0
	v_mfma_scale_f32_16x16x128_f8f6f4 v[216:219], v[140:143], v[204:211], v[216:219], v240, v241 op_sel_hi:[0,0,0] cbsz:4
	s_lshl_b32 s64, s0, 9
	s_add_u32 s64, s64, 0x2000
	s_add_u32 s76, s28, s64
	s_addc_u32 s77, s29, 0
	global_store_dwordx2 v239, v[250:251], s[76:77]
	s_lshl_b32 s64, s0, 9
	s_add_u32 s64, s64, 0x4000
	s_add_u32 s70, s28, s64
	s_addc_u32 s71, s29, 0
	global_load_dwordx2 v[228:229], v239, s[70:71] nt
	s_waitcnt lgkmcnt(0)
	v_lshl_or_b32 v128, v128, 7, v232
	v_lshl_or_b32 v129, v129, 7, v232
	v_lshl_or_b32 v130, v130, 7, v232
	v_lshl_or_b32 v131, v131, 7, v232
	v_lshl_or_b32 v132, v132, 7, v232
	v_lshl_or_b32 v133, v133, 7, v232
	v_lshl_or_b32 v134, v134, 7, v232
	v_lshl_or_b32 v135, v135, 7, v232
	buffer_load_dwordx4 v[96:99], v128, s[20:23], s1 offen
	buffer_load_dwordx4 v[100:103], v129, s[20:23], s1 offen
	buffer_load_dwordx4 v[104:107], v130, s[20:23], s1 offen
	buffer_load_dwordx4 v[108:111], v131, s[20:23], s1 offen
	buffer_load_dwordx4 v[112:115], v132, s[20:23], s1 offen
	buffer_load_dwordx4 v[116:119], v133, s[20:23], s1 offen
	buffer_load_dwordx4 v[120:123], v134, s[20:23], s1 offen
	buffer_load_dwordx4 v[124:127], v135, s[20:23], s1 offen
	ds_read_b32 v128, v243 offset:3072
	ds_read_b32 v129, v243 offset:3104
	ds_read_b32 v130, v243 offset:3136
	ds_read_b32 v131, v243 offset:3168
	ds_read_b32 v132, v243 offset:3200
	ds_read_b32 v133, v243 offset:3232
	ds_read_b32 v134, v243 offset:3264
	ds_read_b32 v135, v243 offset:3296
	ds_read_b64 v[176:177], v234 offset:2304
	ds_read_b64 v[178:179], v234 offset:2336
	ds_read_b64 v[180:181], v234 offset:2368
	ds_read_b64 v[182:183], v234 offset:2400
	ds_read_b64 v[184:185], v234 offset:2432
	ds_read_b64 v[186:187], v234 offset:2464
	ds_read_b64 v[188:189], v234 offset:2496
	ds_read_b64 v[190:191], v234 offset:2528
	s_waitcnt vmcnt(28)
	v_and_b32_e32 v144, v160, v235
	v_and_b32_e32 v145, v160, v236
	v_and_b32_e32 v146, v160, v237
	v_and_b32_e32 v147, v160, v238
	v_and_b32_e32 v148, v161, v235
	v_and_b32_e32 v149, v161, v236
	v_and_b32_e32 v150, v161, v237
	v_and_b32_e32 v151, v161, v238
	s_mov_b64 vcc, s[4:5]
	v_cndmask_b32_dpp v138, v0, v2, vcc row_shl:4 row_mask:0xf bank_mask:0xf bound_ctrl:1
	v_cndmask_b32_dpp v139, v1, v3, vcc row_shl:4 row_mask:0xf bank_mask:0xf bound_ctrl:1
	s_mov_b64 vcc, s[6:7]
	v_cndmask_b32_dpp v136, v2, v0, vcc row_shr:4 row_mask:0xf bank_mask:0xf bound_ctrl:1
	v_cndmask_b32_dpp v137, v3, v1, vcc row_shr:4 row_mask:0xf bank_mask:0xf bound_ctrl:1
	v_and_b32_e32 v204, v162, v235
	v_and_b32_e32 v205, v162, v236
	v_and_b32_e32 v206, v162, v237
	v_and_b32_e32 v207, v162, v238
	v_and_b32_e32 v208, v163, v235
	v_and_b32_e32 v209, v163, v236
	v_and_b32_e32 v210, v163, v237
	v_and_b32_e32 v211, v163, v238
	s_mov_b64 vcc, s[6:7]
	v_cndmask_b32_dpp v140, v6, v4, vcc row_shr:4 row_mask:0xf bank_mask:0xf bound_ctrl:1
	v_cndmask_b32_dpp v141, v7, v5, vcc row_shr:4 row_mask:0xf bank_mask:0xf bound_ctrl:1
	s_mov_b64 vcc, s[4:5]
	v_cndmask_b32_dpp v142, v4, v6, vcc row_shl:4 row_mask:0xf bank_mask:0xf bound_ctrl:1
	v_cndmask_b32_dpp v143, v5, v7, vcc row_shl:4 row_mask:0xf bank_mask:0xf bound_ctrl:1
	v_mfma_scale_f32_16x16x128_f8f6f4 v[212:215], v[136:139], v[144:151], 0, v240, v241 op_sel_hi:[0,0,0] cbsz:4
	v_and_b32_e32 v144, v164, v235
	v_and_b32_e32 v145, v164, v236
	v_and_b32_e32 v146, v164, v237
	v_and_b32_e32 v147, v164, v238
	v_and_b32_e32 v148, v165, v235
	v_and_b32_e32 v149, v165, v236
	v_and_b32_e32 v150, v165, v237
	v_and_b32_e32 v151, v165, v238
	s_mov_b64 vcc, s[4:5]
	v_cndmask_b32_dpp v138, v8, v10, vcc row_shl:4 row_mask:0xf bank_mask:0xf bound_ctrl:1
	v_cndmask_b32_dpp v139, v9, v11, vcc row_shl:4 row_mask:0xf bank_mask:0xf bound_ctrl:1
	s_mov_b64 vcc, s[6:7]
	v_cndmask_b32_dpp v136, v10, v8, vcc row_shr:4 row_mask:0xf bank_mask:0xf bound_ctrl:1
	v_cndmask_b32_dpp v137, v11, v9, vcc row_shr:4 row_mask:0xf bank_mask:0xf bound_ctrl:1
	v_mfma_scale_f32_16x16x128_f8f6f4 v[212:215], v[140:143], v[204:211], v[212:215], v240, v241 op_sel_hi:[0,0,0] cbsz:4
	v_and_b32_e32 v204, v166, v235
	v_and_b32_e32 v205, v166, v236
	v_and_b32_e32 v206, v166, v237
	v_and_b32_e32 v207, v166, v238
	v_and_b32_e32 v208, v167, v235
	v_and_b32_e32 v209, v167, v236
	v_and_b32_e32 v210, v167, v237
	v_and_b32_e32 v211, v167, v238
	s_mov_b64 vcc, s[6:7]
	v_cndmask_b32_dpp v140, v14, v12, vcc row_shr:4 row_mask:0xf bank_mask:0xf bound_ctrl:1
	v_cndmask_b32_dpp v141, v15, v13, vcc row_shr:4 row_mask:0xf bank_mask:0xf bound_ctrl:1
	s_mov_b64 vcc, s[4:5]
	v_cndmask_b32_dpp v142, v12, v14, vcc row_shl:4 row_mask:0xf bank_mask:0xf bound_ctrl:1
	v_cndmask_b32_dpp v143, v13, v15, vcc row_shl:4 row_mask:0xf bank_mask:0xf bound_ctrl:1
	v_mfma_scale_f32_16x16x128_f8f6f4 v[212:215], v[136:139], v[144:151], v[212:215], v240, v241 op_sel_hi:[0,0,0] cbsz:4
	v_and_b32_e32 v144, v168, v235
	v_and_b32_e32 v145, v168, v236
	v_and_b32_e32 v146, v168, v237
	v_and_b32_e32 v147, v168, v238
	v_and_b32_e32 v148, v169, v235
	v_and_b32_e32 v149, v169, v236
	v_and_b32_e32 v150, v169, v237
	v_and_b32_e32 v151, v169, v238
	s_mov_b64 vcc, s[4:5]
	v_cndmask_b32_dpp v138, v16, v18, vcc row_shl:4 row_mask:0xf bank_mask:0xf bound_ctrl:1
	v_cndmask_b32_dpp v139, v17, v19, vcc row_shl:4 row_mask:0xf bank_mask:0xf bound_ctrl:1
	s_mov_b64 vcc, s[6:7]
	v_cndmask_b32_dpp v136, v18, v16, vcc row_shr:4 row_mask:0xf bank_mask:0xf bound_ctrl:1
	v_cndmask_b32_dpp v137, v19, v17, vcc row_shr:4 row_mask:0xf bank_mask:0xf bound_ctrl:1
	v_mfma_scale_f32_16x16x128_f8f6f4 v[212:215], v[140:143], v[204:211], v[212:215], v240, v241 op_sel_hi:[0,0,0] cbsz:4
	v_and_b32_e32 v204, v170, v235
	v_and_b32_e32 v205, v170, v236
	v_and_b32_e32 v206, v170, v237
	v_and_b32_e32 v207, v170, v238
	v_and_b32_e32 v208, v171, v235
	v_and_b32_e32 v209, v171, v236
	v_and_b32_e32 v210, v171, v237
	v_and_b32_e32 v211, v171, v238
	s_mov_b64 vcc, s[6:7]
	v_cndmask_b32_dpp v140, v22, v20, vcc row_shr:4 row_mask:0xf bank_mask:0xf bound_ctrl:1
	v_cndmask_b32_dpp v141, v23, v21, vcc row_shr:4 row_mask:0xf bank_mask:0xf bound_ctrl:1
	s_mov_b64 vcc, s[4:5]
	v_cndmask_b32_dpp v142, v20, v22, vcc row_shl:4 row_mask:0xf bank_mask:0xf bound_ctrl:1
	v_cndmask_b32_dpp v143, v21, v23, vcc row_shl:4 row_mask:0xf bank_mask:0xf bound_ctrl:1
	v_mfma_scale_f32_16x16x128_f8f6f4 v[212:215], v[136:139], v[144:151], v[212:215], v240, v241 op_sel_hi:[0,0,0] cbsz:4
	v_and_b32_e32 v144, v172, v235
	v_and_b32_e32 v145, v172, v236
	v_and_b32_e32 v146, v172, v237
	v_and_b32_e32 v147, v172, v238
	v_and_b32_e32 v148, v173, v235
	v_and_b32_e32 v149, v173, v236
	v_and_b32_e32 v150, v173, v237
	v_and_b32_e32 v151, v173, v238
	s_mov_b64 vcc, s[4:5]
	v_cndmask_b32_dpp v138, v24, v26, vcc row_shl:4 row_mask:0xf bank_mask:0xf bound_ctrl:1
	v_cndmask_b32_dpp v139, v25, v27, vcc row_shl:4 row_mask:0xf bank_mask:0xf bound_ctrl:1
	s_mov_b64 vcc, s[6:7]
	v_cndmask_b32_dpp v136, v26, v24, vcc row_shr:4 row_mask:0xf bank_mask:0xf bound_ctrl:1
	v_cndmask_b32_dpp v137, v27, v25, vcc row_shr:4 row_mask:0xf bank_mask:0xf bound_ctrl:1
	v_mfma_scale_f32_16x16x128_f8f6f4 v[212:215], v[140:143], v[204:211], v[212:215], v240, v241 op_sel_hi:[0,0,0] cbsz:4
	v_and_b32_e32 v204, v174, v235
	v_and_b32_e32 v205, v174, v236
	v_and_b32_e32 v206, v174, v237
	v_and_b32_e32 v207, v174, v238
	v_and_b32_e32 v208, v175, v235
	v_and_b32_e32 v209, v175, v236
	v_and_b32_e32 v210, v175, v237
	v_and_b32_e32 v211, v175, v238
	s_mov_b64 vcc, s[6:7]
	v_cndmask_b32_dpp v140, v30, v28, vcc row_shr:4 row_mask:0xf bank_mask:0xf bound_ctrl:1
	v_cndmask_b32_dpp v141, v31, v29, vcc row_shr:4 row_mask:0xf bank_mask:0xf bound_ctrl:1
	s_mov_b64 vcc, s[4:5]
	v_cndmask_b32_dpp v142, v28, v30, vcc row_shl:4 row_mask:0xf bank_mask:0xf bound_ctrl:1
	v_cndmask_b32_dpp v143, v29, v31, vcc row_shl:4 row_mask:0xf bank_mask:0xf bound_ctrl:1
	v_mfma_scale_f32_16x16x128_f8f6f4 v[212:215], v[136:139], v[144:151], v[212:215], v240, v241 op_sel_hi:[0,0,0] cbsz:4
	s_nop 0
	v_mfma_scale_f32_16x16x128_f8f6f4 v[212:215], v[140:143], v[204:211], v[212:215], v240, v241 op_sel_hi:[0,0,0] cbsz:4
	s_waitcnt lgkmcnt(0)
	v_lshl_or_b32 v128, v128, 7, v232
	v_lshl_or_b32 v129, v129, 7, v232
	v_lshl_or_b32 v130, v130, 7, v232
	v_lshl_or_b32 v131, v131, 7, v232
	v_lshl_or_b32 v132, v132, 7, v232
	v_lshl_or_b32 v133, v133, 7, v232
	v_lshl_or_b32 v134, v134, 7, v232
	v_lshl_or_b32 v135, v135, 7, v232
	buffer_load_dwordx4 v[0:3], v128, s[20:23], s1 offen
	buffer_load_dwordx4 v[4:7], v129, s[20:23], s1 offen
	buffer_load_dwordx4 v[8:11], v130, s[20:23], s1 offen
	buffer_load_dwordx4 v[12:15], v131, s[20:23], s1 offen
	buffer_load_dwordx4 v[16:19], v132, s[20:23], s1 offen
	buffer_load_dwordx4 v[20:23], v133, s[20:23], s1 offen
	buffer_load_dwordx4 v[24:27], v134, s[20:23], s1 offen
	buffer_load_dwordx4 v[28:31], v135, s[20:23], s1 offen
	ds_read_b32 v128, v243 offset:3328
	ds_read_b32 v129, v243 offset:3360
	ds_read_b32 v130, v243 offset:3392
	ds_read_b32 v131, v243 offset:3424
	ds_read_b32 v132, v243 offset:3456
	ds_read_b32 v133, v243 offset:3488
	ds_read_b32 v134, v243 offset:3520
	ds_read_b32 v135, v243 offset:3552
	ds_read_b64 v[160:161], v234 offset:2560
	ds_read_b64 v[162:163], v234 offset:2592
	ds_read_b64 v[164:165], v234 offset:2624
	ds_read_b64 v[166:167], v234 offset:2656
	ds_read_b64 v[168:169], v234 offset:2688
	ds_read_b64 v[170:171], v234 offset:2720
	ds_read_b64 v[172:173], v234 offset:2752
	ds_read_b64 v[174:175], v234 offset:2784
	s_waitcnt vmcnt(26)
	v_and_b32_e32 v144, v176, v235
	v_and_b32_e32 v145, v176, v236
	v_and_b32_e32 v146, v176, v237
	v_and_b32_e32 v147, v176, v238
	v_and_b32_e32 v148, v177, v235
	v_and_b32_e32 v149, v177, v236
	v_and_b32_e32 v150, v177, v237
	v_and_b32_e32 v151, v177, v238
	s_mov_b64 vcc, s[4:5]
	v_cndmask_b32_dpp v138, v32, v34, vcc row_shl:4 row_mask:0xf bank_mask:0xf bound_ctrl:1
	v_cndmask_b32_dpp v139, v33, v35, vcc row_shl:4 row_mask:0xf bank_mask:0xf bound_ctrl:1
	s_mov_b64 vcc, s[6:7]
	v_cndmask_b32_dpp v136, v34, v32, vcc row_shr:4 row_mask:0xf bank_mask:0xf bound_ctrl:1
	v_cndmask_b32_dpp v137, v35, v33, vcc row_shr:4 row_mask:0xf bank_mask:0xf bound_ctrl:1
	v_and_b32_e32 v204, v178, v235
	v_and_b32_e32 v205, v178, v236
	v_and_b32_e32 v206, v178, v237
	v_and_b32_e32 v207, v178, v238
	v_and_b32_e32 v208, v179, v235
	v_and_b32_e32 v209, v179, v236
	v_and_b32_e32 v210, v179, v237
	v_and_b32_e32 v211, v179, v238
	s_mov_b64 vcc, s[6:7]
	v_cndmask_b32_dpp v140, v38, v36, vcc row_shr:4 row_mask:0xf bank_mask:0xf bound_ctrl:1
	v_cndmask_b32_dpp v141, v39, v37, vcc row_shr:4 row_mask:0xf bank_mask:0xf bound_ctrl:1
	s_mov_b64 vcc, s[4:5]
	v_cndmask_b32_dpp v142, v36, v38, vcc row_shl:4 row_mask:0xf bank_mask:0xf bound_ctrl:1
	v_cndmask_b32_dpp v143, v37, v39, vcc row_shl:4 row_mask:0xf bank_mask:0xf bound_ctrl:1
	v_mfma_scale_f32_16x16x128_f8f6f4 v[212:215], v[136:139], v[144:151], v[212:215], v240, v241 op_sel_hi:[0,0,0] cbsz:4
	v_permlane16_swap_b32_e32 v216, v218
	v_permlane16_swap_b32_e32 v217, v219
	v_lshlrev_b32_e32 v252, 16, v230
	v_and_b32_e32 v144, v180, v235
	v_and_b32_e32 v145, v180, v236
	v_and_b32_e32 v146, v180, v237
	v_and_b32_e32 v147, v180, v238
	v_and_b32_e32 v148, v181, v235
	v_and_b32_e32 v149, v181, v236
	v_and_b32_e32 v150, v181, v237
	v_and_b32_e32 v151, v181, v238
	s_mov_b64 vcc, s[4:5]
	v_cndmask_b32_dpp v138, v40, v42, vcc row_shl:4 row_mask:0xf bank_mask:0xf bound_ctrl:1
	v_cndmask_b32_dpp v139, v41, v43, vcc row_shl:4 row_mask:0xf bank_mask:0xf bound_ctrl:1
	s_mov_b64 vcc, s[6:7]
	v_cndmask_b32_dpp v136, v42, v40, vcc row_shr:4 row_mask:0xf bank_mask:0xf bound_ctrl:1
	v_cndmask_b32_dpp v137, v43, v41, vcc row_shr:4 row_mask:0xf bank_mask:0xf bound_ctrl:1
	v_mfma_scale_f32_16x16x128_f8f6f4 v[212:215], v[140:143], v[204:211], v[212:215], v240, v241 op_sel_hi:[0,0,0] cbsz:4
	v_and_b32_e32 v253, 0xffff0000, v230
	v_lshlrev_b32_e32 v254, 16, v231
	v_and_b32_e32 v255, 0xffff0000, v231
	v_and_b32_e32 v204, v182, v235
	v_and_b32_e32 v205, v182, v236
	v_and_b32_e32 v206, v182, v237
	v_and_b32_e32 v207, v182, v238
	v_and_b32_e32 v208, v183, v235
	v_and_b32_e32 v209, v183, v236
	v_and_b32_e32 v210, v183, v237
	v_and_b32_e32 v211, v183, v238
	s_mov_b64 vcc, s[6:7]
	v_cndmask_b32_dpp v140, v46, v44, vcc row_shr:4 row_mask:0xf bank_mask:0xf bound_ctrl:1
	v_cndmask_b32_dpp v141, v47, v45, vcc row_shr:4 row_mask:0xf bank_mask:0xf bound_ctrl:1
	s_mov_b64 vcc, s[4:5]
	v_cndmask_b32_dpp v142, v44, v46, vcc row_shl:4 row_mask:0xf bank_mask:0xf bound_ctrl:1
	v_cndmask_b32_dpp v143, v45, v47, vcc row_shl:4 row_mask:0xf bank_mask:0xf bound_ctrl:1
	v_mfma_scale_f32_16x16x128_f8f6f4 v[212:215], v[136:139], v[144:151], v[212:215], v240, v241 op_sel_hi:[0,0,0] cbsz:4
	v_add_f32_e32 v252, v216, v252
	v_add_f32_e32 v253, v218, v253
	v_add_f32_e32 v254, v217, v254
	v_and_b32_e32 v144, v184, v235
	v_and_b32_e32 v145, v184, v236
	v_and_b32_e32 v146, v184, v237
	v_and_b32_e32 v147, v184, v238
	v_and_b32_e32 v148, v185, v235
	v_and_b32_e32 v149, v185, v236
	v_and_b32_e32 v150, v185, v237
	v_and_b32_e32 v151, v185, v238
	s_mov_b64 vcc, s[4:5]
	v_cndmask_b32_dpp v138, v48, v50, vcc row_shl:4 row_mask:0xf bank_mask:0xf bound_ctrl:1
	v_cndmask_b32_dpp v139, v49, v51, vcc row_shl:4 row_mask:0xf bank_mask:0xf bound_ctrl:1
	s_mov_b64 vcc, s[6:7]
	v_cndmask_b32_dpp v136, v50, v48, vcc row_shr:4 row_mask:0xf bank_mask:0xf bound_ctrl:1
	v_cndmask_b32_dpp v137, v51, v49, vcc row_shr:4 row_mask:0xf bank_mask:0xf bound_ctrl:1
	v_mfma_scale_f32_16x16x128_f8f6f4 v[212:215], v[140:143], v[204:211], v[212:215], v240, v241 op_sel_hi:[0,0,0] cbsz:4
	v_add_f32_e32 v255, v219, v255
	v_mul_f32_e32 v192, v252, v252
	v_mul_f32_e32 v193, v254, v254
	v_and_b32_e32 v204, v186, v235
	v_and_b32_e32 v205, v186, v236
	v_and_b32_e32 v206, v186, v237
	v_and_b32_e32 v207, v186, v238
	v_and_b32_e32 v208, v187, v235
	v_and_b32_e32 v209, v187, v236
	v_and_b32_e32 v210, v187, v237
	v_and_b32_e32 v211, v187, v238
	s_mov_b64 vcc, s[6:7]
	v_cndmask_b32_dpp v140, v54, v52, vcc row_shr:4 row_mask:0xf bank_mask:0xf bound_ctrl:1
	v_cndmask_b32_dpp v141, v55, v53, vcc row_shr:4 row_mask:0xf bank_mask:0xf bound_ctrl:1
	s_mov_b64 vcc, s[4:5]
	v_cndmask_b32_dpp v142, v52, v54, vcc row_shl:4 row_mask:0xf bank_mask:0xf bound_ctrl:1
	v_cndmask_b32_dpp v143, v53, v55, vcc row_shl:4 row_mask:0xf bank_mask:0xf bound_ctrl:1
	v_mfma_scale_f32_16x16x128_f8f6f4 v[212:215], v[136:139], v[144:151], v[212:215], v240, v241 op_sel_hi:[0,0,0] cbsz:4
	v_fmac_f32_e32 v192, v253, v253
	v_fmac_f32_e32 v193, v255, v255
	v_cvt_pk_bf16_f32 v250, v252, v253
	v_and_b32_e32 v144, v188, v235
	v_and_b32_e32 v145, v188, v236
	v_and_b32_e32 v146, v188, v237
	v_and_b32_e32 v147, v188, v238
	v_and_b32_e32 v148, v189, v235
	v_and_b32_e32 v149, v189, v236
	v_and_b32_e32 v150, v189, v237
	v_and_b32_e32 v151, v189, v238
	s_mov_b64 vcc, s[4:5]
	v_cndmask_b32_dpp v138, v56, v58, vcc row_shl:4 row_mask:0xf bank_mask:0xf bound_ctrl:1
	v_cndmask_b32_dpp v139, v57, v59, vcc row_shl:4 row_mask:0xf bank_mask:0xf bound_ctrl:1
	s_mov_b64 vcc, s[6:7]
	v_cndmask_b32_dpp v136, v58, v56, vcc row_shr:4 row_mask:0xf bank_mask:0xf bound_ctrl:1
	v_cndmask_b32_dpp v137, v59, v57, vcc row_shr:4 row_mask:0xf bank_mask:0xf bound_ctrl:1
	v_mfma_scale_f32_16x16x128_f8f6f4 v[212:215], v[140:143], v[204:211], v[212:215], v240, v241 op_sel_hi:[0,0,0] cbsz:4
	v_cvt_pk_bf16_f32 v251, v254, v255
	v_add_f32_e32 v192, v192, v193
	v_add_f32_e32 v223, v223, v192
	v_and_b32_e32 v204, v190, v235
	v_and_b32_e32 v205, v190, v236
	v_and_b32_e32 v206, v190, v237
	v_and_b32_e32 v207, v190, v238
	v_and_b32_e32 v208, v191, v235
	v_and_b32_e32 v209, v191, v236
	v_and_b32_e32 v210, v191, v237
	v_and_b32_e32 v211, v191, v238
	s_mov_b64 vcc, s[6:7]
	v_cndmask_b32_dpp v140, v62, v60, vcc row_shr:4 row_mask:0xf bank_mask:0xf bound_ctrl:1
	v_cndmask_b32_dpp v141, v63, v61, vcc row_shr:4 row_mask:0xf bank_mask:0xf bound_ctrl:1
	s_mov_b64 vcc, s[4:5]
	v_cndmask_b32_dpp v142, v60, v62, vcc row_shl:4 row_mask:0xf bank_mask:0xf bound_ctrl:1
	v_cndmask_b32_dpp v143, v61, v63, vcc row_shl:4 row_mask:0xf bank_mask:0xf bound_ctrl:1
	v_mfma_scale_f32_16x16x128_f8f6f4 v[212:215], v[136:139], v[144:151], v[212:215], v240, v241 op_sel_hi:[0,0,0] cbsz:4
	s_nop 0
	v_mfma_scale_f32_16x16x128_f8f6f4 v[212:215], v[140:143], v[204:211], v[212:215], v240, v241 op_sel_hi:[0,0,0] cbsz:4
	s_lshl_b32 s64, s0, 9
	s_add_u32 s64, s64, 0x3000
	s_add_u32 s76, s28, s64
	s_addc_u32 s77, s29, 0
	global_store_dwordx2 v239, v[250:251], s[76:77]
	s_lshl_b32 s64, s0, 9
	s_add_u32 s64, s64, 0x5000
	s_add_u32 s70, s28, s64
	s_addc_u32 s71, s29, 0
	global_load_dwordx2 v[230:231], v239, s[70:71] nt
	s_waitcnt lgkmcnt(0)
	v_lshl_or_b32 v128, v128, 7, v232
	v_lshl_or_b32 v129, v129, 7, v232
	v_lshl_or_b32 v130, v130, 7, v232
	v_lshl_or_b32 v131, v131, 7, v232
	v_lshl_or_b32 v132, v132, 7, v232
	v_lshl_or_b32 v133, v133, 7, v232
	v_lshl_or_b32 v134, v134, 7, v232
	v_lshl_or_b32 v135, v135, 7, v232
	buffer_load_dwordx4 v[32:35], v128, s[20:23], s1 offen
	buffer_load_dwordx4 v[36:39], v129, s[20:23], s1 offen
	buffer_load_dwordx4 v[40:43], v130, s[20:23], s1 offen
	buffer_load_dwordx4 v[44:47], v131, s[20:23], s1 offen
	buffer_load_dwordx4 v[48:51], v132, s[20:23], s1 offen
	buffer_load_dwordx4 v[52:55], v133, s[20:23], s1 offen
	buffer_load_dwordx4 v[56:59], v134, s[20:23], s1 offen
	buffer_load_dwordx4 v[60:63], v135, s[20:23], s1 offen
	ds_read_b32 v128, v243 offset:3584
	ds_read_b32 v129, v243 offset:3616
	ds_read_b32 v130, v243 offset:3648
	ds_read_b32 v131, v243 offset:3680
	ds_read_b32 v132, v243 offset:3712
	ds_read_b32 v133, v243 offset:3744
	ds_read_b32 v134, v243 offset:3776
	ds_read_b32 v135, v243 offset:3808
	ds_read_b64 v[176:177], v234 offset:2816
	ds_read_b64 v[178:179], v234 offset:2848
	ds_read_b64 v[180:181], v234 offset:2880
	ds_read_b64 v[182:183], v234 offset:2912
	ds_read_b64 v[184:185], v234 offset:2944
	ds_read_b64 v[186:187], v234 offset:2976
	ds_read_b64 v[188:189], v234 offset:3008
	ds_read_b64 v[190:191], v234 offset:3040
	s_waitcnt vmcnt(28)
	v_and_b32_e32 v144, v160, v235
	v_and_b32_e32 v145, v160, v236
	v_and_b32_e32 v146, v160, v237
	v_and_b32_e32 v147, v160, v238
	v_and_b32_e32 v148, v161, v235
	v_and_b32_e32 v149, v161, v236
	v_and_b32_e32 v150, v161, v237
	v_and_b32_e32 v151, v161, v238
	s_mov_b64 vcc, s[4:5]
	v_cndmask_b32_dpp v138, v64, v66, vcc row_shl:4 row_mask:0xf bank_mask:0xf bound_ctrl:1
	v_cndmask_b32_dpp v139, v65, v67, vcc row_shl:4 row_mask:0xf bank_mask:0xf bound_ctrl:1
	s_mov_b64 vcc, s[6:7]
	v_cndmask_b32_dpp v136, v66, v64, vcc row_shr:4 row_mask:0xf bank_mask:0xf bound_ctrl:1
	v_cndmask_b32_dpp v137, v67, v65, vcc row_shr:4 row_mask:0xf bank_mask:0xf bound_ctrl:1
	v_and_b32_e32 v204, v162, v235
	v_and_b32_e32 v205, v162, v236
	v_and_b32_e32 v206, v162, v237
	v_and_b32_e32 v207, v162, v238
	v_and_b32_e32 v208, v163, v235
	v_and_b32_e32 v209, v163, v236
	v_and_b32_e32 v210, v163, v237
	v_and_b32_e32 v211, v163, v238
	s_mov_b64 vcc, s[6:7]
	v_cndmask_b32_dpp v140, v70, v68, vcc row_shr:4 row_mask:0xf bank_mask:0xf bound_ctrl:1
	v_cndmask_b32_dpp v141, v71, v69, vcc row_shr:4 row_mask:0xf bank_mask:0xf bound_ctrl:1
	s_mov_b64 vcc, s[4:5]
	v_cndmask_b32_dpp v142, v68, v70, vcc row_shl:4 row_mask:0xf bank_mask:0xf bound_ctrl:1
	v_cndmask_b32_dpp v143, v69, v71, vcc row_shl:4 row_mask:0xf bank_mask:0xf bound_ctrl:1
	v_mfma_scale_f32_16x16x128_f8f6f4 v[216:219], v[136:139], v[144:151], 0, v240, v241 op_sel_hi:[0,0,0] cbsz:4
	v_and_b32_e32 v144, v164, v235
	v_and_b32_e32 v145, v164, v236
	v_and_b32_e32 v146, v164, v237
	v_and_b32_e32 v147, v164, v238
	v_and_b32_e32 v148, v165, v235
	v_and_b32_e32 v149, v165, v236
	v_and_b32_e32 v150, v165, v237
	v_and_b32_e32 v151, v165, v238
	s_mov_b64 vcc, s[4:5]
	v_cndmask_b32_dpp v138, v72, v74, vcc row_shl:4 row_mask:0xf bank_mask:0xf bound_ctrl:1
	v_cndmask_b32_dpp v139, v73, v75, vcc row_shl:4 row_mask:0xf bank_mask:0xf bound_ctrl:1
	s_mov_b64 vcc, s[6:7]
	v_cndmask_b32_dpp v136, v74, v72, vcc row_shr:4 row_mask:0xf bank_mask:0xf bound_ctrl:1
	v_cndmask_b32_dpp v137, v75, v73, vcc row_shr:4 row_mask:0xf bank_mask:0xf bound_ctrl:1
	v_mfma_scale_f32_16x16x128_f8f6f4 v[216:219], v[140:143], v[204:211], v[216:219], v240, v241 op_sel_hi:[0,0,0] cbsz:4
	v_and_b32_e32 v204, v166, v235
	v_and_b32_e32 v205, v166, v236
	v_and_b32_e32 v206, v166, v237
	v_and_b32_e32 v207, v166, v238
	v_and_b32_e32 v208, v167, v235
	v_and_b32_e32 v209, v167, v236
	v_and_b32_e32 v210, v167, v237
	v_and_b32_e32 v211, v167, v238
	s_mov_b64 vcc, s[6:7]
	v_cndmask_b32_dpp v140, v78, v76, vcc row_shr:4 row_mask:0xf bank_mask:0xf bound_ctrl:1
	v_cndmask_b32_dpp v141, v79, v77, vcc row_shr:4 row_mask:0xf bank_mask:0xf bound_ctrl:1
	s_mov_b64 vcc, s[4:5]
	v_cndmask_b32_dpp v142, v76, v78, vcc row_shl:4 row_mask:0xf bank_mask:0xf bound_ctrl:1
	v_cndmask_b32_dpp v143, v77, v79, vcc row_shl:4 row_mask:0xf bank_mask:0xf bound_ctrl:1
	v_mfma_scale_f32_16x16x128_f8f6f4 v[216:219], v[136:139], v[144:151], v[216:219], v240, v241 op_sel_hi:[0,0,0] cbsz:4
	v_and_b32_e32 v144, v168, v235
	v_and_b32_e32 v145, v168, v236
	v_and_b32_e32 v146, v168, v237
	v_and_b32_e32 v147, v168, v238
	v_and_b32_e32 v148, v169, v235
	v_and_b32_e32 v149, v169, v236
	v_and_b32_e32 v150, v169, v237
	v_and_b32_e32 v151, v169, v238
	s_mov_b64 vcc, s[4:5]
	v_cndmask_b32_dpp v138, v80, v82, vcc row_shl:4 row_mask:0xf bank_mask:0xf bound_ctrl:1
	v_cndmask_b32_dpp v139, v81, v83, vcc row_shl:4 row_mask:0xf bank_mask:0xf bound_ctrl:1
	s_mov_b64 vcc, s[6:7]
	v_cndmask_b32_dpp v136, v82, v80, vcc row_shr:4 row_mask:0xf bank_mask:0xf bound_ctrl:1
	v_cndmask_b32_dpp v137, v83, v81, vcc row_shr:4 row_mask:0xf bank_mask:0xf bound_ctrl:1
	v_mfma_scale_f32_16x16x128_f8f6f4 v[216:219], v[140:143], v[204:211], v[216:219], v240, v241 op_sel_hi:[0,0,0] cbsz:4
	v_and_b32_e32 v204, v170, v235
	v_and_b32_e32 v205, v170, v236
	v_and_b32_e32 v206, v170, v237
	v_and_b32_e32 v207, v170, v238
	v_and_b32_e32 v208, v171, v235
	v_and_b32_e32 v209, v171, v236
	v_and_b32_e32 v210, v171, v237
	v_and_b32_e32 v211, v171, v238
	s_mov_b64 vcc, s[6:7]
	v_cndmask_b32_dpp v140, v86, v84, vcc row_shr:4 row_mask:0xf bank_mask:0xf bound_ctrl:1
	v_cndmask_b32_dpp v141, v87, v85, vcc row_shr:4 row_mask:0xf bank_mask:0xf bound_ctrl:1
	s_mov_b64 vcc, s[4:5]
	v_cndmask_b32_dpp v142, v84, v86, vcc row_shl:4 row_mask:0xf bank_mask:0xf bound_ctrl:1
	v_cndmask_b32_dpp v143, v85, v87, vcc row_shl:4 row_mask:0xf bank_mask:0xf bound_ctrl:1
	v_mfma_scale_f32_16x16x128_f8f6f4 v[216:219], v[136:139], v[144:151], v[216:219], v240, v241 op_sel_hi:[0,0,0] cbsz:4
	v_and_b32_e32 v144, v172, v235
	v_and_b32_e32 v145, v172, v236
	v_and_b32_e32 v146, v172, v237
	v_and_b32_e32 v147, v172, v238
	v_and_b32_e32 v148, v173, v235
	v_and_b32_e32 v149, v173, v236
	v_and_b32_e32 v150, v173, v237
	v_and_b32_e32 v151, v173, v238
	s_mov_b64 vcc, s[4:5]
	v_cndmask_b32_dpp v138, v88, v90, vcc row_shl:4 row_mask:0xf bank_mask:0xf bound_ctrl:1
	v_cndmask_b32_dpp v139, v89, v91, vcc row_shl:4 row_mask:0xf bank_mask:0xf bound_ctrl:1
	s_mov_b64 vcc, s[6:7]
	v_cndmask_b32_dpp v136, v90, v88, vcc row_shr:4 row_mask:0xf bank_mask:0xf bound_ctrl:1
	v_cndmask_b32_dpp v137, v91, v89, vcc row_shr:4 row_mask:0xf bank_mask:0xf bound_ctrl:1
	v_mfma_scale_f32_16x16x128_f8f6f4 v[216:219], v[140:143], v[204:211], v[216:219], v240, v241 op_sel_hi:[0,0,0] cbsz:4
	v_and_b32_e32 v204, v174, v235
	v_and_b32_e32 v205, v174, v236
	v_and_b32_e32 v206, v174, v237
	v_and_b32_e32 v207, v174, v238
	v_and_b32_e32 v208, v175, v235
	v_and_b32_e32 v209, v175, v236
	v_and_b32_e32 v210, v175, v237
	v_and_b32_e32 v211, v175, v238
	s_mov_b64 vcc, s[6:7]
	v_cndmask_b32_dpp v140, v94, v92, vcc row_shr:4 row_mask:0xf bank_mask:0xf bound_ctrl:1
	v_cndmask_b32_dpp v141, v95, v93, vcc row_shr:4 row_mask:0xf bank_mask:0xf bound_ctrl:1
	s_mov_b64 vcc, s[4:5]
	v_cndmask_b32_dpp v142, v92, v94, vcc row_shl:4 row_mask:0xf bank_mask:0xf bound_ctrl:1
	v_cndmask_b32_dpp v143, v93, v95, vcc row_shl:4 row_mask:0xf bank_mask:0xf bound_ctrl:1
	v_mfma_scale_f32_16x16x128_f8f6f4 v[216:219], v[136:139], v[144:151], v[216:219], v240, v241 op_sel_hi:[0,0,0] cbsz:4
	s_nop 0
	v_mfma_scale_f32_16x16x128_f8f6f4 v[216:219], v[140:143], v[204:211], v[216:219], v240, v241 op_sel_hi:[0,0,0] cbsz:4
	s_waitcnt lgkmcnt(0)
	v_lshl_or_b32 v128, v128, 7, v232
	v_lshl_or_b32 v129, v129, 7, v232
	v_lshl_or_b32 v130, v130, 7, v232
	v_lshl_or_b32 v131, v131, 7, v232
	v_lshl_or_b32 v132, v132, 7, v232
	v_lshl_or_b32 v133, v133, 7, v232
	v_lshl_or_b32 v134, v134, 7, v232
	v_lshl_or_b32 v135, v135, 7, v232
	buffer_load_dwordx4 v[64:67], v128, s[20:23], s1 offen
	buffer_load_dwordx4 v[68:71], v129, s[20:23], s1 offen
	buffer_load_dwordx4 v[72:75], v130, s[20:23], s1 offen
	buffer_load_dwordx4 v[76:79], v131, s[20:23], s1 offen
	buffer_load_dwordx4 v[80:83], v132, s[20:23], s1 offen
	buffer_load_dwordx4 v[84:87], v133, s[20:23], s1 offen
	buffer_load_dwordx4 v[88:91], v134, s[20:23], s1 offen
	buffer_load_dwordx4 v[92:95], v135, s[20:23], s1 offen
	ds_read_b32 v128, v243 offset:3840
	ds_read_b32 v129, v243 offset:3872
	ds_read_b32 v130, v243 offset:3904
	ds_read_b32 v131, v243 offset:3936
	ds_read_b32 v132, v243 offset:3968
	ds_read_b32 v133, v243 offset:4000
	ds_read_b32 v134, v243 offset:4032
	ds_read_b32 v135, v243 offset:4064
	ds_read_b64 v[160:161], v234 offset:3072
	ds_read_b64 v[162:163], v234 offset:3104
	ds_read_b64 v[164:165], v234 offset:3136
	ds_read_b64 v[166:167], v234 offset:3168
	ds_read_b64 v[168:169], v234 offset:3200
	ds_read_b64 v[170:171], v234 offset:3232
	ds_read_b64 v[172:173], v234 offset:3264
	ds_read_b64 v[174:175], v234 offset:3296
	s_waitcnt vmcnt(26)
	v_and_b32_e32 v144, v176, v235
	v_and_b32_e32 v145, v176, v236
	v_and_b32_e32 v146, v176, v237
	v_and_b32_e32 v147, v176, v238
	v_and_b32_e32 v148, v177, v235
	v_and_b32_e32 v149, v177, v236
	v_and_b32_e32 v150, v177, v237
	v_and_b32_e32 v151, v177, v238
	s_mov_b64 vcc, s[4:5]
	v_cndmask_b32_dpp v138, v96, v98, vcc row_shl:4 row_mask:0xf bank_mask:0xf bound_ctrl:1
	v_cndmask_b32_dpp v139, v97, v99, vcc row_shl:4 row_mask:0xf bank_mask:0xf bound_ctrl:1
	s_mov_b64 vcc, s[6:7]
	v_cndmask_b32_dpp v136, v98, v96, vcc row_shr:4 row_mask:0xf bank_mask:0xf bound_ctrl:1
	v_cndmask_b32_dpp v137, v99, v97, vcc row_shr:4 row_mask:0xf bank_mask:0xf bound_ctrl:1
	v_and_b32_e32 v204, v178, v235
	v_and_b32_e32 v205, v178, v236
	v_and_b32_e32 v206, v178, v237
	v_and_b32_e32 v207, v178, v238
	v_and_b32_e32 v208, v179, v235
	v_and_b32_e32 v209, v179, v236
	v_and_b32_e32 v210, v179, v237
	v_and_b32_e32 v211, v179, v238
	s_mov_b64 vcc, s[6:7]
	v_cndmask_b32_dpp v140, v102, v100, vcc row_shr:4 row_mask:0xf bank_mask:0xf bound_ctrl:1
	v_cndmask_b32_dpp v141, v103, v101, vcc row_shr:4 row_mask:0xf bank_mask:0xf bound_ctrl:1
	s_mov_b64 vcc, s[4:5]
	v_cndmask_b32_dpp v142, v100, v102, vcc row_shl:4 row_mask:0xf bank_mask:0xf bound_ctrl:1
	v_cndmask_b32_dpp v143, v101, v103, vcc row_shl:4 row_mask:0xf bank_mask:0xf bound_ctrl:1
	v_mfma_scale_f32_16x16x128_f8f6f4 v[216:219], v[136:139], v[144:151], v[216:219], v240, v241 op_sel_hi:[0,0,0] cbsz:4
	v_permlane16_swap_b32_e32 v212, v214
	v_permlane16_swap_b32_e32 v213, v215
	v_lshlrev_b32_e32 v252, 16, v228
	v_and_b32_e32 v144, v180, v235
	v_and_b32_e32 v145, v180, v236
	v_and_b32_e32 v146, v180, v237
	v_and_b32_e32 v147, v180, v238
	v_and_b32_e32 v148, v181, v235
	v_and_b32_e32 v149, v181, v236
	v_and_b32_e32 v150, v181, v237
	v_and_b32_e32 v151, v181, v238
	s_mov_b64 vcc, s[4:5]
	v_cndmask_b32_dpp v138, v104, v106, vcc row_shl:4 row_mask:0xf bank_mask:0xf bound_ctrl:1
	v_cndmask_b32_dpp v139, v105, v107, vcc row_shl:4 row_mask:0xf bank_mask:0xf bound_ctrl:1
	s_mov_b64 vcc, s[6:7]
	v_cndmask_b32_dpp v136, v106, v104, vcc row_shr:4 row_mask:0xf bank_mask:0xf bound_ctrl:1
	v_cndmask_b32_dpp v137, v107, v105, vcc row_shr:4 row_mask:0xf bank_mask:0xf bound_ctrl:1
	v_mfma_scale_f32_16x16x128_f8f6f4 v[216:219], v[140:143], v[204:211], v[216:219], v240, v241 op_sel_hi:[0,0,0] cbsz:4
	v_and_b32_e32 v253, 0xffff0000, v228
	v_lshlrev_b32_e32 v254, 16, v229
	v_and_b32_e32 v255, 0xffff0000, v229
	v_and_b32_e32 v204, v182, v235
	v_and_b32_e32 v205, v182, v236
	v_and_b32_e32 v206, v182, v237
	v_and_b32_e32 v207, v182, v238
	v_and_b32_e32 v208, v183, v235
	v_and_b32_e32 v209, v183, v236
	v_and_b32_e32 v210, v183, v237
	v_and_b32_e32 v211, v183, v238
	s_mov_b64 vcc, s[6:7]
	v_cndmask_b32_dpp v140, v110, v108, vcc row_shr:4 row_mask:0xf bank_mask:0xf bound_ctrl:1
	v_cndmask_b32_dpp v141, v111, v109, vcc row_shr:4 row_mask:0xf bank_mask:0xf bound_ctrl:1
	s_mov_b64 vcc, s[4:5]
	v_cndmask_b32_dpp v142, v108, v110, vcc row_shl:4 row_mask:0xf bank_mask:0xf bound_ctrl:1
	v_cndmask_b32_dpp v143, v109, v111, vcc row_shl:4 row_mask:0xf bank_mask:0xf bound_ctrl:1
	v_mfma_scale_f32_16x16x128_f8f6f4 v[216:219], v[136:139], v[144:151], v[216:219], v240, v241 op_sel_hi:[0,0,0] cbsz:4
	v_add_f32_e32 v252, v212, v252
	v_add_f32_e32 v253, v214, v253
	v_add_f32_e32 v254, v213, v254
	v_and_b32_e32 v144, v184, v235
	v_and_b32_e32 v145, v184, v236
	v_and_b32_e32 v146, v184, v237
	v_and_b32_e32 v147, v184, v238
	v_and_b32_e32 v148, v185, v235
	v_and_b32_e32 v149, v185, v236
	v_and_b32_e32 v150, v185, v237
	v_and_b32_e32 v151, v185, v238
	s_mov_b64 vcc, s[4:5]
	v_cndmask_b32_dpp v138, v112, v114, vcc row_shl:4 row_mask:0xf bank_mask:0xf bound_ctrl:1
	v_cndmask_b32_dpp v139, v113, v115, vcc row_shl:4 row_mask:0xf bank_mask:0xf bound_ctrl:1
	s_mov_b64 vcc, s[6:7]
	v_cndmask_b32_dpp v136, v114, v112, vcc row_shr:4 row_mask:0xf bank_mask:0xf bound_ctrl:1
	v_cndmask_b32_dpp v137, v115, v113, vcc row_shr:4 row_mask:0xf bank_mask:0xf bound_ctrl:1
	v_mfma_scale_f32_16x16x128_f8f6f4 v[216:219], v[140:143], v[204:211], v[216:219], v240, v241 op_sel_hi:[0,0,0] cbsz:4
	v_add_f32_e32 v255, v215, v255
	v_mul_f32_e32 v192, v252, v252
	v_mul_f32_e32 v193, v254, v254
	v_and_b32_e32 v204, v186, v235
	v_and_b32_e32 v205, v186, v236
	v_and_b32_e32 v206, v186, v237
	v_and_b32_e32 v207, v186, v238
	v_and_b32_e32 v208, v187, v235
	v_and_b32_e32 v209, v187, v236
	v_and_b32_e32 v210, v187, v237
	v_and_b32_e32 v211, v187, v238
	s_mov_b64 vcc, s[6:7]
	v_cndmask_b32_dpp v140, v118, v116, vcc row_shr:4 row_mask:0xf bank_mask:0xf bound_ctrl:1
	v_cndmask_b32_dpp v141, v119, v117, vcc row_shr:4 row_mask:0xf bank_mask:0xf bound_ctrl:1
	s_mov_b64 vcc, s[4:5]
	v_cndmask_b32_dpp v142, v116, v118, vcc row_shl:4 row_mask:0xf bank_mask:0xf bound_ctrl:1
	v_cndmask_b32_dpp v143, v117, v119, vcc row_shl:4 row_mask:0xf bank_mask:0xf bound_ctrl:1
	v_mfma_scale_f32_16x16x128_f8f6f4 v[216:219], v[136:139], v[144:151], v[216:219], v240, v241 op_sel_hi:[0,0,0] cbsz:4
	v_fmac_f32_e32 v192, v253, v253
	v_fmac_f32_e32 v193, v255, v255
	v_cvt_pk_bf16_f32 v250, v252, v253
	v_and_b32_e32 v144, v188, v235
	v_and_b32_e32 v145, v188, v236
	v_and_b32_e32 v146, v188, v237
	v_and_b32_e32 v147, v188, v238
	v_and_b32_e32 v148, v189, v235
	v_and_b32_e32 v149, v189, v236
	v_and_b32_e32 v150, v189, v237
	v_and_b32_e32 v151, v189, v238
	s_mov_b64 vcc, s[4:5]
	v_cndmask_b32_dpp v138, v120, v122, vcc row_shl:4 row_mask:0xf bank_mask:0xf bound_ctrl:1
	v_cndmask_b32_dpp v139, v121, v123, vcc row_shl:4 row_mask:0xf bank_mask:0xf bound_ctrl:1
	s_mov_b64 vcc, s[6:7]
	v_cndmask_b32_dpp v136, v122, v120, vcc row_shr:4 row_mask:0xf bank_mask:0xf bound_ctrl:1
	v_cndmask_b32_dpp v137, v123, v121, vcc row_shr:4 row_mask:0xf bank_mask:0xf bound_ctrl:1
	v_mfma_scale_f32_16x16x128_f8f6f4 v[216:219], v[140:143], v[204:211], v[216:219], v240, v241 op_sel_hi:[0,0,0] cbsz:4
	v_cvt_pk_bf16_f32 v251, v254, v255
	v_add_f32_e32 v192, v192, v193
	v_add_f32_e32 v224, v224, v192
	v_and_b32_e32 v204, v190, v235
	v_and_b32_e32 v205, v190, v236
	v_and_b32_e32 v206, v190, v237
	v_and_b32_e32 v207, v190, v238
	v_and_b32_e32 v208, v191, v235
	v_and_b32_e32 v209, v191, v236
	v_and_b32_e32 v210, v191, v237
	v_and_b32_e32 v211, v191, v238
	s_mov_b64 vcc, s[6:7]
	v_cndmask_b32_dpp v140, v126, v124, vcc row_shr:4 row_mask:0xf bank_mask:0xf bound_ctrl:1
	v_cndmask_b32_dpp v141, v127, v125, vcc row_shr:4 row_mask:0xf bank_mask:0xf bound_ctrl:1
	s_mov_b64 vcc, s[4:5]
	v_cndmask_b32_dpp v142, v124, v126, vcc row_shl:4 row_mask:0xf bank_mask:0xf bound_ctrl:1
	v_cndmask_b32_dpp v143, v125, v127, vcc row_shl:4 row_mask:0xf bank_mask:0xf bound_ctrl:1
	v_mfma_scale_f32_16x16x128_f8f6f4 v[216:219], v[136:139], v[144:151], v[216:219], v240, v241 op_sel_hi:[0,0,0] cbsz:4
	s_nop 0
	v_mfma_scale_f32_16x16x128_f8f6f4 v[216:219], v[140:143], v[204:211], v[216:219], v240, v241 op_sel_hi:[0,0,0] cbsz:4
	s_lshl_b32 s64, s0, 9
	s_add_u32 s64, s64, 0x4000
	s_add_u32 s76, s28, s64
	s_addc_u32 s77, s29, 0
	global_store_dwordx2 v239, v[250:251], s[76:77]
	s_lshl_b32 s64, s0, 9
	s_add_u32 s64, s64, 0x6000
	s_add_u32 s70, s28, s64
	s_addc_u32 s71, s29, 0
	global_load_dwordx2 v[228:229], v239, s[70:71] nt
	s_waitcnt lgkmcnt(0)
	v_lshl_or_b32 v128, v128, 7, v232
	v_lshl_or_b32 v129, v129, 7, v232
	v_lshl_or_b32 v130, v130, 7, v232
	v_lshl_or_b32 v131, v131, 7, v232
	v_lshl_or_b32 v132, v132, 7, v232
	v_lshl_or_b32 v133, v133, 7, v232
	v_lshl_or_b32 v134, v134, 7, v232
	v_lshl_or_b32 v135, v135, 7, v232
	buffer_load_dwordx4 v[96:99], v128, s[20:23], s1 offen
	buffer_load_dwordx4 v[100:103], v129, s[20:23], s1 offen
	buffer_load_dwordx4 v[104:107], v130, s[20:23], s1 offen
	buffer_load_dwordx4 v[108:111], v131, s[20:23], s1 offen
	buffer_load_dwordx4 v[112:115], v132, s[20:23], s1 offen
	buffer_load_dwordx4 v[116:119], v133, s[20:23], s1 offen
	buffer_load_dwordx4 v[120:123], v134, s[20:23], s1 offen
	buffer_load_dwordx4 v[124:127], v135, s[20:23], s1 offen
	ds_read_b32 v128, v243 offset:0
	ds_read_b32 v129, v243 offset:32
	ds_read_b32 v130, v243 offset:64
	ds_read_b32 v131, v243 offset:96
	ds_read_b32 v132, v243 offset:128
	ds_read_b32 v133, v243 offset:160
	ds_read_b32 v134, v243 offset:192
	ds_read_b32 v135, v243 offset:224
	ds_read_b64 v[176:177], v234 offset:3328
	ds_read_b64 v[178:179], v234 offset:3360
	ds_read_b64 v[180:181], v234 offset:3392
	ds_read_b64 v[182:183], v234 offset:3424
	ds_read_b64 v[184:185], v234 offset:3456
	ds_read_b64 v[186:187], v234 offset:3488
	ds_read_b64 v[188:189], v234 offset:3520
	ds_read_b64 v[190:191], v234 offset:3552
	s_waitcnt vmcnt(28)
	v_and_b32_e32 v144, v160, v235
	v_and_b32_e32 v145, v160, v236
	v_and_b32_e32 v146, v160, v237
	v_and_b32_e32 v147, v160, v238
	v_and_b32_e32 v148, v161, v235
	v_and_b32_e32 v149, v161, v236
	v_and_b32_e32 v150, v161, v237
	v_and_b32_e32 v151, v161, v238
	s_mov_b64 vcc, s[4:5]
	v_cndmask_b32_dpp v138, v0, v2, vcc row_shl:4 row_mask:0xf bank_mask:0xf bound_ctrl:1
	v_cndmask_b32_dpp v139, v1, v3, vcc row_shl:4 row_mask:0xf bank_mask:0xf bound_ctrl:1
	s_mov_b64 vcc, s[6:7]
	v_cndmask_b32_dpp v136, v2, v0, vcc row_shr:4 row_mask:0xf bank_mask:0xf bound_ctrl:1
	v_cndmask_b32_dpp v137, v3, v1, vcc row_shr:4 row_mask:0xf bank_mask:0xf bound_ctrl:1
	v_and_b32_e32 v204, v162, v235
	v_and_b32_e32 v205, v162, v236
	v_and_b32_e32 v206, v162, v237
	v_and_b32_e32 v207, v162, v238
	v_and_b32_e32 v208, v163, v235
	v_and_b32_e32 v209, v163, v236
	v_and_b32_e32 v210, v163, v237
	v_and_b32_e32 v211, v163, v238
	s_mov_b64 vcc, s[6:7]
	v_cndmask_b32_dpp v140, v6, v4, vcc row_shr:4 row_mask:0xf bank_mask:0xf bound_ctrl:1
	v_cndmask_b32_dpp v141, v7, v5, vcc row_shr:4 row_mask:0xf bank_mask:0xf bound_ctrl:1
	s_mov_b64 vcc, s[4:5]
	v_cndmask_b32_dpp v142, v4, v6, vcc row_shl:4 row_mask:0xf bank_mask:0xf bound_ctrl:1
	v_cndmask_b32_dpp v143, v5, v7, vcc row_shl:4 row_mask:0xf bank_mask:0xf bound_ctrl:1
	v_mfma_scale_f32_16x16x128_f8f6f4 v[212:215], v[136:139], v[144:151], 0, v240, v241 op_sel_hi:[0,0,0] cbsz:4
	v_and_b32_e32 v144, v164, v235
	v_and_b32_e32 v145, v164, v236
	v_and_b32_e32 v146, v164, v237
	v_and_b32_e32 v147, v164, v238
	v_and_b32_e32 v148, v165, v235
	v_and_b32_e32 v149, v165, v236
	v_and_b32_e32 v150, v165, v237
	v_and_b32_e32 v151, v165, v238
	s_mov_b64 vcc, s[4:5]
	v_cndmask_b32_dpp v138, v8, v10, vcc row_shl:4 row_mask:0xf bank_mask:0xf bound_ctrl:1
	v_cndmask_b32_dpp v139, v9, v11, vcc row_shl:4 row_mask:0xf bank_mask:0xf bound_ctrl:1
	s_mov_b64 vcc, s[6:7]
	v_cndmask_b32_dpp v136, v10, v8, vcc row_shr:4 row_mask:0xf bank_mask:0xf bound_ctrl:1
	v_cndmask_b32_dpp v137, v11, v9, vcc row_shr:4 row_mask:0xf bank_mask:0xf bound_ctrl:1
	v_mfma_scale_f32_16x16x128_f8f6f4 v[212:215], v[140:143], v[204:211], v[212:215], v240, v241 op_sel_hi:[0,0,0] cbsz:4
	v_and_b32_e32 v204, v166, v235
	v_and_b32_e32 v205, v166, v236
	v_and_b32_e32 v206, v166, v237
	v_and_b32_e32 v207, v166, v238
	v_and_b32_e32 v208, v167, v235
	v_and_b32_e32 v209, v167, v236
	v_and_b32_e32 v210, v167, v237
	v_and_b32_e32 v211, v167, v238
	s_mov_b64 vcc, s[6:7]
	v_cndmask_b32_dpp v140, v14, v12, vcc row_shr:4 row_mask:0xf bank_mask:0xf bound_ctrl:1
	v_cndmask_b32_dpp v141, v15, v13, vcc row_shr:4 row_mask:0xf bank_mask:0xf bound_ctrl:1
	s_mov_b64 vcc, s[4:5]
	v_cndmask_b32_dpp v142, v12, v14, vcc row_shl:4 row_mask:0xf bank_mask:0xf bound_ctrl:1
	v_cndmask_b32_dpp v143, v13, v15, vcc row_shl:4 row_mask:0xf bank_mask:0xf bound_ctrl:1
	v_mfma_scale_f32_16x16x128_f8f6f4 v[212:215], v[136:139], v[144:151], v[212:215], v240, v241 op_sel_hi:[0,0,0] cbsz:4
	v_and_b32_e32 v144, v168, v235
	v_and_b32_e32 v145, v168, v236
	v_and_b32_e32 v146, v168, v237
	v_and_b32_e32 v147, v168, v238
	v_and_b32_e32 v148, v169, v235
	v_and_b32_e32 v149, v169, v236
	v_and_b32_e32 v150, v169, v237
	v_and_b32_e32 v151, v169, v238
	s_mov_b64 vcc, s[4:5]
	v_cndmask_b32_dpp v138, v16, v18, vcc row_shl:4 row_mask:0xf bank_mask:0xf bound_ctrl:1
	v_cndmask_b32_dpp v139, v17, v19, vcc row_shl:4 row_mask:0xf bank_mask:0xf bound_ctrl:1
	s_mov_b64 vcc, s[6:7]
	v_cndmask_b32_dpp v136, v18, v16, vcc row_shr:4 row_mask:0xf bank_mask:0xf bound_ctrl:1
	v_cndmask_b32_dpp v137, v19, v17, vcc row_shr:4 row_mask:0xf bank_mask:0xf bound_ctrl:1
	v_mfma_scale_f32_16x16x128_f8f6f4 v[212:215], v[140:143], v[204:211], v[212:215], v240, v241 op_sel_hi:[0,0,0] cbsz:4
	v_and_b32_e32 v204, v170, v235
	v_and_b32_e32 v205, v170, v236
	v_and_b32_e32 v206, v170, v237
	v_and_b32_e32 v207, v170, v238
	v_and_b32_e32 v208, v171, v235
	v_and_b32_e32 v209, v171, v236
	v_and_b32_e32 v210, v171, v237
	v_and_b32_e32 v211, v171, v238
	s_mov_b64 vcc, s[6:7]
	v_cndmask_b32_dpp v140, v22, v20, vcc row_shr:4 row_mask:0xf bank_mask:0xf bound_ctrl:1
	v_cndmask_b32_dpp v141, v23, v21, vcc row_shr:4 row_mask:0xf bank_mask:0xf bound_ctrl:1
	s_mov_b64 vcc, s[4:5]
	v_cndmask_b32_dpp v142, v20, v22, vcc row_shl:4 row_mask:0xf bank_mask:0xf bound_ctrl:1
	v_cndmask_b32_dpp v143, v21, v23, vcc row_shl:4 row_mask:0xf bank_mask:0xf bound_ctrl:1
	v_mfma_scale_f32_16x16x128_f8f6f4 v[212:215], v[136:139], v[144:151], v[212:215], v240, v241 op_sel_hi:[0,0,0] cbsz:4
	v_and_b32_e32 v144, v172, v235
	v_and_b32_e32 v145, v172, v236
	v_and_b32_e32 v146, v172, v237
	v_and_b32_e32 v147, v172, v238
	v_and_b32_e32 v148, v173, v235
	v_and_b32_e32 v149, v173, v236
	v_and_b32_e32 v150, v173, v237
	v_and_b32_e32 v151, v173, v238
	s_mov_b64 vcc, s[4:5]
	v_cndmask_b32_dpp v138, v24, v26, vcc row_shl:4 row_mask:0xf bank_mask:0xf bound_ctrl:1
	v_cndmask_b32_dpp v139, v25, v27, vcc row_shl:4 row_mask:0xf bank_mask:0xf bound_ctrl:1
	s_mov_b64 vcc, s[6:7]
	v_cndmask_b32_dpp v136, v26, v24, vcc row_shr:4 row_mask:0xf bank_mask:0xf bound_ctrl:1
	v_cndmask_b32_dpp v137, v27, v25, vcc row_shr:4 row_mask:0xf bank_mask:0xf bound_ctrl:1
	v_mfma_scale_f32_16x16x128_f8f6f4 v[212:215], v[140:143], v[204:211], v[212:215], v240, v241 op_sel_hi:[0,0,0] cbsz:4
	v_and_b32_e32 v204, v174, v235
	v_and_b32_e32 v205, v174, v236
	v_and_b32_e32 v206, v174, v237
	v_and_b32_e32 v207, v174, v238
	v_and_b32_e32 v208, v175, v235
	v_and_b32_e32 v209, v175, v236
	v_and_b32_e32 v210, v175, v237
	v_and_b32_e32 v211, v175, v238
	s_mov_b64 vcc, s[6:7]
	v_cndmask_b32_dpp v140, v30, v28, vcc row_shr:4 row_mask:0xf bank_mask:0xf bound_ctrl:1
	v_cndmask_b32_dpp v141, v31, v29, vcc row_shr:4 row_mask:0xf bank_mask:0xf bound_ctrl:1
	s_mov_b64 vcc, s[4:5]
	v_cndmask_b32_dpp v142, v28, v30, vcc row_shl:4 row_mask:0xf bank_mask:0xf bound_ctrl:1
	v_cndmask_b32_dpp v143, v29, v31, vcc row_shl:4 row_mask:0xf bank_mask:0xf bound_ctrl:1
	v_mfma_scale_f32_16x16x128_f8f6f4 v[212:215], v[136:139], v[144:151], v[212:215], v240, v241 op_sel_hi:[0,0,0] cbsz:4
	s_nop 0
	v_mfma_scale_f32_16x16x128_f8f6f4 v[212:215], v[140:143], v[204:211], v[212:215], v240, v241 op_sel_hi:[0,0,0] cbsz:4
	s_waitcnt lgkmcnt(0)
	v_lshl_or_b32 v128, v128, 7, v232
	v_lshl_or_b32 v129, v129, 7, v232
	v_lshl_or_b32 v130, v130, 7, v232
	v_lshl_or_b32 v131, v131, 7, v232
	v_lshl_or_b32 v132, v132, 7, v232
	v_lshl_or_b32 v133, v133, 7, v232
	v_lshl_or_b32 v134, v134, 7, v232
	v_lshl_or_b32 v135, v135, 7, v232
	buffer_load_dwordx4 v[0:3], v128, s[20:23], s60 offen
	buffer_load_dwordx4 v[4:7], v129, s[20:23], s60 offen
	buffer_load_dwordx4 v[8:11], v130, s[20:23], s60 offen
	buffer_load_dwordx4 v[12:15], v131, s[20:23], s60 offen
	buffer_load_dwordx4 v[16:19], v132, s[20:23], s60 offen
	buffer_load_dwordx4 v[20:23], v133, s[20:23], s60 offen
	buffer_load_dwordx4 v[24:27], v134, s[20:23], s60 offen
	buffer_load_dwordx4 v[28:31], v135, s[20:23], s60 offen
	ds_read_b32 v128, v243 offset:256
	ds_read_b32 v129, v243 offset:288
	ds_read_b32 v130, v243 offset:320
	ds_read_b32 v131, v243 offset:352
	ds_read_b32 v132, v243 offset:384
	ds_read_b32 v133, v243 offset:416
	ds_read_b32 v134, v243 offset:448
	ds_read_b32 v135, v243 offset:480
	ds_read_b64 v[160:161], v234 offset:3584
	ds_read_b64 v[162:163], v234 offset:3616
	ds_read_b64 v[164:165], v234 offset:3648
	ds_read_b64 v[166:167], v234 offset:3680
	ds_read_b64 v[168:169], v234 offset:3712
	ds_read_b64 v[170:171], v234 offset:3744
	ds_read_b64 v[172:173], v234 offset:3776
	ds_read_b64 v[174:175], v234 offset:3808
	s_waitcnt vmcnt(26)
	v_and_b32_e32 v144, v176, v235
	v_and_b32_e32 v145, v176, v236
	v_and_b32_e32 v146, v176, v237
	v_and_b32_e32 v147, v176, v238
	v_and_b32_e32 v148, v177, v235
	v_and_b32_e32 v149, v177, v236
	v_and_b32_e32 v150, v177, v237
	v_and_b32_e32 v151, v177, v238
	s_mov_b64 vcc, s[4:5]
	v_cndmask_b32_dpp v138, v32, v34, vcc row_shl:4 row_mask:0xf bank_mask:0xf bound_ctrl:1
	v_cndmask_b32_dpp v139, v33, v35, vcc row_shl:4 row_mask:0xf bank_mask:0xf bound_ctrl:1
	s_mov_b64 vcc, s[6:7]
	v_cndmask_b32_dpp v136, v34, v32, vcc row_shr:4 row_mask:0xf bank_mask:0xf bound_ctrl:1
	v_cndmask_b32_dpp v137, v35, v33, vcc row_shr:4 row_mask:0xf bank_mask:0xf bound_ctrl:1
	v_and_b32_e32 v204, v178, v235
	v_and_b32_e32 v205, v178, v236
	v_and_b32_e32 v206, v178, v237
	v_and_b32_e32 v207, v178, v238
	v_and_b32_e32 v208, v179, v235
	v_and_b32_e32 v209, v179, v236
	v_and_b32_e32 v210, v179, v237
	v_and_b32_e32 v211, v179, v238
	s_mov_b64 vcc, s[6:7]
	v_cndmask_b32_dpp v140, v38, v36, vcc row_shr:4 row_mask:0xf bank_mask:0xf bound_ctrl:1
	v_cndmask_b32_dpp v141, v39, v37, vcc row_shr:4 row_mask:0xf bank_mask:0xf bound_ctrl:1
	s_mov_b64 vcc, s[4:5]
	v_cndmask_b32_dpp v142, v36, v38, vcc row_shl:4 row_mask:0xf bank_mask:0xf bound_ctrl:1
	v_cndmask_b32_dpp v143, v37, v39, vcc row_shl:4 row_mask:0xf bank_mask:0xf bound_ctrl:1
	v_mfma_scale_f32_16x16x128_f8f6f4 v[212:215], v[136:139], v[144:151], v[212:215], v240, v241 op_sel_hi:[0,0,0] cbsz:4
	v_permlane16_swap_b32_e32 v216, v218
	v_permlane16_swap_b32_e32 v217, v219
	v_lshlrev_b32_e32 v252, 16, v230
	v_and_b32_e32 v144, v180, v235
	v_and_b32_e32 v145, v180, v236
	v_and_b32_e32 v146, v180, v237
	v_and_b32_e32 v147, v180, v238
	v_and_b32_e32 v148, v181, v235
	v_and_b32_e32 v149, v181, v236
	v_and_b32_e32 v150, v181, v237
	v_and_b32_e32 v151, v181, v238
	s_mov_b64 vcc, s[4:5]
	v_cndmask_b32_dpp v138, v40, v42, vcc row_shl:4 row_mask:0xf bank_mask:0xf bound_ctrl:1
	v_cndmask_b32_dpp v139, v41, v43, vcc row_shl:4 row_mask:0xf bank_mask:0xf bound_ctrl:1
	s_mov_b64 vcc, s[6:7]
	v_cndmask_b32_dpp v136, v42, v40, vcc row_shr:4 row_mask:0xf bank_mask:0xf bound_ctrl:1
	v_cndmask_b32_dpp v137, v43, v41, vcc row_shr:4 row_mask:0xf bank_mask:0xf bound_ctrl:1
	v_mfma_scale_f32_16x16x128_f8f6f4 v[212:215], v[140:143], v[204:211], v[212:215], v240, v241 op_sel_hi:[0,0,0] cbsz:4
	v_and_b32_e32 v253, 0xffff0000, v230
	v_lshlrev_b32_e32 v254, 16, v231
	v_and_b32_e32 v255, 0xffff0000, v231
	v_and_b32_e32 v204, v182, v235
	v_and_b32_e32 v205, v182, v236
	v_and_b32_e32 v206, v182, v237
	v_and_b32_e32 v207, v182, v238
	v_and_b32_e32 v208, v183, v235
	v_and_b32_e32 v209, v183, v236
	v_and_b32_e32 v210, v183, v237
	v_and_b32_e32 v211, v183, v238
	s_mov_b64 vcc, s[6:7]
	v_cndmask_b32_dpp v140, v46, v44, vcc row_shr:4 row_mask:0xf bank_mask:0xf bound_ctrl:1
	v_cndmask_b32_dpp v141, v47, v45, vcc row_shr:4 row_mask:0xf bank_mask:0xf bound_ctrl:1
	s_mov_b64 vcc, s[4:5]
	v_cndmask_b32_dpp v142, v44, v46, vcc row_shl:4 row_mask:0xf bank_mask:0xf bound_ctrl:1
	v_cndmask_b32_dpp v143, v45, v47, vcc row_shl:4 row_mask:0xf bank_mask:0xf bound_ctrl:1
	v_mfma_scale_f32_16x16x128_f8f6f4 v[212:215], v[136:139], v[144:151], v[212:215], v240, v241 op_sel_hi:[0,0,0] cbsz:4
	v_add_f32_e32 v252, v216, v252
	v_add_f32_e32 v253, v218, v253
	v_add_f32_e32 v254, v217, v254
	v_and_b32_e32 v144, v184, v235
	v_and_b32_e32 v145, v184, v236
	v_and_b32_e32 v146, v184, v237
	v_and_b32_e32 v147, v184, v238
	v_and_b32_e32 v148, v185, v235
	v_and_b32_e32 v149, v185, v236
	v_and_b32_e32 v150, v185, v237
	v_and_b32_e32 v151, v185, v238
	s_mov_b64 vcc, s[4:5]
	v_cndmask_b32_dpp v138, v48, v50, vcc row_shl:4 row_mask:0xf bank_mask:0xf bound_ctrl:1
	v_cndmask_b32_dpp v139, v49, v51, vcc row_shl:4 row_mask:0xf bank_mask:0xf bound_ctrl:1
	s_mov_b64 vcc, s[6:7]
	v_cndmask_b32_dpp v136, v50, v48, vcc row_shr:4 row_mask:0xf bank_mask:0xf bound_ctrl:1
	v_cndmask_b32_dpp v137, v51, v49, vcc row_shr:4 row_mask:0xf bank_mask:0xf bound_ctrl:1
	v_mfma_scale_f32_16x16x128_f8f6f4 v[212:215], v[140:143], v[204:211], v[212:215], v240, v241 op_sel_hi:[0,0,0] cbsz:4
	v_add_f32_e32 v255, v219, v255
	v_mul_f32_e32 v192, v252, v252
	v_mul_f32_e32 v193, v254, v254
	v_and_b32_e32 v204, v186, v235
	v_and_b32_e32 v205, v186, v236
	v_and_b32_e32 v206, v186, v237
	v_and_b32_e32 v207, v186, v238
	v_and_b32_e32 v208, v187, v235
	v_and_b32_e32 v209, v187, v236
	v_and_b32_e32 v210, v187, v237
	v_and_b32_e32 v211, v187, v238
	s_mov_b64 vcc, s[6:7]
	v_cndmask_b32_dpp v140, v54, v52, vcc row_shr:4 row_mask:0xf bank_mask:0xf bound_ctrl:1
	v_cndmask_b32_dpp v141, v55, v53, vcc row_shr:4 row_mask:0xf bank_mask:0xf bound_ctrl:1
	s_mov_b64 vcc, s[4:5]
	v_cndmask_b32_dpp v142, v52, v54, vcc row_shl:4 row_mask:0xf bank_mask:0xf bound_ctrl:1
	v_cndmask_b32_dpp v143, v53, v55, vcc row_shl:4 row_mask:0xf bank_mask:0xf bound_ctrl:1
	v_mfma_scale_f32_16x16x128_f8f6f4 v[212:215], v[136:139], v[144:151], v[212:215], v240, v241 op_sel_hi:[0,0,0] cbsz:4
	v_fmac_f32_e32 v192, v253, v253
	v_fmac_f32_e32 v193, v255, v255
	v_cvt_pk_bf16_f32 v250, v252, v253
	v_and_b32_e32 v144, v188, v235
	v_and_b32_e32 v145, v188, v236
	v_and_b32_e32 v146, v188, v237
	v_and_b32_e32 v147, v188, v238
	v_and_b32_e32 v148, v189, v235
	v_and_b32_e32 v149, v189, v236
	v_and_b32_e32 v150, v189, v237
	v_and_b32_e32 v151, v189, v238
	s_mov_b64 vcc, s[4:5]
	v_cndmask_b32_dpp v138, v56, v58, vcc row_shl:4 row_mask:0xf bank_mask:0xf bound_ctrl:1
	v_cndmask_b32_dpp v139, v57, v59, vcc row_shl:4 row_mask:0xf bank_mask:0xf bound_ctrl:1
	s_mov_b64 vcc, s[6:7]
	v_cndmask_b32_dpp v136, v58, v56, vcc row_shr:4 row_mask:0xf bank_mask:0xf bound_ctrl:1
	v_cndmask_b32_dpp v137, v59, v57, vcc row_shr:4 row_mask:0xf bank_mask:0xf bound_ctrl:1
	v_mfma_scale_f32_16x16x128_f8f6f4 v[212:215], v[140:143], v[204:211], v[212:215], v240, v241 op_sel_hi:[0,0,0] cbsz:4
	v_cvt_pk_bf16_f32 v251, v254, v255
	v_add_f32_e32 v192, v192, v193
	v_add_f32_e32 v225, v225, v192
	v_and_b32_e32 v204, v190, v235
	v_and_b32_e32 v205, v190, v236
	v_and_b32_e32 v206, v190, v237
	v_and_b32_e32 v207, v190, v238
	v_and_b32_e32 v208, v191, v235
	v_and_b32_e32 v209, v191, v236
	v_and_b32_e32 v210, v191, v237
	v_and_b32_e32 v211, v191, v238
	s_mov_b64 vcc, s[6:7]
	v_cndmask_b32_dpp v140, v62, v60, vcc row_shr:4 row_mask:0xf bank_mask:0xf bound_ctrl:1
	v_cndmask_b32_dpp v141, v63, v61, vcc row_shr:4 row_mask:0xf bank_mask:0xf bound_ctrl:1
	s_mov_b64 vcc, s[4:5]
	v_cndmask_b32_dpp v142, v60, v62, vcc row_shl:4 row_mask:0xf bank_mask:0xf bound_ctrl:1
	v_cndmask_b32_dpp v143, v61, v63, vcc row_shl:4 row_mask:0xf bank_mask:0xf bound_ctrl:1
	v_mfma_scale_f32_16x16x128_f8f6f4 v[212:215], v[136:139], v[144:151], v[212:215], v240, v241 op_sel_hi:[0,0,0] cbsz:4
	s_nop 0
	v_mfma_scale_f32_16x16x128_f8f6f4 v[212:215], v[140:143], v[204:211], v[212:215], v240, v241 op_sel_hi:[0,0,0] cbsz:4
	s_lshl_b32 s64, s0, 9
	s_add_u32 s64, s64, 0x5000
	s_add_u32 s76, s28, s64
	s_addc_u32 s77, s29, 0
	global_store_dwordx2 v239, v[250:251], s[76:77]
	s_lshl_b32 s64, s0, 9
	s_add_u32 s64, s64, 0x7000
	s_add_u32 s70, s28, s64
	s_addc_u32 s71, s29, 0
	global_load_dwordx2 v[230:231], v239, s[70:71] nt
	s_waitcnt lgkmcnt(0)
	v_lshl_or_b32 v128, v128, 7, v232
	v_lshl_or_b32 v129, v129, 7, v232
	v_lshl_or_b32 v130, v130, 7, v232
	v_lshl_or_b32 v131, v131, 7, v232
	v_lshl_or_b32 v132, v132, 7, v232
	v_lshl_or_b32 v133, v133, 7, v232
	v_lshl_or_b32 v134, v134, 7, v232
	v_lshl_or_b32 v135, v135, 7, v232
	buffer_load_dwordx4 v[32:35], v128, s[20:23], s60 offen
	buffer_load_dwordx4 v[36:39], v129, s[20:23], s60 offen
	buffer_load_dwordx4 v[40:43], v130, s[20:23], s60 offen
	buffer_load_dwordx4 v[44:47], v131, s[20:23], s60 offen
	buffer_load_dwordx4 v[48:51], v132, s[20:23], s60 offen
	buffer_load_dwordx4 v[52:55], v133, s[20:23], s60 offen
	buffer_load_dwordx4 v[56:59], v134, s[20:23], s60 offen
	buffer_load_dwordx4 v[60:63], v135, s[20:23], s60 offen
	ds_read_b32 v128, v243 offset:512
	ds_read_b32 v129, v243 offset:544
	ds_read_b32 v130, v243 offset:576
	ds_read_b32 v131, v243 offset:608
	ds_read_b32 v132, v243 offset:640
	ds_read_b32 v133, v243 offset:672
	ds_read_b32 v134, v243 offset:704
	ds_read_b32 v135, v243 offset:736
	ds_read_b64 v[176:177], v234 offset:3840
	ds_read_b64 v[178:179], v234 offset:3872
	ds_read_b64 v[180:181], v234 offset:3904
	ds_read_b64 v[182:183], v234 offset:3936
	ds_read_b64 v[184:185], v234 offset:3968
	ds_read_b64 v[186:187], v234 offset:4000
	ds_read_b64 v[188:189], v234 offset:4032
	ds_read_b64 v[190:191], v234 offset:4064
	s_waitcnt vmcnt(28)
	v_and_b32_e32 v144, v160, v235
	v_and_b32_e32 v145, v160, v236
	v_and_b32_e32 v146, v160, v237
	v_and_b32_e32 v147, v160, v238
	v_and_b32_e32 v148, v161, v235
	v_and_b32_e32 v149, v161, v236
	v_and_b32_e32 v150, v161, v237
	v_and_b32_e32 v151, v161, v238
	s_mov_b64 vcc, s[4:5]
	v_cndmask_b32_dpp v138, v64, v66, vcc row_shl:4 row_mask:0xf bank_mask:0xf bound_ctrl:1
	v_cndmask_b32_dpp v139, v65, v67, vcc row_shl:4 row_mask:0xf bank_mask:0xf bound_ctrl:1
	s_mov_b64 vcc, s[6:7]
	v_cndmask_b32_dpp v136, v66, v64, vcc row_shr:4 row_mask:0xf bank_mask:0xf bound_ctrl:1
	v_cndmask_b32_dpp v137, v67, v65, vcc row_shr:4 row_mask:0xf bank_mask:0xf bound_ctrl:1
	v_and_b32_e32 v204, v162, v235
	v_and_b32_e32 v205, v162, v236
	v_and_b32_e32 v206, v162, v237
	v_and_b32_e32 v207, v162, v238
	v_and_b32_e32 v208, v163, v235
	v_and_b32_e32 v209, v163, v236
	v_and_b32_e32 v210, v163, v237
	v_and_b32_e32 v211, v163, v238
	s_mov_b64 vcc, s[6:7]
	v_cndmask_b32_dpp v140, v70, v68, vcc row_shr:4 row_mask:0xf bank_mask:0xf bound_ctrl:1
	v_cndmask_b32_dpp v141, v71, v69, vcc row_shr:4 row_mask:0xf bank_mask:0xf bound_ctrl:1
	s_mov_b64 vcc, s[4:5]
	v_cndmask_b32_dpp v142, v68, v70, vcc row_shl:4 row_mask:0xf bank_mask:0xf bound_ctrl:1
	v_cndmask_b32_dpp v143, v69, v71, vcc row_shl:4 row_mask:0xf bank_mask:0xf bound_ctrl:1
	v_mfma_scale_f32_16x16x128_f8f6f4 v[216:219], v[136:139], v[144:151], 0, v240, v241 op_sel_hi:[0,0,0] cbsz:4
	v_and_b32_e32 v144, v164, v235
	v_and_b32_e32 v145, v164, v236
	v_and_b32_e32 v146, v164, v237
	v_and_b32_e32 v147, v164, v238
	v_and_b32_e32 v148, v165, v235
	v_and_b32_e32 v149, v165, v236
	v_and_b32_e32 v150, v165, v237
	v_and_b32_e32 v151, v165, v238
	s_mov_b64 vcc, s[4:5]
	v_cndmask_b32_dpp v138, v72, v74, vcc row_shl:4 row_mask:0xf bank_mask:0xf bound_ctrl:1
	v_cndmask_b32_dpp v139, v73, v75, vcc row_shl:4 row_mask:0xf bank_mask:0xf bound_ctrl:1
	s_mov_b64 vcc, s[6:7]
	v_cndmask_b32_dpp v136, v74, v72, vcc row_shr:4 row_mask:0xf bank_mask:0xf bound_ctrl:1
	v_cndmask_b32_dpp v137, v75, v73, vcc row_shr:4 row_mask:0xf bank_mask:0xf bound_ctrl:1
	v_mfma_scale_f32_16x16x128_f8f6f4 v[216:219], v[140:143], v[204:211], v[216:219], v240, v241 op_sel_hi:[0,0,0] cbsz:4
	v_and_b32_e32 v204, v166, v235
	v_and_b32_e32 v205, v166, v236
	v_and_b32_e32 v206, v166, v237
	v_and_b32_e32 v207, v166, v238
	v_and_b32_e32 v208, v167, v235
	v_and_b32_e32 v209, v167, v236
	v_and_b32_e32 v210, v167, v237
	v_and_b32_e32 v211, v167, v238
	s_mov_b64 vcc, s[6:7]
	v_cndmask_b32_dpp v140, v78, v76, vcc row_shr:4 row_mask:0xf bank_mask:0xf bound_ctrl:1
	v_cndmask_b32_dpp v141, v79, v77, vcc row_shr:4 row_mask:0xf bank_mask:0xf bound_ctrl:1
	s_mov_b64 vcc, s[4:5]
	v_cndmask_b32_dpp v142, v76, v78, vcc row_shl:4 row_mask:0xf bank_mask:0xf bound_ctrl:1
	v_cndmask_b32_dpp v143, v77, v79, vcc row_shl:4 row_mask:0xf bank_mask:0xf bound_ctrl:1
	v_mfma_scale_f32_16x16x128_f8f6f4 v[216:219], v[136:139], v[144:151], v[216:219], v240, v241 op_sel_hi:[0,0,0] cbsz:4
	v_and_b32_e32 v144, v168, v235
	v_and_b32_e32 v145, v168, v236
	v_and_b32_e32 v146, v168, v237
	v_and_b32_e32 v147, v168, v238
	v_and_b32_e32 v148, v169, v235
	v_and_b32_e32 v149, v169, v236
	v_and_b32_e32 v150, v169, v237
	v_and_b32_e32 v151, v169, v238
	s_mov_b64 vcc, s[4:5]
	v_cndmask_b32_dpp v138, v80, v82, vcc row_shl:4 row_mask:0xf bank_mask:0xf bound_ctrl:1
	v_cndmask_b32_dpp v139, v81, v83, vcc row_shl:4 row_mask:0xf bank_mask:0xf bound_ctrl:1
	s_mov_b64 vcc, s[6:7]
	v_cndmask_b32_dpp v136, v82, v80, vcc row_shr:4 row_mask:0xf bank_mask:0xf bound_ctrl:1
	v_cndmask_b32_dpp v137, v83, v81, vcc row_shr:4 row_mask:0xf bank_mask:0xf bound_ctrl:1
	v_mfma_scale_f32_16x16x128_f8f6f4 v[216:219], v[140:143], v[204:211], v[216:219], v240, v241 op_sel_hi:[0,0,0] cbsz:4
	v_and_b32_e32 v204, v170, v235
	v_and_b32_e32 v205, v170, v236
	v_and_b32_e32 v206, v170, v237
	v_and_b32_e32 v207, v170, v238
	v_and_b32_e32 v208, v171, v235
	v_and_b32_e32 v209, v171, v236
	v_and_b32_e32 v210, v171, v237
	v_and_b32_e32 v211, v171, v238
	s_mov_b64 vcc, s[6:7]
	v_cndmask_b32_dpp v140, v86, v84, vcc row_shr:4 row_mask:0xf bank_mask:0xf bound_ctrl:1
	v_cndmask_b32_dpp v141, v87, v85, vcc row_shr:4 row_mask:0xf bank_mask:0xf bound_ctrl:1
	s_mov_b64 vcc, s[4:5]
	v_cndmask_b32_dpp v142, v84, v86, vcc row_shl:4 row_mask:0xf bank_mask:0xf bound_ctrl:1
	v_cndmask_b32_dpp v143, v85, v87, vcc row_shl:4 row_mask:0xf bank_mask:0xf bound_ctrl:1
	v_mfma_scale_f32_16x16x128_f8f6f4 v[216:219], v[136:139], v[144:151], v[216:219], v240, v241 op_sel_hi:[0,0,0] cbsz:4
	v_and_b32_e32 v144, v172, v235
	v_and_b32_e32 v145, v172, v236
	v_and_b32_e32 v146, v172, v237
	v_and_b32_e32 v147, v172, v238
	v_and_b32_e32 v148, v173, v235
	v_and_b32_e32 v149, v173, v236
	v_and_b32_e32 v150, v173, v237
	v_and_b32_e32 v151, v173, v238
	s_mov_b64 vcc, s[4:5]
	v_cndmask_b32_dpp v138, v88, v90, vcc row_shl:4 row_mask:0xf bank_mask:0xf bound_ctrl:1
	v_cndmask_b32_dpp v139, v89, v91, vcc row_shl:4 row_mask:0xf bank_mask:0xf bound_ctrl:1
	s_mov_b64 vcc, s[6:7]
	v_cndmask_b32_dpp v136, v90, v88, vcc row_shr:4 row_mask:0xf bank_mask:0xf bound_ctrl:1
	v_cndmask_b32_dpp v137, v91, v89, vcc row_shr:4 row_mask:0xf bank_mask:0xf bound_ctrl:1
	v_mfma_scale_f32_16x16x128_f8f6f4 v[216:219], v[140:143], v[204:211], v[216:219], v240, v241 op_sel_hi:[0,0,0] cbsz:4
	v_and_b32_e32 v204, v174, v235
	v_and_b32_e32 v205, v174, v236
	v_and_b32_e32 v206, v174, v237
	v_and_b32_e32 v207, v174, v238
	v_and_b32_e32 v208, v175, v235
	v_and_b32_e32 v209, v175, v236
	v_and_b32_e32 v210, v175, v237
	v_and_b32_e32 v211, v175, v238
	s_mov_b64 vcc, s[6:7]
	v_cndmask_b32_dpp v140, v94, v92, vcc row_shr:4 row_mask:0xf bank_mask:0xf bound_ctrl:1
	v_cndmask_b32_dpp v141, v95, v93, vcc row_shr:4 row_mask:0xf bank_mask:0xf bound_ctrl:1
	s_mov_b64 vcc, s[4:5]
	v_cndmask_b32_dpp v142, v92, v94, vcc row_shl:4 row_mask:0xf bank_mask:0xf bound_ctrl:1
	v_cndmask_b32_dpp v143, v93, v95, vcc row_shl:4 row_mask:0xf bank_mask:0xf bound_ctrl:1
	v_mfma_scale_f32_16x16x128_f8f6f4 v[216:219], v[136:139], v[144:151], v[216:219], v240, v241 op_sel_hi:[0,0,0] cbsz:4
	s_nop 0
	v_mfma_scale_f32_16x16x128_f8f6f4 v[216:219], v[140:143], v[204:211], v[216:219], v240, v241 op_sel_hi:[0,0,0] cbsz:4
	s_waitcnt lgkmcnt(0)
	v_lshl_or_b32 v128, v128, 7, v232
	v_lshl_or_b32 v129, v129, 7, v232
	v_lshl_or_b32 v130, v130, 7, v232
	v_lshl_or_b32 v131, v131, 7, v232
	v_lshl_or_b32 v132, v132, 7, v232
	v_lshl_or_b32 v133, v133, 7, v232
	v_lshl_or_b32 v134, v134, 7, v232
	v_lshl_or_b32 v135, v135, 7, v232
	buffer_load_dwordx4 v[64:67], v128, s[20:23], s60 offen
	buffer_load_dwordx4 v[68:71], v129, s[20:23], s60 offen
	buffer_load_dwordx4 v[72:75], v130, s[20:23], s60 offen
	buffer_load_dwordx4 v[76:79], v131, s[20:23], s60 offen
	buffer_load_dwordx4 v[80:83], v132, s[20:23], s60 offen
	buffer_load_dwordx4 v[84:87], v133, s[20:23], s60 offen
	buffer_load_dwordx4 v[88:91], v134, s[20:23], s60 offen
	buffer_load_dwordx4 v[92:95], v135, s[20:23], s60 offen
	ds_read_b32 v128, v243 offset:768
	ds_read_b32 v129, v243 offset:800
	ds_read_b32 v130, v243 offset:832
	ds_read_b32 v131, v243 offset:864
	ds_read_b32 v132, v243 offset:896
	ds_read_b32 v133, v243 offset:928
	ds_read_b32 v134, v243 offset:960
	ds_read_b32 v135, v243 offset:992
	ds_read_b64 v[160:161], v247 offset:0
	ds_read_b64 v[162:163], v247 offset:32
	ds_read_b64 v[164:165], v247 offset:64
	ds_read_b64 v[166:167], v247 offset:96
	ds_read_b64 v[168:169], v247 offset:128
	ds_read_b64 v[170:171], v247 offset:160
	ds_read_b64 v[172:173], v247 offset:192
	ds_read_b64 v[174:175], v247 offset:224
	s_waitcnt vmcnt(26)
	v_and_b32_e32 v144, v176, v235
	v_and_b32_e32 v145, v176, v236
	v_and_b32_e32 v146, v176, v237
	v_and_b32_e32 v147, v176, v238
	v_and_b32_e32 v148, v177, v235
	v_and_b32_e32 v149, v177, v236
	v_and_b32_e32 v150, v177, v237
	v_and_b32_e32 v151, v177, v238
	s_mov_b64 vcc, s[4:5]
	v_cndmask_b32_dpp v138, v96, v98, vcc row_shl:4 row_mask:0xf bank_mask:0xf bound_ctrl:1
	v_cndmask_b32_dpp v139, v97, v99, vcc row_shl:4 row_mask:0xf bank_mask:0xf bound_ctrl:1
	s_mov_b64 vcc, s[6:7]
	v_cndmask_b32_dpp v136, v98, v96, vcc row_shr:4 row_mask:0xf bank_mask:0xf bound_ctrl:1
	v_cndmask_b32_dpp v137, v99, v97, vcc row_shr:4 row_mask:0xf bank_mask:0xf bound_ctrl:1
	v_and_b32_e32 v204, v178, v235
	v_and_b32_e32 v205, v178, v236
	v_and_b32_e32 v206, v178, v237
	v_and_b32_e32 v207, v178, v238
	v_and_b32_e32 v208, v179, v235
	v_and_b32_e32 v209, v179, v236
	v_and_b32_e32 v210, v179, v237
	v_and_b32_e32 v211, v179, v238
	s_mov_b64 vcc, s[6:7]
	v_cndmask_b32_dpp v140, v102, v100, vcc row_shr:4 row_mask:0xf bank_mask:0xf bound_ctrl:1
	v_cndmask_b32_dpp v141, v103, v101, vcc row_shr:4 row_mask:0xf bank_mask:0xf bound_ctrl:1
	s_mov_b64 vcc, s[4:5]
	v_cndmask_b32_dpp v142, v100, v102, vcc row_shl:4 row_mask:0xf bank_mask:0xf bound_ctrl:1
	v_cndmask_b32_dpp v143, v101, v103, vcc row_shl:4 row_mask:0xf bank_mask:0xf bound_ctrl:1
	v_mfma_scale_f32_16x16x128_f8f6f4 v[216:219], v[136:139], v[144:151], v[216:219], v240, v241 op_sel_hi:[0,0,0] cbsz:4
	v_permlane16_swap_b32_e32 v212, v214
	v_permlane16_swap_b32_e32 v213, v215
	v_lshlrev_b32_e32 v252, 16, v228
	v_and_b32_e32 v144, v180, v235
	v_and_b32_e32 v145, v180, v236
	v_and_b32_e32 v146, v180, v237
	v_and_b32_e32 v147, v180, v238
	v_and_b32_e32 v148, v181, v235
	v_and_b32_e32 v149, v181, v236
	v_and_b32_e32 v150, v181, v237
	v_and_b32_e32 v151, v181, v238
	s_mov_b64 vcc, s[4:5]
	v_cndmask_b32_dpp v138, v104, v106, vcc row_shl:4 row_mask:0xf bank_mask:0xf bound_ctrl:1
	v_cndmask_b32_dpp v139, v105, v107, vcc row_shl:4 row_mask:0xf bank_mask:0xf bound_ctrl:1
	s_mov_b64 vcc, s[6:7]
	v_cndmask_b32_dpp v136, v106, v104, vcc row_shr:4 row_mask:0xf bank_mask:0xf bound_ctrl:1
	v_cndmask_b32_dpp v137, v107, v105, vcc row_shr:4 row_mask:0xf bank_mask:0xf bound_ctrl:1
	v_mfma_scale_f32_16x16x128_f8f6f4 v[216:219], v[140:143], v[204:211], v[216:219], v240, v241 op_sel_hi:[0,0,0] cbsz:4
	v_and_b32_e32 v253, 0xffff0000, v228
	v_lshlrev_b32_e32 v254, 16, v229
	v_and_b32_e32 v255, 0xffff0000, v229
	v_and_b32_e32 v204, v182, v235
	v_and_b32_e32 v205, v182, v236
	v_and_b32_e32 v206, v182, v237
	v_and_b32_e32 v207, v182, v238
	v_and_b32_e32 v208, v183, v235
	v_and_b32_e32 v209, v183, v236
	v_and_b32_e32 v210, v183, v237
	v_and_b32_e32 v211, v183, v238
	s_mov_b64 vcc, s[6:7]
	v_cndmask_b32_dpp v140, v110, v108, vcc row_shr:4 row_mask:0xf bank_mask:0xf bound_ctrl:1
	v_cndmask_b32_dpp v141, v111, v109, vcc row_shr:4 row_mask:0xf bank_mask:0xf bound_ctrl:1
	s_mov_b64 vcc, s[4:5]
	v_cndmask_b32_dpp v142, v108, v110, vcc row_shl:4 row_mask:0xf bank_mask:0xf bound_ctrl:1
	v_cndmask_b32_dpp v143, v109, v111, vcc row_shl:4 row_mask:0xf bank_mask:0xf bound_ctrl:1
	v_mfma_scale_f32_16x16x128_f8f6f4 v[216:219], v[136:139], v[144:151], v[216:219], v240, v241 op_sel_hi:[0,0,0] cbsz:4
	v_add_f32_e32 v252, v212, v252
	v_add_f32_e32 v253, v214, v253
	v_add_f32_e32 v254, v213, v254
	v_and_b32_e32 v144, v184, v235
	v_and_b32_e32 v145, v184, v236
	v_and_b32_e32 v146, v184, v237
	v_and_b32_e32 v147, v184, v238
	v_and_b32_e32 v148, v185, v235
	v_and_b32_e32 v149, v185, v236
	v_and_b32_e32 v150, v185, v237
	v_and_b32_e32 v151, v185, v238
	s_mov_b64 vcc, s[4:5]
	v_cndmask_b32_dpp v138, v112, v114, vcc row_shl:4 row_mask:0xf bank_mask:0xf bound_ctrl:1
	v_cndmask_b32_dpp v139, v113, v115, vcc row_shl:4 row_mask:0xf bank_mask:0xf bound_ctrl:1
	s_mov_b64 vcc, s[6:7]
	v_cndmask_b32_dpp v136, v114, v112, vcc row_shr:4 row_mask:0xf bank_mask:0xf bound_ctrl:1
	v_cndmask_b32_dpp v137, v115, v113, vcc row_shr:4 row_mask:0xf bank_mask:0xf bound_ctrl:1
	v_mfma_scale_f32_16x16x128_f8f6f4 v[216:219], v[140:143], v[204:211], v[216:219], v240, v241 op_sel_hi:[0,0,0] cbsz:4
	v_add_f32_e32 v255, v215, v255
	v_mul_f32_e32 v192, v252, v252
	v_mul_f32_e32 v193, v254, v254
	v_and_b32_e32 v204, v186, v235
	v_and_b32_e32 v205, v186, v236
	v_and_b32_e32 v206, v186, v237
	v_and_b32_e32 v207, v186, v238
	v_and_b32_e32 v208, v187, v235
	v_and_b32_e32 v209, v187, v236
	v_and_b32_e32 v210, v187, v237
	v_and_b32_e32 v211, v187, v238
	s_mov_b64 vcc, s[6:7]
	v_cndmask_b32_dpp v140, v118, v116, vcc row_shr:4 row_mask:0xf bank_mask:0xf bound_ctrl:1
	v_cndmask_b32_dpp v141, v119, v117, vcc row_shr:4 row_mask:0xf bank_mask:0xf bound_ctrl:1
	s_mov_b64 vcc, s[4:5]
	v_cndmask_b32_dpp v142, v116, v118, vcc row_shl:4 row_mask:0xf bank_mask:0xf bound_ctrl:1
	v_cndmask_b32_dpp v143, v117, v119, vcc row_shl:4 row_mask:0xf bank_mask:0xf bound_ctrl:1
	v_mfma_scale_f32_16x16x128_f8f6f4 v[216:219], v[136:139], v[144:151], v[216:219], v240, v241 op_sel_hi:[0,0,0] cbsz:4
	v_fmac_f32_e32 v192, v253, v253
	v_fmac_f32_e32 v193, v255, v255
	v_cvt_pk_bf16_f32 v250, v252, v253
	v_and_b32_e32 v144, v188, v235
	v_and_b32_e32 v145, v188, v236
	v_and_b32_e32 v146, v188, v237
	v_and_b32_e32 v147, v188, v238
	v_and_b32_e32 v148, v189, v235
	v_and_b32_e32 v149, v189, v236
	v_and_b32_e32 v150, v189, v237
	v_and_b32_e32 v151, v189, v238
	s_mov_b64 vcc, s[4:5]
	v_cndmask_b32_dpp v138, v120, v122, vcc row_shl:4 row_mask:0xf bank_mask:0xf bound_ctrl:1
	v_cndmask_b32_dpp v139, v121, v123, vcc row_shl:4 row_mask:0xf bank_mask:0xf bound_ctrl:1
	s_mov_b64 vcc, s[6:7]
	v_cndmask_b32_dpp v136, v122, v120, vcc row_shr:4 row_mask:0xf bank_mask:0xf bound_ctrl:1
	v_cndmask_b32_dpp v137, v123, v121, vcc row_shr:4 row_mask:0xf bank_mask:0xf bound_ctrl:1
	v_mfma_scale_f32_16x16x128_f8f6f4 v[216:219], v[140:143], v[204:211], v[216:219], v240, v241 op_sel_hi:[0,0,0] cbsz:4
	v_cvt_pk_bf16_f32 v251, v254, v255
	v_add_f32_e32 v192, v192, v193
	v_add_f32_e32 v226, v226, v192
	v_and_b32_e32 v204, v190, v235
	v_and_b32_e32 v205, v190, v236
	v_and_b32_e32 v206, v190, v237
	v_and_b32_e32 v207, v190, v238
	v_and_b32_e32 v208, v191, v235
	v_and_b32_e32 v209, v191, v236
	v_and_b32_e32 v210, v191, v237
	v_and_b32_e32 v211, v191, v238
	s_mov_b64 vcc, s[6:7]
	v_cndmask_b32_dpp v140, v126, v124, vcc row_shr:4 row_mask:0xf bank_mask:0xf bound_ctrl:1
	v_cndmask_b32_dpp v141, v127, v125, vcc row_shr:4 row_mask:0xf bank_mask:0xf bound_ctrl:1
	s_mov_b64 vcc, s[4:5]
	v_cndmask_b32_dpp v142, v124, v126, vcc row_shl:4 row_mask:0xf bank_mask:0xf bound_ctrl:1
	v_cndmask_b32_dpp v143, v125, v127, vcc row_shl:4 row_mask:0xf bank_mask:0xf bound_ctrl:1
	v_mfma_scale_f32_16x16x128_f8f6f4 v[216:219], v[136:139], v[144:151], v[216:219], v240, v241 op_sel_hi:[0,0,0] cbsz:4
	s_nop 0
	v_mfma_scale_f32_16x16x128_f8f6f4 v[216:219], v[140:143], v[204:211], v[216:219], v240, v241 op_sel_hi:[0,0,0] cbsz:4
	s_lshl_b32 s64, s0, 9
	s_add_u32 s64, s64, 0x6000
	s_add_u32 s76, s28, s64
	s_addc_u32 s77, s29, 0
	global_store_dwordx2 v239, v[250:251], s[76:77]
	s_add_u32 s0, s0, 1
	s_lshl_b32 s1, s0, 21
	s_add_u32 s60, s1, 0x200000
	s_cmp_ge_u32 s0, 3
	s_movk_i32 s65, 0x2000
	s_cselect_b32 s64, s65, 0x1000
	v_mov_b32_e32 v234, v247
	v_add_u32_e32 v247, s64, v233
	s_cmp_lt_u32 s0, 8
	s_cbranch_scc1 .LpgL0_vloopv0
	s_waitcnt vmcnt(0)
	s_nop 15
	v_permlane16_swap_b32_e32 v216, v218
	v_permlane16_swap_b32_e32 v217, v219
	v_lshlrev_b32_e32 v252, 16, v230
	v_and_b32_e32 v253, 0xffff0000, v230
	v_lshlrev_b32_e32 v254, 16, v231
	v_and_b32_e32 v255, 0xffff0000, v231
	v_add_f32_e32 v252, v216, v252
	v_add_f32_e32 v253, v218, v253
	v_add_f32_e32 v254, v217, v254
	v_add_f32_e32 v255, v219, v255
	v_mul_f32_e32 v192, v252, v252
	v_mul_f32_e32 v193, v254, v254
	v_fmac_f32_e32 v192, v253, v253
	v_fmac_f32_e32 v193, v255, v255
	v_cvt_pk_bf16_f32 v250, v252, v253
	v_cvt_pk_bf16_f32 v251, v254, v255
	v_add_f32_e32 v192, v192, v193
	v_add_f32_e32 v227, v227, v192
	s_lshl_b32 s64, s0, 9
	s_add_u32 s64, s64, 0x6e00
	s_add_u32 s76, s28, s64
	s_addc_u32 s77, s29, 0
	global_store_dwordx2 v239, v[250:251], s[76:77]
	s_nop 1
	v_add_f32_dpp v220, v220, v220 quad_perm:[1,0,3,2] row_mask:0xf bank_mask:0xf bound_ctrl:1
	s_nop 1
	v_add_f32_dpp v220, v220, v220 quad_perm:[2,3,0,1] row_mask:0xf bank_mask:0xf bound_ctrl:1
	s_nop 1
	v_add_f32_dpp v220, v220, v220 row_half_mirror row_mask:0xf bank_mask:0xf bound_ctrl:1
	s_nop 1
	v_add_f32_dpp v220, v220, v220 row_mirror row_mask:0xf bank_mask:0xf bound_ctrl:1
	v_mov_b32_e32 v249, v220
	s_nop 1
	v_permlane16_swap_b32_e32 v220, v249
	v_add_f32_e32 v220, v220, v249
	v_mov_b32_e32 v249, v220
	s_nop 1
	v_permlane32_swap_b32_e32 v220, v249
	v_add_f32_e32 v220, v220, v249
	s_nop 1
	v_add_f32_dpp v221, v221, v221 quad_perm:[1,0,3,2] row_mask:0xf bank_mask:0xf bound_ctrl:1
	s_nop 1
	v_add_f32_dpp v221, v221, v221 quad_perm:[2,3,0,1] row_mask:0xf bank_mask:0xf bound_ctrl:1
	s_nop 1
	v_add_f32_dpp v221, v221, v221 row_half_mirror row_mask:0xf bank_mask:0xf bound_ctrl:1
	s_nop 1
	v_add_f32_dpp v221, v221, v221 row_mirror row_mask:0xf bank_mask:0xf bound_ctrl:1
	v_mov_b32_e32 v249, v221
	s_nop 1
	v_permlane16_swap_b32_e32 v221, v249
	v_add_f32_e32 v221, v221, v249
	v_mov_b32_e32 v249, v221
	s_nop 1
	v_permlane32_swap_b32_e32 v221, v249
	v_add_f32_e32 v221, v221, v249
	s_nop 1
	v_add_f32_dpp v222, v222, v222 quad_perm:[1,0,3,2] row_mask:0xf bank_mask:0xf bound_ctrl:1
	s_nop 1
	v_add_f32_dpp v222, v222, v222 quad_perm:[2,3,0,1] row_mask:0xf bank_mask:0xf bound_ctrl:1
	s_nop 1
	v_add_f32_dpp v222, v222, v222 row_half_mirror row_mask:0xf bank_mask:0xf bound_ctrl:1
	s_nop 1
	v_add_f32_dpp v222, v222, v222 row_mirror row_mask:0xf bank_mask:0xf bound_ctrl:1
	v_mov_b32_e32 v249, v222
	s_nop 1
	v_permlane16_swap_b32_e32 v222, v249
	v_add_f32_e32 v222, v222, v249
	v_mov_b32_e32 v249, v222
	s_nop 1
	v_permlane32_swap_b32_e32 v222, v249
	v_add_f32_e32 v222, v222, v249
	s_nop 1
	v_add_f32_dpp v223, v223, v223 quad_perm:[1,0,3,2] row_mask:0xf bank_mask:0xf bound_ctrl:1
	s_nop 1
	v_add_f32_dpp v223, v223, v223 quad_perm:[2,3,0,1] row_mask:0xf bank_mask:0xf bound_ctrl:1
	s_nop 1
	v_add_f32_dpp v223, v223, v223 row_half_mirror row_mask:0xf bank_mask:0xf bound_ctrl:1
	s_nop 1
	v_add_f32_dpp v223, v223, v223 row_mirror row_mask:0xf bank_mask:0xf bound_ctrl:1
	v_mov_b32_e32 v249, v223
	s_nop 1
	v_permlane16_swap_b32_e32 v223, v249
	v_add_f32_e32 v223, v223, v249
	v_mov_b32_e32 v249, v223
	s_nop 1
	v_permlane32_swap_b32_e32 v223, v249
	v_add_f32_e32 v223, v223, v249
	s_nop 1
	v_add_f32_dpp v224, v224, v224 quad_perm:[1,0,3,2] row_mask:0xf bank_mask:0xf bound_ctrl:1
	s_nop 1
	v_add_f32_dpp v224, v224, v224 quad_perm:[2,3,0,1] row_mask:0xf bank_mask:0xf bound_ctrl:1
	s_nop 1
	v_add_f32_dpp v224, v224, v224 row_half_mirror row_mask:0xf bank_mask:0xf bound_ctrl:1
	s_nop 1
	v_add_f32_dpp v224, v224, v224 row_mirror row_mask:0xf bank_mask:0xf bound_ctrl:1
	v_mov_b32_e32 v249, v224
	s_nop 1
	v_permlane16_swap_b32_e32 v224, v249
	v_add_f32_e32 v224, v224, v249
	v_mov_b32_e32 v249, v224
	s_nop 1
	v_permlane32_swap_b32_e32 v224, v249
	v_add_f32_e32 v224, v224, v249
	s_nop 1
	v_add_f32_dpp v225, v225, v225 quad_perm:[1,0,3,2] row_mask:0xf bank_mask:0xf bound_ctrl:1
	s_nop 1
	v_add_f32_dpp v225, v225, v225 quad_perm:[2,3,0,1] row_mask:0xf bank_mask:0xf bound_ctrl:1
	s_nop 1
	v_add_f32_dpp v225, v225, v225 row_half_mirror row_mask:0xf bank_mask:0xf bound_ctrl:1
	s_nop 1
	v_add_f32_dpp v225, v225, v225 row_mirror row_mask:0xf bank_mask:0xf bound_ctrl:1
	v_mov_b32_e32 v249, v225
	s_nop 1
	v_permlane16_swap_b32_e32 v225, v249
	v_add_f32_e32 v225, v225, v249
	v_mov_b32_e32 v249, v225
	s_nop 1
	v_permlane32_swap_b32_e32 v225, v249
	v_add_f32_e32 v225, v225, v249
	s_nop 1
	v_add_f32_dpp v226, v226, v226 quad_perm:[1,0,3,2] row_mask:0xf bank_mask:0xf bound_ctrl:1
	s_nop 1
	v_add_f32_dpp v226, v226, v226 quad_perm:[2,3,0,1] row_mask:0xf bank_mask:0xf bound_ctrl:1
	s_nop 1
	v_add_f32_dpp v226, v226, v226 row_half_mirror row_mask:0xf bank_mask:0xf bound_ctrl:1
	s_nop 1
	v_add_f32_dpp v226, v226, v226 row_mirror row_mask:0xf bank_mask:0xf bound_ctrl:1
	v_mov_b32_e32 v249, v226
	s_nop 1
	v_permlane16_swap_b32_e32 v226, v249
	v_add_f32_e32 v226, v226, v249
	v_mov_b32_e32 v249, v226
	s_nop 1
	v_permlane32_swap_b32_e32 v226, v249
	v_add_f32_e32 v226, v226, v249
	s_nop 1
	v_add_f32_dpp v227, v227, v227 quad_perm:[1,0,3,2] row_mask:0xf bank_mask:0xf bound_ctrl:1
	s_nop 1
	v_add_f32_dpp v227, v227, v227 quad_perm:[2,3,0,1] row_mask:0xf bank_mask:0xf bound_ctrl:1
	s_nop 1
	v_add_f32_dpp v227, v227, v227 row_half_mirror row_mask:0xf bank_mask:0xf bound_ctrl:1
	s_nop 1
	v_add_f32_dpp v227, v227, v227 row_mirror row_mask:0xf bank_mask:0xf bound_ctrl:1
	v_mov_b32_e32 v249, v227
	s_nop 1
	v_permlane16_swap_b32_e32 v227, v249
	v_add_f32_e32 v227, v227, v249
	v_mov_b32_e32 v249, v227
	s_nop 1
	v_permlane32_swap_b32_e32 v227, v249
	v_add_f32_e32 v227, v227, v249
	s_mov_b64 s[78:79], exec
	s_mov_b64 exec, s[10:11]
	global_store_dword v246, v220, s[44:45] offset:0
	global_store_dword v246, v221, s[44:45] offset:4
	global_store_dword v246, v222, s[44:45] offset:8
	global_store_dword v246, v223, s[44:45] offset:12
	global_store_dword v246, v224, s[44:45] offset:16
	global_store_dword v246, v225, s[44:45] offset:20
	global_store_dword v246, v226, s[44:45] offset:24
	global_store_dword v246, v227, s[44:45] offset:28
	s_mov_b64 exec, s[78:79]
	s_add_u32 s63, s63, s90
	s_cmpk_lt_i32 s63, 0x800
	s_cbranch_scc1 .LpgL0_group

.LBB0_869:
	v_lshl_add_u32 v188, s30, 8, v129
	v_lshlrev_b32_e32 v253, 2, v188
	v_lshlrev_b32_e32 v188, 11, v188
	v_lshl_add_u32 v188, s28, 8, v188
	v_or_b32_e32 v252, v188, v128
	v_lshlrev_b32_e32 v251, 1, v252
	v_xor_b32_e32 v254, 16, v148
	v_xor_b32_e32 v255, 32, v148
	v_lshlrev_b32_e32 v254, 2, v254
	v_lshlrev_b32_e32 v255, 2, v255
	v_mov_b32_e32 v192, v251
	global_load_dwordx4 v[204:207], v192, s[68:69] offset:0 nt
	global_load_dwordx4 v[208:211], v192, s[68:69] offset:256 nt
	v_add_u32_e32 v192, 0x10000, v251
	global_load_dwordx4 v[212:215], v192, s[68:69] offset:0 nt
	global_load_dwordx4 v[216:219], v192, s[68:69] offset:256 nt
	v_add_u32_e32 v192, 0x20000, v251
	global_load_dwordx4 v[220:223], v192, s[68:69] offset:0 nt
	global_load_dwordx4 v[224:227], v192, s[68:69] offset:256 nt
	v_add_u32_e32 v192, 0x30000, v251
	global_load_dwordx4 v[228:231], v192, s[68:69] offset:0 nt
	global_load_dwordx4 v[232:235], v192, s[68:69] offset:256 nt
	v_add_u32_e32 v192, 0x80000, v251
	global_load_dwordx4 v[236:239], v192, s[68:69] offset:0 nt
	global_load_dwordx4 v[240:243], v192, s[68:69] offset:256 nt
	v_add_u32_e32 v192, 0x90000, v251
	global_load_dwordx4 v[244:247], v192, s[68:69] offset:0 nt
	global_load_dwordx4 v[168:171], v192, s[68:69] offset:256 nt
	v_add_u32_e32 v192, 0xa0000, v251
	global_load_dwordx4 v[172:175], v192, s[68:69] offset:0 nt
	global_load_dwordx4 v[176:179], v192, s[68:69] offset:256 nt
	v_add_u32_e32 v192, 0xb0000, v251
	global_load_dwordx4 v[180:183], v192, s[68:69] offset:0 nt
	global_load_dwordx4 v[184:187], v192, s[68:69] offset:256 nt
	s_waitcnt vmcnt(15)
	v_lshlrev_b32_e32 v188, 16, v204
	v_and_b32_e32 v189, 0xffff0000, v204
	v_pk_add_f32 v[124:125], v[124:125], v[188:189]
	v_lshlrev_b32_e32 v188, 16, v205
	v_and_b32_e32 v189, 0xffff0000, v205
	v_pk_add_f32 v[126:127], v[126:127], v[188:189]
	v_lshlrev_b32_e32 v188, 16, v206
	v_and_b32_e32 v189, 0xffff0000, v206
	v_pk_add_f32 v[120:121], v[120:121], v[188:189]
	v_lshlrev_b32_e32 v188, 16, v207
	v_and_b32_e32 v189, 0xffff0000, v207
	v_pk_add_f32 v[122:123], v[122:123], v[188:189]
	v_cvt_pk_bf16_f32 v188, v124, v125
	v_cvt_pk_bf16_f32 v189, v126, v127
	v_cvt_pk_bf16_f32 v190, v120, v121
	v_cvt_pk_bf16_f32 v191, v122, v123
	v_cvt_pk_fp8_f32 v192, v124, v125
	v_cvt_pk_fp8_f32 v193, v120, v121
	v_cvt_pk_fp8_f32 v192, v126, v127 op_sel:[0,0,1]
	v_cvt_pk_fp8_f32 v193, v122, v123 op_sel:[0,0,1]
	v_mov_b32_e32 v204, v251
	v_mov_b32_e32 v205, v252
	global_store_dwordx4 v204, v[188:191], s[68:69] offset:0
	global_store_dwordx2 v205, v[192:193], s[14:15] offset:0
	v_mul_f32_e32 v125, v125, v125
	v_mul_f32_e32 v127, v127, v127
	v_mul_f32_e32 v121, v121, v121
	v_mul_f32_e32 v123, v123, v123
	v_fmac_f32_e32 v125, v124, v124
	v_fmac_f32_e32 v127, v126, v126
	v_fmac_f32_e32 v121, v120, v120
	v_fmac_f32_e32 v123, v122, v122
	v_add_f32_e32 v125, v125, v127
	v_add_f32_e32 v125, v125, v121
	v_add_f32_e32 v194, v123, v125
	s_waitcnt vmcnt(16)
	v_lshlrev_b32_e32 v188, 16, v208
	v_and_b32_e32 v189, 0xffff0000, v208
	v_pk_add_f32 v[116:117], v[116:117], v[188:189]
	v_lshlrev_b32_e32 v188, 16, v209
	v_and_b32_e32 v189, 0xffff0000, v209
	v_pk_add_f32 v[118:119], v[118:119], v[188:189]
	v_lshlrev_b32_e32 v188, 16, v210
	v_and_b32_e32 v189, 0xffff0000, v210
	v_pk_add_f32 v[112:113], v[112:113], v[188:189]
	v_lshlrev_b32_e32 v188, 16, v211
	v_and_b32_e32 v189, 0xffff0000, v211
	v_pk_add_f32 v[114:115], v[114:115], v[188:189]
	v_cvt_pk_bf16_f32 v188, v116, v117
	v_cvt_pk_bf16_f32 v189, v118, v119
	v_cvt_pk_bf16_f32 v190, v112, v113
	v_cvt_pk_bf16_f32 v191, v114, v115
	v_cvt_pk_fp8_f32 v192, v116, v117
	v_cvt_pk_fp8_f32 v193, v112, v113
	v_cvt_pk_fp8_f32 v192, v118, v119 op_sel:[0,0,1]
	v_cvt_pk_fp8_f32 v193, v114, v115 op_sel:[0,0,1]
	v_mov_b32_e32 v208, v251
	v_mov_b32_e32 v209, v252
	global_store_dwordx4 v208, v[188:191], s[68:69] offset:256
	global_store_dwordx2 v209, v[192:193], s[14:15] offset:128
	v_mul_f32_e32 v117, v117, v117
	v_mul_f32_e32 v119, v119, v119
	v_mul_f32_e32 v113, v113, v113
	v_mul_f32_e32 v115, v115, v115
	v_fmac_f32_e32 v117, v116, v116
	v_fmac_f32_e32 v119, v118, v118
	v_fmac_f32_e32 v113, v112, v112
	v_fmac_f32_e32 v115, v114, v114
	v_add_f32_e32 v117, v117, v119
	v_add_f32_e32 v117, v117, v113
	v_add_f32_e32 v117, v115, v117
	v_add_f32_e32 v194, v194, v117
	s_waitcnt vmcnt(17)
	v_lshlrev_b32_e32 v188, 16, v212
	v_and_b32_e32 v189, 0xffff0000, v212
	v_pk_add_f32 v[108:109], v[108:109], v[188:189]
	v_lshlrev_b32_e32 v188, 16, v213
	v_and_b32_e32 v189, 0xffff0000, v213
	v_pk_add_f32 v[110:111], v[110:111], v[188:189]
	v_lshlrev_b32_e32 v188, 16, v214
	v_and_b32_e32 v189, 0xffff0000, v214
	v_pk_add_f32 v[104:105], v[104:105], v[188:189]
	v_lshlrev_b32_e32 v188, 16, v215
	v_and_b32_e32 v189, 0xffff0000, v215
	v_pk_add_f32 v[106:107], v[106:107], v[188:189]
	v_cvt_pk_bf16_f32 v188, v108, v109
	v_cvt_pk_bf16_f32 v189, v110, v111
	v_cvt_pk_bf16_f32 v190, v104, v105
	v_cvt_pk_bf16_f32 v191, v106, v107
	v_cvt_pk_fp8_f32 v192, v108, v109
	v_cvt_pk_fp8_f32 v193, v104, v105
	v_cvt_pk_fp8_f32 v192, v110, v111 op_sel:[0,0,1]
	v_cvt_pk_fp8_f32 v193, v106, v107 op_sel:[0,0,1]
	v_add_u32_e32 v212, 0x10000, v251
	v_add_u32_e32 v213, 0x8000, v252
	global_store_dwordx4 v212, v[188:191], s[68:69] offset:0
	global_store_dwordx2 v213, v[192:193], s[14:15] offset:0
	v_mul_f32_e32 v109, v109, v109
	v_mul_f32_e32 v111, v111, v111
	v_mul_f32_e32 v105, v105, v105
	v_mul_f32_e32 v107, v107, v107
	v_fmac_f32_e32 v109, v108, v108
	v_fmac_f32_e32 v111, v110, v110
	v_fmac_f32_e32 v105, v104, v104
	v_fmac_f32_e32 v107, v106, v106
	v_add_f32_e32 v109, v109, v111
	v_add_f32_e32 v109, v109, v105
	v_add_f32_e32 v195, v107, v109
	s_waitcnt vmcnt(18)
	v_lshlrev_b32_e32 v188, 16, v216
	v_and_b32_e32 v189, 0xffff0000, v216
	v_pk_add_f32 v[100:101], v[100:101], v[188:189]
	v_lshlrev_b32_e32 v188, 16, v217
	v_and_b32_e32 v189, 0xffff0000, v217
	v_pk_add_f32 v[102:103], v[102:103], v[188:189]
	v_lshlrev_b32_e32 v188, 16, v218
	v_and_b32_e32 v189, 0xffff0000, v218
	v_pk_add_f32 v[96:97], v[96:97], v[188:189]
	v_lshlrev_b32_e32 v188, 16, v219
	v_and_b32_e32 v189, 0xffff0000, v219
	v_pk_add_f32 v[98:99], v[98:99], v[188:189]
	v_cvt_pk_bf16_f32 v188, v100, v101
	v_cvt_pk_bf16_f32 v189, v102, v103
	v_cvt_pk_bf16_f32 v190, v96, v97
	v_cvt_pk_bf16_f32 v191, v98, v99
	v_cvt_pk_fp8_f32 v192, v100, v101
	v_cvt_pk_fp8_f32 v193, v96, v97
	v_cvt_pk_fp8_f32 v192, v102, v103 op_sel:[0,0,1]
	v_cvt_pk_fp8_f32 v193, v98, v99 op_sel:[0,0,1]
	v_add_u32_e32 v216, 0x10000, v251
	v_add_u32_e32 v217, 0x8000, v252
	global_store_dwordx4 v216, v[188:191], s[68:69] offset:256
	global_store_dwordx2 v217, v[192:193], s[14:15] offset:128
	v_mul_f32_e32 v101, v101, v101
	v_mul_f32_e32 v103, v103, v103
	v_mul_f32_e32 v97, v97, v97
	v_mul_f32_e32 v99, v99, v99
	v_fmac_f32_e32 v101, v100, v100
	v_fmac_f32_e32 v103, v102, v102
	v_fmac_f32_e32 v97, v96, v96
	v_fmac_f32_e32 v99, v98, v98
	v_add_f32_e32 v101, v101, v103
	v_add_f32_e32 v101, v101, v97
	v_add_f32_e32 v101, v99, v101
	v_add_f32_e32 v195, v195, v101
	s_waitcnt vmcnt(19)
	v_lshlrev_b32_e32 v188, 16, v220
	v_and_b32_e32 v189, 0xffff0000, v220
	v_pk_add_f32 v[92:93], v[92:93], v[188:189]
	v_lshlrev_b32_e32 v188, 16, v221
	v_and_b32_e32 v189, 0xffff0000, v221
	v_pk_add_f32 v[94:95], v[94:95], v[188:189]
	v_lshlrev_b32_e32 v188, 16, v222
	v_and_b32_e32 v189, 0xffff0000, v222
	v_pk_add_f32 v[88:89], v[88:89], v[188:189]
	v_lshlrev_b32_e32 v188, 16, v223
	v_and_b32_e32 v189, 0xffff0000, v223
	v_pk_add_f32 v[90:91], v[90:91], v[188:189]
	v_cvt_pk_bf16_f32 v188, v92, v93
	v_cvt_pk_bf16_f32 v189, v94, v95
	v_cvt_pk_bf16_f32 v190, v88, v89
	v_cvt_pk_bf16_f32 v191, v90, v91
	v_cvt_pk_fp8_f32 v192, v92, v93
	v_cvt_pk_fp8_f32 v193, v88, v89
	v_cvt_pk_fp8_f32 v192, v94, v95 op_sel:[0,0,1]
	v_cvt_pk_fp8_f32 v193, v90, v91 op_sel:[0,0,1]
	v_add_u32_e32 v220, 0x20000, v251
	v_add_u32_e32 v221, 0x10000, v252
	global_store_dwordx4 v220, v[188:191], s[68:69] offset:0
	global_store_dwordx2 v221, v[192:193], s[14:15] offset:0
	v_mul_f32_e32 v93, v93, v93
	v_mul_f32_e32 v95, v95, v95
	v_mul_f32_e32 v89, v89, v89
	v_mul_f32_e32 v91, v91, v91
	v_fmac_f32_e32 v93, v92, v92
	v_fmac_f32_e32 v95, v94, v94
	v_fmac_f32_e32 v89, v88, v88
	v_fmac_f32_e32 v91, v90, v90
	v_add_f32_e32 v93, v93, v95
	v_add_f32_e32 v93, v93, v89
	v_add_f32_e32 v196, v91, v93
	s_waitcnt vmcnt(20)
	v_lshlrev_b32_e32 v188, 16, v224
	v_and_b32_e32 v189, 0xffff0000, v224
	v_pk_add_f32 v[84:85], v[84:85], v[188:189]
	v_lshlrev_b32_e32 v188, 16, v225
	v_and_b32_e32 v189, 0xffff0000, v225
	v_pk_add_f32 v[86:87], v[86:87], v[188:189]
	v_lshlrev_b32_e32 v188, 16, v226
	v_and_b32_e32 v189, 0xffff0000, v226
	v_pk_add_f32 v[80:81], v[80:81], v[188:189]
	v_lshlrev_b32_e32 v188, 16, v227
	v_and_b32_e32 v189, 0xffff0000, v227
	v_pk_add_f32 v[82:83], v[82:83], v[188:189]
	v_cvt_pk_bf16_f32 v188, v84, v85
	v_cvt_pk_bf16_f32 v189, v86, v87
	v_cvt_pk_bf16_f32 v190, v80, v81
	v_cvt_pk_bf16_f32 v191, v82, v83
	v_cvt_pk_fp8_f32 v192, v84, v85
	v_cvt_pk_fp8_f32 v193, v80, v81
	v_cvt_pk_fp8_f32 v192, v86, v87 op_sel:[0,0,1]
	v_cvt_pk_fp8_f32 v193, v82, v83 op_sel:[0,0,1]
	v_add_u32_e32 v224, 0x20000, v251
	v_add_u32_e32 v225, 0x10000, v252
	global_store_dwordx4 v224, v[188:191], s[68:69] offset:256
	global_store_dwordx2 v225, v[192:193], s[14:15] offset:128
	v_mul_f32_e32 v85, v85, v85
	v_mul_f32_e32 v87, v87, v87
	v_mul_f32_e32 v81, v81, v81
	v_mul_f32_e32 v83, v83, v83
	v_fmac_f32_e32 v85, v84, v84
	v_fmac_f32_e32 v87, v86, v86
	v_fmac_f32_e32 v81, v80, v80
	v_fmac_f32_e32 v83, v82, v82
	v_add_f32_e32 v85, v85, v87
	v_add_f32_e32 v85, v85, v81
	v_add_f32_e32 v85, v83, v85
	v_add_f32_e32 v196, v196, v85
	s_waitcnt vmcnt(21)
	v_lshlrev_b32_e32 v188, 16, v228
	v_and_b32_e32 v189, 0xffff0000, v228
	v_pk_add_f32 v[76:77], v[76:77], v[188:189]
	v_lshlrev_b32_e32 v188, 16, v229
	v_and_b32_e32 v189, 0xffff0000, v229
	v_pk_add_f32 v[78:79], v[78:79], v[188:189]
	v_lshlrev_b32_e32 v188, 16, v230
	v_and_b32_e32 v189, 0xffff0000, v230
	v_pk_add_f32 v[72:73], v[72:73], v[188:189]
	v_lshlrev_b32_e32 v188, 16, v231
	v_and_b32_e32 v189, 0xffff0000, v231
	v_pk_add_f32 v[74:75], v[74:75], v[188:189]
	v_cvt_pk_bf16_f32 v188, v76, v77
	v_cvt_pk_bf16_f32 v189, v78, v79
	v_cvt_pk_bf16_f32 v190, v72, v73
	v_cvt_pk_bf16_f32 v191, v74, v75
	v_cvt_pk_fp8_f32 v192, v76, v77
	v_cvt_pk_fp8_f32 v193, v72, v73
	v_cvt_pk_fp8_f32 v192, v78, v79 op_sel:[0,0,1]
	v_cvt_pk_fp8_f32 v193, v74, v75 op_sel:[0,0,1]
	v_add_u32_e32 v228, 0x30000, v251
	v_add_u32_e32 v229, 0x18000, v252
	global_store_dwordx4 v228, v[188:191], s[68:69] offset:0
	global_store_dwordx2 v229, v[192:193], s[14:15] offset:0
	v_mul_f32_e32 v77, v77, v77
	v_mul_f32_e32 v79, v79, v79
	v_mul_f32_e32 v73, v73, v73
	v_mul_f32_e32 v75, v75, v75
	v_fmac_f32_e32 v77, v76, v76
	v_fmac_f32_e32 v79, v78, v78
	v_fmac_f32_e32 v73, v72, v72
	v_fmac_f32_e32 v75, v74, v74
	v_add_f32_e32 v77, v77, v79
	v_add_f32_e32 v77, v77, v73
	v_add_f32_e32 v249, v75, v77
	s_waitcnt vmcnt(22)
	v_lshlrev_b32_e32 v188, 16, v232
	v_and_b32_e32 v189, 0xffff0000, v232
	v_pk_add_f32 v[68:69], v[68:69], v[188:189]
	v_lshlrev_b32_e32 v188, 16, v233
	v_and_b32_e32 v189, 0xffff0000, v233
	v_pk_add_f32 v[70:71], v[70:71], v[188:189]
	v_lshlrev_b32_e32 v188, 16, v234
	v_and_b32_e32 v189, 0xffff0000, v234
	v_pk_add_f32 v[64:65], v[64:65], v[188:189]
	v_lshlrev_b32_e32 v188, 16, v235
	v_and_b32_e32 v189, 0xffff0000, v235
	v_pk_add_f32 v[66:67], v[66:67], v[188:189]
	v_cvt_pk_bf16_f32 v188, v68, v69
	v_cvt_pk_bf16_f32 v189, v70, v71
	v_cvt_pk_bf16_f32 v190, v64, v65
	v_cvt_pk_bf16_f32 v191, v66, v67
	v_cvt_pk_fp8_f32 v192, v68, v69
	v_cvt_pk_fp8_f32 v193, v64, v65
	v_cvt_pk_fp8_f32 v192, v70, v71 op_sel:[0,0,1]
	v_cvt_pk_fp8_f32 v193, v66, v67 op_sel:[0,0,1]
	v_add_u32_e32 v232, 0x30000, v251
	v_add_u32_e32 v233, 0x18000, v252
	global_store_dwordx4 v232, v[188:191], s[68:69] offset:256
	global_store_dwordx2 v233, v[192:193], s[14:15] offset:128
	v_mul_f32_e32 v69, v69, v69
	v_mul_f32_e32 v71, v71, v71
	v_mul_f32_e32 v65, v65, v65
	v_mul_f32_e32 v67, v67, v67
	v_fmac_f32_e32 v69, v68, v68
	v_fmac_f32_e32 v71, v70, v70
	v_fmac_f32_e32 v65, v64, v64
	v_fmac_f32_e32 v67, v66, v66
	v_add_f32_e32 v69, v69, v71
	v_add_f32_e32 v69, v69, v65
	v_add_f32_e32 v69, v67, v69
	v_add_f32_e32 v249, v249, v69
	ds_bpermute_b32 v188, v254, v194
	ds_bpermute_b32 v189, v254, v195
	ds_bpermute_b32 v190, v254, v196
	ds_bpermute_b32 v191, v254, v249
	s_waitcnt lgkmcnt(0)
	v_add_f32_e32 v194, v194, v188
	v_add_f32_e32 v195, v195, v189
	v_add_f32_e32 v196, v196, v190
	v_add_f32_e32 v249, v249, v191
	ds_bpermute_b32 v188, v255, v194
	ds_bpermute_b32 v189, v255, v195
	ds_bpermute_b32 v190, v255, v196
	ds_bpermute_b32 v191, v255, v249
	s_waitcnt lgkmcnt(0)
	v_add_f32_e32 v194, v194, v188
	v_add_f32_e32 v195, v195, v189
	v_add_f32_e32 v196, v196, v190
	v_add_f32_e32 v249, v249, v191
	s_and_saveexec_b64 s[28:29], s[4:5]
	global_atomic_add_f32 v253, v194, s[12:13] offset:0
	global_atomic_add_f32 v253, v195, s[12:13] offset:64
	global_atomic_add_f32 v253, v196, s[12:13] offset:128
	global_atomic_add_f32 v253, v249, s[12:13] offset:192
	s_or_b64 exec, exec, s[28:29]
	s_waitcnt vmcnt(27)
	v_lshlrev_b32_e32 v188, 16, v236
	v_and_b32_e32 v189, 0xffff0000, v236
	v_pk_add_f32 v[60:61], v[60:61], v[188:189]
	v_lshlrev_b32_e32 v188, 16, v237
	v_and_b32_e32 v189, 0xffff0000, v237
	v_pk_add_f32 v[62:63], v[62:63], v[188:189]
	v_lshlrev_b32_e32 v188, 16, v238
	v_and_b32_e32 v189, 0xffff0000, v238
	v_pk_add_f32 v[56:57], v[56:57], v[188:189]
	v_lshlrev_b32_e32 v188, 16, v239
	v_and_b32_e32 v189, 0xffff0000, v239
	v_pk_add_f32 v[58:59], v[58:59], v[188:189]
	v_cvt_pk_bf16_f32 v188, v60, v61
	v_cvt_pk_bf16_f32 v189, v62, v63
	v_cvt_pk_bf16_f32 v190, v56, v57
	v_cvt_pk_bf16_f32 v191, v58, v59
	v_cvt_pk_fp8_f32 v192, v60, v61
	v_cvt_pk_fp8_f32 v193, v56, v57
	v_cvt_pk_fp8_f32 v192, v62, v63 op_sel:[0,0,1]
	v_cvt_pk_fp8_f32 v193, v58, v59 op_sel:[0,0,1]
	v_add_u32_e32 v236, 0x80000, v251
	v_add_u32_e32 v237, 0x40000, v252
	global_store_dwordx4 v236, v[188:191], s[68:69] offset:0
	global_store_dwordx2 v237, v[192:193], s[14:15] offset:0
	v_mul_f32_e32 v61, v61, v61
	v_mul_f32_e32 v63, v63, v63
	v_mul_f32_e32 v57, v57, v57
	v_mul_f32_e32 v59, v59, v59
	v_fmac_f32_e32 v61, v60, v60
	v_fmac_f32_e32 v63, v62, v62
	v_fmac_f32_e32 v57, v56, v56
	v_fmac_f32_e32 v59, v58, v58
	v_add_f32_e32 v61, v61, v63
	v_add_f32_e32 v61, v61, v57
	v_add_f32_e32 v194, v59, v61
	s_waitcnt vmcnt(28)
	v_lshlrev_b32_e32 v188, 16, v240
	v_and_b32_e32 v189, 0xffff0000, v240
	v_pk_add_f32 v[52:53], v[52:53], v[188:189]
	v_lshlrev_b32_e32 v188, 16, v241
	v_and_b32_e32 v189, 0xffff0000, v241
	v_pk_add_f32 v[54:55], v[54:55], v[188:189]
	v_lshlrev_b32_e32 v188, 16, v242
	v_and_b32_e32 v189, 0xffff0000, v242
	v_pk_add_f32 v[48:49], v[48:49], v[188:189]
	v_lshlrev_b32_e32 v188, 16, v243
	v_and_b32_e32 v189, 0xffff0000, v243
	v_pk_add_f32 v[50:51], v[50:51], v[188:189]
	v_cvt_pk_bf16_f32 v188, v52, v53
	v_cvt_pk_bf16_f32 v189, v54, v55
	v_cvt_pk_bf16_f32 v190, v48, v49
	v_cvt_pk_bf16_f32 v191, v50, v51
	v_cvt_pk_fp8_f32 v192, v52, v53
	v_cvt_pk_fp8_f32 v193, v48, v49
	v_cvt_pk_fp8_f32 v192, v54, v55 op_sel:[0,0,1]
	v_cvt_pk_fp8_f32 v193, v50, v51 op_sel:[0,0,1]
	v_add_u32_e32 v240, 0x80000, v251
	v_add_u32_e32 v241, 0x40000, v252
	global_store_dwordx4 v240, v[188:191], s[68:69] offset:256
	global_store_dwordx2 v241, v[192:193], s[14:15] offset:128
	v_mul_f32_e32 v53, v53, v53
	v_mul_f32_e32 v55, v55, v55
	v_mul_f32_e32 v49, v49, v49
	v_mul_f32_e32 v51, v51, v51
	v_fmac_f32_e32 v53, v52, v52
	v_fmac_f32_e32 v55, v54, v54
	v_fmac_f32_e32 v49, v48, v48
	v_fmac_f32_e32 v51, v50, v50
	v_add_f32_e32 v53, v53, v55
	v_add_f32_e32 v53, v53, v49
	v_add_f32_e32 v53, v51, v53
	v_add_f32_e32 v194, v194, v53
	s_waitcnt vmcnt(29)
	v_lshlrev_b32_e32 v188, 16, v244
	v_and_b32_e32 v189, 0xffff0000, v244
	v_pk_add_f32 v[44:45], v[44:45], v[188:189]
	v_lshlrev_b32_e32 v188, 16, v245
	v_and_b32_e32 v189, 0xffff0000, v245
	v_pk_add_f32 v[46:47], v[46:47], v[188:189]
	v_lshlrev_b32_e32 v188, 16, v246
	v_and_b32_e32 v189, 0xffff0000, v246
	v_pk_add_f32 v[40:41], v[40:41], v[188:189]
	v_lshlrev_b32_e32 v188, 16, v247
	v_and_b32_e32 v189, 0xffff0000, v247
	v_pk_add_f32 v[42:43], v[42:43], v[188:189]
	v_cvt_pk_bf16_f32 v188, v44, v45
	v_cvt_pk_bf16_f32 v189, v46, v47
	v_cvt_pk_bf16_f32 v190, v40, v41
	v_cvt_pk_bf16_f32 v191, v42, v43
	v_cvt_pk_fp8_f32 v192, v44, v45
	v_cvt_pk_fp8_f32 v193, v40, v41
	v_cvt_pk_fp8_f32 v192, v46, v47 op_sel:[0,0,1]
	v_cvt_pk_fp8_f32 v193, v42, v43 op_sel:[0,0,1]
	v_add_u32_e32 v244, 0x90000, v251
	v_add_u32_e32 v245, 0x48000, v252
	global_store_dwordx4 v244, v[188:191], s[68:69] offset:0
	global_store_dwordx2 v245, v[192:193], s[14:15] offset:0
	v_mul_f32_e32 v45, v45, v45
	v_mul_f32_e32 v47, v47, v47
	v_mul_f32_e32 v41, v41, v41
	v_mul_f32_e32 v43, v43, v43
	v_fmac_f32_e32 v45, v44, v44
	v_fmac_f32_e32 v47, v46, v46
	v_fmac_f32_e32 v41, v40, v40
	v_fmac_f32_e32 v43, v42, v42
	v_add_f32_e32 v45, v45, v47
	v_add_f32_e32 v45, v45, v41
	v_add_f32_e32 v195, v43, v45
	s_waitcnt vmcnt(30)
	v_lshlrev_b32_e32 v188, 16, v168
	v_and_b32_e32 v189, 0xffff0000, v168
	v_pk_add_f32 v[36:37], v[36:37], v[188:189]
	v_lshlrev_b32_e32 v188, 16, v169
	v_and_b32_e32 v189, 0xffff0000, v169
	v_pk_add_f32 v[38:39], v[38:39], v[188:189]
	v_lshlrev_b32_e32 v188, 16, v170
	v_and_b32_e32 v189, 0xffff0000, v170
	v_pk_add_f32 v[32:33], v[32:33], v[188:189]
	v_lshlrev_b32_e32 v188, 16, v171
	v_and_b32_e32 v189, 0xffff0000, v171
	v_pk_add_f32 v[34:35], v[34:35], v[188:189]
	v_cvt_pk_bf16_f32 v188, v36, v37
	v_cvt_pk_bf16_f32 v189, v38, v39
	v_cvt_pk_bf16_f32 v190, v32, v33
	v_cvt_pk_bf16_f32 v191, v34, v35
	v_cvt_pk_fp8_f32 v192, v36, v37
	v_cvt_pk_fp8_f32 v193, v32, v33
	v_cvt_pk_fp8_f32 v192, v38, v39 op_sel:[0,0,1]
	v_cvt_pk_fp8_f32 v193, v34, v35 op_sel:[0,0,1]
	v_add_u32_e32 v168, 0x90000, v251
	v_add_u32_e32 v169, 0x48000, v252
	global_store_dwordx4 v168, v[188:191], s[68:69] offset:256
	global_store_dwordx2 v169, v[192:193], s[14:15] offset:128
	v_mul_f32_e32 v37, v37, v37
	v_mul_f32_e32 v39, v39, v39
	v_mul_f32_e32 v33, v33, v33
	v_mul_f32_e32 v35, v35, v35
	v_fmac_f32_e32 v37, v36, v36
	v_fmac_f32_e32 v39, v38, v38
	v_fmac_f32_e32 v33, v32, v32
	v_fmac_f32_e32 v35, v34, v34
	v_add_f32_e32 v37, v37, v39
	v_add_f32_e32 v37, v37, v33
	v_add_f32_e32 v37, v35, v37
	v_add_f32_e32 v195, v195, v37
	s_waitcnt vmcnt(31)
	v_lshlrev_b32_e32 v188, 16, v172
	v_and_b32_e32 v189, 0xffff0000, v172
	v_pk_add_f32 v[28:29], v[28:29], v[188:189]
	v_lshlrev_b32_e32 v188, 16, v173
	v_and_b32_e32 v189, 0xffff0000, v173
	v_pk_add_f32 v[30:31], v[30:31], v[188:189]
	v_lshlrev_b32_e32 v188, 16, v174
	v_and_b32_e32 v189, 0xffff0000, v174
	v_pk_add_f32 v[24:25], v[24:25], v[188:189]
	v_lshlrev_b32_e32 v188, 16, v175
	v_and_b32_e32 v189, 0xffff0000, v175
	v_pk_add_f32 v[26:27], v[26:27], v[188:189]
	v_cvt_pk_bf16_f32 v188, v28, v29
	v_cvt_pk_bf16_f32 v189, v30, v31
	v_cvt_pk_bf16_f32 v190, v24, v25
	v_cvt_pk_bf16_f32 v191, v26, v27
	v_cvt_pk_fp8_f32 v192, v28, v29
	v_cvt_pk_fp8_f32 v193, v24, v25
	v_cvt_pk_fp8_f32 v192, v30, v31 op_sel:[0,0,1]
	v_cvt_pk_fp8_f32 v193, v26, v27 op_sel:[0,0,1]
	v_add_u32_e32 v172, 0xa0000, v251
	v_add_u32_e32 v173, 0x50000, v252
	global_store_dwordx4 v172, v[188:191], s[68:69] offset:0
	global_store_dwordx2 v173, v[192:193], s[14:15] offset:0
	v_mul_f32_e32 v29, v29, v29
	v_mul_f32_e32 v31, v31, v31
	v_mul_f32_e32 v25, v25, v25
	v_mul_f32_e32 v27, v27, v27
	v_fmac_f32_e32 v29, v28, v28
	v_fmac_f32_e32 v31, v30, v30
	v_fmac_f32_e32 v25, v24, v24
	v_fmac_f32_e32 v27, v26, v26
	v_add_f32_e32 v29, v29, v31
	v_add_f32_e32 v29, v29, v25
	v_add_f32_e32 v196, v27, v29
	s_waitcnt vmcnt(32)
	v_lshlrev_b32_e32 v188, 16, v176
	v_and_b32_e32 v189, 0xffff0000, v176
	v_pk_add_f32 v[20:21], v[20:21], v[188:189]
	v_lshlrev_b32_e32 v188, 16, v177
	v_and_b32_e32 v189, 0xffff0000, v177
	v_pk_add_f32 v[22:23], v[22:23], v[188:189]
	v_lshlrev_b32_e32 v188, 16, v178
	v_and_b32_e32 v189, 0xffff0000, v178
	v_pk_add_f32 v[16:17], v[16:17], v[188:189]
	v_lshlrev_b32_e32 v188, 16, v179
	v_and_b32_e32 v189, 0xffff0000, v179
	v_pk_add_f32 v[18:19], v[18:19], v[188:189]
	v_cvt_pk_bf16_f32 v188, v20, v21
	v_cvt_pk_bf16_f32 v189, v22, v23
	v_cvt_pk_bf16_f32 v190, v16, v17
	v_cvt_pk_bf16_f32 v191, v18, v19
	v_cvt_pk_fp8_f32 v192, v20, v21
	v_cvt_pk_fp8_f32 v193, v16, v17
	v_cvt_pk_fp8_f32 v192, v22, v23 op_sel:[0,0,1]
	v_cvt_pk_fp8_f32 v193, v18, v19 op_sel:[0,0,1]
	v_add_u32_e32 v176, 0xa0000, v251
	v_add_u32_e32 v177, 0x50000, v252
	global_store_dwordx4 v176, v[188:191], s[68:69] offset:256
	global_store_dwordx2 v177, v[192:193], s[14:15] offset:128
	v_mul_f32_e32 v21, v21, v21
	v_mul_f32_e32 v23, v23, v23
	v_mul_f32_e32 v17, v17, v17
	v_mul_f32_e32 v19, v19, v19
	v_fmac_f32_e32 v21, v20, v20
	v_fmac_f32_e32 v23, v22, v22
	v_fmac_f32_e32 v17, v16, v16
	v_fmac_f32_e32 v19, v18, v18
	v_add_f32_e32 v21, v21, v23
	v_add_f32_e32 v21, v21, v17
	v_add_f32_e32 v21, v19, v21
	v_add_f32_e32 v196, v196, v21
	s_waitcnt vmcnt(33)
	v_lshlrev_b32_e32 v188, 16, v180
	v_and_b32_e32 v189, 0xffff0000, v180
	v_pk_add_f32 v[12:13], v[12:13], v[188:189]
	v_lshlrev_b32_e32 v188, 16, v181
	v_and_b32_e32 v189, 0xffff0000, v181
	v_pk_add_f32 v[14:15], v[14:15], v[188:189]
	v_lshlrev_b32_e32 v188, 16, v182
	v_and_b32_e32 v189, 0xffff0000, v182
	v_pk_add_f32 v[8:9], v[8:9], v[188:189]
	v_lshlrev_b32_e32 v188, 16, v183
	v_and_b32_e32 v189, 0xffff0000, v183
	v_pk_add_f32 v[10:11], v[10:11], v[188:189]
	v_cvt_pk_bf16_f32 v188, v12, v13
	v_cvt_pk_bf16_f32 v189, v14, v15
	v_cvt_pk_bf16_f32 v190, v8, v9
	v_cvt_pk_bf16_f32 v191, v10, v11
	v_cvt_pk_fp8_f32 v192, v12, v13
	v_cvt_pk_fp8_f32 v193, v8, v9
	v_cvt_pk_fp8_f32 v192, v14, v15 op_sel:[0,0,1]
	v_cvt_pk_fp8_f32 v193, v10, v11 op_sel:[0,0,1]
	v_add_u32_e32 v180, 0xb0000, v251
	v_add_u32_e32 v181, 0x58000, v252
	global_store_dwordx4 v180, v[188:191], s[68:69] offset:0
	global_store_dwordx2 v181, v[192:193], s[14:15] offset:0
	v_mul_f32_e32 v13, v13, v13
	v_mul_f32_e32 v15, v15, v15
	v_mul_f32_e32 v9, v9, v9
	v_mul_f32_e32 v11, v11, v11
	v_fmac_f32_e32 v13, v12, v12
	v_fmac_f32_e32 v15, v14, v14
	v_fmac_f32_e32 v9, v8, v8
	v_fmac_f32_e32 v11, v10, v10
	v_add_f32_e32 v13, v13, v15
	v_add_f32_e32 v13, v13, v9
	v_add_f32_e32 v249, v11, v13
	s_waitcnt vmcnt(34)
	v_lshlrev_b32_e32 v188, 16, v184
	v_and_b32_e32 v189, 0xffff0000, v184
	v_pk_add_f32 v[4:5], v[4:5], v[188:189]
	v_lshlrev_b32_e32 v188, 16, v185
	v_and_b32_e32 v189, 0xffff0000, v185
	v_pk_add_f32 v[6:7], v[6:7], v[188:189]
	v_lshlrev_b32_e32 v188, 16, v186
	v_and_b32_e32 v189, 0xffff0000, v186
	v_pk_add_f32 v[0:1], v[0:1], v[188:189]
	v_lshlrev_b32_e32 v188, 16, v187
	v_and_b32_e32 v189, 0xffff0000, v187
	v_pk_add_f32 v[2:3], v[2:3], v[188:189]
	v_cvt_pk_bf16_f32 v188, v4, v5
	v_cvt_pk_bf16_f32 v189, v6, v7
	v_cvt_pk_bf16_f32 v190, v0, v1
	v_cvt_pk_bf16_f32 v191, v2, v3
	v_cvt_pk_fp8_f32 v192, v4, v5
	v_cvt_pk_fp8_f32 v193, v0, v1
	v_cvt_pk_fp8_f32 v192, v6, v7 op_sel:[0,0,1]
	v_cvt_pk_fp8_f32 v193, v2, v3 op_sel:[0,0,1]
	v_add_u32_e32 v184, 0xb0000, v251
	v_add_u32_e32 v185, 0x58000, v252
	global_store_dwordx4 v184, v[188:191], s[68:69] offset:256
	global_store_dwordx2 v185, v[192:193], s[14:15] offset:128
	v_mul_f32_e32 v5, v5, v5
	v_mul_f32_e32 v7, v7, v7
	v_mul_f32_e32 v1, v1, v1
	v_mul_f32_e32 v3, v3, v3
	v_fmac_f32_e32 v5, v4, v4
	v_fmac_f32_e32 v7, v6, v6
	v_fmac_f32_e32 v1, v0, v0
	v_fmac_f32_e32 v3, v2, v2
	v_add_f32_e32 v5, v5, v7
	v_add_f32_e32 v5, v5, v1
	v_add_f32_e32 v5, v3, v5
	v_add_f32_e32 v249, v249, v5
	ds_bpermute_b32 v188, v254, v194
	ds_bpermute_b32 v189, v254, v195
	ds_bpermute_b32 v190, v254, v196
	ds_bpermute_b32 v191, v254, v249
	s_waitcnt lgkmcnt(0)
	v_add_f32_e32 v194, v194, v188
	v_add_f32_e32 v195, v195, v189
	v_add_f32_e32 v196, v196, v190
	v_add_f32_e32 v249, v249, v191
	ds_bpermute_b32 v188, v255, v194
	ds_bpermute_b32 v189, v255, v195
	ds_bpermute_b32 v190, v255, v196
	ds_bpermute_b32 v191, v255, v249
	s_waitcnt lgkmcnt(0)
	v_add_f32_e32 v194, v194, v188
	v_add_f32_e32 v195, v195, v189
	v_add_f32_e32 v196, v196, v190
	v_add_f32_e32 v249, v249, v191
	s_and_saveexec_b64 s[28:29], s[4:5]
	global_atomic_add_f32 v253, v194, s[12:13] offset:512
	global_atomic_add_f32 v253, v195, s[12:13] offset:576
	global_atomic_add_f32 v253, v196, s[12:13] offset:640
	global_atomic_add_f32 v253, v249, s[12:13] offset:704
	s_or_b64 exec, exec, s[28:29]
	s_andn2_b64 vcc, exec, s[6:7]
	s_mov_b64 s[6:7], -1
	s_cbranch_vccnz .LBB0_858
	s_andn2_b64 vcc, exec, s[10:11]
	s_cbranch_vccnz .LBB0_857
	s_barrier
	s_branch .LBB0_857

.LpgL1_vjoinv0:
	s_lshl_b32 s64, s0, 9
	s_add_u32 s64, s64, 0x1000
	s_add_u32 s70, s28, s64
	s_addc_u32 s71, s29, 0
	global_load_dwordx2 v[230:231], v239, s[70:71] nt
	s_waitcnt lgkmcnt(0)
	v_lshl_or_b32 v128, v128, 7, v232
	v_lshl_or_b32 v129, v129, 7, v232
	v_lshl_or_b32 v130, v130, 7, v232
	v_lshl_or_b32 v131, v131, 7, v232
	v_lshl_or_b32 v132, v132, 7, v232
	v_lshl_or_b32 v133, v133, 7, v232
	v_lshl_or_b32 v134, v134, 7, v232
	v_lshl_or_b32 v135, v135, 7, v232
	buffer_load_dwordx4 v[32:35], v128, s[20:23], s1 offen
	buffer_load_dwordx4 v[36:39], v129, s[20:23], s1 offen
	buffer_load_dwordx4 v[40:43], v130, s[20:23], s1 offen
	buffer_load_dwordx4 v[44:47], v131, s[20:23], s1 offen
	buffer_load_dwordx4 v[48:51], v132, s[20:23], s1 offen
	buffer_load_dwordx4 v[52:55], v133, s[20:23], s1 offen
	buffer_load_dwordx4 v[56:59], v134, s[20:23], s1 offen
	buffer_load_dwordx4 v[60:63], v135, s[20:23], s1 offen
	ds_read_b32 v128, v243 offset:1536
	ds_read_b32 v129, v243 offset:1568
	ds_read_b32 v130, v243 offset:1600
	ds_read_b32 v131, v243 offset:1632
	ds_read_b32 v132, v243 offset:1664
	ds_read_b32 v133, v243 offset:1696
	ds_read_b32 v134, v243 offset:1728
	ds_read_b32 v135, v243 offset:1760
	ds_read_b64 v[176:177], v234 offset:768
	ds_read_b64 v[178:179], v234 offset:800
	ds_read_b64 v[180:181], v234 offset:832
	ds_read_b64 v[182:183], v234 offset:864
	ds_read_b64 v[184:185], v234 offset:896
	ds_read_b64 v[186:187], v234 offset:928
	ds_read_b64 v[188:189], v234 offset:960
	ds_read_b64 v[190:191], v234 offset:992
	s_waitcnt vmcnt(28)
	v_and_b32_e32 v144, v160, v235
	v_and_b32_e32 v145, v160, v236
	v_and_b32_e32 v146, v160, v237
	v_and_b32_e32 v147, v160, v238
	v_and_b32_e32 v148, v161, v235
	v_and_b32_e32 v149, v161, v236
	v_and_b32_e32 v150, v161, v237
	v_and_b32_e32 v151, v161, v238
	s_mov_b64 vcc, s[4:5]
	v_cndmask_b32_dpp v138, v64, v66, vcc row_shl:4 row_mask:0xf bank_mask:0xf bound_ctrl:1
	v_cndmask_b32_dpp v139, v65, v67, vcc row_shl:4 row_mask:0xf bank_mask:0xf bound_ctrl:1
	s_mov_b64 vcc, s[6:7]
	v_cndmask_b32_dpp v136, v66, v64, vcc row_shr:4 row_mask:0xf bank_mask:0xf bound_ctrl:1
	v_cndmask_b32_dpp v137, v67, v65, vcc row_shr:4 row_mask:0xf bank_mask:0xf bound_ctrl:1
	v_and_b32_e32 v204, v162, v235
	v_and_b32_e32 v205, v162, v236
	v_and_b32_e32 v206, v162, v237
	v_and_b32_e32 v207, v162, v238
	v_and_b32_e32 v208, v163, v235
	v_and_b32_e32 v209, v163, v236
	v_and_b32_e32 v210, v163, v237
	v_and_b32_e32 v211, v163, v238
	s_mov_b64 vcc, s[6:7]
	v_cndmask_b32_dpp v140, v70, v68, vcc row_shr:4 row_mask:0xf bank_mask:0xf bound_ctrl:1
	v_cndmask_b32_dpp v141, v71, v69, vcc row_shr:4 row_mask:0xf bank_mask:0xf bound_ctrl:1
	s_mov_b64 vcc, s[4:5]
	v_cndmask_b32_dpp v142, v68, v70, vcc row_shl:4 row_mask:0xf bank_mask:0xf bound_ctrl:1
	v_cndmask_b32_dpp v143, v69, v71, vcc row_shl:4 row_mask:0xf bank_mask:0xf bound_ctrl:1
	v_mfma_scale_f32_16x16x128_f8f6f4 v[216:219], v[136:139], v[144:151], 0, v240, v241 op_sel_hi:[0,0,0] cbsz:4
	v_and_b32_e32 v144, v164, v235
	v_and_b32_e32 v145, v164, v236
	v_and_b32_e32 v146, v164, v237
	v_and_b32_e32 v147, v164, v238
	v_and_b32_e32 v148, v165, v235
	v_and_b32_e32 v149, v165, v236
	v_and_b32_e32 v150, v165, v237
	v_and_b32_e32 v151, v165, v238
	s_mov_b64 vcc, s[4:5]
	v_cndmask_b32_dpp v138, v72, v74, vcc row_shl:4 row_mask:0xf bank_mask:0xf bound_ctrl:1
	v_cndmask_b32_dpp v139, v73, v75, vcc row_shl:4 row_mask:0xf bank_mask:0xf bound_ctrl:1
	s_mov_b64 vcc, s[6:7]
	v_cndmask_b32_dpp v136, v74, v72, vcc row_shr:4 row_mask:0xf bank_mask:0xf bound_ctrl:1
	v_cndmask_b32_dpp v137, v75, v73, vcc row_shr:4 row_mask:0xf bank_mask:0xf bound_ctrl:1
	v_mfma_scale_f32_16x16x128_f8f6f4 v[216:219], v[140:143], v[204:211], v[216:219], v240, v241 op_sel_hi:[0,0,0] cbsz:4
	v_and_b32_e32 v204, v166, v235
	v_and_b32_e32 v205, v166, v236
	v_and_b32_e32 v206, v166, v237
	v_and_b32_e32 v207, v166, v238
	v_and_b32_e32 v208, v167, v235
	v_and_b32_e32 v209, v167, v236
	v_and_b32_e32 v210, v167, v237
	v_and_b32_e32 v211, v167, v238
	s_mov_b64 vcc, s[6:7]
	v_cndmask_b32_dpp v140, v78, v76, vcc row_shr:4 row_mask:0xf bank_mask:0xf bound_ctrl:1
	v_cndmask_b32_dpp v141, v79, v77, vcc row_shr:4 row_mask:0xf bank_mask:0xf bound_ctrl:1
	s_mov_b64 vcc, s[4:5]
	v_cndmask_b32_dpp v142, v76, v78, vcc row_shl:4 row_mask:0xf bank_mask:0xf bound_ctrl:1
	v_cndmask_b32_dpp v143, v77, v79, vcc row_shl:4 row_mask:0xf bank_mask:0xf bound_ctrl:1
	v_mfma_scale_f32_16x16x128_f8f6f4 v[216:219], v[136:139], v[144:151], v[216:219], v240, v241 op_sel_hi:[0,0,0] cbsz:4
	v_and_b32_e32 v144, v168, v235
	v_and_b32_e32 v145, v168, v236
	v_and_b32_e32 v146, v168, v237
	v_and_b32_e32 v147, v168, v238
	v_and_b32_e32 v148, v169, v235
	v_and_b32_e32 v149, v169, v236
	v_and_b32_e32 v150, v169, v237
	v_and_b32_e32 v151, v169, v238
	s_mov_b64 vcc, s[4:5]
	v_cndmask_b32_dpp v138, v80, v82, vcc row_shl:4 row_mask:0xf bank_mask:0xf bound_ctrl:1
	v_cndmask_b32_dpp v139, v81, v83, vcc row_shl:4 row_mask:0xf bank_mask:0xf bound_ctrl:1
	s_mov_b64 vcc, s[6:7]
	v_cndmask_b32_dpp v136, v82, v80, vcc row_shr:4 row_mask:0xf bank_mask:0xf bound_ctrl:1
	v_cndmask_b32_dpp v137, v83, v81, vcc row_shr:4 row_mask:0xf bank_mask:0xf bound_ctrl:1
	v_mfma_scale_f32_16x16x128_f8f6f4 v[216:219], v[140:143], v[204:211], v[216:219], v240, v241 op_sel_hi:[0,0,0] cbsz:4
	v_and_b32_e32 v204, v170, v235
	v_and_b32_e32 v205, v170, v236
	v_and_b32_e32 v206, v170, v237
	v_and_b32_e32 v207, v170, v238
	v_and_b32_e32 v208, v171, v235
	v_and_b32_e32 v209, v171, v236
	v_and_b32_e32 v210, v171, v237
	v_and_b32_e32 v211, v171, v238
	s_mov_b64 vcc, s[6:7]
	v_cndmask_b32_dpp v140, v86, v84, vcc row_shr:4 row_mask:0xf bank_mask:0xf bound_ctrl:1
	v_cndmask_b32_dpp v141, v87, v85, vcc row_shr:4 row_mask:0xf bank_mask:0xf bound_ctrl:1
	s_mov_b64 vcc, s[4:5]
	v_cndmask_b32_dpp v142, v84, v86, vcc row_shl:4 row_mask:0xf bank_mask:0xf bound_ctrl:1
	v_cndmask_b32_dpp v143, v85, v87, vcc row_shl:4 row_mask:0xf bank_mask:0xf bound_ctrl:1
	v_mfma_scale_f32_16x16x128_f8f6f4 v[216:219], v[136:139], v[144:151], v[216:219], v240, v241 op_sel_hi:[0,0,0] cbsz:4
	v_and_b32_e32 v144, v172, v235
	v_and_b32_e32 v145, v172, v236
	v_and_b32_e32 v146, v172, v237
	v_and_b32_e32 v147, v172, v238
	v_and_b32_e32 v148, v173, v235
	v_and_b32_e32 v149, v173, v236
	v_and_b32_e32 v150, v173, v237
	v_and_b32_e32 v151, v173, v238
	s_mov_b64 vcc, s[4:5]
	v_cndmask_b32_dpp v138, v88, v90, vcc row_shl:4 row_mask:0xf bank_mask:0xf bound_ctrl:1
	v_cndmask_b32_dpp v139, v89, v91, vcc row_shl:4 row_mask:0xf bank_mask:0xf bound_ctrl:1
	s_mov_b64 vcc, s[6:7]
	v_cndmask_b32_dpp v136, v90, v88, vcc row_shr:4 row_mask:0xf bank_mask:0xf bound_ctrl:1
	v_cndmask_b32_dpp v137, v91, v89, vcc row_shr:4 row_mask:0xf bank_mask:0xf bound_ctrl:1
	v_mfma_scale_f32_16x16x128_f8f6f4 v[216:219], v[140:143], v[204:211], v[216:219], v240, v241 op_sel_hi:[0,0,0] cbsz:4
	v_and_b32_e32 v204, v174, v235
	v_and_b32_e32 v205, v174, v236
	v_and_b32_e32 v206, v174, v237
	v_and_b32_e32 v207, v174, v238
	v_and_b32_e32 v208, v175, v235
	v_and_b32_e32 v209, v175, v236
	v_and_b32_e32 v210, v175, v237
	v_and_b32_e32 v211, v175, v238
	s_mov_b64 vcc, s[6:7]
	v_cndmask_b32_dpp v140, v94, v92, vcc row_shr:4 row_mask:0xf bank_mask:0xf bound_ctrl:1
	v_cndmask_b32_dpp v141, v95, v93, vcc row_shr:4 row_mask:0xf bank_mask:0xf bound_ctrl:1
	s_mov_b64 vcc, s[4:5]
	v_cndmask_b32_dpp v142, v92, v94, vcc row_shl:4 row_mask:0xf bank_mask:0xf bound_ctrl:1
	v_cndmask_b32_dpp v143, v93, v95, vcc row_shl:4 row_mask:0xf bank_mask:0xf bound_ctrl:1
	v_mfma_scale_f32_16x16x128_f8f6f4 v[216:219], v[136:139], v[144:151], v[216:219], v240, v241 op_sel_hi:[0,0,0] cbsz:4
	s_nop 0
	v_mfma_scale_f32_16x16x128_f8f6f4 v[216:219], v[140:143], v[204:211], v[216:219], v240, v241 op_sel_hi:[0,0,0] cbsz:4
	s_waitcnt lgkmcnt(0)
	v_lshl_or_b32 v128, v128, 7, v232
	v_lshl_or_b32 v129, v129, 7, v232
	v_lshl_or_b32 v130, v130, 7, v232
	v_lshl_or_b32 v131, v131, 7, v232
	v_lshl_or_b32 v132, v132, 7, v232
	v_lshl_or_b32 v133, v133, 7, v232
	v_lshl_or_b32 v134, v134, 7, v232
	v_lshl_or_b32 v135, v135, 7, v232
	buffer_load_dwordx4 v[64:67], v128, s[20:23], s1 offen
	buffer_load_dwordx4 v[68:71], v129, s[20:23], s1 offen
	buffer_load_dwordx4 v[72:75], v130, s[20:23], s1 offen
	buffer_load_dwordx4 v[76:79], v131, s[20:23], s1 offen
	buffer_load_dwordx4 v[80:83], v132, s[20:23], s1 offen
	buffer_load_dwordx4 v[84:87], v133, s[20:23], s1 offen
	buffer_load_dwordx4 v[88:91], v134, s[20:23], s1 offen
	buffer_load_dwordx4 v[92:95], v135, s[20:23], s1 offen
	ds_read_b32 v128, v243 offset:1792
	ds_read_b32 v129, v243 offset:1824
	ds_read_b32 v130, v243 offset:1856
	ds_read_b32 v131, v243 offset:1888
	ds_read_b32 v132, v243 offset:1920
	ds_read_b32 v133, v243 offset:1952
	ds_read_b32 v134, v243 offset:1984
	ds_read_b32 v135, v243 offset:2016
	ds_read_b64 v[160:161], v234 offset:1024
	ds_read_b64 v[162:163], v234 offset:1056
	ds_read_b64 v[164:165], v234 offset:1088
	ds_read_b64 v[166:167], v234 offset:1120
	ds_read_b64 v[168:169], v234 offset:1152
	ds_read_b64 v[170:171], v234 offset:1184
	ds_read_b64 v[172:173], v234 offset:1216
	ds_read_b64 v[174:175], v234 offset:1248
	s_waitcnt vmcnt(26)
	v_and_b32_e32 v144, v176, v235
	v_and_b32_e32 v145, v176, v236
	v_and_b32_e32 v146, v176, v237
	v_and_b32_e32 v147, v176, v238
	v_and_b32_e32 v148, v177, v235
	v_and_b32_e32 v149, v177, v236
	v_and_b32_e32 v150, v177, v237
	v_and_b32_e32 v151, v177, v238
	s_mov_b64 vcc, s[4:5]
	v_cndmask_b32_dpp v138, v96, v98, vcc row_shl:4 row_mask:0xf bank_mask:0xf bound_ctrl:1
	v_cndmask_b32_dpp v139, v97, v99, vcc row_shl:4 row_mask:0xf bank_mask:0xf bound_ctrl:1
	s_mov_b64 vcc, s[6:7]
	v_cndmask_b32_dpp v136, v98, v96, vcc row_shr:4 row_mask:0xf bank_mask:0xf bound_ctrl:1
	v_cndmask_b32_dpp v137, v99, v97, vcc row_shr:4 row_mask:0xf bank_mask:0xf bound_ctrl:1
	v_and_b32_e32 v204, v178, v235
	v_and_b32_e32 v205, v178, v236
	v_and_b32_e32 v206, v178, v237
	v_and_b32_e32 v207, v178, v238
	v_and_b32_e32 v208, v179, v235
	v_and_b32_e32 v209, v179, v236
	v_and_b32_e32 v210, v179, v237
	v_and_b32_e32 v211, v179, v238
	s_mov_b64 vcc, s[6:7]
	v_cndmask_b32_dpp v140, v102, v100, vcc row_shr:4 row_mask:0xf bank_mask:0xf bound_ctrl:1
	v_cndmask_b32_dpp v141, v103, v101, vcc row_shr:4 row_mask:0xf bank_mask:0xf bound_ctrl:1
	s_mov_b64 vcc, s[4:5]
	v_cndmask_b32_dpp v142, v100, v102, vcc row_shl:4 row_mask:0xf bank_mask:0xf bound_ctrl:1
	v_cndmask_b32_dpp v143, v101, v103, vcc row_shl:4 row_mask:0xf bank_mask:0xf bound_ctrl:1
	v_mfma_scale_f32_16x16x128_f8f6f4 v[216:219], v[136:139], v[144:151], v[216:219], v240, v241 op_sel_hi:[0,0,0] cbsz:4
	v_permlane16_swap_b32_e32 v212, v214
	v_permlane16_swap_b32_e32 v213, v215
	v_lshlrev_b32_e32 v252, 16, v228
	v_and_b32_e32 v144, v180, v235
	v_and_b32_e32 v145, v180, v236
	v_and_b32_e32 v146, v180, v237
	v_and_b32_e32 v147, v180, v238
	v_and_b32_e32 v148, v181, v235
	v_and_b32_e32 v149, v181, v236
	v_and_b32_e32 v150, v181, v237
	v_and_b32_e32 v151, v181, v238
	s_mov_b64 vcc, s[4:5]
	v_cndmask_b32_dpp v138, v104, v106, vcc row_shl:4 row_mask:0xf bank_mask:0xf bound_ctrl:1
	v_cndmask_b32_dpp v139, v105, v107, vcc row_shl:4 row_mask:0xf bank_mask:0xf bound_ctrl:1
	s_mov_b64 vcc, s[6:7]
	v_cndmask_b32_dpp v136, v106, v104, vcc row_shr:4 row_mask:0xf bank_mask:0xf bound_ctrl:1
	v_cndmask_b32_dpp v137, v107, v105, vcc row_shr:4 row_mask:0xf bank_mask:0xf bound_ctrl:1
	v_mfma_scale_f32_16x16x128_f8f6f4 v[216:219], v[140:143], v[204:211], v[216:219], v240, v241 op_sel_hi:[0,0,0] cbsz:4
	v_and_b32_e32 v253, 0xffff0000, v228
	v_lshlrev_b32_e32 v254, 16, v229
	v_and_b32_e32 v255, 0xffff0000, v229
	v_and_b32_e32 v204, v182, v235
	v_and_b32_e32 v205, v182, v236
	v_and_b32_e32 v206, v182, v237
	v_and_b32_e32 v207, v182, v238
	v_and_b32_e32 v208, v183, v235
	v_and_b32_e32 v209, v183, v236
	v_and_b32_e32 v210, v183, v237
	v_and_b32_e32 v211, v183, v238
	s_mov_b64 vcc, s[6:7]
	v_cndmask_b32_dpp v140, v110, v108, vcc row_shr:4 row_mask:0xf bank_mask:0xf bound_ctrl:1
	v_cndmask_b32_dpp v141, v111, v109, vcc row_shr:4 row_mask:0xf bank_mask:0xf bound_ctrl:1
	s_mov_b64 vcc, s[4:5]
	v_cndmask_b32_dpp v142, v108, v110, vcc row_shl:4 row_mask:0xf bank_mask:0xf bound_ctrl:1
	v_cndmask_b32_dpp v143, v109, v111, vcc row_shl:4 row_mask:0xf bank_mask:0xf bound_ctrl:1
	v_mfma_scale_f32_16x16x128_f8f6f4 v[216:219], v[136:139], v[144:151], v[216:219], v240, v241 op_sel_hi:[0,0,0] cbsz:4
	v_add_f32_e32 v252, v212, v252
	v_add_f32_e32 v253, v214, v253
	v_add_f32_e32 v254, v213, v254
	v_and_b32_e32 v144, v184, v235
	v_and_b32_e32 v145, v184, v236
	v_and_b32_e32 v146, v184, v237
	v_and_b32_e32 v147, v184, v238
	v_and_b32_e32 v148, v185, v235
	v_and_b32_e32 v149, v185, v236
	v_and_b32_e32 v150, v185, v237
	v_and_b32_e32 v151, v185, v238
	s_mov_b64 vcc, s[4:5]
	v_cndmask_b32_dpp v138, v112, v114, vcc row_shl:4 row_mask:0xf bank_mask:0xf bound_ctrl:1
	v_cndmask_b32_dpp v139, v113, v115, vcc row_shl:4 row_mask:0xf bank_mask:0xf bound_ctrl:1
	s_mov_b64 vcc, s[6:7]
	v_cndmask_b32_dpp v136, v114, v112, vcc row_shr:4 row_mask:0xf bank_mask:0xf bound_ctrl:1
	v_cndmask_b32_dpp v137, v115, v113, vcc row_shr:4 row_mask:0xf bank_mask:0xf bound_ctrl:1
	v_mfma_scale_f32_16x16x128_f8f6f4 v[216:219], v[140:143], v[204:211], v[216:219], v240, v241 op_sel_hi:[0,0,0] cbsz:4
	v_add_f32_e32 v255, v215, v255
	v_mul_f32_e32 v192, v252, v252
	v_mul_f32_e32 v193, v254, v254
	v_and_b32_e32 v204, v186, v235
	v_and_b32_e32 v205, v186, v236
	v_and_b32_e32 v206, v186, v237
	v_and_b32_e32 v207, v186, v238
	v_and_b32_e32 v208, v187, v235
	v_and_b32_e32 v209, v187, v236
	v_and_b32_e32 v210, v187, v237
	v_and_b32_e32 v211, v187, v238
	s_mov_b64 vcc, s[6:7]
	v_cndmask_b32_dpp v140, v118, v116, vcc row_shr:4 row_mask:0xf bank_mask:0xf bound_ctrl:1
	v_cndmask_b32_dpp v141, v119, v117, vcc row_shr:4 row_mask:0xf bank_mask:0xf bound_ctrl:1
	s_mov_b64 vcc, s[4:5]
	v_cndmask_b32_dpp v142, v116, v118, vcc row_shl:4 row_mask:0xf bank_mask:0xf bound_ctrl:1
	v_cndmask_b32_dpp v143, v117, v119, vcc row_shl:4 row_mask:0xf bank_mask:0xf bound_ctrl:1
	v_mfma_scale_f32_16x16x128_f8f6f4 v[216:219], v[136:139], v[144:151], v[216:219], v240, v241 op_sel_hi:[0,0,0] cbsz:4
	v_fmac_f32_e32 v192, v253, v253
	v_fmac_f32_e32 v193, v255, v255
	v_cvt_pk_bf16_f32 v250, v252, v253
	v_and_b32_e32 v144, v188, v235
	v_and_b32_e32 v145, v188, v236
	v_and_b32_e32 v146, v188, v237
	v_and_b32_e32 v147, v188, v238
	v_and_b32_e32 v148, v189, v235
	v_and_b32_e32 v149, v189, v236
	v_and_b32_e32 v150, v189, v237
	v_and_b32_e32 v151, v189, v238
	s_mov_b64 vcc, s[4:5]
	v_cndmask_b32_dpp v138, v120, v122, vcc row_shl:4 row_mask:0xf bank_mask:0xf bound_ctrl:1
	v_cndmask_b32_dpp v139, v121, v123, vcc row_shl:4 row_mask:0xf bank_mask:0xf bound_ctrl:1
	s_mov_b64 vcc, s[6:7]
	v_cndmask_b32_dpp v136, v122, v120, vcc row_shr:4 row_mask:0xf bank_mask:0xf bound_ctrl:1
	v_cndmask_b32_dpp v137, v123, v121, vcc row_shr:4 row_mask:0xf bank_mask:0xf bound_ctrl:1
	v_mfma_scale_f32_16x16x128_f8f6f4 v[216:219], v[140:143], v[204:211], v[216:219], v240, v241 op_sel_hi:[0,0,0] cbsz:4
	v_cvt_pk_bf16_f32 v251, v254, v255
	v_add_f32_e32 v192, v192, v193
	v_add_f32_e32 v220, v220, v192
	v_and_b32_e32 v204, v190, v235
	v_and_b32_e32 v205, v190, v236
	v_and_b32_e32 v206, v190, v237
	v_and_b32_e32 v207, v190, v238
	v_and_b32_e32 v208, v191, v235
	v_and_b32_e32 v209, v191, v236
	v_and_b32_e32 v210, v191, v237
	v_and_b32_e32 v211, v191, v238
	s_mov_b64 vcc, s[6:7]
	v_cndmask_b32_dpp v140, v126, v124, vcc row_shr:4 row_mask:0xf bank_mask:0xf bound_ctrl:1
	v_cndmask_b32_dpp v141, v127, v125, vcc row_shr:4 row_mask:0xf bank_mask:0xf bound_ctrl:1
	s_mov_b64 vcc, s[4:5]
	v_cndmask_b32_dpp v142, v124, v126, vcc row_shl:4 row_mask:0xf bank_mask:0xf bound_ctrl:1
	v_cndmask_b32_dpp v143, v125, v127, vcc row_shl:4 row_mask:0xf bank_mask:0xf bound_ctrl:1
	v_mfma_scale_f32_16x16x128_f8f6f4 v[216:219], v[136:139], v[144:151], v[216:219], v240, v241 op_sel_hi:[0,0,0] cbsz:4
	s_nop 0
	v_mfma_scale_f32_16x16x128_f8f6f4 v[216:219], v[140:143], v[204:211], v[216:219], v240, v241 op_sel_hi:[0,0,0] cbsz:4
	s_lshl_b32 s64, s0, 9
	s_add_u32 s64, s64, 0x0
	s_add_u32 s76, s28, s64
	s_addc_u32 s77, s29, 0
	global_store_dwordx2 v239, v[250:251], s[76:77]
	s_lshl_b32 s64, s0, 9
	s_add_u32 s64, s64, 0x2000
	s_add_u32 s70, s28, s64
	s_addc_u32 s71, s29, 0
	global_load_dwordx2 v[228:229], v239, s[70:71] nt
	s_waitcnt lgkmcnt(0)
	v_lshl_or_b32 v128, v128, 7, v232
	v_lshl_or_b32 v129, v129, 7, v232
	v_lshl_or_b32 v130, v130, 7, v232
	v_lshl_or_b32 v131, v131, 7, v232
	v_lshl_or_b32 v132, v132, 7, v232
	v_lshl_or_b32 v133, v133, 7, v232
	v_lshl_or_b32 v134, v134, 7, v232
	v_lshl_or_b32 v135, v135, 7, v232
	buffer_load_dwordx4 v[96:99], v128, s[20:23], s1 offen
	buffer_load_dwordx4 v[100:103], v129, s[20:23], s1 offen
	buffer_load_dwordx4 v[104:107], v130, s[20:23], s1 offen
	buffer_load_dwordx4 v[108:111], v131, s[20:23], s1 offen
	buffer_load_dwordx4 v[112:115], v132, s[20:23], s1 offen
	buffer_load_dwordx4 v[116:119], v133, s[20:23], s1 offen
	buffer_load_dwordx4 v[120:123], v134, s[20:23], s1 offen
	buffer_load_dwordx4 v[124:127], v135, s[20:23], s1 offen
	ds_read_b32 v128, v243 offset:2048
	ds_read_b32 v129, v243 offset:2080
	ds_read_b32 v130, v243 offset:2112
	ds_read_b32 v131, v243 offset:2144
	ds_read_b32 v132, v243 offset:2176
	ds_read_b32 v133, v243 offset:2208
	ds_read_b32 v134, v243 offset:2240
	ds_read_b32 v135, v243 offset:2272
	ds_read_b64 v[176:177], v234 offset:1280
	ds_read_b64 v[178:179], v234 offset:1312
	ds_read_b64 v[180:181], v234 offset:1344
	ds_read_b64 v[182:183], v234 offset:1376
	ds_read_b64 v[184:185], v234 offset:1408
	ds_read_b64 v[186:187], v234 offset:1440
	ds_read_b64 v[188:189], v234 offset:1472
	ds_read_b64 v[190:191], v234 offset:1504
	s_waitcnt vmcnt(28)
	v_and_b32_e32 v144, v160, v235
	v_and_b32_e32 v145, v160, v236
	v_and_b32_e32 v146, v160, v237
	v_and_b32_e32 v147, v160, v238
	v_and_b32_e32 v148, v161, v235
	v_and_b32_e32 v149, v161, v236
	v_and_b32_e32 v150, v161, v237
	v_and_b32_e32 v151, v161, v238
	s_mov_b64 vcc, s[4:5]
	v_cndmask_b32_dpp v138, v0, v2, vcc row_shl:4 row_mask:0xf bank_mask:0xf bound_ctrl:1
	v_cndmask_b32_dpp v139, v1, v3, vcc row_shl:4 row_mask:0xf bank_mask:0xf bound_ctrl:1
	s_mov_b64 vcc, s[6:7]
	v_cndmask_b32_dpp v136, v2, v0, vcc row_shr:4 row_mask:0xf bank_mask:0xf bound_ctrl:1
	v_cndmask_b32_dpp v137, v3, v1, vcc row_shr:4 row_mask:0xf bank_mask:0xf bound_ctrl:1
	v_and_b32_e32 v204, v162, v235
	v_and_b32_e32 v205, v162, v236
	v_and_b32_e32 v206, v162, v237
	v_and_b32_e32 v207, v162, v238
	v_and_b32_e32 v208, v163, v235
	v_and_b32_e32 v209, v163, v236
	v_and_b32_e32 v210, v163, v237
	v_and_b32_e32 v211, v163, v238
	s_mov_b64 vcc, s[6:7]
	v_cndmask_b32_dpp v140, v6, v4, vcc row_shr:4 row_mask:0xf bank_mask:0xf bound_ctrl:1
	v_cndmask_b32_dpp v141, v7, v5, vcc row_shr:4 row_mask:0xf bank_mask:0xf bound_ctrl:1
	s_mov_b64 vcc, s[4:5]
	v_cndmask_b32_dpp v142, v4, v6, vcc row_shl:4 row_mask:0xf bank_mask:0xf bound_ctrl:1
	v_cndmask_b32_dpp v143, v5, v7, vcc row_shl:4 row_mask:0xf bank_mask:0xf bound_ctrl:1
	v_mfma_scale_f32_16x16x128_f8f6f4 v[212:215], v[136:139], v[144:151], 0, v240, v241 op_sel_hi:[0,0,0] cbsz:4
	v_and_b32_e32 v144, v164, v235
	v_and_b32_e32 v145, v164, v236
	v_and_b32_e32 v146, v164, v237
	v_and_b32_e32 v147, v164, v238
	v_and_b32_e32 v148, v165, v235
	v_and_b32_e32 v149, v165, v236
	v_and_b32_e32 v150, v165, v237
	v_and_b32_e32 v151, v165, v238
	s_mov_b64 vcc, s[4:5]
	v_cndmask_b32_dpp v138, v8, v10, vcc row_shl:4 row_mask:0xf bank_mask:0xf bound_ctrl:1
	v_cndmask_b32_dpp v139, v9, v11, vcc row_shl:4 row_mask:0xf bank_mask:0xf bound_ctrl:1
	s_mov_b64 vcc, s[6:7]
	v_cndmask_b32_dpp v136, v10, v8, vcc row_shr:4 row_mask:0xf bank_mask:0xf bound_ctrl:1
	v_cndmask_b32_dpp v137, v11, v9, vcc row_shr:4 row_mask:0xf bank_mask:0xf bound_ctrl:1
	v_mfma_scale_f32_16x16x128_f8f6f4 v[212:215], v[140:143], v[204:211], v[212:215], v240, v241 op_sel_hi:[0,0,0] cbsz:4
	v_and_b32_e32 v204, v166, v235
	v_and_b32_e32 v205, v166, v236
	v_and_b32_e32 v206, v166, v237
	v_and_b32_e32 v207, v166, v238
	v_and_b32_e32 v208, v167, v235
	v_and_b32_e32 v209, v167, v236
	v_and_b32_e32 v210, v167, v237
	v_and_b32_e32 v211, v167, v238
	s_mov_b64 vcc, s[6:7]
	v_cndmask_b32_dpp v140, v14, v12, vcc row_shr:4 row_mask:0xf bank_mask:0xf bound_ctrl:1
	v_cndmask_b32_dpp v141, v15, v13, vcc row_shr:4 row_mask:0xf bank_mask:0xf bound_ctrl:1
	s_mov_b64 vcc, s[4:5]
	v_cndmask_b32_dpp v142, v12, v14, vcc row_shl:4 row_mask:0xf bank_mask:0xf bound_ctrl:1
	v_cndmask_b32_dpp v143, v13, v15, vcc row_shl:4 row_mask:0xf bank_mask:0xf bound_ctrl:1
	v_mfma_scale_f32_16x16x128_f8f6f4 v[212:215], v[136:139], v[144:151], v[212:215], v240, v241 op_sel_hi:[0,0,0] cbsz:4
	v_and_b32_e32 v144, v168, v235
	v_and_b32_e32 v145, v168, v236
	v_and_b32_e32 v146, v168, v237
	v_and_b32_e32 v147, v168, v238
	v_and_b32_e32 v148, v169, v235
	v_and_b32_e32 v149, v169, v236
	v_and_b32_e32 v150, v169, v237
	v_and_b32_e32 v151, v169, v238
	s_mov_b64 vcc, s[4:5]
	v_cndmask_b32_dpp v138, v16, v18, vcc row_shl:4 row_mask:0xf bank_mask:0xf bound_ctrl:1
	v_cndmask_b32_dpp v139, v17, v19, vcc row_shl:4 row_mask:0xf bank_mask:0xf bound_ctrl:1
	s_mov_b64 vcc, s[6:7]
	v_cndmask_b32_dpp v136, v18, v16, vcc row_shr:4 row_mask:0xf bank_mask:0xf bound_ctrl:1
	v_cndmask_b32_dpp v137, v19, v17, vcc row_shr:4 row_mask:0xf bank_mask:0xf bound_ctrl:1
	v_mfma_scale_f32_16x16x128_f8f6f4 v[212:215], v[140:143], v[204:211], v[212:215], v240, v241 op_sel_hi:[0,0,0] cbsz:4
	v_and_b32_e32 v204, v170, v235
	v_and_b32_e32 v205, v170, v236
	v_and_b32_e32 v206, v170, v237
	v_and_b32_e32 v207, v170, v238
	v_and_b32_e32 v208, v171, v235
	v_and_b32_e32 v209, v171, v236
	v_and_b32_e32 v210, v171, v237
	v_and_b32_e32 v211, v171, v238
	s_mov_b64 vcc, s[6:7]
	v_cndmask_b32_dpp v140, v22, v20, vcc row_shr:4 row_mask:0xf bank_mask:0xf bound_ctrl:1
	v_cndmask_b32_dpp v141, v23, v21, vcc row_shr:4 row_mask:0xf bank_mask:0xf bound_ctrl:1
	s_mov_b64 vcc, s[4:5]
	v_cndmask_b32_dpp v142, v20, v22, vcc row_shl:4 row_mask:0xf bank_mask:0xf bound_ctrl:1
	v_cndmask_b32_dpp v143, v21, v23, vcc row_shl:4 row_mask:0xf bank_mask:0xf bound_ctrl:1
	v_mfma_scale_f32_16x16x128_f8f6f4 v[212:215], v[136:139], v[144:151], v[212:215], v240, v241 op_sel_hi:[0,0,0] cbsz:4
	v_and_b32_e32 v144, v172, v235
	v_and_b32_e32 v145, v172, v236
	v_and_b32_e32 v146, v172, v237
	v_and_b32_e32 v147, v172, v238
	v_and_b32_e32 v148, v173, v235
	v_and_b32_e32 v149, v173, v236
	v_and_b32_e32 v150, v173, v237
	v_and_b32_e32 v151, v173, v238
	s_mov_b64 vcc, s[4:5]
	v_cndmask_b32_dpp v138, v24, v26, vcc row_shl:4 row_mask:0xf bank_mask:0xf bound_ctrl:1
	v_cndmask_b32_dpp v139, v25, v27, vcc row_shl:4 row_mask:0xf bank_mask:0xf bound_ctrl:1
	s_mov_b64 vcc, s[6:7]
	v_cndmask_b32_dpp v136, v26, v24, vcc row_shr:4 row_mask:0xf bank_mask:0xf bound_ctrl:1
	v_cndmask_b32_dpp v137, v27, v25, vcc row_shr:4 row_mask:0xf bank_mask:0xf bound_ctrl:1
	v_mfma_scale_f32_16x16x128_f8f6f4 v[212:215], v[140:143], v[204:211], v[212:215], v240, v241 op_sel_hi:[0,0,0] cbsz:4
	v_and_b32_e32 v204, v174, v235
	v_and_b32_e32 v205, v174, v236
	v_and_b32_e32 v206, v174, v237
	v_and_b32_e32 v207, v174, v238
	v_and_b32_e32 v208, v175, v235
	v_and_b32_e32 v209, v175, v236
	v_and_b32_e32 v210, v175, v237
	v_and_b32_e32 v211, v175, v238
	s_mov_b64 vcc, s[6:7]
	v_cndmask_b32_dpp v140, v30, v28, vcc row_shr:4 row_mask:0xf bank_mask:0xf bound_ctrl:1
	v_cndmask_b32_dpp v141, v31, v29, vcc row_shr:4 row_mask:0xf bank_mask:0xf bound_ctrl:1
	s_mov_b64 vcc, s[4:5]
	v_cndmask_b32_dpp v142, v28, v30, vcc row_shl:4 row_mask:0xf bank_mask:0xf bound_ctrl:1
	v_cndmask_b32_dpp v143, v29, v31, vcc row_shl:4 row_mask:0xf bank_mask:0xf bound_ctrl:1
	v_mfma_scale_f32_16x16x128_f8f6f4 v[212:215], v[136:139], v[144:151], v[212:215], v240, v241 op_sel_hi:[0,0,0] cbsz:4
	s_nop 0
	v_mfma_scale_f32_16x16x128_f8f6f4 v[212:215], v[140:143], v[204:211], v[212:215], v240, v241 op_sel_hi:[0,0,0] cbsz:4
	s_waitcnt lgkmcnt(0)
	v_lshl_or_b32 v128, v128, 7, v232
	v_lshl_or_b32 v129, v129, 7, v232
	v_lshl_or_b32 v130, v130, 7, v232
	v_lshl_or_b32 v131, v131, 7, v232
	v_lshl_or_b32 v132, v132, 7, v232
	v_lshl_or_b32 v133, v133, 7, v232
	v_lshl_or_b32 v134, v134, 7, v232
	v_lshl_or_b32 v135, v135, 7, v232
	buffer_load_dwordx4 v[0:3], v128, s[20:23], s1 offen
	buffer_load_dwordx4 v[4:7], v129, s[20:23], s1 offen
	buffer_load_dwordx4 v[8:11], v130, s[20:23], s1 offen
	buffer_load_dwordx4 v[12:15], v131, s[20:23], s1 offen
	buffer_load_dwordx4 v[16:19], v132, s[20:23], s1 offen
	buffer_load_dwordx4 v[20:23], v133, s[20:23], s1 offen
	buffer_load_dwordx4 v[24:27], v134, s[20:23], s1 offen
	buffer_load_dwordx4 v[28:31], v135, s[20:23], s1 offen
	ds_read_b32 v128, v243 offset:2304
	ds_read_b32 v129, v243 offset:2336
	ds_read_b32 v130, v243 offset:2368
	ds_read_b32 v131, v243 offset:2400
	ds_read_b32 v132, v243 offset:2432
	ds_read_b32 v133, v243 offset:2464
	ds_read_b32 v134, v243 offset:2496
	ds_read_b32 v135, v243 offset:2528
	ds_read_b64 v[160:161], v234 offset:1536
	ds_read_b64 v[162:163], v234 offset:1568
	ds_read_b64 v[164:165], v234 offset:1600
	ds_read_b64 v[166:167], v234 offset:1632
	ds_read_b64 v[168:169], v234 offset:1664
	ds_read_b64 v[170:171], v234 offset:1696
	ds_read_b64 v[172:173], v234 offset:1728
	ds_read_b64 v[174:175], v234 offset:1760
	s_waitcnt vmcnt(26)
	v_and_b32_e32 v144, v176, v235
	v_and_b32_e32 v145, v176, v236
	v_and_b32_e32 v146, v176, v237
	v_and_b32_e32 v147, v176, v238
	v_and_b32_e32 v148, v177, v235
	v_and_b32_e32 v149, v177, v236
	v_and_b32_e32 v150, v177, v237
	v_and_b32_e32 v151, v177, v238
	s_mov_b64 vcc, s[4:5]
	v_cndmask_b32_dpp v138, v32, v34, vcc row_shl:4 row_mask:0xf bank_mask:0xf bound_ctrl:1
	v_cndmask_b32_dpp v139, v33, v35, vcc row_shl:4 row_mask:0xf bank_mask:0xf bound_ctrl:1
	s_mov_b64 vcc, s[6:7]
	v_cndmask_b32_dpp v136, v34, v32, vcc row_shr:4 row_mask:0xf bank_mask:0xf bound_ctrl:1
	v_cndmask_b32_dpp v137, v35, v33, vcc row_shr:4 row_mask:0xf bank_mask:0xf bound_ctrl:1
	v_and_b32_e32 v204, v178, v235
	v_and_b32_e32 v205, v178, v236
	v_and_b32_e32 v206, v178, v237
	v_and_b32_e32 v207, v178, v238
	v_and_b32_e32 v208, v179, v235
	v_and_b32_e32 v209, v179, v236
	v_and_b32_e32 v210, v179, v237
	v_and_b32_e32 v211, v179, v238
	s_mov_b64 vcc, s[6:7]
	v_cndmask_b32_dpp v140, v38, v36, vcc row_shr:4 row_mask:0xf bank_mask:0xf bound_ctrl:1
	v_cndmask_b32_dpp v141, v39, v37, vcc row_shr:4 row_mask:0xf bank_mask:0xf bound_ctrl:1
	s_mov_b64 vcc, s[4:5]
	v_cndmask_b32_dpp v142, v36, v38, vcc row_shl:4 row_mask:0xf bank_mask:0xf bound_ctrl:1
	v_cndmask_b32_dpp v143, v37, v39, vcc row_shl:4 row_mask:0xf bank_mask:0xf bound_ctrl:1
	v_mfma_scale_f32_16x16x128_f8f6f4 v[212:215], v[136:139], v[144:151], v[212:215], v240, v241 op_sel_hi:[0,0,0] cbsz:4
	v_permlane16_swap_b32_e32 v216, v218
	v_permlane16_swap_b32_e32 v217, v219
	v_lshlrev_b32_e32 v252, 16, v230
	v_and_b32_e32 v144, v180, v235
	v_and_b32_e32 v145, v180, v236
	v_and_b32_e32 v146, v180, v237
	v_and_b32_e32 v147, v180, v238
	v_and_b32_e32 v148, v181, v235
	v_and_b32_e32 v149, v181, v236
	v_and_b32_e32 v150, v181, v237
	v_and_b32_e32 v151, v181, v238
	s_mov_b64 vcc, s[4:5]
	v_cndmask_b32_dpp v138, v40, v42, vcc row_shl:4 row_mask:0xf bank_mask:0xf bound_ctrl:1
	v_cndmask_b32_dpp v139, v41, v43, vcc row_shl:4 row_mask:0xf bank_mask:0xf bound_ctrl:1
	s_mov_b64 vcc, s[6:7]
	v_cndmask_b32_dpp v136, v42, v40, vcc row_shr:4 row_mask:0xf bank_mask:0xf bound_ctrl:1
	v_cndmask_b32_dpp v137, v43, v41, vcc row_shr:4 row_mask:0xf bank_mask:0xf bound_ctrl:1
	v_mfma_scale_f32_16x16x128_f8f6f4 v[212:215], v[140:143], v[204:211], v[212:215], v240, v241 op_sel_hi:[0,0,0] cbsz:4
	v_and_b32_e32 v253, 0xffff0000, v230
	v_lshlrev_b32_e32 v254, 16, v231
	v_and_b32_e32 v255, 0xffff0000, v231
	v_and_b32_e32 v204, v182, v235
	v_and_b32_e32 v205, v182, v236
	v_and_b32_e32 v206, v182, v237
	v_and_b32_e32 v207, v182, v238
	v_and_b32_e32 v208, v183, v235
	v_and_b32_e32 v209, v183, v236
	v_and_b32_e32 v210, v183, v237
	v_and_b32_e32 v211, v183, v238
	s_mov_b64 vcc, s[6:7]
	v_cndmask_b32_dpp v140, v46, v44, vcc row_shr:4 row_mask:0xf bank_mask:0xf bound_ctrl:1
	v_cndmask_b32_dpp v141, v47, v45, vcc row_shr:4 row_mask:0xf bank_mask:0xf bound_ctrl:1
	s_mov_b64 vcc, s[4:5]
	v_cndmask_b32_dpp v142, v44, v46, vcc row_shl:4 row_mask:0xf bank_mask:0xf bound_ctrl:1
	v_cndmask_b32_dpp v143, v45, v47, vcc row_shl:4 row_mask:0xf bank_mask:0xf bound_ctrl:1
	v_mfma_scale_f32_16x16x128_f8f6f4 v[212:215], v[136:139], v[144:151], v[212:215], v240, v241 op_sel_hi:[0,0,0] cbsz:4
	v_add_f32_e32 v252, v216, v252
	v_add_f32_e32 v253, v218, v253
	v_add_f32_e32 v254, v217, v254
	v_and_b32_e32 v144, v184, v235
	v_and_b32_e32 v145, v184, v236
	v_and_b32_e32 v146, v184, v237
	v_and_b32_e32 v147, v184, v238
	v_and_b32_e32 v148, v185, v235
	v_and_b32_e32 v149, v185, v236
	v_and_b32_e32 v150, v185, v237
	v_and_b32_e32 v151, v185, v238
	s_mov_b64 vcc, s[4:5]
	v_cndmask_b32_dpp v138, v48, v50, vcc row_shl:4 row_mask:0xf bank_mask:0xf bound_ctrl:1
	v_cndmask_b32_dpp v139, v49, v51, vcc row_shl:4 row_mask:0xf bank_mask:0xf bound_ctrl:1
	s_mov_b64 vcc, s[6:7]
	v_cndmask_b32_dpp v136, v50, v48, vcc row_shr:4 row_mask:0xf bank_mask:0xf bound_ctrl:1
	v_cndmask_b32_dpp v137, v51, v49, vcc row_shr:4 row_mask:0xf bank_mask:0xf bound_ctrl:1
	v_mfma_scale_f32_16x16x128_f8f6f4 v[212:215], v[140:143], v[204:211], v[212:215], v240, v241 op_sel_hi:[0,0,0] cbsz:4
	v_add_f32_e32 v255, v219, v255
	v_mul_f32_e32 v192, v252, v252
	v_mul_f32_e32 v193, v254, v254
	v_and_b32_e32 v204, v186, v235
	v_and_b32_e32 v205, v186, v236
	v_and_b32_e32 v206, v186, v237
	v_and_b32_e32 v207, v186, v238
	v_and_b32_e32 v208, v187, v235
	v_and_b32_e32 v209, v187, v236
	v_and_b32_e32 v210, v187, v237
	v_and_b32_e32 v211, v187, v238
	s_mov_b64 vcc, s[6:7]
	v_cndmask_b32_dpp v140, v54, v52, vcc row_shr:4 row_mask:0xf bank_mask:0xf bound_ctrl:1
	v_cndmask_b32_dpp v141, v55, v53, vcc row_shr:4 row_mask:0xf bank_mask:0xf bound_ctrl:1
	s_mov_b64 vcc, s[4:5]
	v_cndmask_b32_dpp v142, v52, v54, vcc row_shl:4 row_mask:0xf bank_mask:0xf bound_ctrl:1
	v_cndmask_b32_dpp v143, v53, v55, vcc row_shl:4 row_mask:0xf bank_mask:0xf bound_ctrl:1
	v_mfma_scale_f32_16x16x128_f8f6f4 v[212:215], v[136:139], v[144:151], v[212:215], v240, v241 op_sel_hi:[0,0,0] cbsz:4
	v_fmac_f32_e32 v192, v253, v253
	v_fmac_f32_e32 v193, v255, v255
	v_cvt_pk_bf16_f32 v250, v252, v253
	v_and_b32_e32 v144, v188, v235
	v_and_b32_e32 v145, v188, v236
	v_and_b32_e32 v146, v188, v237
	v_and_b32_e32 v147, v188, v238
	v_and_b32_e32 v148, v189, v235
	v_and_b32_e32 v149, v189, v236
	v_and_b32_e32 v150, v189, v237
	v_and_b32_e32 v151, v189, v238
	s_mov_b64 vcc, s[4:5]
	v_cndmask_b32_dpp v138, v56, v58, vcc row_shl:4 row_mask:0xf bank_mask:0xf bound_ctrl:1
	v_cndmask_b32_dpp v139, v57, v59, vcc row_shl:4 row_mask:0xf bank_mask:0xf bound_ctrl:1
	s_mov_b64 vcc, s[6:7]
	v_cndmask_b32_dpp v136, v58, v56, vcc row_shr:4 row_mask:0xf bank_mask:0xf bound_ctrl:1
	v_cndmask_b32_dpp v137, v59, v57, vcc row_shr:4 row_mask:0xf bank_mask:0xf bound_ctrl:1
	v_mfma_scale_f32_16x16x128_f8f6f4 v[212:215], v[140:143], v[204:211], v[212:215], v240, v241 op_sel_hi:[0,0,0] cbsz:4
	v_cvt_pk_bf16_f32 v251, v254, v255
	v_add_f32_e32 v192, v192, v193
	v_add_f32_e32 v221, v221, v192
	v_and_b32_e32 v204, v190, v235
	v_and_b32_e32 v205, v190, v236
	v_and_b32_e32 v206, v190, v237
	v_and_b32_e32 v207, v190, v238
	v_and_b32_e32 v208, v191, v235
	v_and_b32_e32 v209, v191, v236
	v_and_b32_e32 v210, v191, v237
	v_and_b32_e32 v211, v191, v238
	s_mov_b64 vcc, s[6:7]
	v_cndmask_b32_dpp v140, v62, v60, vcc row_shr:4 row_mask:0xf bank_mask:0xf bound_ctrl:1
	v_cndmask_b32_dpp v141, v63, v61, vcc row_shr:4 row_mask:0xf bank_mask:0xf bound_ctrl:1
	s_mov_b64 vcc, s[4:5]
	v_cndmask_b32_dpp v142, v60, v62, vcc row_shl:4 row_mask:0xf bank_mask:0xf bound_ctrl:1
	v_cndmask_b32_dpp v143, v61, v63, vcc row_shl:4 row_mask:0xf bank_mask:0xf bound_ctrl:1
	v_mfma_scale_f32_16x16x128_f8f6f4 v[212:215], v[136:139], v[144:151], v[212:215], v240, v241 op_sel_hi:[0,0,0] cbsz:4
	s_nop 0
	v_mfma_scale_f32_16x16x128_f8f6f4 v[212:215], v[140:143], v[204:211], v[212:215], v240, v241 op_sel_hi:[0,0,0] cbsz:4
	s_lshl_b32 s64, s0, 9
	s_add_u32 s64, s64, 0x1000
	s_add_u32 s76, s28, s64
	s_addc_u32 s77, s29, 0
	global_store_dwordx2 v239, v[250:251], s[76:77]
	s_lshl_b32 s64, s0, 9
	s_add_u32 s64, s64, 0x3000
	s_add_u32 s70, s28, s64
	s_addc_u32 s71, s29, 0
	global_load_dwordx2 v[230:231], v239, s[70:71] nt
	s_waitcnt lgkmcnt(0)
	v_lshl_or_b32 v128, v128, 7, v232
	v_lshl_or_b32 v129, v129, 7, v232
	v_lshl_or_b32 v130, v130, 7, v232
	v_lshl_or_b32 v131, v131, 7, v232
	v_lshl_or_b32 v132, v132, 7, v232
	v_lshl_or_b32 v133, v133, 7, v232
	v_lshl_or_b32 v134, v134, 7, v232
	v_lshl_or_b32 v135, v135, 7, v232
	buffer_load_dwordx4 v[32:35], v128, s[20:23], s1 offen
	buffer_load_dwordx4 v[36:39], v129, s[20:23], s1 offen
	buffer_load_dwordx4 v[40:43], v130, s[20:23], s1 offen
	buffer_load_dwordx4 v[44:47], v131, s[20:23], s1 offen
	buffer_load_dwordx4 v[48:51], v132, s[20:23], s1 offen
	buffer_load_dwordx4 v[52:55], v133, s[20:23], s1 offen
	buffer_load_dwordx4 v[56:59], v134, s[20:23], s1 offen
	buffer_load_dwordx4 v[60:63], v135, s[20:23], s1 offen
	ds_read_b32 v128, v243 offset:2560
	ds_read_b32 v129, v243 offset:2592
	ds_read_b32 v130, v243 offset:2624
	ds_read_b32 v131, v243 offset:2656
	ds_read_b32 v132, v243 offset:2688
	ds_read_b32 v133, v243 offset:2720
	ds_read_b32 v134, v243 offset:2752
	ds_read_b32 v135, v243 offset:2784
	ds_read_b64 v[176:177], v234 offset:1792
	ds_read_b64 v[178:179], v234 offset:1824
	ds_read_b64 v[180:181], v234 offset:1856
	ds_read_b64 v[182:183], v234 offset:1888
	ds_read_b64 v[184:185], v234 offset:1920
	ds_read_b64 v[186:187], v234 offset:1952
	ds_read_b64 v[188:189], v234 offset:1984
	ds_read_b64 v[190:191], v234 offset:2016
	s_waitcnt vmcnt(28)
	v_and_b32_e32 v144, v160, v235
	v_and_b32_e32 v145, v160, v236
	v_and_b32_e32 v146, v160, v237
	v_and_b32_e32 v147, v160, v238
	v_and_b32_e32 v148, v161, v235
	v_and_b32_e32 v149, v161, v236
	v_and_b32_e32 v150, v161, v237
	v_and_b32_e32 v151, v161, v238
	s_mov_b64 vcc, s[4:5]
	v_cndmask_b32_dpp v138, v64, v66, vcc row_shl:4 row_mask:0xf bank_mask:0xf bound_ctrl:1
	v_cndmask_b32_dpp v139, v65, v67, vcc row_shl:4 row_mask:0xf bank_mask:0xf bound_ctrl:1
	s_mov_b64 vcc, s[6:7]
	v_cndmask_b32_dpp v136, v66, v64, vcc row_shr:4 row_mask:0xf bank_mask:0xf bound_ctrl:1
	v_cndmask_b32_dpp v137, v67, v65, vcc row_shr:4 row_mask:0xf bank_mask:0xf bound_ctrl:1
	v_and_b32_e32 v204, v162, v235
	v_and_b32_e32 v205, v162, v236
	v_and_b32_e32 v206, v162, v237
	v_and_b32_e32 v207, v162, v238
	v_and_b32_e32 v208, v163, v235
	v_and_b32_e32 v209, v163, v236
	v_and_b32_e32 v210, v163, v237
	v_and_b32_e32 v211, v163, v238
	s_mov_b64 vcc, s[6:7]
	v_cndmask_b32_dpp v140, v70, v68, vcc row_shr:4 row_mask:0xf bank_mask:0xf bound_ctrl:1
	v_cndmask_b32_dpp v141, v71, v69, vcc row_shr:4 row_mask:0xf bank_mask:0xf bound_ctrl:1
	s_mov_b64 vcc, s[4:5]
	v_cndmask_b32_dpp v142, v68, v70, vcc row_shl:4 row_mask:0xf bank_mask:0xf bound_ctrl:1
	v_cndmask_b32_dpp v143, v69, v71, vcc row_shl:4 row_mask:0xf bank_mask:0xf bound_ctrl:1
	v_mfma_scale_f32_16x16x128_f8f6f4 v[216:219], v[136:139], v[144:151], 0, v240, v241 op_sel_hi:[0,0,0] cbsz:4
	v_and_b32_e32 v144, v164, v235
	v_and_b32_e32 v145, v164, v236
	v_and_b32_e32 v146, v164, v237
	v_and_b32_e32 v147, v164, v238
	v_and_b32_e32 v148, v165, v235
	v_and_b32_e32 v149, v165, v236
	v_and_b32_e32 v150, v165, v237
	v_and_b32_e32 v151, v165, v238
	s_mov_b64 vcc, s[4:5]
	v_cndmask_b32_dpp v138, v72, v74, vcc row_shl:4 row_mask:0xf bank_mask:0xf bound_ctrl:1
	v_cndmask_b32_dpp v139, v73, v75, vcc row_shl:4 row_mask:0xf bank_mask:0xf bound_ctrl:1
	s_mov_b64 vcc, s[6:7]
	v_cndmask_b32_dpp v136, v74, v72, vcc row_shr:4 row_mask:0xf bank_mask:0xf bound_ctrl:1
	v_cndmask_b32_dpp v137, v75, v73, vcc row_shr:4 row_mask:0xf bank_mask:0xf bound_ctrl:1
	v_mfma_scale_f32_16x16x128_f8f6f4 v[216:219], v[140:143], v[204:211], v[216:219], v240, v241 op_sel_hi:[0,0,0] cbsz:4
	v_and_b32_e32 v204, v166, v235
	v_and_b32_e32 v205, v166, v236
	v_and_b32_e32 v206, v166, v237
	v_and_b32_e32 v207, v166, v238
	v_and_b32_e32 v208, v167, v235
	v_and_b32_e32 v209, v167, v236
	v_and_b32_e32 v210, v167, v237
	v_and_b32_e32 v211, v167, v238
	s_mov_b64 vcc, s[6:7]
	v_cndmask_b32_dpp v140, v78, v76, vcc row_shr:4 row_mask:0xf bank_mask:0xf bound_ctrl:1
	v_cndmask_b32_dpp v141, v79, v77, vcc row_shr:4 row_mask:0xf bank_mask:0xf bound_ctrl:1
	s_mov_b64 vcc, s[4:5]
	v_cndmask_b32_dpp v142, v76, v78, vcc row_shl:4 row_mask:0xf bank_mask:0xf bound_ctrl:1
	v_cndmask_b32_dpp v143, v77, v79, vcc row_shl:4 row_mask:0xf bank_mask:0xf bound_ctrl:1
	v_mfma_scale_f32_16x16x128_f8f6f4 v[216:219], v[136:139], v[144:151], v[216:219], v240, v241 op_sel_hi:[0,0,0] cbsz:4
	v_and_b32_e32 v144, v168, v235
	v_and_b32_e32 v145, v168, v236
	v_and_b32_e32 v146, v168, v237
	v_and_b32_e32 v147, v168, v238
	v_and_b32_e32 v148, v169, v235
	v_and_b32_e32 v149, v169, v236
	v_and_b32_e32 v150, v169, v237
	v_and_b32_e32 v151, v169, v238
	s_mov_b64 vcc, s[4:5]
	v_cndmask_b32_dpp v138, v80, v82, vcc row_shl:4 row_mask:0xf bank_mask:0xf bound_ctrl:1
	v_cndmask_b32_dpp v139, v81, v83, vcc row_shl:4 row_mask:0xf bank_mask:0xf bound_ctrl:1
	s_mov_b64 vcc, s[6:7]
	v_cndmask_b32_dpp v136, v82, v80, vcc row_shr:4 row_mask:0xf bank_mask:0xf bound_ctrl:1
	v_cndmask_b32_dpp v137, v83, v81, vcc row_shr:4 row_mask:0xf bank_mask:0xf bound_ctrl:1
	v_mfma_scale_f32_16x16x128_f8f6f4 v[216:219], v[140:143], v[204:211], v[216:219], v240, v241 op_sel_hi:[0,0,0] cbsz:4
	v_and_b32_e32 v204, v170, v235
	v_and_b32_e32 v205, v170, v236
	v_and_b32_e32 v206, v170, v237
	v_and_b32_e32 v207, v170, v238
	v_and_b32_e32 v208, v171, v235
	v_and_b32_e32 v209, v171, v236
	v_and_b32_e32 v210, v171, v237
	v_and_b32_e32 v211, v171, v238
	s_mov_b64 vcc, s[6:7]
	v_cndmask_b32_dpp v140, v86, v84, vcc row_shr:4 row_mask:0xf bank_mask:0xf bound_ctrl:1
	v_cndmask_b32_dpp v141, v87, v85, vcc row_shr:4 row_mask:0xf bank_mask:0xf bound_ctrl:1
	s_mov_b64 vcc, s[4:5]
	v_cndmask_b32_dpp v142, v84, v86, vcc row_shl:4 row_mask:0xf bank_mask:0xf bound_ctrl:1
	v_cndmask_b32_dpp v143, v85, v87, vcc row_shl:4 row_mask:0xf bank_mask:0xf bound_ctrl:1
	v_mfma_scale_f32_16x16x128_f8f6f4 v[216:219], v[136:139], v[144:151], v[216:219], v240, v241 op_sel_hi:[0,0,0] cbsz:4
	v_and_b32_e32 v144, v172, v235
	v_and_b32_e32 v145, v172, v236
	v_and_b32_e32 v146, v172, v237
	v_and_b32_e32 v147, v172, v238
	v_and_b32_e32 v148, v173, v235
	v_and_b32_e32 v149, v173, v236
	v_and_b32_e32 v150, v173, v237
	v_and_b32_e32 v151, v173, v238
	s_mov_b64 vcc, s[4:5]
	v_cndmask_b32_dpp v138, v88, v90, vcc row_shl:4 row_mask:0xf bank_mask:0xf bound_ctrl:1
	v_cndmask_b32_dpp v139, v89, v91, vcc row_shl:4 row_mask:0xf bank_mask:0xf bound_ctrl:1
	s_mov_b64 vcc, s[6:7]
	v_cndmask_b32_dpp v136, v90, v88, vcc row_shr:4 row_mask:0xf bank_mask:0xf bound_ctrl:1
	v_cndmask_b32_dpp v137, v91, v89, vcc row_shr:4 row_mask:0xf bank_mask:0xf bound_ctrl:1
	v_mfma_scale_f32_16x16x128_f8f6f4 v[216:219], v[140:143], v[204:211], v[216:219], v240, v241 op_sel_hi:[0,0,0] cbsz:4
	v_and_b32_e32 v204, v174, v235
	v_and_b32_e32 v205, v174, v236
	v_and_b32_e32 v206, v174, v237
	v_and_b32_e32 v207, v174, v238
	v_and_b32_e32 v208, v175, v235
	v_and_b32_e32 v209, v175, v236
	v_and_b32_e32 v210, v175, v237
	v_and_b32_e32 v211, v175, v238
	s_mov_b64 vcc, s[6:7]
	v_cndmask_b32_dpp v140, v94, v92, vcc row_shr:4 row_mask:0xf bank_mask:0xf bound_ctrl:1
	v_cndmask_b32_dpp v141, v95, v93, vcc row_shr:4 row_mask:0xf bank_mask:0xf bound_ctrl:1
	s_mov_b64 vcc, s[4:5]
	v_cndmask_b32_dpp v142, v92, v94, vcc row_shl:4 row_mask:0xf bank_mask:0xf bound_ctrl:1
	v_cndmask_b32_dpp v143, v93, v95, vcc row_shl:4 row_mask:0xf bank_mask:0xf bound_ctrl:1
	v_mfma_scale_f32_16x16x128_f8f6f4 v[216:219], v[136:139], v[144:151], v[216:219], v240, v241 op_sel_hi:[0,0,0] cbsz:4
	s_nop 0
	v_mfma_scale_f32_16x16x128_f8f6f4 v[216:219], v[140:143], v[204:211], v[216:219], v240, v241 op_sel_hi:[0,0,0] cbsz:4
	s_waitcnt lgkmcnt(0)
	v_lshl_or_b32 v128, v128, 7, v232
	v_lshl_or_b32 v129, v129, 7, v232
	v_lshl_or_b32 v130, v130, 7, v232
	v_lshl_or_b32 v131, v131, 7, v232
	v_lshl_or_b32 v132, v132, 7, v232
	v_lshl_or_b32 v133, v133, 7, v232
	v_lshl_or_b32 v134, v134, 7, v232
	v_lshl_or_b32 v135, v135, 7, v232
	buffer_load_dwordx4 v[64:67], v128, s[20:23], s1 offen
	buffer_load_dwordx4 v[68:71], v129, s[20:23], s1 offen
	buffer_load_dwordx4 v[72:75], v130, s[20:23], s1 offen
	buffer_load_dwordx4 v[76:79], v131, s[20:23], s1 offen
	buffer_load_dwordx4 v[80:83], v132, s[20:23], s1 offen
	buffer_load_dwordx4 v[84:87], v133, s[20:23], s1 offen
	buffer_load_dwordx4 v[88:91], v134, s[20:23], s1 offen
	buffer_load_dwordx4 v[92:95], v135, s[20:23], s1 offen
	ds_read_b32 v128, v243 offset:2816
	ds_read_b32 v129, v243 offset:2848
	ds_read_b32 v130, v243 offset:2880
	ds_read_b32 v131, v243 offset:2912
	ds_read_b32 v132, v243 offset:2944
	ds_read_b32 v133, v243 offset:2976
	ds_read_b32 v134, v243 offset:3008
	ds_read_b32 v135, v243 offset:3040
	ds_read_b64 v[160:161], v234 offset:2048
	ds_read_b64 v[162:163], v234 offset:2080
	ds_read_b64 v[164:165], v234 offset:2112
	ds_read_b64 v[166:167], v234 offset:2144
	ds_read_b64 v[168:169], v234 offset:2176
	ds_read_b64 v[170:171], v234 offset:2208
	ds_read_b64 v[172:173], v234 offset:2240
	ds_read_b64 v[174:175], v234 offset:2272
	s_waitcnt vmcnt(26)
	v_and_b32_e32 v144, v176, v235
	v_and_b32_e32 v145, v176, v236
	v_and_b32_e32 v146, v176, v237
	v_and_b32_e32 v147, v176, v238
	v_and_b32_e32 v148, v177, v235
	v_and_b32_e32 v149, v177, v236
	v_and_b32_e32 v150, v177, v237
	v_and_b32_e32 v151, v177, v238
	s_mov_b64 vcc, s[4:5]
	v_cndmask_b32_dpp v138, v96, v98, vcc row_shl:4 row_mask:0xf bank_mask:0xf bound_ctrl:1
	v_cndmask_b32_dpp v139, v97, v99, vcc row_shl:4 row_mask:0xf bank_mask:0xf bound_ctrl:1
	s_mov_b64 vcc, s[6:7]
	v_cndmask_b32_dpp v136, v98, v96, vcc row_shr:4 row_mask:0xf bank_mask:0xf bound_ctrl:1
	v_cndmask_b32_dpp v137, v99, v97, vcc row_shr:4 row_mask:0xf bank_mask:0xf bound_ctrl:1
	v_and_b32_e32 v204, v178, v235
	v_and_b32_e32 v205, v178, v236
	v_and_b32_e32 v206, v178, v237
	v_and_b32_e32 v207, v178, v238
	v_and_b32_e32 v208, v179, v235
	v_and_b32_e32 v209, v179, v236
	v_and_b32_e32 v210, v179, v237
	v_and_b32_e32 v211, v179, v238
	s_mov_b64 vcc, s[6:7]
	v_cndmask_b32_dpp v140, v102, v100, vcc row_shr:4 row_mask:0xf bank_mask:0xf bound_ctrl:1
	v_cndmask_b32_dpp v141, v103, v101, vcc row_shr:4 row_mask:0xf bank_mask:0xf bound_ctrl:1
	s_mov_b64 vcc, s[4:5]
	v_cndmask_b32_dpp v142, v100, v102, vcc row_shl:4 row_mask:0xf bank_mask:0xf bound_ctrl:1
	v_cndmask_b32_dpp v143, v101, v103, vcc row_shl:4 row_mask:0xf bank_mask:0xf bound_ctrl:1
	v_mfma_scale_f32_16x16x128_f8f6f4 v[216:219], v[136:139], v[144:151], v[216:219], v240, v241 op_sel_hi:[0,0,0] cbsz:4
	v_permlane16_swap_b32_e32 v212, v214
	v_permlane16_swap_b32_e32 v213, v215
	v_lshlrev_b32_e32 v252, 16, v228
	v_and_b32_e32 v144, v180, v235
	v_and_b32_e32 v145, v180, v236
	v_and_b32_e32 v146, v180, v237
	v_and_b32_e32 v147, v180, v238
	v_and_b32_e32 v148, v181, v235
	v_and_b32_e32 v149, v181, v236
	v_and_b32_e32 v150, v181, v237
	v_and_b32_e32 v151, v181, v238
	s_mov_b64 vcc, s[4:5]
	v_cndmask_b32_dpp v138, v104, v106, vcc row_shl:4 row_mask:0xf bank_mask:0xf bound_ctrl:1
	v_cndmask_b32_dpp v139, v105, v107, vcc row_shl:4 row_mask:0xf bank_mask:0xf bound_ctrl:1
	s_mov_b64 vcc, s[6:7]
	v_cndmask_b32_dpp v136, v106, v104, vcc row_shr:4 row_mask:0xf bank_mask:0xf bound_ctrl:1
	v_cndmask_b32_dpp v137, v107, v105, vcc row_shr:4 row_mask:0xf bank_mask:0xf bound_ctrl:1
	v_mfma_scale_f32_16x16x128_f8f6f4 v[216:219], v[140:143], v[204:211], v[216:219], v240, v241 op_sel_hi:[0,0,0] cbsz:4
	v_and_b32_e32 v253, 0xffff0000, v228
	v_lshlrev_b32_e32 v254, 16, v229
	v_and_b32_e32 v255, 0xffff0000, v229
	v_and_b32_e32 v204, v182, v235
	v_and_b32_e32 v205, v182, v236
	v_and_b32_e32 v206, v182, v237
	v_and_b32_e32 v207, v182, v238
	v_and_b32_e32 v208, v183, v235
	v_and_b32_e32 v209, v183, v236
	v_and_b32_e32 v210, v183, v237
	v_and_b32_e32 v211, v183, v238
	s_mov_b64 vcc, s[6:7]
	v_cndmask_b32_dpp v140, v110, v108, vcc row_shr:4 row_mask:0xf bank_mask:0xf bound_ctrl:1
	v_cndmask_b32_dpp v141, v111, v109, vcc row_shr:4 row_mask:0xf bank_mask:0xf bound_ctrl:1
	s_mov_b64 vcc, s[4:5]
	v_cndmask_b32_dpp v142, v108, v110, vcc row_shl:4 row_mask:0xf bank_mask:0xf bound_ctrl:1
	v_cndmask_b32_dpp v143, v109, v111, vcc row_shl:4 row_mask:0xf bank_mask:0xf bound_ctrl:1
	v_mfma_scale_f32_16x16x128_f8f6f4 v[216:219], v[136:139], v[144:151], v[216:219], v240, v241 op_sel_hi:[0,0,0] cbsz:4
	v_add_f32_e32 v252, v212, v252
	v_add_f32_e32 v253, v214, v253
	v_add_f32_e32 v254, v213, v254
	v_and_b32_e32 v144, v184, v235
	v_and_b32_e32 v145, v184, v236
	v_and_b32_e32 v146, v184, v237
	v_and_b32_e32 v147, v184, v238
	v_and_b32_e32 v148, v185, v235
	v_and_b32_e32 v149, v185, v236
	v_and_b32_e32 v150, v185, v237
	v_and_b32_e32 v151, v185, v238
	s_mov_b64 vcc, s[4:5]
	v_cndmask_b32_dpp v138, v112, v114, vcc row_shl:4 row_mask:0xf bank_mask:0xf bound_ctrl:1
	v_cndmask_b32_dpp v139, v113, v115, vcc row_shl:4 row_mask:0xf bank_mask:0xf bound_ctrl:1
	s_mov_b64 vcc, s[6:7]
	v_cndmask_b32_dpp v136, v114, v112, vcc row_shr:4 row_mask:0xf bank_mask:0xf bound_ctrl:1
	v_cndmask_b32_dpp v137, v115, v113, vcc row_shr:4 row_mask:0xf bank_mask:0xf bound_ctrl:1
	v_mfma_scale_f32_16x16x128_f8f6f4 v[216:219], v[140:143], v[204:211], v[216:219], v240, v241 op_sel_hi:[0,0,0] cbsz:4
	v_add_f32_e32 v255, v215, v255
	v_mul_f32_e32 v192, v252, v252
	v_mul_f32_e32 v193, v254, v254
	v_and_b32_e32 v204, v186, v235
	v_and_b32_e32 v205, v186, v236
	v_and_b32_e32 v206, v186, v237
	v_and_b32_e32 v207, v186, v238
	v_and_b32_e32 v208, v187, v235
	v_and_b32_e32 v209, v187, v236
	v_and_b32_e32 v210, v187, v237
	v_and_b32_e32 v211, v187, v238
	s_mov_b64 vcc, s[6:7]
	v_cndmask_b32_dpp v140, v118, v116, vcc row_shr:4 row_mask:0xf bank_mask:0xf bound_ctrl:1
	v_cndmask_b32_dpp v141, v119, v117, vcc row_shr:4 row_mask:0xf bank_mask:0xf bound_ctrl:1
	s_mov_b64 vcc, s[4:5]
	v_cndmask_b32_dpp v142, v116, v118, vcc row_shl:4 row_mask:0xf bank_mask:0xf bound_ctrl:1
	v_cndmask_b32_dpp v143, v117, v119, vcc row_shl:4 row_mask:0xf bank_mask:0xf bound_ctrl:1
	v_mfma_scale_f32_16x16x128_f8f6f4 v[216:219], v[136:139], v[144:151], v[216:219], v240, v241 op_sel_hi:[0,0,0] cbsz:4
	v_fmac_f32_e32 v192, v253, v253
	v_fmac_f32_e32 v193, v255, v255
	v_cvt_pk_bf16_f32 v250, v252, v253
	v_and_b32_e32 v144, v188, v235
	v_and_b32_e32 v145, v188, v236
	v_and_b32_e32 v146, v188, v237
	v_and_b32_e32 v147, v188, v238
	v_and_b32_e32 v148, v189, v235
	v_and_b32_e32 v149, v189, v236
	v_and_b32_e32 v150, v189, v237
	v_and_b32_e32 v151, v189, v238
	s_mov_b64 vcc, s[4:5]
	v_cndmask_b32_dpp v138, v120, v122, vcc row_shl:4 row_mask:0xf bank_mask:0xf bound_ctrl:1
	v_cndmask_b32_dpp v139, v121, v123, vcc row_shl:4 row_mask:0xf bank_mask:0xf bound_ctrl:1
	s_mov_b64 vcc, s[6:7]
	v_cndmask_b32_dpp v136, v122, v120, vcc row_shr:4 row_mask:0xf bank_mask:0xf bound_ctrl:1
	v_cndmask_b32_dpp v137, v123, v121, vcc row_shr:4 row_mask:0xf bank_mask:0xf bound_ctrl:1
	v_mfma_scale_f32_16x16x128_f8f6f4 v[216:219], v[140:143], v[204:211], v[216:219], v240, v241 op_sel_hi:[0,0,0] cbsz:4
	v_cvt_pk_bf16_f32 v251, v254, v255
	v_add_f32_e32 v192, v192, v193
	v_add_f32_e32 v222, v222, v192
	v_and_b32_e32 v204, v190, v235
	v_and_b32_e32 v205, v190, v236
	v_and_b32_e32 v206, v190, v237
	v_and_b32_e32 v207, v190, v238
	v_and_b32_e32 v208, v191, v235
	v_and_b32_e32 v209, v191, v236
	v_and_b32_e32 v210, v191, v237
	v_and_b32_e32 v211, v191, v238
	s_mov_b64 vcc, s[6:7]
	v_cndmask_b32_dpp v140, v126, v124, vcc row_shr:4 row_mask:0xf bank_mask:0xf bound_ctrl:1
	v_cndmask_b32_dpp v141, v127, v125, vcc row_shr:4 row_mask:0xf bank_mask:0xf bound_ctrl:1
	s_mov_b64 vcc, s[4:5]
	v_cndmask_b32_dpp v142, v124, v126, vcc row_shl:4 row_mask:0xf bank_mask:0xf bound_ctrl:1
	v_cndmask_b32_dpp v143, v125, v127, vcc row_shl:4 row_mask:0xf bank_mask:0xf bound_ctrl:1
	v_mfma_scale_f32_16x16x128_f8f6f4 v[216:219], v[136:139], v[144:151], v[216:219], v240, v241 op_sel_hi:[0,0,0] cbsz:4
	s_nop 0
	v_mfma_scale_f32_16x16x128_f8f6f4 v[216:219], v[140:143], v[204:211], v[216:219], v240, v241 op_sel_hi:[0,0,0] cbsz:4
	s_lshl_b32 s64, s0, 9
	s_add_u32 s64, s64, 0x2000
	s_add_u32 s76, s28, s64
	s_addc_u32 s77, s29, 0
	global_store_dwordx2 v239, v[250:251], s[76:77]
	s_lshl_b32 s64, s0, 9
	s_add_u32 s64, s64, 0x4000
	s_add_u32 s70, s28, s64
	s_addc_u32 s71, s29, 0
	global_load_dwordx2 v[228:229], v239, s[70:71] nt
	s_waitcnt lgkmcnt(0)
	v_lshl_or_b32 v128, v128, 7, v232
	v_lshl_or_b32 v129, v129, 7, v232
	v_lshl_or_b32 v130, v130, 7, v232
	v_lshl_or_b32 v131, v131, 7, v232
	v_lshl_or_b32 v132, v132, 7, v232
	v_lshl_or_b32 v133, v133, 7, v232
	v_lshl_or_b32 v134, v134, 7, v232
	v_lshl_or_b32 v135, v135, 7, v232
	buffer_load_dwordx4 v[96:99], v128, s[20:23], s1 offen
	buffer_load_dwordx4 v[100:103], v129, s[20:23], s1 offen
	buffer_load_dwordx4 v[104:107], v130, s[20:23], s1 offen
	buffer_load_dwordx4 v[108:111], v131, s[20:23], s1 offen
	buffer_load_dwordx4 v[112:115], v132, s[20:23], s1 offen
	buffer_load_dwordx4 v[116:119], v133, s[20:23], s1 offen
	buffer_load_dwordx4 v[120:123], v134, s[20:23], s1 offen
	buffer_load_dwordx4 v[124:127], v135, s[20:23], s1 offen
	ds_read_b32 v128, v243 offset:3072
	ds_read_b32 v129, v243 offset:3104
	ds_read_b32 v130, v243 offset:3136
	ds_read_b32 v131, v243 offset:3168
	ds_read_b32 v132, v243 offset:3200
	ds_read_b32 v133, v243 offset:3232
	ds_read_b32 v134, v243 offset:3264
	ds_read_b32 v135, v243 offset:3296
	ds_read_b64 v[176:177], v234 offset:2304
	ds_read_b64 v[178:179], v234 offset:2336
	ds_read_b64 v[180:181], v234 offset:2368
	ds_read_b64 v[182:183], v234 offset:2400
	ds_read_b64 v[184:185], v234 offset:2432
	ds_read_b64 v[186:187], v234 offset:2464
	ds_read_b64 v[188:189], v234 offset:2496
	ds_read_b64 v[190:191], v234 offset:2528
	s_waitcnt vmcnt(28)
	v_and_b32_e32 v144, v160, v235
	v_and_b32_e32 v145, v160, v236
	v_and_b32_e32 v146, v160, v237
	v_and_b32_e32 v147, v160, v238
	v_and_b32_e32 v148, v161, v235
	v_and_b32_e32 v149, v161, v236
	v_and_b32_e32 v150, v161, v237
	v_and_b32_e32 v151, v161, v238
	s_mov_b64 vcc, s[4:5]
	v_cndmask_b32_dpp v138, v0, v2, vcc row_shl:4 row_mask:0xf bank_mask:0xf bound_ctrl:1
	v_cndmask_b32_dpp v139, v1, v3, vcc row_shl:4 row_mask:0xf bank_mask:0xf bound_ctrl:1
	s_mov_b64 vcc, s[6:7]
	v_cndmask_b32_dpp v136, v2, v0, vcc row_shr:4 row_mask:0xf bank_mask:0xf bound_ctrl:1
	v_cndmask_b32_dpp v137, v3, v1, vcc row_shr:4 row_mask:0xf bank_mask:0xf bound_ctrl:1
	v_and_b32_e32 v204, v162, v235
	v_and_b32_e32 v205, v162, v236
	v_and_b32_e32 v206, v162, v237
	v_and_b32_e32 v207, v162, v238
	v_and_b32_e32 v208, v163, v235
	v_and_b32_e32 v209, v163, v236
	v_and_b32_e32 v210, v163, v237
	v_and_b32_e32 v211, v163, v238
	s_mov_b64 vcc, s[6:7]
	v_cndmask_b32_dpp v140, v6, v4, vcc row_shr:4 row_mask:0xf bank_mask:0xf bound_ctrl:1
	v_cndmask_b32_dpp v141, v7, v5, vcc row_shr:4 row_mask:0xf bank_mask:0xf bound_ctrl:1
	s_mov_b64 vcc, s[4:5]
	v_cndmask_b32_dpp v142, v4, v6, vcc row_shl:4 row_mask:0xf bank_mask:0xf bound_ctrl:1
	v_cndmask_b32_dpp v143, v5, v7, vcc row_shl:4 row_mask:0xf bank_mask:0xf bound_ctrl:1
	v_mfma_scale_f32_16x16x128_f8f6f4 v[212:215], v[136:139], v[144:151], 0, v240, v241 op_sel_hi:[0,0,0] cbsz:4
	v_and_b32_e32 v144, v164, v235
	v_and_b32_e32 v145, v164, v236
	v_and_b32_e32 v146, v164, v237
	v_and_b32_e32 v147, v164, v238
	v_and_b32_e32 v148, v165, v235
	v_and_b32_e32 v149, v165, v236
	v_and_b32_e32 v150, v165, v237
	v_and_b32_e32 v151, v165, v238
	s_mov_b64 vcc, s[4:5]
	v_cndmask_b32_dpp v138, v8, v10, vcc row_shl:4 row_mask:0xf bank_mask:0xf bound_ctrl:1
	v_cndmask_b32_dpp v139, v9, v11, vcc row_shl:4 row_mask:0xf bank_mask:0xf bound_ctrl:1
	s_mov_b64 vcc, s[6:7]
	v_cndmask_b32_dpp v136, v10, v8, vcc row_shr:4 row_mask:0xf bank_mask:0xf bound_ctrl:1
	v_cndmask_b32_dpp v137, v11, v9, vcc row_shr:4 row_mask:0xf bank_mask:0xf bound_ctrl:1
	v_mfma_scale_f32_16x16x128_f8f6f4 v[212:215], v[140:143], v[204:211], v[212:215], v240, v241 op_sel_hi:[0,0,0] cbsz:4
	v_and_b32_e32 v204, v166, v235
	v_and_b32_e32 v205, v166, v236
	v_and_b32_e32 v206, v166, v237
	v_and_b32_e32 v207, v166, v238
	v_and_b32_e32 v208, v167, v235
	v_and_b32_e32 v209, v167, v236
	v_and_b32_e32 v210, v167, v237
	v_and_b32_e32 v211, v167, v238
	s_mov_b64 vcc, s[6:7]
	v_cndmask_b32_dpp v140, v14, v12, vcc row_shr:4 row_mask:0xf bank_mask:0xf bound_ctrl:1
	v_cndmask_b32_dpp v141, v15, v13, vcc row_shr:4 row_mask:0xf bank_mask:0xf bound_ctrl:1
	s_mov_b64 vcc, s[4:5]
	v_cndmask_b32_dpp v142, v12, v14, vcc row_shl:4 row_mask:0xf bank_mask:0xf bound_ctrl:1
	v_cndmask_b32_dpp v143, v13, v15, vcc row_shl:4 row_mask:0xf bank_mask:0xf bound_ctrl:1
	v_mfma_scale_f32_16x16x128_f8f6f4 v[212:215], v[136:139], v[144:151], v[212:215], v240, v241 op_sel_hi:[0,0,0] cbsz:4
	v_and_b32_e32 v144, v168, v235
	v_and_b32_e32 v145, v168, v236
	v_and_b32_e32 v146, v168, v237
	v_and_b32_e32 v147, v168, v238
	v_and_b32_e32 v148, v169, v235
	v_and_b32_e32 v149, v169, v236
	v_and_b32_e32 v150, v169, v237
	v_and_b32_e32 v151, v169, v238
	s_mov_b64 vcc, s[4:5]
	v_cndmask_b32_dpp v138, v16, v18, vcc row_shl:4 row_mask:0xf bank_mask:0xf bound_ctrl:1
	v_cndmask_b32_dpp v139, v17, v19, vcc row_shl:4 row_mask:0xf bank_mask:0xf bound_ctrl:1
	s_mov_b64 vcc, s[6:7]
	v_cndmask_b32_dpp v136, v18, v16, vcc row_shr:4 row_mask:0xf bank_mask:0xf bound_ctrl:1
	v_cndmask_b32_dpp v137, v19, v17, vcc row_shr:4 row_mask:0xf bank_mask:0xf bound_ctrl:1
	v_mfma_scale_f32_16x16x128_f8f6f4 v[212:215], v[140:143], v[204:211], v[212:215], v240, v241 op_sel_hi:[0,0,0] cbsz:4
	v_and_b32_e32 v204, v170, v235
	v_and_b32_e32 v205, v170, v236
	v_and_b32_e32 v206, v170, v237
	v_and_b32_e32 v207, v170, v238
	v_and_b32_e32 v208, v171, v235
	v_and_b32_e32 v209, v171, v236
	v_and_b32_e32 v210, v171, v237
	v_and_b32_e32 v211, v171, v238
	s_mov_b64 vcc, s[6:7]
	v_cndmask_b32_dpp v140, v22, v20, vcc row_shr:4 row_mask:0xf bank_mask:0xf bound_ctrl:1
	v_cndmask_b32_dpp v141, v23, v21, vcc row_shr:4 row_mask:0xf bank_mask:0xf bound_ctrl:1
	s_mov_b64 vcc, s[4:5]
	v_cndmask_b32_dpp v142, v20, v22, vcc row_shl:4 row_mask:0xf bank_mask:0xf bound_ctrl:1
	v_cndmask_b32_dpp v143, v21, v23, vcc row_shl:4 row_mask:0xf bank_mask:0xf bound_ctrl:1
	v_mfma_scale_f32_16x16x128_f8f6f4 v[212:215], v[136:139], v[144:151], v[212:215], v240, v241 op_sel_hi:[0,0,0] cbsz:4
	v_and_b32_e32 v144, v172, v235
	v_and_b32_e32 v145, v172, v236
	v_and_b32_e32 v146, v172, v237
	v_and_b32_e32 v147, v172, v238
	v_and_b32_e32 v148, v173, v235
	v_and_b32_e32 v149, v173, v236
	v_and_b32_e32 v150, v173, v237
	v_and_b32_e32 v151, v173, v238
	s_mov_b64 vcc, s[4:5]
	v_cndmask_b32_dpp v138, v24, v26, vcc row_shl:4 row_mask:0xf bank_mask:0xf bound_ctrl:1
	v_cndmask_b32_dpp v139, v25, v27, vcc row_shl:4 row_mask:0xf bank_mask:0xf bound_ctrl:1
	s_mov_b64 vcc, s[6:7]
	v_cndmask_b32_dpp v136, v26, v24, vcc row_shr:4 row_mask:0xf bank_mask:0xf bound_ctrl:1
	v_cndmask_b32_dpp v137, v27, v25, vcc row_shr:4 row_mask:0xf bank_mask:0xf bound_ctrl:1
	v_mfma_scale_f32_16x16x128_f8f6f4 v[212:215], v[140:143], v[204:211], v[212:215], v240, v241 op_sel_hi:[0,0,0] cbsz:4
	v_and_b32_e32 v204, v174, v235
	v_and_b32_e32 v205, v174, v236
	v_and_b32_e32 v206, v174, v237
	v_and_b32_e32 v207, v174, v238
	v_and_b32_e32 v208, v175, v235
	v_and_b32_e32 v209, v175, v236
	v_and_b32_e32 v210, v175, v237
	v_and_b32_e32 v211, v175, v238
	s_mov_b64 vcc, s[6:7]
	v_cndmask_b32_dpp v140, v30, v28, vcc row_shr:4 row_mask:0xf bank_mask:0xf bound_ctrl:1
	v_cndmask_b32_dpp v141, v31, v29, vcc row_shr:4 row_mask:0xf bank_mask:0xf bound_ctrl:1
	s_mov_b64 vcc, s[4:5]
	v_cndmask_b32_dpp v142, v28, v30, vcc row_shl:4 row_mask:0xf bank_mask:0xf bound_ctrl:1
	v_cndmask_b32_dpp v143, v29, v31, vcc row_shl:4 row_mask:0xf bank_mask:0xf bound_ctrl:1
	v_mfma_scale_f32_16x16x128_f8f6f4 v[212:215], v[136:139], v[144:151], v[212:215], v240, v241 op_sel_hi:[0,0,0] cbsz:4
	s_nop 0
	v_mfma_scale_f32_16x16x128_f8f6f4 v[212:215], v[140:143], v[204:211], v[212:215], v240, v241 op_sel_hi:[0,0,0] cbsz:4
	s_waitcnt lgkmcnt(0)
	v_lshl_or_b32 v128, v128, 7, v232
	v_lshl_or_b32 v129, v129, 7, v232
	v_lshl_or_b32 v130, v130, 7, v232
	v_lshl_or_b32 v131, v131, 7, v232
	v_lshl_or_b32 v132, v132, 7, v232
	v_lshl_or_b32 v133, v133, 7, v232
	v_lshl_or_b32 v134, v134, 7, v232
	v_lshl_or_b32 v135, v135, 7, v232
	buffer_load_dwordx4 v[0:3], v128, s[20:23], s1 offen
	buffer_load_dwordx4 v[4:7], v129, s[20:23], s1 offen
	buffer_load_dwordx4 v[8:11], v130, s[20:23], s1 offen
	buffer_load_dwordx4 v[12:15], v131, s[20:23], s1 offen
	buffer_load_dwordx4 v[16:19], v132, s[20:23], s1 offen
	buffer_load_dwordx4 v[20:23], v133, s[20:23], s1 offen
	buffer_load_dwordx4 v[24:27], v134, s[20:23], s1 offen
	buffer_load_dwordx4 v[28:31], v135, s[20:23], s1 offen
	ds_read_b32 v128, v243 offset:3328
	ds_read_b32 v129, v243 offset:3360
	ds_read_b32 v130, v243 offset:3392
	ds_read_b32 v131, v243 offset:3424
	ds_read_b32 v132, v243 offset:3456
	ds_read_b32 v133, v243 offset:3488
	ds_read_b32 v134, v243 offset:3520
	ds_read_b32 v135, v243 offset:3552
	ds_read_b64 v[160:161], v234 offset:2560
	ds_read_b64 v[162:163], v234 offset:2592
	ds_read_b64 v[164:165], v234 offset:2624
	ds_read_b64 v[166:167], v234 offset:2656
	ds_read_b64 v[168:169], v234 offset:2688
	ds_read_b64 v[170:171], v234 offset:2720
	ds_read_b64 v[172:173], v234 offset:2752
	ds_read_b64 v[174:175], v234 offset:2784
	s_waitcnt vmcnt(26)
	v_and_b32_e32 v144, v176, v235
	v_and_b32_e32 v145, v176, v236
	v_and_b32_e32 v146, v176, v237
	v_and_b32_e32 v147, v176, v238
	v_and_b32_e32 v148, v177, v235
	v_and_b32_e32 v149, v177, v236
	v_and_b32_e32 v150, v177, v237
	v_and_b32_e32 v151, v177, v238
	s_mov_b64 vcc, s[4:5]
	v_cndmask_b32_dpp v138, v32, v34, vcc row_shl:4 row_mask:0xf bank_mask:0xf bound_ctrl:1
	v_cndmask_b32_dpp v139, v33, v35, vcc row_shl:4 row_mask:0xf bank_mask:0xf bound_ctrl:1
	s_mov_b64 vcc, s[6:7]
	v_cndmask_b32_dpp v136, v34, v32, vcc row_shr:4 row_mask:0xf bank_mask:0xf bound_ctrl:1
	v_cndmask_b32_dpp v137, v35, v33, vcc row_shr:4 row_mask:0xf bank_mask:0xf bound_ctrl:1
	v_and_b32_e32 v204, v178, v235
	v_and_b32_e32 v205, v178, v236
	v_and_b32_e32 v206, v178, v237
	v_and_b32_e32 v207, v178, v238
	v_and_b32_e32 v208, v179, v235
	v_and_b32_e32 v209, v179, v236
	v_and_b32_e32 v210, v179, v237
	v_and_b32_e32 v211, v179, v238
	s_mov_b64 vcc, s[6:7]
	v_cndmask_b32_dpp v140, v38, v36, vcc row_shr:4 row_mask:0xf bank_mask:0xf bound_ctrl:1
	v_cndmask_b32_dpp v141, v39, v37, vcc row_shr:4 row_mask:0xf bank_mask:0xf bound_ctrl:1
	s_mov_b64 vcc, s[4:5]
	v_cndmask_b32_dpp v142, v36, v38, vcc row_shl:4 row_mask:0xf bank_mask:0xf bound_ctrl:1
	v_cndmask_b32_dpp v143, v37, v39, vcc row_shl:4 row_mask:0xf bank_mask:0xf bound_ctrl:1
	v_mfma_scale_f32_16x16x128_f8f6f4 v[212:215], v[136:139], v[144:151], v[212:215], v240, v241 op_sel_hi:[0,0,0] cbsz:4
	v_permlane16_swap_b32_e32 v216, v218
	v_permlane16_swap_b32_e32 v217, v219
	v_lshlrev_b32_e32 v252, 16, v230
	v_and_b32_e32 v144, v180, v235
	v_and_b32_e32 v145, v180, v236
	v_and_b32_e32 v146, v180, v237
	v_and_b32_e32 v147, v180, v238
	v_and_b32_e32 v148, v181, v235
	v_and_b32_e32 v149, v181, v236
	v_and_b32_e32 v150, v181, v237
	v_and_b32_e32 v151, v181, v238
	s_mov_b64 vcc, s[4:5]
	v_cndmask_b32_dpp v138, v40, v42, vcc row_shl:4 row_mask:0xf bank_mask:0xf bound_ctrl:1
	v_cndmask_b32_dpp v139, v41, v43, vcc row_shl:4 row_mask:0xf bank_mask:0xf bound_ctrl:1
	s_mov_b64 vcc, s[6:7]
	v_cndmask_b32_dpp v136, v42, v40, vcc row_shr:4 row_mask:0xf bank_mask:0xf bound_ctrl:1
	v_cndmask_b32_dpp v137, v43, v41, vcc row_shr:4 row_mask:0xf bank_mask:0xf bound_ctrl:1
	v_mfma_scale_f32_16x16x128_f8f6f4 v[212:215], v[140:143], v[204:211], v[212:215], v240, v241 op_sel_hi:[0,0,0] cbsz:4
	v_and_b32_e32 v253, 0xffff0000, v230
	v_lshlrev_b32_e32 v254, 16, v231
	v_and_b32_e32 v255, 0xffff0000, v231
	v_and_b32_e32 v204, v182, v235
	v_and_b32_e32 v205, v182, v236
	v_and_b32_e32 v206, v182, v237
	v_and_b32_e32 v207, v182, v238
	v_and_b32_e32 v208, v183, v235
	v_and_b32_e32 v209, v183, v236
	v_and_b32_e32 v210, v183, v237
	v_and_b32_e32 v211, v183, v238
	s_mov_b64 vcc, s[6:7]
	v_cndmask_b32_dpp v140, v46, v44, vcc row_shr:4 row_mask:0xf bank_mask:0xf bound_ctrl:1
	v_cndmask_b32_dpp v141, v47, v45, vcc row_shr:4 row_mask:0xf bank_mask:0xf bound_ctrl:1
	s_mov_b64 vcc, s[4:5]
	v_cndmask_b32_dpp v142, v44, v46, vcc row_shl:4 row_mask:0xf bank_mask:0xf bound_ctrl:1
	v_cndmask_b32_dpp v143, v45, v47, vcc row_shl:4 row_mask:0xf bank_mask:0xf bound_ctrl:1
	v_mfma_scale_f32_16x16x128_f8f6f4 v[212:215], v[136:139], v[144:151], v[212:215], v240, v241 op_sel_hi:[0,0,0] cbsz:4
	v_add_f32_e32 v252, v216, v252
	v_add_f32_e32 v253, v218, v253
	v_add_f32_e32 v254, v217, v254
	v_and_b32_e32 v144, v184, v235
	v_and_b32_e32 v145, v184, v236
	v_and_b32_e32 v146, v184, v237
	v_and_b32_e32 v147, v184, v238
	v_and_b32_e32 v148, v185, v235
	v_and_b32_e32 v149, v185, v236
	v_and_b32_e32 v150, v185, v237
	v_and_b32_e32 v151, v185, v238
	s_mov_b64 vcc, s[4:5]
	v_cndmask_b32_dpp v138, v48, v50, vcc row_shl:4 row_mask:0xf bank_mask:0xf bound_ctrl:1
	v_cndmask_b32_dpp v139, v49, v51, vcc row_shl:4 row_mask:0xf bank_mask:0xf bound_ctrl:1
	s_mov_b64 vcc, s[6:7]
	v_cndmask_b32_dpp v136, v50, v48, vcc row_shr:4 row_mask:0xf bank_mask:0xf bound_ctrl:1
	v_cndmask_b32_dpp v137, v51, v49, vcc row_shr:4 row_mask:0xf bank_mask:0xf bound_ctrl:1
	v_mfma_scale_f32_16x16x128_f8f6f4 v[212:215], v[140:143], v[204:211], v[212:215], v240, v241 op_sel_hi:[0,0,0] cbsz:4
	v_add_f32_e32 v255, v219, v255
	v_mul_f32_e32 v192, v252, v252
	v_mul_f32_e32 v193, v254, v254
	v_and_b32_e32 v204, v186, v235
	v_and_b32_e32 v205, v186, v236
	v_and_b32_e32 v206, v186, v237
	v_and_b32_e32 v207, v186, v238
	v_and_b32_e32 v208, v187, v235
	v_and_b32_e32 v209, v187, v236
	v_and_b32_e32 v210, v187, v237
	v_and_b32_e32 v211, v187, v238
	s_mov_b64 vcc, s[6:7]
	v_cndmask_b32_dpp v140, v54, v52, vcc row_shr:4 row_mask:0xf bank_mask:0xf bound_ctrl:1
	v_cndmask_b32_dpp v141, v55, v53, vcc row_shr:4 row_mask:0xf bank_mask:0xf bound_ctrl:1
	s_mov_b64 vcc, s[4:5]
	v_cndmask_b32_dpp v142, v52, v54, vcc row_shl:4 row_mask:0xf bank_mask:0xf bound_ctrl:1
	v_cndmask_b32_dpp v143, v53, v55, vcc row_shl:4 row_mask:0xf bank_mask:0xf bound_ctrl:1
	v_mfma_scale_f32_16x16x128_f8f6f4 v[212:215], v[136:139], v[144:151], v[212:215], v240, v241 op_sel_hi:[0,0,0] cbsz:4
	v_fmac_f32_e32 v192, v253, v253
	v_fmac_f32_e32 v193, v255, v255
	v_cvt_pk_bf16_f32 v250, v252, v253
	v_and_b32_e32 v144, v188, v235
	v_and_b32_e32 v145, v188, v236
	v_and_b32_e32 v146, v188, v237
	v_and_b32_e32 v147, v188, v238
	v_and_b32_e32 v148, v189, v235
	v_and_b32_e32 v149, v189, v236
	v_and_b32_e32 v150, v189, v237
	v_and_b32_e32 v151, v189, v238
	s_mov_b64 vcc, s[4:5]
	v_cndmask_b32_dpp v138, v56, v58, vcc row_shl:4 row_mask:0xf bank_mask:0xf bound_ctrl:1
	v_cndmask_b32_dpp v139, v57, v59, vcc row_shl:4 row_mask:0xf bank_mask:0xf bound_ctrl:1
	s_mov_b64 vcc, s[6:7]
	v_cndmask_b32_dpp v136, v58, v56, vcc row_shr:4 row_mask:0xf bank_mask:0xf bound_ctrl:1
	v_cndmask_b32_dpp v137, v59, v57, vcc row_shr:4 row_mask:0xf bank_mask:0xf bound_ctrl:1
	v_mfma_scale_f32_16x16x128_f8f6f4 v[212:215], v[140:143], v[204:211], v[212:215], v240, v241 op_sel_hi:[0,0,0] cbsz:4
	v_cvt_pk_bf16_f32 v251, v254, v255
	v_add_f32_e32 v192, v192, v193
	v_add_f32_e32 v223, v223, v192
	v_and_b32_e32 v204, v190, v235
	v_and_b32_e32 v205, v190, v236
	v_and_b32_e32 v206, v190, v237
	v_and_b32_e32 v207, v190, v238
	v_and_b32_e32 v208, v191, v235
	v_and_b32_e32 v209, v191, v236
	v_and_b32_e32 v210, v191, v237
	v_and_b32_e32 v211, v191, v238
	s_mov_b64 vcc, s[6:7]
	v_cndmask_b32_dpp v140, v62, v60, vcc row_shr:4 row_mask:0xf bank_mask:0xf bound_ctrl:1
	v_cndmask_b32_dpp v141, v63, v61, vcc row_shr:4 row_mask:0xf bank_mask:0xf bound_ctrl:1
	s_mov_b64 vcc, s[4:5]
	v_cndmask_b32_dpp v142, v60, v62, vcc row_shl:4 row_mask:0xf bank_mask:0xf bound_ctrl:1
	v_cndmask_b32_dpp v143, v61, v63, vcc row_shl:4 row_mask:0xf bank_mask:0xf bound_ctrl:1
	v_mfma_scale_f32_16x16x128_f8f6f4 v[212:215], v[136:139], v[144:151], v[212:215], v240, v241 op_sel_hi:[0,0,0] cbsz:4
	s_nop 0
	v_mfma_scale_f32_16x16x128_f8f6f4 v[212:215], v[140:143], v[204:211], v[212:215], v240, v241 op_sel_hi:[0,0,0] cbsz:4
	s_lshl_b32 s64, s0, 9
	s_add_u32 s64, s64, 0x3000
	s_add_u32 s76, s28, s64
	s_addc_u32 s77, s29, 0
	global_store_dwordx2 v239, v[250:251], s[76:77]
	s_lshl_b32 s64, s0, 9
	s_add_u32 s64, s64, 0x5000
	s_add_u32 s70, s28, s64
	s_addc_u32 s71, s29, 0
	global_load_dwordx2 v[230:231], v239, s[70:71] nt
	s_waitcnt lgkmcnt(0)
	v_lshl_or_b32 v128, v128, 7, v232
	v_lshl_or_b32 v129, v129, 7, v232
	v_lshl_or_b32 v130, v130, 7, v232
	v_lshl_or_b32 v131, v131, 7, v232
	v_lshl_or_b32 v132, v132, 7, v232
	v_lshl_or_b32 v133, v133, 7, v232
	v_lshl_or_b32 v134, v134, 7, v232
	v_lshl_or_b32 v135, v135, 7, v232
	buffer_load_dwordx4 v[32:35], v128, s[20:23], s1 offen
	buffer_load_dwordx4 v[36:39], v129, s[20:23], s1 offen
	buffer_load_dwordx4 v[40:43], v130, s[20:23], s1 offen
	buffer_load_dwordx4 v[44:47], v131, s[20:23], s1 offen
	buffer_load_dwordx4 v[48:51], v132, s[20:23], s1 offen
	buffer_load_dwordx4 v[52:55], v133, s[20:23], s1 offen
	buffer_load_dwordx4 v[56:59], v134, s[20:23], s1 offen
	buffer_load_dwordx4 v[60:63], v135, s[20:23], s1 offen
	ds_read_b32 v128, v243 offset:3584
	ds_read_b32 v129, v243 offset:3616
	ds_read_b32 v130, v243 offset:3648
	ds_read_b32 v131, v243 offset:3680
	ds_read_b32 v132, v243 offset:3712
	ds_read_b32 v133, v243 offset:3744
	ds_read_b32 v134, v243 offset:3776
	ds_read_b32 v135, v243 offset:3808
	ds_read_b64 v[176:177], v234 offset:2816
	ds_read_b64 v[178:179], v234 offset:2848
	ds_read_b64 v[180:181], v234 offset:2880
	ds_read_b64 v[182:183], v234 offset:2912
	ds_read_b64 v[184:185], v234 offset:2944
	ds_read_b64 v[186:187], v234 offset:2976
	ds_read_b64 v[188:189], v234 offset:3008
	ds_read_b64 v[190:191], v234 offset:3040
	s_waitcnt vmcnt(28)
	v_and_b32_e32 v144, v160, v235
	v_and_b32_e32 v145, v160, v236
	v_and_b32_e32 v146, v160, v237
	v_and_b32_e32 v147, v160, v238
	v_and_b32_e32 v148, v161, v235
	v_and_b32_e32 v149, v161, v236
	v_and_b32_e32 v150, v161, v237
	v_and_b32_e32 v151, v161, v238
	s_mov_b64 vcc, s[4:5]
	v_cndmask_b32_dpp v138, v64, v66, vcc row_shl:4 row_mask:0xf bank_mask:0xf bound_ctrl:1
	v_cndmask_b32_dpp v139, v65, v67, vcc row_shl:4 row_mask:0xf bank_mask:0xf bound_ctrl:1
	s_mov_b64 vcc, s[6:7]
	v_cndmask_b32_dpp v136, v66, v64, vcc row_shr:4 row_mask:0xf bank_mask:0xf bound_ctrl:1
	v_cndmask_b32_dpp v137, v67, v65, vcc row_shr:4 row_mask:0xf bank_mask:0xf bound_ctrl:1
	v_and_b32_e32 v204, v162, v235
	v_and_b32_e32 v205, v162, v236
	v_and_b32_e32 v206, v162, v237
	v_and_b32_e32 v207, v162, v238
	v_and_b32_e32 v208, v163, v235
	v_and_b32_e32 v209, v163, v236
	v_and_b32_e32 v210, v163, v237
	v_and_b32_e32 v211, v163, v238
	s_mov_b64 vcc, s[6:7]
	v_cndmask_b32_dpp v140, v70, v68, vcc row_shr:4 row_mask:0xf bank_mask:0xf bound_ctrl:1
	v_cndmask_b32_dpp v141, v71, v69, vcc row_shr:4 row_mask:0xf bank_mask:0xf bound_ctrl:1
	s_mov_b64 vcc, s[4:5]
	v_cndmask_b32_dpp v142, v68, v70, vcc row_shl:4 row_mask:0xf bank_mask:0xf bound_ctrl:1
	v_cndmask_b32_dpp v143, v69, v71, vcc row_shl:4 row_mask:0xf bank_mask:0xf bound_ctrl:1
	v_mfma_scale_f32_16x16x128_f8f6f4 v[216:219], v[136:139], v[144:151], 0, v240, v241 op_sel_hi:[0,0,0] cbsz:4
	v_and_b32_e32 v144, v164, v235
	v_and_b32_e32 v145, v164, v236
	v_and_b32_e32 v146, v164, v237
	v_and_b32_e32 v147, v164, v238
	v_and_b32_e32 v148, v165, v235
	v_and_b32_e32 v149, v165, v236
	v_and_b32_e32 v150, v165, v237
	v_and_b32_e32 v151, v165, v238
	s_mov_b64 vcc, s[4:5]
	v_cndmask_b32_dpp v138, v72, v74, vcc row_shl:4 row_mask:0xf bank_mask:0xf bound_ctrl:1
	v_cndmask_b32_dpp v139, v73, v75, vcc row_shl:4 row_mask:0xf bank_mask:0xf bound_ctrl:1
	s_mov_b64 vcc, s[6:7]
	v_cndmask_b32_dpp v136, v74, v72, vcc row_shr:4 row_mask:0xf bank_mask:0xf bound_ctrl:1
	v_cndmask_b32_dpp v137, v75, v73, vcc row_shr:4 row_mask:0xf bank_mask:0xf bound_ctrl:1
	v_mfma_scale_f32_16x16x128_f8f6f4 v[216:219], v[140:143], v[204:211], v[216:219], v240, v241 op_sel_hi:[0,0,0] cbsz:4
	v_and_b32_e32 v204, v166, v235
	v_and_b32_e32 v205, v166, v236
	v_and_b32_e32 v206, v166, v237
	v_and_b32_e32 v207, v166, v238
	v_and_b32_e32 v208, v167, v235
	v_and_b32_e32 v209, v167, v236
	v_and_b32_e32 v210, v167, v237
	v_and_b32_e32 v211, v167, v238
	s_mov_b64 vcc, s[6:7]
	v_cndmask_b32_dpp v140, v78, v76, vcc row_shr:4 row_mask:0xf bank_mask:0xf bound_ctrl:1
	v_cndmask_b32_dpp v141, v79, v77, vcc row_shr:4 row_mask:0xf bank_mask:0xf bound_ctrl:1
	s_mov_b64 vcc, s[4:5]
	v_cndmask_b32_dpp v142, v76, v78, vcc row_shl:4 row_mask:0xf bank_mask:0xf bound_ctrl:1
	v_cndmask_b32_dpp v143, v77, v79, vcc row_shl:4 row_mask:0xf bank_mask:0xf bound_ctrl:1
	v_mfma_scale_f32_16x16x128_f8f6f4 v[216:219], v[136:139], v[144:151], v[216:219], v240, v241 op_sel_hi:[0,0,0] cbsz:4
	v_and_b32_e32 v144, v168, v235
	v_and_b32_e32 v145, v168, v236
	v_and_b32_e32 v146, v168, v237
	v_and_b32_e32 v147, v168, v238
	v_and_b32_e32 v148, v169, v235
	v_and_b32_e32 v149, v169, v236
	v_and_b32_e32 v150, v169, v237
	v_and_b32_e32 v151, v169, v238
	s_mov_b64 vcc, s[4:5]
	v_cndmask_b32_dpp v138, v80, v82, vcc row_shl:4 row_mask:0xf bank_mask:0xf bound_ctrl:1
	v_cndmask_b32_dpp v139, v81, v83, vcc row_shl:4 row_mask:0xf bank_mask:0xf bound_ctrl:1
	s_mov_b64 vcc, s[6:7]
	v_cndmask_b32_dpp v136, v82, v80, vcc row_shr:4 row_mask:0xf bank_mask:0xf bound_ctrl:1
	v_cndmask_b32_dpp v137, v83, v81, vcc row_shr:4 row_mask:0xf bank_mask:0xf bound_ctrl:1
	v_mfma_scale_f32_16x16x128_f8f6f4 v[216:219], v[140:143], v[204:211], v[216:219], v240, v241 op_sel_hi:[0,0,0] cbsz:4
	v_and_b32_e32 v204, v170, v235
	v_and_b32_e32 v205, v170, v236
	v_and_b32_e32 v206, v170, v237
	v_and_b32_e32 v207, v170, v238
	v_and_b32_e32 v208, v171, v235
	v_and_b32_e32 v209, v171, v236
	v_and_b32_e32 v210, v171, v237
	v_and_b32_e32 v211, v171, v238
	s_mov_b64 vcc, s[6:7]
	v_cndmask_b32_dpp v140, v86, v84, vcc row_shr:4 row_mask:0xf bank_mask:0xf bound_ctrl:1
	v_cndmask_b32_dpp v141, v87, v85, vcc row_shr:4 row_mask:0xf bank_mask:0xf bound_ctrl:1
	s_mov_b64 vcc, s[4:5]
	v_cndmask_b32_dpp v142, v84, v86, vcc row_shl:4 row_mask:0xf bank_mask:0xf bound_ctrl:1
	v_cndmask_b32_dpp v143, v85, v87, vcc row_shl:4 row_mask:0xf bank_mask:0xf bound_ctrl:1
	v_mfma_scale_f32_16x16x128_f8f6f4 v[216:219], v[136:139], v[144:151], v[216:219], v240, v241 op_sel_hi:[0,0,0] cbsz:4
	v_and_b32_e32 v144, v172, v235
	v_and_b32_e32 v145, v172, v236
	v_and_b32_e32 v146, v172, v237
	v_and_b32_e32 v147, v172, v238
	v_and_b32_e32 v148, v173, v235
	v_and_b32_e32 v149, v173, v236
	v_and_b32_e32 v150, v173, v237
	v_and_b32_e32 v151, v173, v238
	s_mov_b64 vcc, s[4:5]
	v_cndmask_b32_dpp v138, v88, v90, vcc row_shl:4 row_mask:0xf bank_mask:0xf bound_ctrl:1
	v_cndmask_b32_dpp v139, v89, v91, vcc row_shl:4 row_mask:0xf bank_mask:0xf bound_ctrl:1
	s_mov_b64 vcc, s[6:7]
	v_cndmask_b32_dpp v136, v90, v88, vcc row_shr:4 row_mask:0xf bank_mask:0xf bound_ctrl:1
	v_cndmask_b32_dpp v137, v91, v89, vcc row_shr:4 row_mask:0xf bank_mask:0xf bound_ctrl:1
	v_mfma_scale_f32_16x16x128_f8f6f4 v[216:219], v[140:143], v[204:211], v[216:219], v240, v241 op_sel_hi:[0,0,0] cbsz:4
	v_and_b32_e32 v204, v174, v235
	v_and_b32_e32 v205, v174, v236
	v_and_b32_e32 v206, v174, v237
	v_and_b32_e32 v207, v174, v238
	v_and_b32_e32 v208, v175, v235
	v_and_b32_e32 v209, v175, v236
	v_and_b32_e32 v210, v175, v237
	v_and_b32_e32 v211, v175, v238
	s_mov_b64 vcc, s[6:7]
	v_cndmask_b32_dpp v140, v94, v92, vcc row_shr:4 row_mask:0xf bank_mask:0xf bound_ctrl:1
	v_cndmask_b32_dpp v141, v95, v93, vcc row_shr:4 row_mask:0xf bank_mask:0xf bound_ctrl:1
	s_mov_b64 vcc, s[4:5]
	v_cndmask_b32_dpp v142, v92, v94, vcc row_shl:4 row_mask:0xf bank_mask:0xf bound_ctrl:1
	v_cndmask_b32_dpp v143, v93, v95, vcc row_shl:4 row_mask:0xf bank_mask:0xf bound_ctrl:1
	v_mfma_scale_f32_16x16x128_f8f6f4 v[216:219], v[136:139], v[144:151], v[216:219], v240, v241 op_sel_hi:[0,0,0] cbsz:4
	s_nop 0
	v_mfma_scale_f32_16x16x128_f8f6f4 v[216:219], v[140:143], v[204:211], v[216:219], v240, v241 op_sel_hi:[0,0,0] cbsz:4
	s_waitcnt lgkmcnt(0)
	v_lshl_or_b32 v128, v128, 7, v232
	v_lshl_or_b32 v129, v129, 7, v232
	v_lshl_or_b32 v130, v130, 7, v232
	v_lshl_or_b32 v131, v131, 7, v232
	v_lshl_or_b32 v132, v132, 7, v232
	v_lshl_or_b32 v133, v133, 7, v232
	v_lshl_or_b32 v134, v134, 7, v232
	v_lshl_or_b32 v135, v135, 7, v232
	buffer_load_dwordx4 v[64:67], v128, s[20:23], s1 offen
	buffer_load_dwordx4 v[68:71], v129, s[20:23], s1 offen
	buffer_load_dwordx4 v[72:75], v130, s[20:23], s1 offen
	buffer_load_dwordx4 v[76:79], v131, s[20:23], s1 offen
	buffer_load_dwordx4 v[80:83], v132, s[20:23], s1 offen
	buffer_load_dwordx4 v[84:87], v133, s[20:23], s1 offen
	buffer_load_dwordx4 v[88:91], v134, s[20:23], s1 offen
	buffer_load_dwordx4 v[92:95], v135, s[20:23], s1 offen
	ds_read_b32 v128, v243 offset:3840
	ds_read_b32 v129, v243 offset:3872
	ds_read_b32 v130, v243 offset:3904
	ds_read_b32 v131, v243 offset:3936
	ds_read_b32 v132, v243 offset:3968
	ds_read_b32 v133, v243 offset:4000
	ds_read_b32 v134, v243 offset:4032
	ds_read_b32 v135, v243 offset:4064
	ds_read_b64 v[160:161], v234 offset:3072
	ds_read_b64 v[162:163], v234 offset:3104
	ds_read_b64 v[164:165], v234 offset:3136
	ds_read_b64 v[166:167], v234 offset:3168
	ds_read_b64 v[168:169], v234 offset:3200
	ds_read_b64 v[170:171], v234 offset:3232
	ds_read_b64 v[172:173], v234 offset:3264
	ds_read_b64 v[174:175], v234 offset:3296
	s_waitcnt vmcnt(26)
	v_and_b32_e32 v144, v176, v235
	v_and_b32_e32 v145, v176, v236
	v_and_b32_e32 v146, v176, v237
	v_and_b32_e32 v147, v176, v238
	v_and_b32_e32 v148, v177, v235
	v_and_b32_e32 v149, v177, v236
	v_and_b32_e32 v150, v177, v237
	v_and_b32_e32 v151, v177, v238
	s_mov_b64 vcc, s[4:5]
	v_cndmask_b32_dpp v138, v96, v98, vcc row_shl:4 row_mask:0xf bank_mask:0xf bound_ctrl:1
	v_cndmask_b32_dpp v139, v97, v99, vcc row_shl:4 row_mask:0xf bank_mask:0xf bound_ctrl:1
	s_mov_b64 vcc, s[6:7]
	v_cndmask_b32_dpp v136, v98, v96, vcc row_shr:4 row_mask:0xf bank_mask:0xf bound_ctrl:1
	v_cndmask_b32_dpp v137, v99, v97, vcc row_shr:4 row_mask:0xf bank_mask:0xf bound_ctrl:1
	v_and_b32_e32 v204, v178, v235
	v_and_b32_e32 v205, v178, v236
	v_and_b32_e32 v206, v178, v237
	v_and_b32_e32 v207, v178, v238
	v_and_b32_e32 v208, v179, v235
	v_and_b32_e32 v209, v179, v236
	v_and_b32_e32 v210, v179, v237
	v_and_b32_e32 v211, v179, v238
	s_mov_b64 vcc, s[6:7]
	v_cndmask_b32_dpp v140, v102, v100, vcc row_shr:4 row_mask:0xf bank_mask:0xf bound_ctrl:1
	v_cndmask_b32_dpp v141, v103, v101, vcc row_shr:4 row_mask:0xf bank_mask:0xf bound_ctrl:1
	s_mov_b64 vcc, s[4:5]
	v_cndmask_b32_dpp v142, v100, v102, vcc row_shl:4 row_mask:0xf bank_mask:0xf bound_ctrl:1
	v_cndmask_b32_dpp v143, v101, v103, vcc row_shl:4 row_mask:0xf bank_mask:0xf bound_ctrl:1
	v_mfma_scale_f32_16x16x128_f8f6f4 v[216:219], v[136:139], v[144:151], v[216:219], v240, v241 op_sel_hi:[0,0,0] cbsz:4
	v_permlane16_swap_b32_e32 v212, v214
	v_permlane16_swap_b32_e32 v213, v215
	v_lshlrev_b32_e32 v252, 16, v228
	v_and_b32_e32 v144, v180, v235
	v_and_b32_e32 v145, v180, v236
	v_and_b32_e32 v146, v180, v237
	v_and_b32_e32 v147, v180, v238
	v_and_b32_e32 v148, v181, v235
	v_and_b32_e32 v149, v181, v236
	v_and_b32_e32 v150, v181, v237
	v_and_b32_e32 v151, v181, v238
	s_mov_b64 vcc, s[4:5]
	v_cndmask_b32_dpp v138, v104, v106, vcc row_shl:4 row_mask:0xf bank_mask:0xf bound_ctrl:1
	v_cndmask_b32_dpp v139, v105, v107, vcc row_shl:4 row_mask:0xf bank_mask:0xf bound_ctrl:1
	s_mov_b64 vcc, s[6:7]
	v_cndmask_b32_dpp v136, v106, v104, vcc row_shr:4 row_mask:0xf bank_mask:0xf bound_ctrl:1
	v_cndmask_b32_dpp v137, v107, v105, vcc row_shr:4 row_mask:0xf bank_mask:0xf bound_ctrl:1
	v_mfma_scale_f32_16x16x128_f8f6f4 v[216:219], v[140:143], v[204:211], v[216:219], v240, v241 op_sel_hi:[0,0,0] cbsz:4
	v_and_b32_e32 v253, 0xffff0000, v228
	v_lshlrev_b32_e32 v254, 16, v229
	v_and_b32_e32 v255, 0xffff0000, v229
	v_and_b32_e32 v204, v182, v235
	v_and_b32_e32 v205, v182, v236
	v_and_b32_e32 v206, v182, v237
	v_and_b32_e32 v207, v182, v238
	v_and_b32_e32 v208, v183, v235
	v_and_b32_e32 v209, v183, v236
	v_and_b32_e32 v210, v183, v237
	v_and_b32_e32 v211, v183, v238
	s_mov_b64 vcc, s[6:7]
	v_cndmask_b32_dpp v140, v110, v108, vcc row_shr:4 row_mask:0xf bank_mask:0xf bound_ctrl:1
	v_cndmask_b32_dpp v141, v111, v109, vcc row_shr:4 row_mask:0xf bank_mask:0xf bound_ctrl:1
	s_mov_b64 vcc, s[4:5]
	v_cndmask_b32_dpp v142, v108, v110, vcc row_shl:4 row_mask:0xf bank_mask:0xf bound_ctrl:1
	v_cndmask_b32_dpp v143, v109, v111, vcc row_shl:4 row_mask:0xf bank_mask:0xf bound_ctrl:1
	v_mfma_scale_f32_16x16x128_f8f6f4 v[216:219], v[136:139], v[144:151], v[216:219], v240, v241 op_sel_hi:[0,0,0] cbsz:4
	v_add_f32_e32 v252, v212, v252
	v_add_f32_e32 v253, v214, v253
	v_add_f32_e32 v254, v213, v254
	v_and_b32_e32 v144, v184, v235
	v_and_b32_e32 v145, v184, v236
	v_and_b32_e32 v146, v184, v237
	v_and_b32_e32 v147, v184, v238
	v_and_b32_e32 v148, v185, v235
	v_and_b32_e32 v149, v185, v236
	v_and_b32_e32 v150, v185, v237
	v_and_b32_e32 v151, v185, v238
	s_mov_b64 vcc, s[4:5]
	v_cndmask_b32_dpp v138, v112, v114, vcc row_shl:4 row_mask:0xf bank_mask:0xf bound_ctrl:1
	v_cndmask_b32_dpp v139, v113, v115, vcc row_shl:4 row_mask:0xf bank_mask:0xf bound_ctrl:1
	s_mov_b64 vcc, s[6:7]
	v_cndmask_b32_dpp v136, v114, v112, vcc row_shr:4 row_mask:0xf bank_mask:0xf bound_ctrl:1
	v_cndmask_b32_dpp v137, v115, v113, vcc row_shr:4 row_mask:0xf bank_mask:0xf bound_ctrl:1
	v_mfma_scale_f32_16x16x128_f8f6f4 v[216:219], v[140:143], v[204:211], v[216:219], v240, v241 op_sel_hi:[0,0,0] cbsz:4
	v_add_f32_e32 v255, v215, v255
	v_mul_f32_e32 v192, v252, v252
	v_mul_f32_e32 v193, v254, v254
	v_and_b32_e32 v204, v186, v235
	v_and_b32_e32 v205, v186, v236
	v_and_b32_e32 v206, v186, v237
	v_and_b32_e32 v207, v186, v238
	v_and_b32_e32 v208, v187, v235
	v_and_b32_e32 v209, v187, v236
	v_and_b32_e32 v210, v187, v237
	v_and_b32_e32 v211, v187, v238
	s_mov_b64 vcc, s[6:7]
	v_cndmask_b32_dpp v140, v118, v116, vcc row_shr:4 row_mask:0xf bank_mask:0xf bound_ctrl:1
	v_cndmask_b32_dpp v141, v119, v117, vcc row_shr:4 row_mask:0xf bank_mask:0xf bound_ctrl:1
	s_mov_b64 vcc, s[4:5]
	v_cndmask_b32_dpp v142, v116, v118, vcc row_shl:4 row_mask:0xf bank_mask:0xf bound_ctrl:1
	v_cndmask_b32_dpp v143, v117, v119, vcc row_shl:4 row_mask:0xf bank_mask:0xf bound_ctrl:1
	v_mfma_scale_f32_16x16x128_f8f6f4 v[216:219], v[136:139], v[144:151], v[216:219], v240, v241 op_sel_hi:[0,0,0] cbsz:4
	v_fmac_f32_e32 v192, v253, v253
	v_fmac_f32_e32 v193, v255, v255
	v_cvt_pk_bf16_f32 v250, v252, v253
	v_and_b32_e32 v144, v188, v235
	v_and_b32_e32 v145, v188, v236
	v_and_b32_e32 v146, v188, v237
	v_and_b32_e32 v147, v188, v238
	v_and_b32_e32 v148, v189, v235
	v_and_b32_e32 v149, v189, v236
	v_and_b32_e32 v150, v189, v237
	v_and_b32_e32 v151, v189, v238
	s_mov_b64 vcc, s[4:5]
	v_cndmask_b32_dpp v138, v120, v122, vcc row_shl:4 row_mask:0xf bank_mask:0xf bound_ctrl:1
	v_cndmask_b32_dpp v139, v121, v123, vcc row_shl:4 row_mask:0xf bank_mask:0xf bound_ctrl:1
	s_mov_b64 vcc, s[6:7]
	v_cndmask_b32_dpp v136, v122, v120, vcc row_shr:4 row_mask:0xf bank_mask:0xf bound_ctrl:1
	v_cndmask_b32_dpp v137, v123, v121, vcc row_shr:4 row_mask:0xf bank_mask:0xf bound_ctrl:1
	v_mfma_scale_f32_16x16x128_f8f6f4 v[216:219], v[140:143], v[204:211], v[216:219], v240, v241 op_sel_hi:[0,0,0] cbsz:4
	v_cvt_pk_bf16_f32 v251, v254, v255
	v_add_f32_e32 v192, v192, v193
	v_add_f32_e32 v224, v224, v192
	v_and_b32_e32 v204, v190, v235
	v_and_b32_e32 v205, v190, v236
	v_and_b32_e32 v206, v190, v237
	v_and_b32_e32 v207, v190, v238
	v_and_b32_e32 v208, v191, v235
	v_and_b32_e32 v209, v191, v236
	v_and_b32_e32 v210, v191, v237
	v_and_b32_e32 v211, v191, v238
	s_mov_b64 vcc, s[6:7]
	v_cndmask_b32_dpp v140, v126, v124, vcc row_shr:4 row_mask:0xf bank_mask:0xf bound_ctrl:1
	v_cndmask_b32_dpp v141, v127, v125, vcc row_shr:4 row_mask:0xf bank_mask:0xf bound_ctrl:1
	s_mov_b64 vcc, s[4:5]
	v_cndmask_b32_dpp v142, v124, v126, vcc row_shl:4 row_mask:0xf bank_mask:0xf bound_ctrl:1
	v_cndmask_b32_dpp v143, v125, v127, vcc row_shl:4 row_mask:0xf bank_mask:0xf bound_ctrl:1
	v_mfma_scale_f32_16x16x128_f8f6f4 v[216:219], v[136:139], v[144:151], v[216:219], v240, v241 op_sel_hi:[0,0,0] cbsz:4
	s_nop 0
	v_mfma_scale_f32_16x16x128_f8f6f4 v[216:219], v[140:143], v[204:211], v[216:219], v240, v241 op_sel_hi:[0,0,0] cbsz:4
	s_lshl_b32 s64, s0, 9
	s_add_u32 s64, s64, 0x4000
	s_add_u32 s76, s28, s64
	s_addc_u32 s77, s29, 0
	global_store_dwordx2 v239, v[250:251], s[76:77]
	s_lshl_b32 s64, s0, 9
	s_add_u32 s64, s64, 0x6000
	s_add_u32 s70, s28, s64
	s_addc_u32 s71, s29, 0
	global_load_dwordx2 v[228:229], v239, s[70:71] nt
	s_waitcnt lgkmcnt(0)
	v_lshl_or_b32 v128, v128, 7, v232
	v_lshl_or_b32 v129, v129, 7, v232
	v_lshl_or_b32 v130, v130, 7, v232
	v_lshl_or_b32 v131, v131, 7, v232
	v_lshl_or_b32 v132, v132, 7, v232
	v_lshl_or_b32 v133, v133, 7, v232
	v_lshl_or_b32 v134, v134, 7, v232
	v_lshl_or_b32 v135, v135, 7, v232
	buffer_load_dwordx4 v[96:99], v128, s[20:23], s1 offen
	buffer_load_dwordx4 v[100:103], v129, s[20:23], s1 offen
	buffer_load_dwordx4 v[104:107], v130, s[20:23], s1 offen
	buffer_load_dwordx4 v[108:111], v131, s[20:23], s1 offen
	buffer_load_dwordx4 v[112:115], v132, s[20:23], s1 offen
	buffer_load_dwordx4 v[116:119], v133, s[20:23], s1 offen
	buffer_load_dwordx4 v[120:123], v134, s[20:23], s1 offen
	buffer_load_dwordx4 v[124:127], v135, s[20:23], s1 offen
	ds_read_b32 v128, v243 offset:0
	ds_read_b32 v129, v243 offset:32
	ds_read_b32 v130, v243 offset:64
	ds_read_b32 v131, v243 offset:96
	ds_read_b32 v132, v243 offset:128
	ds_read_b32 v133, v243 offset:160
	ds_read_b32 v134, v243 offset:192
	ds_read_b32 v135, v243 offset:224
	ds_read_b64 v[176:177], v234 offset:3328
	ds_read_b64 v[178:179], v234 offset:3360
	ds_read_b64 v[180:181], v234 offset:3392
	ds_read_b64 v[182:183], v234 offset:3424
	ds_read_b64 v[184:185], v234 offset:3456
	ds_read_b64 v[186:187], v234 offset:3488
	ds_read_b64 v[188:189], v234 offset:3520
	ds_read_b64 v[190:191], v234 offset:3552
	s_waitcnt vmcnt(28)
	v_and_b32_e32 v144, v160, v235
	v_and_b32_e32 v145, v160, v236
	v_and_b32_e32 v146, v160, v237
	v_and_b32_e32 v147, v160, v238
	v_and_b32_e32 v148, v161, v235
	v_and_b32_e32 v149, v161, v236
	v_and_b32_e32 v150, v161, v237
	v_and_b32_e32 v151, v161, v238
	s_mov_b64 vcc, s[4:5]
	v_cndmask_b32_dpp v138, v0, v2, vcc row_shl:4 row_mask:0xf bank_mask:0xf bound_ctrl:1
	v_cndmask_b32_dpp v139, v1, v3, vcc row_shl:4 row_mask:0xf bank_mask:0xf bound_ctrl:1
	s_mov_b64 vcc, s[6:7]
	v_cndmask_b32_dpp v136, v2, v0, vcc row_shr:4 row_mask:0xf bank_mask:0xf bound_ctrl:1
	v_cndmask_b32_dpp v137, v3, v1, vcc row_shr:4 row_mask:0xf bank_mask:0xf bound_ctrl:1
	v_and_b32_e32 v204, v162, v235
	v_and_b32_e32 v205, v162, v236
	v_and_b32_e32 v206, v162, v237
	v_and_b32_e32 v207, v162, v238
	v_and_b32_e32 v208, v163, v235
	v_and_b32_e32 v209, v163, v236
	v_and_b32_e32 v210, v163, v237
	v_and_b32_e32 v211, v163, v238
	s_mov_b64 vcc, s[6:7]
	v_cndmask_b32_dpp v140, v6, v4, vcc row_shr:4 row_mask:0xf bank_mask:0xf bound_ctrl:1
	v_cndmask_b32_dpp v141, v7, v5, vcc row_shr:4 row_mask:0xf bank_mask:0xf bound_ctrl:1
	s_mov_b64 vcc, s[4:5]
	v_cndmask_b32_dpp v142, v4, v6, vcc row_shl:4 row_mask:0xf bank_mask:0xf bound_ctrl:1
	v_cndmask_b32_dpp v143, v5, v7, vcc row_shl:4 row_mask:0xf bank_mask:0xf bound_ctrl:1
	v_mfma_scale_f32_16x16x128_f8f6f4 v[212:215], v[136:139], v[144:151], 0, v240, v241 op_sel_hi:[0,0,0] cbsz:4
	v_and_b32_e32 v144, v164, v235
	v_and_b32_e32 v145, v164, v236
	v_and_b32_e32 v146, v164, v237
	v_and_b32_e32 v147, v164, v238
	v_and_b32_e32 v148, v165, v235
	v_and_b32_e32 v149, v165, v236
	v_and_b32_e32 v150, v165, v237
	v_and_b32_e32 v151, v165, v238
	s_mov_b64 vcc, s[4:5]
	v_cndmask_b32_dpp v138, v8, v10, vcc row_shl:4 row_mask:0xf bank_mask:0xf bound_ctrl:1
	v_cndmask_b32_dpp v139, v9, v11, vcc row_shl:4 row_mask:0xf bank_mask:0xf bound_ctrl:1
	s_mov_b64 vcc, s[6:7]
	v_cndmask_b32_dpp v136, v10, v8, vcc row_shr:4 row_mask:0xf bank_mask:0xf bound_ctrl:1
	v_cndmask_b32_dpp v137, v11, v9, vcc row_shr:4 row_mask:0xf bank_mask:0xf bound_ctrl:1
	v_mfma_scale_f32_16x16x128_f8f6f4 v[212:215], v[140:143], v[204:211], v[212:215], v240, v241 op_sel_hi:[0,0,0] cbsz:4
	v_and_b32_e32 v204, v166, v235
	v_and_b32_e32 v205, v166, v236
	v_and_b32_e32 v206, v166, v237
	v_and_b32_e32 v207, v166, v238
	v_and_b32_e32 v208, v167, v235
	v_and_b32_e32 v209, v167, v236
	v_and_b32_e32 v210, v167, v237
	v_and_b32_e32 v211, v167, v238
	s_mov_b64 vcc, s[6:7]
	v_cndmask_b32_dpp v140, v14, v12, vcc row_shr:4 row_mask:0xf bank_mask:0xf bound_ctrl:1
	v_cndmask_b32_dpp v141, v15, v13, vcc row_shr:4 row_mask:0xf bank_mask:0xf bound_ctrl:1
	s_mov_b64 vcc, s[4:5]
	v_cndmask_b32_dpp v142, v12, v14, vcc row_shl:4 row_mask:0xf bank_mask:0xf bound_ctrl:1
	v_cndmask_b32_dpp v143, v13, v15, vcc row_shl:4 row_mask:0xf bank_mask:0xf bound_ctrl:1
	v_mfma_scale_f32_16x16x128_f8f6f4 v[212:215], v[136:139], v[144:151], v[212:215], v240, v241 op_sel_hi:[0,0,0] cbsz:4
	v_and_b32_e32 v144, v168, v235
	v_and_b32_e32 v145, v168, v236
	v_and_b32_e32 v146, v168, v237
	v_and_b32_e32 v147, v168, v238
	v_and_b32_e32 v148, v169, v235
	v_and_b32_e32 v149, v169, v236
	v_and_b32_e32 v150, v169, v237
	v_and_b32_e32 v151, v169, v238
	s_mov_b64 vcc, s[4:5]
	v_cndmask_b32_dpp v138, v16, v18, vcc row_shl:4 row_mask:0xf bank_mask:0xf bound_ctrl:1
	v_cndmask_b32_dpp v139, v17, v19, vcc row_shl:4 row_mask:0xf bank_mask:0xf bound_ctrl:1
	s_mov_b64 vcc, s[6:7]
	v_cndmask_b32_dpp v136, v18, v16, vcc row_shr:4 row_mask:0xf bank_mask:0xf bound_ctrl:1
	v_cndmask_b32_dpp v137, v19, v17, vcc row_shr:4 row_mask:0xf bank_mask:0xf bound_ctrl:1
	v_mfma_scale_f32_16x16x128_f8f6f4 v[212:215], v[140:143], v[204:211], v[212:215], v240, v241 op_sel_hi:[0,0,0] cbsz:4
	v_and_b32_e32 v204, v170, v235
	v_and_b32_e32 v205, v170, v236
	v_and_b32_e32 v206, v170, v237
	v_and_b32_e32 v207, v170, v238
	v_and_b32_e32 v208, v171, v235
	v_and_b32_e32 v209, v171, v236
	v_and_b32_e32 v210, v171, v237
	v_and_b32_e32 v211, v171, v238
	s_mov_b64 vcc, s[6:7]
	v_cndmask_b32_dpp v140, v22, v20, vcc row_shr:4 row_mask:0xf bank_mask:0xf bound_ctrl:1
	v_cndmask_b32_dpp v141, v23, v21, vcc row_shr:4 row_mask:0xf bank_mask:0xf bound_ctrl:1
	s_mov_b64 vcc, s[4:5]
	v_cndmask_b32_dpp v142, v20, v22, vcc row_shl:4 row_mask:0xf bank_mask:0xf bound_ctrl:1
	v_cndmask_b32_dpp v143, v21, v23, vcc row_shl:4 row_mask:0xf bank_mask:0xf bound_ctrl:1
	v_mfma_scale_f32_16x16x128_f8f6f4 v[212:215], v[136:139], v[144:151], v[212:215], v240, v241 op_sel_hi:[0,0,0] cbsz:4
	v_and_b32_e32 v144, v172, v235
	v_and_b32_e32 v145, v172, v236
	v_and_b32_e32 v146, v172, v237
	v_and_b32_e32 v147, v172, v238
	v_and_b32_e32 v148, v173, v235
	v_and_b32_e32 v149, v173, v236
	v_and_b32_e32 v150, v173, v237
	v_and_b32_e32 v151, v173, v238
	s_mov_b64 vcc, s[4:5]
	v_cndmask_b32_dpp v138, v24, v26, vcc row_shl:4 row_mask:0xf bank_mask:0xf bound_ctrl:1
	v_cndmask_b32_dpp v139, v25, v27, vcc row_shl:4 row_mask:0xf bank_mask:0xf bound_ctrl:1
	s_mov_b64 vcc, s[6:7]
	v_cndmask_b32_dpp v136, v26, v24, vcc row_shr:4 row_mask:0xf bank_mask:0xf bound_ctrl:1
	v_cndmask_b32_dpp v137, v27, v25, vcc row_shr:4 row_mask:0xf bank_mask:0xf bound_ctrl:1
	v_mfma_scale_f32_16x16x128_f8f6f4 v[212:215], v[140:143], v[204:211], v[212:215], v240, v241 op_sel_hi:[0,0,0] cbsz:4
	v_and_b32_e32 v204, v174, v235
	v_and_b32_e32 v205, v174, v236
	v_and_b32_e32 v206, v174, v237
	v_and_b32_e32 v207, v174, v238
	v_and_b32_e32 v208, v175, v235
	v_and_b32_e32 v209, v175, v236
	v_and_b32_e32 v210, v175, v237
	v_and_b32_e32 v211, v175, v238
	s_mov_b64 vcc, s[6:7]
	v_cndmask_b32_dpp v140, v30, v28, vcc row_shr:4 row_mask:0xf bank_mask:0xf bound_ctrl:1
	v_cndmask_b32_dpp v141, v31, v29, vcc row_shr:4 row_mask:0xf bank_mask:0xf bound_ctrl:1
	s_mov_b64 vcc, s[4:5]
	v_cndmask_b32_dpp v142, v28, v30, vcc row_shl:4 row_mask:0xf bank_mask:0xf bound_ctrl:1
	v_cndmask_b32_dpp v143, v29, v31, vcc row_shl:4 row_mask:0xf bank_mask:0xf bound_ctrl:1
	v_mfma_scale_f32_16x16x128_f8f6f4 v[212:215], v[136:139], v[144:151], v[212:215], v240, v241 op_sel_hi:[0,0,0] cbsz:4
	s_nop 0
	v_mfma_scale_f32_16x16x128_f8f6f4 v[212:215], v[140:143], v[204:211], v[212:215], v240, v241 op_sel_hi:[0,0,0] cbsz:4
	s_waitcnt lgkmcnt(0)
	v_lshl_or_b32 v128, v128, 7, v232
	v_lshl_or_b32 v129, v129, 7, v232
	v_lshl_or_b32 v130, v130, 7, v232
	v_lshl_or_b32 v131, v131, 7, v232
	v_lshl_or_b32 v132, v132, 7, v232
	v_lshl_or_b32 v133, v133, 7, v232
	v_lshl_or_b32 v134, v134, 7, v232
	v_lshl_or_b32 v135, v135, 7, v232
	buffer_load_dwordx4 v[0:3], v128, s[20:23], s60 offen
	buffer_load_dwordx4 v[4:7], v129, s[20:23], s60 offen
	buffer_load_dwordx4 v[8:11], v130, s[20:23], s60 offen
	buffer_load_dwordx4 v[12:15], v131, s[20:23], s60 offen
	buffer_load_dwordx4 v[16:19], v132, s[20:23], s60 offen
	buffer_load_dwordx4 v[20:23], v133, s[20:23], s60 offen
	buffer_load_dwordx4 v[24:27], v134, s[20:23], s60 offen
	buffer_load_dwordx4 v[28:31], v135, s[20:23], s60 offen
	ds_read_b32 v128, v243 offset:256
	ds_read_b32 v129, v243 offset:288
	ds_read_b32 v130, v243 offset:320
	ds_read_b32 v131, v243 offset:352
	ds_read_b32 v132, v243 offset:384
	ds_read_b32 v133, v243 offset:416
	ds_read_b32 v134, v243 offset:448
	ds_read_b32 v135, v243 offset:480
	ds_read_b64 v[160:161], v234 offset:3584
	ds_read_b64 v[162:163], v234 offset:3616
	ds_read_b64 v[164:165], v234 offset:3648
	ds_read_b64 v[166:167], v234 offset:3680
	ds_read_b64 v[168:169], v234 offset:3712
	ds_read_b64 v[170:171], v234 offset:3744
	ds_read_b64 v[172:173], v234 offset:3776
	ds_read_b64 v[174:175], v234 offset:3808
	s_waitcnt vmcnt(26)
	v_and_b32_e32 v144, v176, v235
	v_and_b32_e32 v145, v176, v236
	v_and_b32_e32 v146, v176, v237
	v_and_b32_e32 v147, v176, v238
	v_and_b32_e32 v148, v177, v235
	v_and_b32_e32 v149, v177, v236
	v_and_b32_e32 v150, v177, v237
	v_and_b32_e32 v151, v177, v238
	s_mov_b64 vcc, s[4:5]
	v_cndmask_b32_dpp v138, v32, v34, vcc row_shl:4 row_mask:0xf bank_mask:0xf bound_ctrl:1
	v_cndmask_b32_dpp v139, v33, v35, vcc row_shl:4 row_mask:0xf bank_mask:0xf bound_ctrl:1
	s_mov_b64 vcc, s[6:7]
	v_cndmask_b32_dpp v136, v34, v32, vcc row_shr:4 row_mask:0xf bank_mask:0xf bound_ctrl:1
	v_cndmask_b32_dpp v137, v35, v33, vcc row_shr:4 row_mask:0xf bank_mask:0xf bound_ctrl:1
	v_and_b32_e32 v204, v178, v235
	v_and_b32_e32 v205, v178, v236
	v_and_b32_e32 v206, v178, v237
	v_and_b32_e32 v207, v178, v238
	v_and_b32_e32 v208, v179, v235
	v_and_b32_e32 v209, v179, v236
	v_and_b32_e32 v210, v179, v237
	v_and_b32_e32 v211, v179, v238
	s_mov_b64 vcc, s[6:7]
	v_cndmask_b32_dpp v140, v38, v36, vcc row_shr:4 row_mask:0xf bank_mask:0xf bound_ctrl:1
	v_cndmask_b32_dpp v141, v39, v37, vcc row_shr:4 row_mask:0xf bank_mask:0xf bound_ctrl:1
	s_mov_b64 vcc, s[4:5]
	v_cndmask_b32_dpp v142, v36, v38, vcc row_shl:4 row_mask:0xf bank_mask:0xf bound_ctrl:1
	v_cndmask_b32_dpp v143, v37, v39, vcc row_shl:4 row_mask:0xf bank_mask:0xf bound_ctrl:1
	v_mfma_scale_f32_16x16x128_f8f6f4 v[212:215], v[136:139], v[144:151], v[212:215], v240, v241 op_sel_hi:[0,0,0] cbsz:4
	v_permlane16_swap_b32_e32 v216, v218
	v_permlane16_swap_b32_e32 v217, v219
	v_lshlrev_b32_e32 v252, 16, v230
	v_and_b32_e32 v144, v180, v235
	v_and_b32_e32 v145, v180, v236
	v_and_b32_e32 v146, v180, v237
	v_and_b32_e32 v147, v180, v238
	v_and_b32_e32 v148, v181, v235
	v_and_b32_e32 v149, v181, v236
	v_and_b32_e32 v150, v181, v237
	v_and_b32_e32 v151, v181, v238
	s_mov_b64 vcc, s[4:5]
	v_cndmask_b32_dpp v138, v40, v42, vcc row_shl:4 row_mask:0xf bank_mask:0xf bound_ctrl:1
	v_cndmask_b32_dpp v139, v41, v43, vcc row_shl:4 row_mask:0xf bank_mask:0xf bound_ctrl:1
	s_mov_b64 vcc, s[6:7]
	v_cndmask_b32_dpp v136, v42, v40, vcc row_shr:4 row_mask:0xf bank_mask:0xf bound_ctrl:1
	v_cndmask_b32_dpp v137, v43, v41, vcc row_shr:4 row_mask:0xf bank_mask:0xf bound_ctrl:1
	v_mfma_scale_f32_16x16x128_f8f6f4 v[212:215], v[140:143], v[204:211], v[212:215], v240, v241 op_sel_hi:[0,0,0] cbsz:4
	v_and_b32_e32 v253, 0xffff0000, v230
	v_lshlrev_b32_e32 v254, 16, v231
	v_and_b32_e32 v255, 0xffff0000, v231
	v_and_b32_e32 v204, v182, v235
	v_and_b32_e32 v205, v182, v236
	v_and_b32_e32 v206, v182, v237
	v_and_b32_e32 v207, v182, v238
	v_and_b32_e32 v208, v183, v235
	v_and_b32_e32 v209, v183, v236
	v_and_b32_e32 v210, v183, v237
	v_and_b32_e32 v211, v183, v238
	s_mov_b64 vcc, s[6:7]
	v_cndmask_b32_dpp v140, v46, v44, vcc row_shr:4 row_mask:0xf bank_mask:0xf bound_ctrl:1
	v_cndmask_b32_dpp v141, v47, v45, vcc row_shr:4 row_mask:0xf bank_mask:0xf bound_ctrl:1
	s_mov_b64 vcc, s[4:5]
	v_cndmask_b32_dpp v142, v44, v46, vcc row_shl:4 row_mask:0xf bank_mask:0xf bound_ctrl:1
	v_cndmask_b32_dpp v143, v45, v47, vcc row_shl:4 row_mask:0xf bank_mask:0xf bound_ctrl:1
	v_mfma_scale_f32_16x16x128_f8f6f4 v[212:215], v[136:139], v[144:151], v[212:215], v240, v241 op_sel_hi:[0,0,0] cbsz:4
	v_add_f32_e32 v252, v216, v252
	v_add_f32_e32 v253, v218, v253
	v_add_f32_e32 v254, v217, v254
	v_and_b32_e32 v144, v184, v235
	v_and_b32_e32 v145, v184, v236
	v_and_b32_e32 v146, v184, v237
	v_and_b32_e32 v147, v184, v238
	v_and_b32_e32 v148, v185, v235
	v_and_b32_e32 v149, v185, v236
	v_and_b32_e32 v150, v185, v237
	v_and_b32_e32 v151, v185, v238
	s_mov_b64 vcc, s[4:5]
	v_cndmask_b32_dpp v138, v48, v50, vcc row_shl:4 row_mask:0xf bank_mask:0xf bound_ctrl:1
	v_cndmask_b32_dpp v139, v49, v51, vcc row_shl:4 row_mask:0xf bank_mask:0xf bound_ctrl:1
	s_mov_b64 vcc, s[6:7]
	v_cndmask_b32_dpp v136, v50, v48, vcc row_shr:4 row_mask:0xf bank_mask:0xf bound_ctrl:1
	v_cndmask_b32_dpp v137, v51, v49, vcc row_shr:4 row_mask:0xf bank_mask:0xf bound_ctrl:1
	v_mfma_scale_f32_16x16x128_f8f6f4 v[212:215], v[140:143], v[204:211], v[212:215], v240, v241 op_sel_hi:[0,0,0] cbsz:4
	v_add_f32_e32 v255, v219, v255
	v_mul_f32_e32 v192, v252, v252
	v_mul_f32_e32 v193, v254, v254
	v_and_b32_e32 v204, v186, v235
	v_and_b32_e32 v205, v186, v236
	v_and_b32_e32 v206, v186, v237
	v_and_b32_e32 v207, v186, v238
	v_and_b32_e32 v208, v187, v235
	v_and_b32_e32 v209, v187, v236
	v_and_b32_e32 v210, v187, v237
	v_and_b32_e32 v211, v187, v238
	s_mov_b64 vcc, s[6:7]
	v_cndmask_b32_dpp v140, v54, v52, vcc row_shr:4 row_mask:0xf bank_mask:0xf bound_ctrl:1
	v_cndmask_b32_dpp v141, v55, v53, vcc row_shr:4 row_mask:0xf bank_mask:0xf bound_ctrl:1
	s_mov_b64 vcc, s[4:5]
	v_cndmask_b32_dpp v142, v52, v54, vcc row_shl:4 row_mask:0xf bank_mask:0xf bound_ctrl:1
	v_cndmask_b32_dpp v143, v53, v55, vcc row_shl:4 row_mask:0xf bank_mask:0xf bound_ctrl:1
	v_mfma_scale_f32_16x16x128_f8f6f4 v[212:215], v[136:139], v[144:151], v[212:215], v240, v241 op_sel_hi:[0,0,0] cbsz:4
	v_fmac_f32_e32 v192, v253, v253
	v_fmac_f32_e32 v193, v255, v255
	v_cvt_pk_bf16_f32 v250, v252, v253
	v_and_b32_e32 v144, v188, v235
	v_and_b32_e32 v145, v188, v236
	v_and_b32_e32 v146, v188, v237
	v_and_b32_e32 v147, v188, v238
	v_and_b32_e32 v148, v189, v235
	v_and_b32_e32 v149, v189, v236
	v_and_b32_e32 v150, v189, v237
	v_and_b32_e32 v151, v189, v238
	s_mov_b64 vcc, s[4:5]
	v_cndmask_b32_dpp v138, v56, v58, vcc row_shl:4 row_mask:0xf bank_mask:0xf bound_ctrl:1
	v_cndmask_b32_dpp v139, v57, v59, vcc row_shl:4 row_mask:0xf bank_mask:0xf bound_ctrl:1
	s_mov_b64 vcc, s[6:7]
	v_cndmask_b32_dpp v136, v58, v56, vcc row_shr:4 row_mask:0xf bank_mask:0xf bound_ctrl:1
	v_cndmask_b32_dpp v137, v59, v57, vcc row_shr:4 row_mask:0xf bank_mask:0xf bound_ctrl:1
	v_mfma_scale_f32_16x16x128_f8f6f4 v[212:215], v[140:143], v[204:211], v[212:215], v240, v241 op_sel_hi:[0,0,0] cbsz:4
	v_cvt_pk_bf16_f32 v251, v254, v255
	v_add_f32_e32 v192, v192, v193
	v_add_f32_e32 v225, v225, v192
	v_and_b32_e32 v204, v190, v235
	v_and_b32_e32 v205, v190, v236
	v_and_b32_e32 v206, v190, v237
	v_and_b32_e32 v207, v190, v238
	v_and_b32_e32 v208, v191, v235
	v_and_b32_e32 v209, v191, v236
	v_and_b32_e32 v210, v191, v237
	v_and_b32_e32 v211, v191, v238
	s_mov_b64 vcc, s[6:7]
	v_cndmask_b32_dpp v140, v62, v60, vcc row_shr:4 row_mask:0xf bank_mask:0xf bound_ctrl:1
	v_cndmask_b32_dpp v141, v63, v61, vcc row_shr:4 row_mask:0xf bank_mask:0xf bound_ctrl:1
	s_mov_b64 vcc, s[4:5]
	v_cndmask_b32_dpp v142, v60, v62, vcc row_shl:4 row_mask:0xf bank_mask:0xf bound_ctrl:1
	v_cndmask_b32_dpp v143, v61, v63, vcc row_shl:4 row_mask:0xf bank_mask:0xf bound_ctrl:1
	v_mfma_scale_f32_16x16x128_f8f6f4 v[212:215], v[136:139], v[144:151], v[212:215], v240, v241 op_sel_hi:[0,0,0] cbsz:4
	s_nop 0
	v_mfma_scale_f32_16x16x128_f8f6f4 v[212:215], v[140:143], v[204:211], v[212:215], v240, v241 op_sel_hi:[0,0,0] cbsz:4
	s_lshl_b32 s64, s0, 9
	s_add_u32 s64, s64, 0x5000
	s_add_u32 s76, s28, s64
	s_addc_u32 s77, s29, 0
	global_store_dwordx2 v239, v[250:251], s[76:77]
	s_lshl_b32 s64, s0, 9
	s_add_u32 s64, s64, 0x7000
	s_add_u32 s70, s28, s64
	s_addc_u32 s71, s29, 0
	global_load_dwordx2 v[230:231], v239, s[70:71] nt
	s_waitcnt lgkmcnt(0)
	v_lshl_or_b32 v128, v128, 7, v232
	v_lshl_or_b32 v129, v129, 7, v232
	v_lshl_or_b32 v130, v130, 7, v232
	v_lshl_or_b32 v131, v131, 7, v232
	v_lshl_or_b32 v132, v132, 7, v232
	v_lshl_or_b32 v133, v133, 7, v232
	v_lshl_or_b32 v134, v134, 7, v232
	v_lshl_or_b32 v135, v135, 7, v232
	buffer_load_dwordx4 v[32:35], v128, s[20:23], s60 offen
	buffer_load_dwordx4 v[36:39], v129, s[20:23], s60 offen
	buffer_load_dwordx4 v[40:43], v130, s[20:23], s60 offen
	buffer_load_dwordx4 v[44:47], v131, s[20:23], s60 offen
	buffer_load_dwordx4 v[48:51], v132, s[20:23], s60 offen
	buffer_load_dwordx4 v[52:55], v133, s[20:23], s60 offen
	buffer_load_dwordx4 v[56:59], v134, s[20:23], s60 offen
	buffer_load_dwordx4 v[60:63], v135, s[20:23], s60 offen
	ds_read_b32 v128, v243 offset:512
	ds_read_b32 v129, v243 offset:544
	ds_read_b32 v130, v243 offset:576
	ds_read_b32 v131, v243 offset:608
	ds_read_b32 v132, v243 offset:640
	ds_read_b32 v133, v243 offset:672
	ds_read_b32 v134, v243 offset:704
	ds_read_b32 v135, v243 offset:736
	ds_read_b64 v[176:177], v234 offset:3840
	ds_read_b64 v[178:179], v234 offset:3872
	ds_read_b64 v[180:181], v234 offset:3904
	ds_read_b64 v[182:183], v234 offset:3936
	ds_read_b64 v[184:185], v234 offset:3968
	ds_read_b64 v[186:187], v234 offset:4000
	ds_read_b64 v[188:189], v234 offset:4032
	ds_read_b64 v[190:191], v234 offset:4064
	s_waitcnt vmcnt(28)
	v_and_b32_e32 v144, v160, v235
	v_and_b32_e32 v145, v160, v236
	v_and_b32_e32 v146, v160, v237
	v_and_b32_e32 v147, v160, v238
	v_and_b32_e32 v148, v161, v235
	v_and_b32_e32 v149, v161, v236
	v_and_b32_e32 v150, v161, v237
	v_and_b32_e32 v151, v161, v238
	s_mov_b64 vcc, s[4:5]
	v_cndmask_b32_dpp v138, v64, v66, vcc row_shl:4 row_mask:0xf bank_mask:0xf bound_ctrl:1
	v_cndmask_b32_dpp v139, v65, v67, vcc row_shl:4 row_mask:0xf bank_mask:0xf bound_ctrl:1
	s_mov_b64 vcc, s[6:7]
	v_cndmask_b32_dpp v136, v66, v64, vcc row_shr:4 row_mask:0xf bank_mask:0xf bound_ctrl:1
	v_cndmask_b32_dpp v137, v67, v65, vcc row_shr:4 row_mask:0xf bank_mask:0xf bound_ctrl:1
	v_and_b32_e32 v204, v162, v235
	v_and_b32_e32 v205, v162, v236
	v_and_b32_e32 v206, v162, v237
	v_and_b32_e32 v207, v162, v238
	v_and_b32_e32 v208, v163, v235
	v_and_b32_e32 v209, v163, v236
	v_and_b32_e32 v210, v163, v237
	v_and_b32_e32 v211, v163, v238
	s_mov_b64 vcc, s[6:7]
	v_cndmask_b32_dpp v140, v70, v68, vcc row_shr:4 row_mask:0xf bank_mask:0xf bound_ctrl:1
	v_cndmask_b32_dpp v141, v71, v69, vcc row_shr:4 row_mask:0xf bank_mask:0xf bound_ctrl:1
	s_mov_b64 vcc, s[4:5]
	v_cndmask_b32_dpp v142, v68, v70, vcc row_shl:4 row_mask:0xf bank_mask:0xf bound_ctrl:1
	v_cndmask_b32_dpp v143, v69, v71, vcc row_shl:4 row_mask:0xf bank_mask:0xf bound_ctrl:1
	v_mfma_scale_f32_16x16x128_f8f6f4 v[216:219], v[136:139], v[144:151], 0, v240, v241 op_sel_hi:[0,0,0] cbsz:4
	v_and_b32_e32 v144, v164, v235
	v_and_b32_e32 v145, v164, v236
	v_and_b32_e32 v146, v164, v237
	v_and_b32_e32 v147, v164, v238
	v_and_b32_e32 v148, v165, v235
	v_and_b32_e32 v149, v165, v236
	v_and_b32_e32 v150, v165, v237
	v_and_b32_e32 v151, v165, v238
	s_mov_b64 vcc, s[4:5]
	v_cndmask_b32_dpp v138, v72, v74, vcc row_shl:4 row_mask:0xf bank_mask:0xf bound_ctrl:1
	v_cndmask_b32_dpp v139, v73, v75, vcc row_shl:4 row_mask:0xf bank_mask:0xf bound_ctrl:1
	s_mov_b64 vcc, s[6:7]
	v_cndmask_b32_dpp v136, v74, v72, vcc row_shr:4 row_mask:0xf bank_mask:0xf bound_ctrl:1
	v_cndmask_b32_dpp v137, v75, v73, vcc row_shr:4 row_mask:0xf bank_mask:0xf bound_ctrl:1
	v_mfma_scale_f32_16x16x128_f8f6f4 v[216:219], v[140:143], v[204:211], v[216:219], v240, v241 op_sel_hi:[0,0,0] cbsz:4
	v_and_b32_e32 v204, v166, v235
	v_and_b32_e32 v205, v166, v236
	v_and_b32_e32 v206, v166, v237
	v_and_b32_e32 v207, v166, v238
	v_and_b32_e32 v208, v167, v235
	v_and_b32_e32 v209, v167, v236
	v_and_b32_e32 v210, v167, v237
	v_and_b32_e32 v211, v167, v238
	s_mov_b64 vcc, s[6:7]
	v_cndmask_b32_dpp v140, v78, v76, vcc row_shr:4 row_mask:0xf bank_mask:0xf bound_ctrl:1
	v_cndmask_b32_dpp v141, v79, v77, vcc row_shr:4 row_mask:0xf bank_mask:0xf bound_ctrl:1
	s_mov_b64 vcc, s[4:5]
	v_cndmask_b32_dpp v142, v76, v78, vcc row_shl:4 row_mask:0xf bank_mask:0xf bound_ctrl:1
	v_cndmask_b32_dpp v143, v77, v79, vcc row_shl:4 row_mask:0xf bank_mask:0xf bound_ctrl:1
	v_mfma_scale_f32_16x16x128_f8f6f4 v[216:219], v[136:139], v[144:151], v[216:219], v240, v241 op_sel_hi:[0,0,0] cbsz:4
	v_and_b32_e32 v144, v168, v235
	v_and_b32_e32 v145, v168, v236
	v_and_b32_e32 v146, v168, v237
	v_and_b32_e32 v147, v168, v238
	v_and_b32_e32 v148, v169, v235
	v_and_b32_e32 v149, v169, v236
	v_and_b32_e32 v150, v169, v237
	v_and_b32_e32 v151, v169, v238
	s_mov_b64 vcc, s[4:5]
	v_cndmask_b32_dpp v138, v80, v82, vcc row_shl:4 row_mask:0xf bank_mask:0xf bound_ctrl:1
	v_cndmask_b32_dpp v139, v81, v83, vcc row_shl:4 row_mask:0xf bank_mask:0xf bound_ctrl:1
	s_mov_b64 vcc, s[6:7]
	v_cndmask_b32_dpp v136, v82, v80, vcc row_shr:4 row_mask:0xf bank_mask:0xf bound_ctrl:1
	v_cndmask_b32_dpp v137, v83, v81, vcc row_shr:4 row_mask:0xf bank_mask:0xf bound_ctrl:1
	v_mfma_scale_f32_16x16x128_f8f6f4 v[216:219], v[140:143], v[204:211], v[216:219], v240, v241 op_sel_hi:[0,0,0] cbsz:4
	v_and_b32_e32 v204, v170, v235
	v_and_b32_e32 v205, v170, v236
	v_and_b32_e32 v206, v170, v237
	v_and_b32_e32 v207, v170, v238
	v_and_b32_e32 v208, v171, v235
	v_and_b32_e32 v209, v171, v236
	v_and_b32_e32 v210, v171, v237
	v_and_b32_e32 v211, v171, v238
	s_mov_b64 vcc, s[6:7]
	v_cndmask_b32_dpp v140, v86, v84, vcc row_shr:4 row_mask:0xf bank_mask:0xf bound_ctrl:1
	v_cndmask_b32_dpp v141, v87, v85, vcc row_shr:4 row_mask:0xf bank_mask:0xf bound_ctrl:1
	s_mov_b64 vcc, s[4:5]
	v_cndmask_b32_dpp v142, v84, v86, vcc row_shl:4 row_mask:0xf bank_mask:0xf bound_ctrl:1
	v_cndmask_b32_dpp v143, v85, v87, vcc row_shl:4 row_mask:0xf bank_mask:0xf bound_ctrl:1
	v_mfma_scale_f32_16x16x128_f8f6f4 v[216:219], v[136:139], v[144:151], v[216:219], v240, v241 op_sel_hi:[0,0,0] cbsz:4
	v_and_b32_e32 v144, v172, v235
	v_and_b32_e32 v145, v172, v236
	v_and_b32_e32 v146, v172, v237
	v_and_b32_e32 v147, v172, v238
	v_and_b32_e32 v148, v173, v235
	v_and_b32_e32 v149, v173, v236
	v_and_b32_e32 v150, v173, v237
	v_and_b32_e32 v151, v173, v238
	s_mov_b64 vcc, s[4:5]
	v_cndmask_b32_dpp v138, v88, v90, vcc row_shl:4 row_mask:0xf bank_mask:0xf bound_ctrl:1
	v_cndmask_b32_dpp v139, v89, v91, vcc row_shl:4 row_mask:0xf bank_mask:0xf bound_ctrl:1
	s_mov_b64 vcc, s[6:7]
	v_cndmask_b32_dpp v136, v90, v88, vcc row_shr:4 row_mask:0xf bank_mask:0xf bound_ctrl:1
	v_cndmask_b32_dpp v137, v91, v89, vcc row_shr:4 row_mask:0xf bank_mask:0xf bound_ctrl:1
	v_mfma_scale_f32_16x16x128_f8f6f4 v[216:219], v[140:143], v[204:211], v[216:219], v240, v241 op_sel_hi:[0,0,0] cbsz:4
	v_and_b32_e32 v204, v174, v235
	v_and_b32_e32 v205, v174, v236
	v_and_b32_e32 v206, v174, v237
	v_and_b32_e32 v207, v174, v238
	v_and_b32_e32 v208, v175, v235
	v_and_b32_e32 v209, v175, v236
	v_and_b32_e32 v210, v175, v237
	v_and_b32_e32 v211, v175, v238
	s_mov_b64 vcc, s[6:7]
	v_cndmask_b32_dpp v140, v94, v92, vcc row_shr:4 row_mask:0xf bank_mask:0xf bound_ctrl:1
	v_cndmask_b32_dpp v141, v95, v93, vcc row_shr:4 row_mask:0xf bank_mask:0xf bound_ctrl:1
	s_mov_b64 vcc, s[4:5]
	v_cndmask_b32_dpp v142, v92, v94, vcc row_shl:4 row_mask:0xf bank_mask:0xf bound_ctrl:1
	v_cndmask_b32_dpp v143, v93, v95, vcc row_shl:4 row_mask:0xf bank_mask:0xf bound_ctrl:1
	v_mfma_scale_f32_16x16x128_f8f6f4 v[216:219], v[136:139], v[144:151], v[216:219], v240, v241 op_sel_hi:[0,0,0] cbsz:4
	s_nop 0
	v_mfma_scale_f32_16x16x128_f8f6f4 v[216:219], v[140:143], v[204:211], v[216:219], v240, v241 op_sel_hi:[0,0,0] cbsz:4
	s_waitcnt lgkmcnt(0)
	v_lshl_or_b32 v128, v128, 7, v232
	v_lshl_or_b32 v129, v129, 7, v232
	v_lshl_or_b32 v130, v130, 7, v232
	v_lshl_or_b32 v131, v131, 7, v232
	v_lshl_or_b32 v132, v132, 7, v232
	v_lshl_or_b32 v133, v133, 7, v232
	v_lshl_or_b32 v134, v134, 7, v232
	v_lshl_or_b32 v135, v135, 7, v232
	buffer_load_dwordx4 v[64:67], v128, s[20:23], s60 offen
	buffer_load_dwordx4 v[68:71], v129, s[20:23], s60 offen
	buffer_load_dwordx4 v[72:75], v130, s[20:23], s60 offen
	buffer_load_dwordx4 v[76:79], v131, s[20:23], s60 offen
	buffer_load_dwordx4 v[80:83], v132, s[20:23], s60 offen
	buffer_load_dwordx4 v[84:87], v133, s[20:23], s60 offen
	buffer_load_dwordx4 v[88:91], v134, s[20:23], s60 offen
	buffer_load_dwordx4 v[92:95], v135, s[20:23], s60 offen
	ds_read_b32 v128, v243 offset:768
	ds_read_b32 v129, v243 offset:800
	ds_read_b32 v130, v243 offset:832
	ds_read_b32 v131, v243 offset:864
	ds_read_b32 v132, v243 offset:896
	ds_read_b32 v133, v243 offset:928
	ds_read_b32 v134, v243 offset:960
	ds_read_b32 v135, v243 offset:992
	ds_read_b64 v[160:161], v247 offset:0
	ds_read_b64 v[162:163], v247 offset:32
	ds_read_b64 v[164:165], v247 offset:64
	ds_read_b64 v[166:167], v247 offset:96
	ds_read_b64 v[168:169], v247 offset:128
	ds_read_b64 v[170:171], v247 offset:160
	ds_read_b64 v[172:173], v247 offset:192
	ds_read_b64 v[174:175], v247 offset:224
	s_waitcnt vmcnt(26)
	v_and_b32_e32 v144, v176, v235
	v_and_b32_e32 v145, v176, v236
	v_and_b32_e32 v146, v176, v237
	v_and_b32_e32 v147, v176, v238
	v_and_b32_e32 v148, v177, v235
	v_and_b32_e32 v149, v177, v236
	v_and_b32_e32 v150, v177, v237
	v_and_b32_e32 v151, v177, v238
	s_mov_b64 vcc, s[4:5]
	v_cndmask_b32_dpp v138, v96, v98, vcc row_shl:4 row_mask:0xf bank_mask:0xf bound_ctrl:1
	v_cndmask_b32_dpp v139, v97, v99, vcc row_shl:4 row_mask:0xf bank_mask:0xf bound_ctrl:1
	s_mov_b64 vcc, s[6:7]
	v_cndmask_b32_dpp v136, v98, v96, vcc row_shr:4 row_mask:0xf bank_mask:0xf bound_ctrl:1
	v_cndmask_b32_dpp v137, v99, v97, vcc row_shr:4 row_mask:0xf bank_mask:0xf bound_ctrl:1
	v_and_b32_e32 v204, v178, v235
	v_and_b32_e32 v205, v178, v236
	v_and_b32_e32 v206, v178, v237
	v_and_b32_e32 v207, v178, v238
	v_and_b32_e32 v208, v179, v235
	v_and_b32_e32 v209, v179, v236
	v_and_b32_e32 v210, v179, v237
	v_and_b32_e32 v211, v179, v238
	s_mov_b64 vcc, s[6:7]
	v_cndmask_b32_dpp v140, v102, v100, vcc row_shr:4 row_mask:0xf bank_mask:0xf bound_ctrl:1
	v_cndmask_b32_dpp v141, v103, v101, vcc row_shr:4 row_mask:0xf bank_mask:0xf bound_ctrl:1
	s_mov_b64 vcc, s[4:5]
	v_cndmask_b32_dpp v142, v100, v102, vcc row_shl:4 row_mask:0xf bank_mask:0xf bound_ctrl:1
	v_cndmask_b32_dpp v143, v101, v103, vcc row_shl:4 row_mask:0xf bank_mask:0xf bound_ctrl:1
	v_mfma_scale_f32_16x16x128_f8f6f4 v[216:219], v[136:139], v[144:151], v[216:219], v240, v241 op_sel_hi:[0,0,0] cbsz:4
	v_permlane16_swap_b32_e32 v212, v214
	v_permlane16_swap_b32_e32 v213, v215
	v_lshlrev_b32_e32 v252, 16, v228
	v_and_b32_e32 v144, v180, v235
	v_and_b32_e32 v145, v180, v236
	v_and_b32_e32 v146, v180, v237
	v_and_b32_e32 v147, v180, v238
	v_and_b32_e32 v148, v181, v235
	v_and_b32_e32 v149, v181, v236
	v_and_b32_e32 v150, v181, v237
	v_and_b32_e32 v151, v181, v238
	s_mov_b64 vcc, s[4:5]
	v_cndmask_b32_dpp v138, v104, v106, vcc row_shl:4 row_mask:0xf bank_mask:0xf bound_ctrl:1
	v_cndmask_b32_dpp v139, v105, v107, vcc row_shl:4 row_mask:0xf bank_mask:0xf bound_ctrl:1
	s_mov_b64 vcc, s[6:7]
	v_cndmask_b32_dpp v136, v106, v104, vcc row_shr:4 row_mask:0xf bank_mask:0xf bound_ctrl:1
	v_cndmask_b32_dpp v137, v107, v105, vcc row_shr:4 row_mask:0xf bank_mask:0xf bound_ctrl:1
	v_mfma_scale_f32_16x16x128_f8f6f4 v[216:219], v[140:143], v[204:211], v[216:219], v240, v241 op_sel_hi:[0,0,0] cbsz:4
	v_and_b32_e32 v253, 0xffff0000, v228
	v_lshlrev_b32_e32 v254, 16, v229
	v_and_b32_e32 v255, 0xffff0000, v229
	v_and_b32_e32 v204, v182, v235
	v_and_b32_e32 v205, v182, v236
	v_and_b32_e32 v206, v182, v237
	v_and_b32_e32 v207, v182, v238
	v_and_b32_e32 v208, v183, v235
	v_and_b32_e32 v209, v183, v236
	v_and_b32_e32 v210, v183, v237
	v_and_b32_e32 v211, v183, v238
	s_mov_b64 vcc, s[6:7]
	v_cndmask_b32_dpp v140, v110, v108, vcc row_shr:4 row_mask:0xf bank_mask:0xf bound_ctrl:1
	v_cndmask_b32_dpp v141, v111, v109, vcc row_shr:4 row_mask:0xf bank_mask:0xf bound_ctrl:1
	s_mov_b64 vcc, s[4:5]
	v_cndmask_b32_dpp v142, v108, v110, vcc row_shl:4 row_mask:0xf bank_mask:0xf bound_ctrl:1
	v_cndmask_b32_dpp v143, v109, v111, vcc row_shl:4 row_mask:0xf bank_mask:0xf bound_ctrl:1
	v_mfma_scale_f32_16x16x128_f8f6f4 v[216:219], v[136:139], v[144:151], v[216:219], v240, v241 op_sel_hi:[0,0,0] cbsz:4
	v_add_f32_e32 v252, v212, v252
	v_add_f32_e32 v253, v214, v253
	v_add_f32_e32 v254, v213, v254
	v_and_b32_e32 v144, v184, v235
	v_and_b32_e32 v145, v184, v236
	v_and_b32_e32 v146, v184, v237
	v_and_b32_e32 v147, v184, v238
	v_and_b32_e32 v148, v185, v235
	v_and_b32_e32 v149, v185, v236
	v_and_b32_e32 v150, v185, v237
	v_and_b32_e32 v151, v185, v238
	s_mov_b64 vcc, s[4:5]
	v_cndmask_b32_dpp v138, v112, v114, vcc row_shl:4 row_mask:0xf bank_mask:0xf bound_ctrl:1
	v_cndmask_b32_dpp v139, v113, v115, vcc row_shl:4 row_mask:0xf bank_mask:0xf bound_ctrl:1
	s_mov_b64 vcc, s[6:7]
	v_cndmask_b32_dpp v136, v114, v112, vcc row_shr:4 row_mask:0xf bank_mask:0xf bound_ctrl:1
	v_cndmask_b32_dpp v137, v115, v113, vcc row_shr:4 row_mask:0xf bank_mask:0xf bound_ctrl:1
	v_mfma_scale_f32_16x16x128_f8f6f4 v[216:219], v[140:143], v[204:211], v[216:219], v240, v241 op_sel_hi:[0,0,0] cbsz:4
	v_add_f32_e32 v255, v215, v255
	v_mul_f32_e32 v192, v252, v252
	v_mul_f32_e32 v193, v254, v254
	v_and_b32_e32 v204, v186, v235
	v_and_b32_e32 v205, v186, v236
	v_and_b32_e32 v206, v186, v237
	v_and_b32_e32 v207, v186, v238
	v_and_b32_e32 v208, v187, v235
	v_and_b32_e32 v209, v187, v236
	v_and_b32_e32 v210, v187, v237
	v_and_b32_e32 v211, v187, v238
	s_mov_b64 vcc, s[6:7]
	v_cndmask_b32_dpp v140, v118, v116, vcc row_shr:4 row_mask:0xf bank_mask:0xf bound_ctrl:1
	v_cndmask_b32_dpp v141, v119, v117, vcc row_shr:4 row_mask:0xf bank_mask:0xf bound_ctrl:1
	s_mov_b64 vcc, s[4:5]
	v_cndmask_b32_dpp v142, v116, v118, vcc row_shl:4 row_mask:0xf bank_mask:0xf bound_ctrl:1
	v_cndmask_b32_dpp v143, v117, v119, vcc row_shl:4 row_mask:0xf bank_mask:0xf bound_ctrl:1
	v_mfma_scale_f32_16x16x128_f8f6f4 v[216:219], v[136:139], v[144:151], v[216:219], v240, v241 op_sel_hi:[0,0,0] cbsz:4
	v_fmac_f32_e32 v192, v253, v253
	v_fmac_f32_e32 v193, v255, v255
	v_cvt_pk_bf16_f32 v250, v252, v253
	v_and_b32_e32 v144, v188, v235
	v_and_b32_e32 v145, v188, v236
	v_and_b32_e32 v146, v188, v237
	v_and_b32_e32 v147, v188, v238
	v_and_b32_e32 v148, v189, v235
	v_and_b32_e32 v149, v189, v236
	v_and_b32_e32 v150, v189, v237
	v_and_b32_e32 v151, v189, v238
	s_mov_b64 vcc, s[4:5]
	v_cndmask_b32_dpp v138, v120, v122, vcc row_shl:4 row_mask:0xf bank_mask:0xf bound_ctrl:1
	v_cndmask_b32_dpp v139, v121, v123, vcc row_shl:4 row_mask:0xf bank_mask:0xf bound_ctrl:1
	s_mov_b64 vcc, s[6:7]
	v_cndmask_b32_dpp v136, v122, v120, vcc row_shr:4 row_mask:0xf bank_mask:0xf bound_ctrl:1
	v_cndmask_b32_dpp v137, v123, v121, vcc row_shr:4 row_mask:0xf bank_mask:0xf bound_ctrl:1
	v_mfma_scale_f32_16x16x128_f8f6f4 v[216:219], v[140:143], v[204:211], v[216:219], v240, v241 op_sel_hi:[0,0,0] cbsz:4
	v_cvt_pk_bf16_f32 v251, v254, v255
	v_add_f32_e32 v192, v192, v193
	v_add_f32_e32 v226, v226, v192
	v_and_b32_e32 v204, v190, v235
	v_and_b32_e32 v205, v190, v236
	v_and_b32_e32 v206, v190, v237
	v_and_b32_e32 v207, v190, v238
	v_and_b32_e32 v208, v191, v235
	v_and_b32_e32 v209, v191, v236
	v_and_b32_e32 v210, v191, v237
	v_and_b32_e32 v211, v191, v238
	s_mov_b64 vcc, s[6:7]
	v_cndmask_b32_dpp v140, v126, v124, vcc row_shr:4 row_mask:0xf bank_mask:0xf bound_ctrl:1
	v_cndmask_b32_dpp v141, v127, v125, vcc row_shr:4 row_mask:0xf bank_mask:0xf bound_ctrl:1
	s_mov_b64 vcc, s[4:5]
	v_cndmask_b32_dpp v142, v124, v126, vcc row_shl:4 row_mask:0xf bank_mask:0xf bound_ctrl:1
	v_cndmask_b32_dpp v143, v125, v127, vcc row_shl:4 row_mask:0xf bank_mask:0xf bound_ctrl:1
	v_mfma_scale_f32_16x16x128_f8f6f4 v[216:219], v[136:139], v[144:151], v[216:219], v240, v241 op_sel_hi:[0,0,0] cbsz:4
	s_nop 0
	v_mfma_scale_f32_16x16x128_f8f6f4 v[216:219], v[140:143], v[204:211], v[216:219], v240, v241 op_sel_hi:[0,0,0] cbsz:4
	s_lshl_b32 s64, s0, 9
	s_add_u32 s64, s64, 0x6000
	s_add_u32 s76, s28, s64
	s_addc_u32 s77, s29, 0
	global_store_dwordx2 v239, v[250:251], s[76:77]
	s_add_u32 s0, s0, 1
	s_lshl_b32 s1, s0, 21
	s_add_u32 s60, s1, 0x200000
	s_cmp_ge_u32 s0, 3
	s_movk_i32 s65, 0x2000
	s_cselect_b32 s64, s65, 0x1000
	v_mov_b32_e32 v234, v247
	v_add_u32_e32 v247, s64, v233
	s_cmp_lt_u32 s0, 8
	s_cbranch_scc1 .LpgL1_vloopv0
	s_waitcnt vmcnt(0)
	s_nop 15
	v_permlane16_swap_b32_e32 v216, v218
	v_permlane16_swap_b32_e32 v217, v219
	v_lshlrev_b32_e32 v252, 16, v230
	v_and_b32_e32 v253, 0xffff0000, v230
	v_lshlrev_b32_e32 v254, 16, v231
	v_and_b32_e32 v255, 0xffff0000, v231
	v_add_f32_e32 v252, v216, v252
	v_add_f32_e32 v253, v218, v253
	v_add_f32_e32 v254, v217, v254
	v_add_f32_e32 v255, v219, v255
	v_mul_f32_e32 v192, v252, v252
	v_mul_f32_e32 v193, v254, v254
	v_fmac_f32_e32 v192, v253, v253
	v_fmac_f32_e32 v193, v255, v255
	v_cvt_pk_bf16_f32 v250, v252, v253
	v_cvt_pk_bf16_f32 v251, v254, v255
	v_add_f32_e32 v192, v192, v193
	v_add_f32_e32 v227, v227, v192
	s_lshl_b32 s64, s0, 9
	s_add_u32 s64, s64, 0x6e00
	s_add_u32 s76, s28, s64
	s_addc_u32 s77, s29, 0
	global_store_dwordx2 v239, v[250:251], s[76:77]
	s_nop 1
	v_add_f32_dpp v220, v220, v220 quad_perm:[1,0,3,2] row_mask:0xf bank_mask:0xf bound_ctrl:1
	s_nop 1
	v_add_f32_dpp v220, v220, v220 quad_perm:[2,3,0,1] row_mask:0xf bank_mask:0xf bound_ctrl:1
	s_nop 1
	v_add_f32_dpp v220, v220, v220 row_half_mirror row_mask:0xf bank_mask:0xf bound_ctrl:1
	s_nop 1
	v_add_f32_dpp v220, v220, v220 row_mirror row_mask:0xf bank_mask:0xf bound_ctrl:1
	v_mov_b32_e32 v249, v220
	s_nop 1
	v_permlane16_swap_b32_e32 v220, v249
	v_add_f32_e32 v220, v220, v249
	v_mov_b32_e32 v249, v220
	s_nop 1
	v_permlane32_swap_b32_e32 v220, v249
	v_add_f32_e32 v220, v220, v249
	s_nop 1
	v_add_f32_dpp v221, v221, v221 quad_perm:[1,0,3,2] row_mask:0xf bank_mask:0xf bound_ctrl:1
	s_nop 1
	v_add_f32_dpp v221, v221, v221 quad_perm:[2,3,0,1] row_mask:0xf bank_mask:0xf bound_ctrl:1
	s_nop 1
	v_add_f32_dpp v221, v221, v221 row_half_mirror row_mask:0xf bank_mask:0xf bound_ctrl:1
	s_nop 1
	v_add_f32_dpp v221, v221, v221 row_mirror row_mask:0xf bank_mask:0xf bound_ctrl:1
	v_mov_b32_e32 v249, v221
	s_nop 1
	v_permlane16_swap_b32_e32 v221, v249
	v_add_f32_e32 v221, v221, v249
	v_mov_b32_e32 v249, v221
	s_nop 1
	v_permlane32_swap_b32_e32 v221, v249
	v_add_f32_e32 v221, v221, v249
	s_nop 1
	v_add_f32_dpp v222, v222, v222 quad_perm:[1,0,3,2] row_mask:0xf bank_mask:0xf bound_ctrl:1
	s_nop 1
	v_add_f32_dpp v222, v222, v222 quad_perm:[2,3,0,1] row_mask:0xf bank_mask:0xf bound_ctrl:1
	s_nop 1
	v_add_f32_dpp v222, v222, v222 row_half_mirror row_mask:0xf bank_mask:0xf bound_ctrl:1
	s_nop 1
	v_add_f32_dpp v222, v222, v222 row_mirror row_mask:0xf bank_mask:0xf bound_ctrl:1
	v_mov_b32_e32 v249, v222
	s_nop 1
	v_permlane16_swap_b32_e32 v222, v249
	v_add_f32_e32 v222, v222, v249
	v_mov_b32_e32 v249, v222
	s_nop 1
	v_permlane32_swap_b32_e32 v222, v249
	v_add_f32_e32 v222, v222, v249
	s_nop 1
	v_add_f32_dpp v223, v223, v223 quad_perm:[1,0,3,2] row_mask:0xf bank_mask:0xf bound_ctrl:1
	s_nop 1
	v_add_f32_dpp v223, v223, v223 quad_perm:[2,3,0,1] row_mask:0xf bank_mask:0xf bound_ctrl:1
	s_nop 1
	v_add_f32_dpp v223, v223, v223 row_half_mirror row_mask:0xf bank_mask:0xf bound_ctrl:1
	s_nop 1
	v_add_f32_dpp v223, v223, v223 row_mirror row_mask:0xf bank_mask:0xf bound_ctrl:1
	v_mov_b32_e32 v249, v223
	s_nop 1
	v_permlane16_swap_b32_e32 v223, v249
	v_add_f32_e32 v223, v223, v249
	v_mov_b32_e32 v249, v223
	s_nop 1
	v_permlane32_swap_b32_e32 v223, v249
	v_add_f32_e32 v223, v223, v249
	s_nop 1
	v_add_f32_dpp v224, v224, v224 quad_perm:[1,0,3,2] row_mask:0xf bank_mask:0xf bound_ctrl:1
	s_nop 1
	v_add_f32_dpp v224, v224, v224 quad_perm:[2,3,0,1] row_mask:0xf bank_mask:0xf bound_ctrl:1
	s_nop 1
	v_add_f32_dpp v224, v224, v224 row_half_mirror row_mask:0xf bank_mask:0xf bound_ctrl:1
	s_nop 1
	v_add_f32_dpp v224, v224, v224 row_mirror row_mask:0xf bank_mask:0xf bound_ctrl:1
	v_mov_b32_e32 v249, v224
	s_nop 1
	v_permlane16_swap_b32_e32 v224, v249
	v_add_f32_e32 v224, v224, v249
	v_mov_b32_e32 v249, v224
	s_nop 1
	v_permlane32_swap_b32_e32 v224, v249
	v_add_f32_e32 v224, v224, v249
	s_nop 1
	v_add_f32_dpp v225, v225, v225 quad_perm:[1,0,3,2] row_mask:0xf bank_mask:0xf bound_ctrl:1
	s_nop 1
	v_add_f32_dpp v225, v225, v225 quad_perm:[2,3,0,1] row_mask:0xf bank_mask:0xf bound_ctrl:1
	s_nop 1
	v_add_f32_dpp v225, v225, v225 row_half_mirror row_mask:0xf bank_mask:0xf bound_ctrl:1
	s_nop 1
	v_add_f32_dpp v225, v225, v225 row_mirror row_mask:0xf bank_mask:0xf bound_ctrl:1
	v_mov_b32_e32 v249, v225
	s_nop 1
	v_permlane16_swap_b32_e32 v225, v249
	v_add_f32_e32 v225, v225, v249
	v_mov_b32_e32 v249, v225
	s_nop 1
	v_permlane32_swap_b32_e32 v225, v249
	v_add_f32_e32 v225, v225, v249
	s_nop 1
	v_add_f32_dpp v226, v226, v226 quad_perm:[1,0,3,2] row_mask:0xf bank_mask:0xf bound_ctrl:1
	s_nop 1
	v_add_f32_dpp v226, v226, v226 quad_perm:[2,3,0,1] row_mask:0xf bank_mask:0xf bound_ctrl:1
	s_nop 1
	v_add_f32_dpp v226, v226, v226 row_half_mirror row_mask:0xf bank_mask:0xf bound_ctrl:1
	s_nop 1
	v_add_f32_dpp v226, v226, v226 row_mirror row_mask:0xf bank_mask:0xf bound_ctrl:1
	v_mov_b32_e32 v249, v226
	s_nop 1
	v_permlane16_swap_b32_e32 v226, v249
	v_add_f32_e32 v226, v226, v249
	v_mov_b32_e32 v249, v226
	s_nop 1
	v_permlane32_swap_b32_e32 v226, v249
	v_add_f32_e32 v226, v226, v249
	s_nop 1
	v_add_f32_dpp v227, v227, v227 quad_perm:[1,0,3,2] row_mask:0xf bank_mask:0xf bound_ctrl:1
	s_nop 1
	v_add_f32_dpp v227, v227, v227 quad_perm:[2,3,0,1] row_mask:0xf bank_mask:0xf bound_ctrl:1
	s_nop 1
	v_add_f32_dpp v227, v227, v227 row_half_mirror row_mask:0xf bank_mask:0xf bound_ctrl:1
	s_nop 1
	v_add_f32_dpp v227, v227, v227 row_mirror row_mask:0xf bank_mask:0xf bound_ctrl:1
	v_mov_b32_e32 v249, v227
	s_nop 1
	v_permlane16_swap_b32_e32 v227, v249
	v_add_f32_e32 v227, v227, v249
	v_mov_b32_e32 v249, v227
	s_nop 1
	v_permlane32_swap_b32_e32 v227, v249
	v_add_f32_e32 v227, v227, v249
	s_waitcnt vmcnt(0)
	v_lshlrev_b32_e32 v250, 1, v239
	v_add_u32_e32 v251, 0x1000, v250
	global_load_dwordx4 v[0:3], v250, s[66:67] offset:0
	global_load_dwordx4 v[4:7], v250, s[66:67] offset:1024
	global_load_dwordx4 v[8:11], v250, s[66:67] offset:2048
	global_load_dwordx4 v[12:15], v250, s[66:67] offset:3072
	global_load_dwordx4 v[16:19], v251, s[66:67] offset:0
	global_load_dwordx4 v[20:23], v251, s[66:67] offset:1024
	global_load_dwordx4 v[24:27], v251, s[66:67] offset:2048
	global_load_dwordx4 v[28:31], v251, s[66:67] offset:3072
	v_mov_b32_e32 v120, 0x358637bd
	v_fmamk_f32 v220, v220, 0x3a000000, v120
	v_cmp_gt_f32_e32 vcc, s96, v220
	v_mul_f32_e32 v121, 0x4b800000, v220
	s_nop 0
	v_cndmask_b32_e32 v220, v220, v121, vcc
	v_rsq_f32_e32 v220, v220
	s_nop 0
	v_mul_f32_e32 v121, 0x45800000, v220
	v_cndmask_b32_e32 v220, v220, v121, vcc
	v_fmamk_f32 v221, v221, 0x3a000000, v120
	v_cmp_gt_f32_e32 vcc, s96, v221
	v_mul_f32_e32 v121, 0x4b800000, v221
	s_nop 0
	v_cndmask_b32_e32 v221, v221, v121, vcc
	v_rsq_f32_e32 v221, v221
	s_nop 0
	v_mul_f32_e32 v121, 0x45800000, v221
	v_cndmask_b32_e32 v221, v221, v121, vcc
	v_fmamk_f32 v222, v222, 0x3a000000, v120
	v_cmp_gt_f32_e32 vcc, s96, v222
	v_mul_f32_e32 v121, 0x4b800000, v222
	s_nop 0
	v_cndmask_b32_e32 v222, v222, v121, vcc
	v_rsq_f32_e32 v222, v222
	s_nop 0
	v_mul_f32_e32 v121, 0x45800000, v222
	v_cndmask_b32_e32 v222, v222, v121, vcc
	v_fmamk_f32 v223, v223, 0x3a000000, v120
	v_cmp_gt_f32_e32 vcc, s96, v223
	v_mul_f32_e32 v121, 0x4b800000, v223
	s_nop 0
	v_cndmask_b32_e32 v223, v223, v121, vcc
	v_rsq_f32_e32 v223, v223
	s_nop 0
	v_mul_f32_e32 v121, 0x45800000, v223
	v_cndmask_b32_e32 v223, v223, v121, vcc
	v_fmamk_f32 v224, v224, 0x3a000000, v120
	v_cmp_gt_f32_e32 vcc, s96, v224
	v_mul_f32_e32 v121, 0x4b800000, v224
	s_nop 0
	v_cndmask_b32_e32 v224, v224, v121, vcc
	v_rsq_f32_e32 v224, v224
	s_nop 0
	v_mul_f32_e32 v121, 0x45800000, v224
	v_cndmask_b32_e32 v224, v224, v121, vcc
	v_fmamk_f32 v225, v225, 0x3a000000, v120
	v_cmp_gt_f32_e32 vcc, s96, v225
	v_mul_f32_e32 v121, 0x4b800000, v225
	s_nop 0
	v_cndmask_b32_e32 v225, v225, v121, vcc
	v_rsq_f32_e32 v225, v225
	s_nop 0
	v_mul_f32_e32 v121, 0x45800000, v225
	v_cndmask_b32_e32 v225, v225, v121, vcc
	v_fmamk_f32 v226, v226, 0x3a000000, v120
	v_cmp_gt_f32_e32 vcc, s96, v226
	v_mul_f32_e32 v121, 0x4b800000, v226
	s_nop 0
	v_cndmask_b32_e32 v226, v226, v121, vcc
	v_rsq_f32_e32 v226, v226
	s_nop 0
	v_mul_f32_e32 v121, 0x45800000, v226
	v_cndmask_b32_e32 v226, v226, v121, vcc
	v_fmamk_f32 v227, v227, 0x3a000000, v120
	v_cmp_gt_f32_e32 vcc, s96, v227
	v_mul_f32_e32 v121, 0x4b800000, v227
	s_nop 0
	v_cndmask_b32_e32 v227, v227, v121, vcc
	v_rsq_f32_e32 v227, v227
	s_nop 0
	v_mul_f32_e32 v121, 0x45800000, v227
	v_cndmask_b32_e32 v227, v227, v121, vcc
	s_add_u32 s70, s28, 0x0
	s_addc_u32 s71, s29, 0
	global_load_dwordx2 v[32:33], v239, s[70:71] offset:0
	global_load_dwordx2 v[34:35], v239, s[70:71] offset:512
	global_load_dwordx2 v[36:37], v239, s[70:71] offset:1024
	global_load_dwordx2 v[38:39], v239, s[70:71] offset:1536
	global_load_dwordx2 v[40:41], v239, s[70:71] offset:2048
	global_load_dwordx2 v[42:43], v239, s[70:71] offset:2560
	global_load_dwordx2 v[44:45], v239, s[70:71] offset:3072
	global_load_dwordx2 v[46:47], v239, s[70:71] offset:3584
	s_add_u32 s70, s28, 0x1000
	s_addc_u32 s71, s29, 0
	global_load_dwordx2 v[48:49], v239, s[70:71] offset:0
	global_load_dwordx2 v[50:51], v239, s[70:71] offset:512
	global_load_dwordx2 v[52:53], v239, s[70:71] offset:1024
	global_load_dwordx2 v[54:55], v239, s[70:71] offset:1536
	global_load_dwordx2 v[56:57], v239, s[70:71] offset:2048
	global_load_dwordx2 v[58:59], v239, s[70:71] offset:2560
	global_load_dwordx2 v[60:61], v239, s[70:71] offset:3072
	global_load_dwordx2 v[62:63], v239, s[70:71] offset:3584
	s_waitcnt vmcnt(8)
	s_add_u32 s76, s46, 0x0
	s_addc_u32 s77, s47, 0
	v_lshlrev_b32_e32 v64, 16, v32
	v_and_b32_e32 v65, 0xffff0000, v32
	v_lshlrev_b32_e32 v66, 16, v33
	v_and_b32_e32 v67, 0xffff0000, v33
	v_mul_f32_e32 v64, v64, v220
	v_mul_f32_e32 v65, v65, v220
	v_mul_f32_e32 v66, v66, v220
	v_mul_f32_e32 v67, v67, v220
	v_mul_f32_e32 v64, v64, v0
	v_mul_f32_e32 v65, v65, v1
	v_mul_f32_e32 v66, v66, v2
	v_mul_f32_e32 v67, v67, v3
	global_store_dwordx4 v250, v[64:67], s[76:77] offset:0 nt
	v_lshlrev_b32_e32 v68, 16, v34
	v_and_b32_e32 v69, 0xffff0000, v34
	v_lshlrev_b32_e32 v70, 16, v35
	v_and_b32_e32 v71, 0xffff0000, v35
	v_mul_f32_e32 v68, v68, v220
	v_mul_f32_e32 v69, v69, v220
	v_mul_f32_e32 v70, v70, v220
	v_mul_f32_e32 v71, v71, v220
	v_mul_f32_e32 v68, v68, v4
	v_mul_f32_e32 v69, v69, v5
	v_mul_f32_e32 v70, v70, v6
	v_mul_f32_e32 v71, v71, v7
	global_store_dwordx4 v250, v[68:71], s[76:77] offset:1024 nt
	v_lshlrev_b32_e32 v72, 16, v36
	v_and_b32_e32 v73, 0xffff0000, v36
	v_lshlrev_b32_e32 v74, 16, v37
	v_and_b32_e32 v75, 0xffff0000, v37
	v_mul_f32_e32 v72, v72, v220
	v_mul_f32_e32 v73, v73, v220
	v_mul_f32_e32 v74, v74, v220
	v_mul_f32_e32 v75, v75, v220
	v_mul_f32_e32 v72, v72, v8
	v_mul_f32_e32 v73, v73, v9
	v_mul_f32_e32 v74, v74, v10
	v_mul_f32_e32 v75, v75, v11
	global_store_dwordx4 v250, v[72:75], s[76:77] offset:2048 nt
	v_lshlrev_b32_e32 v76, 16, v38
	v_and_b32_e32 v77, 0xffff0000, v38
	v_lshlrev_b32_e32 v78, 16, v39
	v_and_b32_e32 v79, 0xffff0000, v39
	v_mul_f32_e32 v76, v76, v220
	v_mul_f32_e32 v77, v77, v220
	v_mul_f32_e32 v78, v78, v220
	v_mul_f32_e32 v79, v79, v220
	v_mul_f32_e32 v76, v76, v12
	v_mul_f32_e32 v77, v77, v13
	v_mul_f32_e32 v78, v78, v14
	v_mul_f32_e32 v79, v79, v15
	global_store_dwordx4 v250, v[76:79], s[76:77] offset:3072 nt
	v_lshlrev_b32_e32 v64, 16, v40
	v_and_b32_e32 v65, 0xffff0000, v40
	v_lshlrev_b32_e32 v66, 16, v41
	v_and_b32_e32 v67, 0xffff0000, v41
	v_mul_f32_e32 v64, v64, v220
	v_mul_f32_e32 v65, v65, v220
	v_mul_f32_e32 v66, v66, v220
	v_mul_f32_e32 v67, v67, v220
	v_mul_f32_e32 v64, v64, v16
	v_mul_f32_e32 v65, v65, v17
	v_mul_f32_e32 v66, v66, v18
	v_mul_f32_e32 v67, v67, v19
	global_store_dwordx4 v251, v[64:67], s[76:77] offset:0 nt
	v_lshlrev_b32_e32 v68, 16, v42
	v_and_b32_e32 v69, 0xffff0000, v42
	v_lshlrev_b32_e32 v70, 16, v43
	v_and_b32_e32 v71, 0xffff0000, v43
	v_mul_f32_e32 v68, v68, v220
	v_mul_f32_e32 v69, v69, v220
	v_mul_f32_e32 v70, v70, v220
	v_mul_f32_e32 v71, v71, v220
	v_mul_f32_e32 v68, v68, v20
	v_mul_f32_e32 v69, v69, v21
	v_mul_f32_e32 v70, v70, v22
	v_mul_f32_e32 v71, v71, v23
	global_store_dwordx4 v251, v[68:71], s[76:77] offset:1024 nt
	v_lshlrev_b32_e32 v72, 16, v44
	v_and_b32_e32 v73, 0xffff0000, v44
	v_lshlrev_b32_e32 v74, 16, v45
	v_and_b32_e32 v75, 0xffff0000, v45
	v_mul_f32_e32 v72, v72, v220
	v_mul_f32_e32 v73, v73, v220
	v_mul_f32_e32 v74, v74, v220
	v_mul_f32_e32 v75, v75, v220
	v_mul_f32_e32 v72, v72, v24
	v_mul_f32_e32 v73, v73, v25
	v_mul_f32_e32 v74, v74, v26
	v_mul_f32_e32 v75, v75, v27
	global_store_dwordx4 v251, v[72:75], s[76:77] offset:2048 nt
	v_lshlrev_b32_e32 v76, 16, v46
	v_and_b32_e32 v77, 0xffff0000, v46
	v_lshlrev_b32_e32 v78, 16, v47
	v_and_b32_e32 v79, 0xffff0000, v47
	v_mul_f32_e32 v76, v76, v220
	v_mul_f32_e32 v77, v77, v220
	v_mul_f32_e32 v78, v78, v220
	v_mul_f32_e32 v79, v79, v220
	v_mul_f32_e32 v76, v76, v28
	v_mul_f32_e32 v77, v77, v29
	v_mul_f32_e32 v78, v78, v30
	v_mul_f32_e32 v79, v79, v31
	global_store_dwordx4 v251, v[76:79], s[76:77] offset:3072 nt
	s_add_u32 s70, s28, 0x2000
	s_addc_u32 s71, s29, 0
	global_load_dwordx2 v[32:33], v239, s[70:71] offset:0
	global_load_dwordx2 v[34:35], v239, s[70:71] offset:512
	global_load_dwordx2 v[36:37], v239, s[70:71] offset:1024
	global_load_dwordx2 v[38:39], v239, s[70:71] offset:1536
	global_load_dwordx2 v[40:41], v239, s[70:71] offset:2048
	global_load_dwordx2 v[42:43], v239, s[70:71] offset:2560
	global_load_dwordx2 v[44:45], v239, s[70:71] offset:3072
	global_load_dwordx2 v[46:47], v239, s[70:71] offset:3584
	s_waitcnt vmcnt(16)
	s_add_u32 s76, s46, 0x2000
	s_addc_u32 s77, s47, 0
	v_lshlrev_b32_e32 v64, 16, v48
	v_and_b32_e32 v65, 0xffff0000, v48
	v_lshlrev_b32_e32 v66, 16, v49
	v_and_b32_e32 v67, 0xffff0000, v49
	v_mul_f32_e32 v64, v64, v221
	v_mul_f32_e32 v65, v65, v221
	v_mul_f32_e32 v66, v66, v221
	v_mul_f32_e32 v67, v67, v221
	v_mul_f32_e32 v64, v64, v0
	v_mul_f32_e32 v65, v65, v1
	v_mul_f32_e32 v66, v66, v2
	v_mul_f32_e32 v67, v67, v3
	global_store_dwordx4 v250, v[64:67], s[76:77] offset:0 nt
	v_lshlrev_b32_e32 v68, 16, v50
	v_and_b32_e32 v69, 0xffff0000, v50
	v_lshlrev_b32_e32 v70, 16, v51
	v_and_b32_e32 v71, 0xffff0000, v51
	v_mul_f32_e32 v68, v68, v221
	v_mul_f32_e32 v69, v69, v221
	v_mul_f32_e32 v70, v70, v221
	v_mul_f32_e32 v71, v71, v221
	v_mul_f32_e32 v68, v68, v4
	v_mul_f32_e32 v69, v69, v5
	v_mul_f32_e32 v70, v70, v6
	v_mul_f32_e32 v71, v71, v7
	global_store_dwordx4 v250, v[68:71], s[76:77] offset:1024 nt
	v_lshlrev_b32_e32 v72, 16, v52
	v_and_b32_e32 v73, 0xffff0000, v52
	v_lshlrev_b32_e32 v74, 16, v53
	v_and_b32_e32 v75, 0xffff0000, v53
	v_mul_f32_e32 v72, v72, v221
	v_mul_f32_e32 v73, v73, v221
	v_mul_f32_e32 v74, v74, v221
	v_mul_f32_e32 v75, v75, v221
	v_mul_f32_e32 v72, v72, v8
	v_mul_f32_e32 v73, v73, v9
	v_mul_f32_e32 v74, v74, v10
	v_mul_f32_e32 v75, v75, v11
	global_store_dwordx4 v250, v[72:75], s[76:77] offset:2048 nt
	v_lshlrev_b32_e32 v76, 16, v54
	v_and_b32_e32 v77, 0xffff0000, v54
	v_lshlrev_b32_e32 v78, 16, v55
	v_and_b32_e32 v79, 0xffff0000, v55
	v_mul_f32_e32 v76, v76, v221
	v_mul_f32_e32 v77, v77, v221
	v_mul_f32_e32 v78, v78, v221
	v_mul_f32_e32 v79, v79, v221
	v_mul_f32_e32 v76, v76, v12
	v_mul_f32_e32 v77, v77, v13
	v_mul_f32_e32 v78, v78, v14
	v_mul_f32_e32 v79, v79, v15
	global_store_dwordx4 v250, v[76:79], s[76:77] offset:3072 nt
	v_lshlrev_b32_e32 v64, 16, v56
	v_and_b32_e32 v65, 0xffff0000, v56
	v_lshlrev_b32_e32 v66, 16, v57
	v_and_b32_e32 v67, 0xffff0000, v57
	v_mul_f32_e32 v64, v64, v221
	v_mul_f32_e32 v65, v65, v221
	v_mul_f32_e32 v66, v66, v221
	v_mul_f32_e32 v67, v67, v221
	v_mul_f32_e32 v64, v64, v16
	v_mul_f32_e32 v65, v65, v17
	v_mul_f32_e32 v66, v66, v18
	v_mul_f32_e32 v67, v67, v19
	global_store_dwordx4 v251, v[64:67], s[76:77] offset:0 nt
	v_lshlrev_b32_e32 v68, 16, v58
	v_and_b32_e32 v69, 0xffff0000, v58
	v_lshlrev_b32_e32 v70, 16, v59
	v_and_b32_e32 v71, 0xffff0000, v59
	v_mul_f32_e32 v68, v68, v221
	v_mul_f32_e32 v69, v69, v221
	v_mul_f32_e32 v70, v70, v221
	v_mul_f32_e32 v71, v71, v221
	v_mul_f32_e32 v68, v68, v20
	v_mul_f32_e32 v69, v69, v21
	v_mul_f32_e32 v70, v70, v22
	v_mul_f32_e32 v71, v71, v23
	global_store_dwordx4 v251, v[68:71], s[76:77] offset:1024 nt
	v_lshlrev_b32_e32 v72, 16, v60
	v_and_b32_e32 v73, 0xffff0000, v60
	v_lshlrev_b32_e32 v74, 16, v61
	v_and_b32_e32 v75, 0xffff0000, v61
	v_mul_f32_e32 v72, v72, v221
	v_mul_f32_e32 v73, v73, v221
	v_mul_f32_e32 v74, v74, v221
	v_mul_f32_e32 v75, v75, v221
	v_mul_f32_e32 v72, v72, v24
	v_mul_f32_e32 v73, v73, v25
	v_mul_f32_e32 v74, v74, v26
	v_mul_f32_e32 v75, v75, v27
	global_store_dwordx4 v251, v[72:75], s[76:77] offset:2048 nt
	v_lshlrev_b32_e32 v76, 16, v62
	v_and_b32_e32 v77, 0xffff0000, v62
	v_lshlrev_b32_e32 v78, 16, v63
	v_and_b32_e32 v79, 0xffff0000, v63
	v_mul_f32_e32 v76, v76, v221
	v_mul_f32_e32 v77, v77, v221
	v_mul_f32_e32 v78, v78, v221
	v_mul_f32_e32 v79, v79, v221
	v_mul_f32_e32 v76, v76, v28
	v_mul_f32_e32 v77, v77, v29
	v_mul_f32_e32 v78, v78, v30
	v_mul_f32_e32 v79, v79, v31
	global_store_dwordx4 v251, v[76:79], s[76:77] offset:3072 nt
	s_add_u32 s70, s28, 0x3000
	s_addc_u32 s71, s29, 0
	global_load_dwordx2 v[48:49], v239, s[70:71] offset:0
	global_load_dwordx2 v[50:51], v239, s[70:71] offset:512
	global_load_dwordx2 v[52:53], v239, s[70:71] offset:1024
	global_load_dwordx2 v[54:55], v239, s[70:71] offset:1536
	global_load_dwordx2 v[56:57], v239, s[70:71] offset:2048
	global_load_dwordx2 v[58:59], v239, s[70:71] offset:2560
	global_load_dwordx2 v[60:61], v239, s[70:71] offset:3072
	global_load_dwordx2 v[62:63], v239, s[70:71] offset:3584
	s_waitcnt vmcnt(16)
	s_add_u32 s76, s46, 0x4000
	s_addc_u32 s77, s47, 0
	v_lshlrev_b32_e32 v64, 16, v32
	v_and_b32_e32 v65, 0xffff0000, v32
	v_lshlrev_b32_e32 v66, 16, v33
	v_and_b32_e32 v67, 0xffff0000, v33
	v_mul_f32_e32 v64, v64, v222
	v_mul_f32_e32 v65, v65, v222
	v_mul_f32_e32 v66, v66, v222
	v_mul_f32_e32 v67, v67, v222
	v_mul_f32_e32 v64, v64, v0
	v_mul_f32_e32 v65, v65, v1
	v_mul_f32_e32 v66, v66, v2
	v_mul_f32_e32 v67, v67, v3
	global_store_dwordx4 v250, v[64:67], s[76:77] offset:0 nt
	v_lshlrev_b32_e32 v68, 16, v34
	v_and_b32_e32 v69, 0xffff0000, v34
	v_lshlrev_b32_e32 v70, 16, v35
	v_and_b32_e32 v71, 0xffff0000, v35
	v_mul_f32_e32 v68, v68, v222
	v_mul_f32_e32 v69, v69, v222
	v_mul_f32_e32 v70, v70, v222
	v_mul_f32_e32 v71, v71, v222
	v_mul_f32_e32 v68, v68, v4
	v_mul_f32_e32 v69, v69, v5
	v_mul_f32_e32 v70, v70, v6
	v_mul_f32_e32 v71, v71, v7
	global_store_dwordx4 v250, v[68:71], s[76:77] offset:1024 nt
	v_lshlrev_b32_e32 v72, 16, v36
	v_and_b32_e32 v73, 0xffff0000, v36
	v_lshlrev_b32_e32 v74, 16, v37
	v_and_b32_e32 v75, 0xffff0000, v37
	v_mul_f32_e32 v72, v72, v222
	v_mul_f32_e32 v73, v73, v222
	v_mul_f32_e32 v74, v74, v222
	v_mul_f32_e32 v75, v75, v222
	v_mul_f32_e32 v72, v72, v8
	v_mul_f32_e32 v73, v73, v9
	v_mul_f32_e32 v74, v74, v10
	v_mul_f32_e32 v75, v75, v11
	global_store_dwordx4 v250, v[72:75], s[76:77] offset:2048 nt
	v_lshlrev_b32_e32 v76, 16, v38
	v_and_b32_e32 v77, 0xffff0000, v38
	v_lshlrev_b32_e32 v78, 16, v39
	v_and_b32_e32 v79, 0xffff0000, v39
	v_mul_f32_e32 v76, v76, v222
	v_mul_f32_e32 v77, v77, v222
	v_mul_f32_e32 v78, v78, v222
	v_mul_f32_e32 v79, v79, v222
	v_mul_f32_e32 v76, v76, v12
	v_mul_f32_e32 v77, v77, v13
	v_mul_f32_e32 v78, v78, v14
	v_mul_f32_e32 v79, v79, v15
	global_store_dwordx4 v250, v[76:79], s[76:77] offset:3072 nt
	v_lshlrev_b32_e32 v64, 16, v40
	v_and_b32_e32 v65, 0xffff0000, v40
	v_lshlrev_b32_e32 v66, 16, v41
	v_and_b32_e32 v67, 0xffff0000, v41
	v_mul_f32_e32 v64, v64, v222
	v_mul_f32_e32 v65, v65, v222
	v_mul_f32_e32 v66, v66, v222
	v_mul_f32_e32 v67, v67, v222
	v_mul_f32_e32 v64, v64, v16
	v_mul_f32_e32 v65, v65, v17
	v_mul_f32_e32 v66, v66, v18
	v_mul_f32_e32 v67, v67, v19
	global_store_dwordx4 v251, v[64:67], s[76:77] offset:0 nt
	v_lshlrev_b32_e32 v68, 16, v42
	v_and_b32_e32 v69, 0xffff0000, v42
	v_lshlrev_b32_e32 v70, 16, v43
	v_and_b32_e32 v71, 0xffff0000, v43
	v_mul_f32_e32 v68, v68, v222
	v_mul_f32_e32 v69, v69, v222
	v_mul_f32_e32 v70, v70, v222
	v_mul_f32_e32 v71, v71, v222
	v_mul_f32_e32 v68, v68, v20
	v_mul_f32_e32 v69, v69, v21
	v_mul_f32_e32 v70, v70, v22
	v_mul_f32_e32 v71, v71, v23
	global_store_dwordx4 v251, v[68:71], s[76:77] offset:1024 nt
	v_lshlrev_b32_e32 v72, 16, v44
	v_and_b32_e32 v73, 0xffff0000, v44
	v_lshlrev_b32_e32 v74, 16, v45
	v_and_b32_e32 v75, 0xffff0000, v45
	v_mul_f32_e32 v72, v72, v222
	v_mul_f32_e32 v73, v73, v222
	v_mul_f32_e32 v74, v74, v222
	v_mul_f32_e32 v75, v75, v222
	v_mul_f32_e32 v72, v72, v24
	v_mul_f32_e32 v73, v73, v25
	v_mul_f32_e32 v74, v74, v26
	v_mul_f32_e32 v75, v75, v27
	global_store_dwordx4 v251, v[72:75], s[76:77] offset:2048 nt
	v_lshlrev_b32_e32 v76, 16, v46
	v_and_b32_e32 v77, 0xffff0000, v46
	v_lshlrev_b32_e32 v78, 16, v47
	v_and_b32_e32 v79, 0xffff0000, v47
	v_mul_f32_e32 v76, v76, v222
	v_mul_f32_e32 v77, v77, v222
	v_mul_f32_e32 v78, v78, v222
	v_mul_f32_e32 v79, v79, v222
	v_mul_f32_e32 v76, v76, v28
	v_mul_f32_e32 v77, v77, v29
	v_mul_f32_e32 v78, v78, v30
	v_mul_f32_e32 v79, v79, v31
	global_store_dwordx4 v251, v[76:79], s[76:77] offset:3072 nt
	s_add_u32 s70, s28, 0x4000
	s_addc_u32 s71, s29, 0
	global_load_dwordx2 v[32:33], v239, s[70:71] offset:0
	global_load_dwordx2 v[34:35], v239, s[70:71] offset:512
	global_load_dwordx2 v[36:37], v239, s[70:71] offset:1024
	global_load_dwordx2 v[38:39], v239, s[70:71] offset:1536
	global_load_dwordx2 v[40:41], v239, s[70:71] offset:2048
	global_load_dwordx2 v[42:43], v239, s[70:71] offset:2560
	global_load_dwordx2 v[44:45], v239, s[70:71] offset:3072
	global_load_dwordx2 v[46:47], v239, s[70:71] offset:3584
	s_waitcnt vmcnt(16)
	s_add_u32 s76, s46, 0x6000
	s_addc_u32 s77, s47, 0
	v_lshlrev_b32_e32 v64, 16, v48
	v_and_b32_e32 v65, 0xffff0000, v48
	v_lshlrev_b32_e32 v66, 16, v49
	v_and_b32_e32 v67, 0xffff0000, v49
	v_mul_f32_e32 v64, v64, v223
	v_mul_f32_e32 v65, v65, v223
	v_mul_f32_e32 v66, v66, v223
	v_mul_f32_e32 v67, v67, v223
	v_mul_f32_e32 v64, v64, v0
	v_mul_f32_e32 v65, v65, v1
	v_mul_f32_e32 v66, v66, v2
	v_mul_f32_e32 v67, v67, v3
	global_store_dwordx4 v250, v[64:67], s[76:77] offset:0 nt
	v_lshlrev_b32_e32 v68, 16, v50
	v_and_b32_e32 v69, 0xffff0000, v50
	v_lshlrev_b32_e32 v70, 16, v51
	v_and_b32_e32 v71, 0xffff0000, v51
	v_mul_f32_e32 v68, v68, v223
	v_mul_f32_e32 v69, v69, v223
	v_mul_f32_e32 v70, v70, v223
	v_mul_f32_e32 v71, v71, v223
	v_mul_f32_e32 v68, v68, v4
	v_mul_f32_e32 v69, v69, v5
	v_mul_f32_e32 v70, v70, v6
	v_mul_f32_e32 v71, v71, v7
	global_store_dwordx4 v250, v[68:71], s[76:77] offset:1024 nt
	v_lshlrev_b32_e32 v72, 16, v52
	v_and_b32_e32 v73, 0xffff0000, v52
	v_lshlrev_b32_e32 v74, 16, v53
	v_and_b32_e32 v75, 0xffff0000, v53
	v_mul_f32_e32 v72, v72, v223
	v_mul_f32_e32 v73, v73, v223
	v_mul_f32_e32 v74, v74, v223
	v_mul_f32_e32 v75, v75, v223
	v_mul_f32_e32 v72, v72, v8
	v_mul_f32_e32 v73, v73, v9
	v_mul_f32_e32 v74, v74, v10
	v_mul_f32_e32 v75, v75, v11
	global_store_dwordx4 v250, v[72:75], s[76:77] offset:2048 nt
	v_lshlrev_b32_e32 v76, 16, v54
	v_and_b32_e32 v77, 0xffff0000, v54
	v_lshlrev_b32_e32 v78, 16, v55
	v_and_b32_e32 v79, 0xffff0000, v55
	v_mul_f32_e32 v76, v76, v223
	v_mul_f32_e32 v77, v77, v223
	v_mul_f32_e32 v78, v78, v223
	v_mul_f32_e32 v79, v79, v223
	v_mul_f32_e32 v76, v76, v12
	v_mul_f32_e32 v77, v77, v13
	v_mul_f32_e32 v78, v78, v14
	v_mul_f32_e32 v79, v79, v15
	global_store_dwordx4 v250, v[76:79], s[76:77] offset:3072 nt
	v_lshlrev_b32_e32 v64, 16, v56
	v_and_b32_e32 v65, 0xffff0000, v56
	v_lshlrev_b32_e32 v66, 16, v57
	v_and_b32_e32 v67, 0xffff0000, v57
	v_mul_f32_e32 v64, v64, v223
	v_mul_f32_e32 v65, v65, v223
	v_mul_f32_e32 v66, v66, v223
	v_mul_f32_e32 v67, v67, v223
	v_mul_f32_e32 v64, v64, v16
	v_mul_f32_e32 v65, v65, v17
	v_mul_f32_e32 v66, v66, v18
	v_mul_f32_e32 v67, v67, v19
	global_store_dwordx4 v251, v[64:67], s[76:77] offset:0 nt
	v_lshlrev_b32_e32 v68, 16, v58
	v_and_b32_e32 v69, 0xffff0000, v58
	v_lshlrev_b32_e32 v70, 16, v59
	v_and_b32_e32 v71, 0xffff0000, v59
	v_mul_f32_e32 v68, v68, v223
	v_mul_f32_e32 v69, v69, v223
	v_mul_f32_e32 v70, v70, v223
	v_mul_f32_e32 v71, v71, v223
	v_mul_f32_e32 v68, v68, v20
	v_mul_f32_e32 v69, v69, v21
	v_mul_f32_e32 v70, v70, v22
	v_mul_f32_e32 v71, v71, v23
	global_store_dwordx4 v251, v[68:71], s[76:77] offset:1024 nt
	v_lshlrev_b32_e32 v72, 16, v60
	v_and_b32_e32 v73, 0xffff0000, v60
	v_lshlrev_b32_e32 v74, 16, v61
	v_and_b32_e32 v75, 0xffff0000, v61
	v_mul_f32_e32 v72, v72, v223
	v_mul_f32_e32 v73, v73, v223
	v_mul_f32_e32 v74, v74, v223
	v_mul_f32_e32 v75, v75, v223
	v_mul_f32_e32 v72, v72, v24
	v_mul_f32_e32 v73, v73, v25
	v_mul_f32_e32 v74, v74, v26
	v_mul_f32_e32 v75, v75, v27
	global_store_dwordx4 v251, v[72:75], s[76:77] offset:2048 nt
	v_lshlrev_b32_e32 v76, 16, v62
	v_and_b32_e32 v77, 0xffff0000, v62
	v_lshlrev_b32_e32 v78, 16, v63
	v_and_b32_e32 v79, 0xffff0000, v63
	v_mul_f32_e32 v76, v76, v223
	v_mul_f32_e32 v77, v77, v223
	v_mul_f32_e32 v78, v78, v223
	v_mul_f32_e32 v79, v79, v223
	v_mul_f32_e32 v76, v76, v28
	v_mul_f32_e32 v77, v77, v29
	v_mul_f32_e32 v78, v78, v30
	v_mul_f32_e32 v79, v79, v31
	global_store_dwordx4 v251, v[76:79], s[76:77] offset:3072 nt
	s_add_u32 s70, s28, 0x5000
	s_addc_u32 s71, s29, 0
	global_load_dwordx2 v[48:49], v239, s[70:71] offset:0
	global_load_dwordx2 v[50:51], v239, s[70:71] offset:512
	global_load_dwordx2 v[52:53], v239, s[70:71] offset:1024
	global_load_dwordx2 v[54:55], v239, s[70:71] offset:1536
	global_load_dwordx2 v[56:57], v239, s[70:71] offset:2048
	global_load_dwordx2 v[58:59], v239, s[70:71] offset:2560
	global_load_dwordx2 v[60:61], v239, s[70:71] offset:3072
	global_load_dwordx2 v[62:63], v239, s[70:71] offset:3584
	s_waitcnt vmcnt(16)
	s_add_u32 s76, s46, 0x8000
	s_addc_u32 s77, s47, 0
	v_lshlrev_b32_e32 v64, 16, v32
	v_and_b32_e32 v65, 0xffff0000, v32
	v_lshlrev_b32_e32 v66, 16, v33
	v_and_b32_e32 v67, 0xffff0000, v33
	v_mul_f32_e32 v64, v64, v224
	v_mul_f32_e32 v65, v65, v224
	v_mul_f32_e32 v66, v66, v224
	v_mul_f32_e32 v67, v67, v224
	v_mul_f32_e32 v64, v64, v0
	v_mul_f32_e32 v65, v65, v1
	v_mul_f32_e32 v66, v66, v2
	v_mul_f32_e32 v67, v67, v3
	global_store_dwordx4 v250, v[64:67], s[76:77] offset:0 nt
	v_lshlrev_b32_e32 v68, 16, v34
	v_and_b32_e32 v69, 0xffff0000, v34
	v_lshlrev_b32_e32 v70, 16, v35
	v_and_b32_e32 v71, 0xffff0000, v35
	v_mul_f32_e32 v68, v68, v224
	v_mul_f32_e32 v69, v69, v224
	v_mul_f32_e32 v70, v70, v224
	v_mul_f32_e32 v71, v71, v224
	v_mul_f32_e32 v68, v68, v4
	v_mul_f32_e32 v69, v69, v5
	v_mul_f32_e32 v70, v70, v6
	v_mul_f32_e32 v71, v71, v7
	global_store_dwordx4 v250, v[68:71], s[76:77] offset:1024 nt
	v_lshlrev_b32_e32 v72, 16, v36
	v_and_b32_e32 v73, 0xffff0000, v36
	v_lshlrev_b32_e32 v74, 16, v37
	v_and_b32_e32 v75, 0xffff0000, v37
	v_mul_f32_e32 v72, v72, v224
	v_mul_f32_e32 v73, v73, v224
	v_mul_f32_e32 v74, v74, v224
	v_mul_f32_e32 v75, v75, v224
	v_mul_f32_e32 v72, v72, v8
	v_mul_f32_e32 v73, v73, v9
	v_mul_f32_e32 v74, v74, v10
	v_mul_f32_e32 v75, v75, v11
	global_store_dwordx4 v250, v[72:75], s[76:77] offset:2048 nt
	v_lshlrev_b32_e32 v76, 16, v38
	v_and_b32_e32 v77, 0xffff0000, v38
	v_lshlrev_b32_e32 v78, 16, v39
	v_and_b32_e32 v79, 0xffff0000, v39
	v_mul_f32_e32 v76, v76, v224
	v_mul_f32_e32 v77, v77, v224
	v_mul_f32_e32 v78, v78, v224
	v_mul_f32_e32 v79, v79, v224
	v_mul_f32_e32 v76, v76, v12
	v_mul_f32_e32 v77, v77, v13
	v_mul_f32_e32 v78, v78, v14
	v_mul_f32_e32 v79, v79, v15
	global_store_dwordx4 v250, v[76:79], s[76:77] offset:3072 nt
	v_lshlrev_b32_e32 v64, 16, v40
	v_and_b32_e32 v65, 0xffff0000, v40
	v_lshlrev_b32_e32 v66, 16, v41
	v_and_b32_e32 v67, 0xffff0000, v41
	v_mul_f32_e32 v64, v64, v224
	v_mul_f32_e32 v65, v65, v224
	v_mul_f32_e32 v66, v66, v224
	v_mul_f32_e32 v67, v67, v224
	v_mul_f32_e32 v64, v64, v16
	v_mul_f32_e32 v65, v65, v17
	v_mul_f32_e32 v66, v66, v18
	v_mul_f32_e32 v67, v67, v19
	global_store_dwordx4 v251, v[64:67], s[76:77] offset:0 nt
	v_lshlrev_b32_e32 v68, 16, v42
	v_and_b32_e32 v69, 0xffff0000, v42
	v_lshlrev_b32_e32 v70, 16, v43
	v_and_b32_e32 v71, 0xffff0000, v43
	v_mul_f32_e32 v68, v68, v224
	v_mul_f32_e32 v69, v69, v224
	v_mul_f32_e32 v70, v70, v224
	v_mul_f32_e32 v71, v71, v224
	v_mul_f32_e32 v68, v68, v20
	v_mul_f32_e32 v69, v69, v21
	v_mul_f32_e32 v70, v70, v22
	v_mul_f32_e32 v71, v71, v23
	global_store_dwordx4 v251, v[68:71], s[76:77] offset:1024 nt
	v_lshlrev_b32_e32 v72, 16, v44
	v_and_b32_e32 v73, 0xffff0000, v44
	v_lshlrev_b32_e32 v74, 16, v45
	v_and_b32_e32 v75, 0xffff0000, v45
	v_mul_f32_e32 v72, v72, v224
	v_mul_f32_e32 v73, v73, v224
	v_mul_f32_e32 v74, v74, v224
	v_mul_f32_e32 v75, v75, v224
	v_mul_f32_e32 v72, v72, v24
	v_mul_f32_e32 v73, v73, v25
	v_mul_f32_e32 v74, v74, v26
	v_mul_f32_e32 v75, v75, v27
	global_store_dwordx4 v251, v[72:75], s[76:77] offset:2048 nt
	v_lshlrev_b32_e32 v76, 16, v46
	v_and_b32_e32 v77, 0xffff0000, v46
	v_lshlrev_b32_e32 v78, 16, v47
	v_and_b32_e32 v79, 0xffff0000, v47
	v_mul_f32_e32 v76, v76, v224
	v_mul_f32_e32 v77, v77, v224
	v_mul_f32_e32 v78, v78, v224
	v_mul_f32_e32 v79, v79, v224
	v_mul_f32_e32 v76, v76, v28
	v_mul_f32_e32 v77, v77, v29
	v_mul_f32_e32 v78, v78, v30
	v_mul_f32_e32 v79, v79, v31
	global_store_dwordx4 v251, v[76:79], s[76:77] offset:3072 nt
	s_add_u32 s70, s28, 0x6000
	s_addc_u32 s71, s29, 0
	global_load_dwordx2 v[32:33], v239, s[70:71] offset:0
	global_load_dwordx2 v[34:35], v239, s[70:71] offset:512
	global_load_dwordx2 v[36:37], v239, s[70:71] offset:1024
	global_load_dwordx2 v[38:39], v239, s[70:71] offset:1536
	global_load_dwordx2 v[40:41], v239, s[70:71] offset:2048
	global_load_dwordx2 v[42:43], v239, s[70:71] offset:2560
	global_load_dwordx2 v[44:45], v239, s[70:71] offset:3072
	global_load_dwordx2 v[46:47], v239, s[70:71] offset:3584
	s_waitcnt vmcnt(16)
	s_add_u32 s76, s46, 0xa000
	s_addc_u32 s77, s47, 0
	v_lshlrev_b32_e32 v64, 16, v48
	v_and_b32_e32 v65, 0xffff0000, v48
	v_lshlrev_b32_e32 v66, 16, v49
	v_and_b32_e32 v67, 0xffff0000, v49
	v_mul_f32_e32 v64, v64, v225
	v_mul_f32_e32 v65, v65, v225
	v_mul_f32_e32 v66, v66, v225
	v_mul_f32_e32 v67, v67, v225
	v_mul_f32_e32 v64, v64, v0
	v_mul_f32_e32 v65, v65, v1
	v_mul_f32_e32 v66, v66, v2
	v_mul_f32_e32 v67, v67, v3
	global_store_dwordx4 v250, v[64:67], s[76:77] offset:0 nt
	v_lshlrev_b32_e32 v68, 16, v50
	v_and_b32_e32 v69, 0xffff0000, v50
	v_lshlrev_b32_e32 v70, 16, v51
	v_and_b32_e32 v71, 0xffff0000, v51
	v_mul_f32_e32 v68, v68, v225
	v_mul_f32_e32 v69, v69, v225
	v_mul_f32_e32 v70, v70, v225
	v_mul_f32_e32 v71, v71, v225
	v_mul_f32_e32 v68, v68, v4
	v_mul_f32_e32 v69, v69, v5
	v_mul_f32_e32 v70, v70, v6
	v_mul_f32_e32 v71, v71, v7
	global_store_dwordx4 v250, v[68:71], s[76:77] offset:1024 nt
	v_lshlrev_b32_e32 v72, 16, v52
	v_and_b32_e32 v73, 0xffff0000, v52
	v_lshlrev_b32_e32 v74, 16, v53
	v_and_b32_e32 v75, 0xffff0000, v53
	v_mul_f32_e32 v72, v72, v225
	v_mul_f32_e32 v73, v73, v225
	v_mul_f32_e32 v74, v74, v225
	v_mul_f32_e32 v75, v75, v225
	v_mul_f32_e32 v72, v72, v8
	v_mul_f32_e32 v73, v73, v9
	v_mul_f32_e32 v74, v74, v10
	v_mul_f32_e32 v75, v75, v11
	global_store_dwordx4 v250, v[72:75], s[76:77] offset:2048 nt
	v_lshlrev_b32_e32 v76, 16, v54
	v_and_b32_e32 v77, 0xffff0000, v54
	v_lshlrev_b32_e32 v78, 16, v55
	v_and_b32_e32 v79, 0xffff0000, v55
	v_mul_f32_e32 v76, v76, v225
	v_mul_f32_e32 v77, v77, v225
	v_mul_f32_e32 v78, v78, v225
	v_mul_f32_e32 v79, v79, v225
	v_mul_f32_e32 v76, v76, v12
	v_mul_f32_e32 v77, v77, v13
	v_mul_f32_e32 v78, v78, v14
	v_mul_f32_e32 v79, v79, v15
	global_store_dwordx4 v250, v[76:79], s[76:77] offset:3072 nt
	v_lshlrev_b32_e32 v64, 16, v56
	v_and_b32_e32 v65, 0xffff0000, v56
	v_lshlrev_b32_e32 v66, 16, v57
	v_and_b32_e32 v67, 0xffff0000, v57
	v_mul_f32_e32 v64, v64, v225
	v_mul_f32_e32 v65, v65, v225
	v_mul_f32_e32 v66, v66, v225
	v_mul_f32_e32 v67, v67, v225
	v_mul_f32_e32 v64, v64, v16
	v_mul_f32_e32 v65, v65, v17
	v_mul_f32_e32 v66, v66, v18
	v_mul_f32_e32 v67, v67, v19
	global_store_dwordx4 v251, v[64:67], s[76:77] offset:0 nt
	v_lshlrev_b32_e32 v68, 16, v58
	v_and_b32_e32 v69, 0xffff0000, v58
	v_lshlrev_b32_e32 v70, 16, v59
	v_and_b32_e32 v71, 0xffff0000, v59
	v_mul_f32_e32 v68, v68, v225
	v_mul_f32_e32 v69, v69, v225
	v_mul_f32_e32 v70, v70, v225
	v_mul_f32_e32 v71, v71, v225
	v_mul_f32_e32 v68, v68, v20
	v_mul_f32_e32 v69, v69, v21
	v_mul_f32_e32 v70, v70, v22
	v_mul_f32_e32 v71, v71, v23
	global_store_dwordx4 v251, v[68:71], s[76:77] offset:1024 nt
	v_lshlrev_b32_e32 v72, 16, v60
	v_and_b32_e32 v73, 0xffff0000, v60
	v_lshlrev_b32_e32 v74, 16, v61
	v_and_b32_e32 v75, 0xffff0000, v61
	v_mul_f32_e32 v72, v72, v225
	v_mul_f32_e32 v73, v73, v225
	v_mul_f32_e32 v74, v74, v225
	v_mul_f32_e32 v75, v75, v225
	v_mul_f32_e32 v72, v72, v24
	v_mul_f32_e32 v73, v73, v25
	v_mul_f32_e32 v74, v74, v26
	v_mul_f32_e32 v75, v75, v27
	global_store_dwordx4 v251, v[72:75], s[76:77] offset:2048 nt
	v_lshlrev_b32_e32 v76, 16, v62
	v_and_b32_e32 v77, 0xffff0000, v62
	v_lshlrev_b32_e32 v78, 16, v63
	v_and_b32_e32 v79, 0xffff0000, v63
	v_mul_f32_e32 v76, v76, v225
	v_mul_f32_e32 v77, v77, v225
	v_mul_f32_e32 v78, v78, v225
	v_mul_f32_e32 v79, v79, v225
	v_mul_f32_e32 v76, v76, v28
	v_mul_f32_e32 v77, v77, v29
	v_mul_f32_e32 v78, v78, v30
	v_mul_f32_e32 v79, v79, v31
	global_store_dwordx4 v251, v[76:79], s[76:77] offset:3072 nt
	s_add_u32 s70, s28, 0x7000
	s_addc_u32 s71, s29, 0
	global_load_dwordx2 v[48:49], v239, s[70:71] offset:0
	global_load_dwordx2 v[50:51], v239, s[70:71] offset:512
	global_load_dwordx2 v[52:53], v239, s[70:71] offset:1024
	global_load_dwordx2 v[54:55], v239, s[70:71] offset:1536
	global_load_dwordx2 v[56:57], v239, s[70:71] offset:2048
	global_load_dwordx2 v[58:59], v239, s[70:71] offset:2560
	global_load_dwordx2 v[60:61], v239, s[70:71] offset:3072
	global_load_dwordx2 v[62:63], v239, s[70:71] offset:3584
	s_waitcnt vmcnt(16)
	s_add_u32 s76, s46, 0xc000
	s_addc_u32 s77, s47, 0
	v_lshlrev_b32_e32 v64, 16, v32
	v_and_b32_e32 v65, 0xffff0000, v32
	v_lshlrev_b32_e32 v66, 16, v33
	v_and_b32_e32 v67, 0xffff0000, v33
	v_mul_f32_e32 v64, v64, v226
	v_mul_f32_e32 v65, v65, v226
	v_mul_f32_e32 v66, v66, v226
	v_mul_f32_e32 v67, v67, v226
	v_mul_f32_e32 v64, v64, v0
	v_mul_f32_e32 v65, v65, v1
	v_mul_f32_e32 v66, v66, v2
	v_mul_f32_e32 v67, v67, v3
	global_store_dwordx4 v250, v[64:67], s[76:77] offset:0 nt
	v_lshlrev_b32_e32 v68, 16, v34
	v_and_b32_e32 v69, 0xffff0000, v34
	v_lshlrev_b32_e32 v70, 16, v35
	v_and_b32_e32 v71, 0xffff0000, v35
	v_mul_f32_e32 v68, v68, v226
	v_mul_f32_e32 v69, v69, v226
	v_mul_f32_e32 v70, v70, v226
	v_mul_f32_e32 v71, v71, v226
	v_mul_f32_e32 v68, v68, v4
	v_mul_f32_e32 v69, v69, v5
	v_mul_f32_e32 v70, v70, v6
	v_mul_f32_e32 v71, v71, v7
	global_store_dwordx4 v250, v[68:71], s[76:77] offset:1024 nt
	v_lshlrev_b32_e32 v72, 16, v36
	v_and_b32_e32 v73, 0xffff0000, v36
	v_lshlrev_b32_e32 v74, 16, v37
	v_and_b32_e32 v75, 0xffff0000, v37
	v_mul_f32_e32 v72, v72, v226
	v_mul_f32_e32 v73, v73, v226
	v_mul_f32_e32 v74, v74, v226
	v_mul_f32_e32 v75, v75, v226
	v_mul_f32_e32 v72, v72, v8
	v_mul_f32_e32 v73, v73, v9
	v_mul_f32_e32 v74, v74, v10
	v_mul_f32_e32 v75, v75, v11
	global_store_dwordx4 v250, v[72:75], s[76:77] offset:2048 nt
	v_lshlrev_b32_e32 v76, 16, v38
	v_and_b32_e32 v77, 0xffff0000, v38
	v_lshlrev_b32_e32 v78, 16, v39
	v_and_b32_e32 v79, 0xffff0000, v39
	v_mul_f32_e32 v76, v76, v226
	v_mul_f32_e32 v77, v77, v226
	v_mul_f32_e32 v78, v78, v226
	v_mul_f32_e32 v79, v79, v226
	v_mul_f32_e32 v76, v76, v12
	v_mul_f32_e32 v77, v77, v13
	v_mul_f32_e32 v78, v78, v14
	v_mul_f32_e32 v79, v79, v15
	global_store_dwordx4 v250, v[76:79], s[76:77] offset:3072 nt
	v_lshlrev_b32_e32 v64, 16, v40
	v_and_b32_e32 v65, 0xffff0000, v40
	v_lshlrev_b32_e32 v66, 16, v41
	v_and_b32_e32 v67, 0xffff0000, v41
	v_mul_f32_e32 v64, v64, v226
	v_mul_f32_e32 v65, v65, v226
	v_mul_f32_e32 v66, v66, v226
	v_mul_f32_e32 v67, v67, v226
	v_mul_f32_e32 v64, v64, v16
	v_mul_f32_e32 v65, v65, v17
	v_mul_f32_e32 v66, v66, v18
	v_mul_f32_e32 v67, v67, v19
	global_store_dwordx4 v251, v[64:67], s[76:77] offset:0 nt
	v_lshlrev_b32_e32 v68, 16, v42
	v_and_b32_e32 v69, 0xffff0000, v42
	v_lshlrev_b32_e32 v70, 16, v43
	v_and_b32_e32 v71, 0xffff0000, v43
	v_mul_f32_e32 v68, v68, v226
	v_mul_f32_e32 v69, v69, v226
	v_mul_f32_e32 v70, v70, v226
	v_mul_f32_e32 v71, v71, v226
	v_mul_f32_e32 v68, v68, v20
	v_mul_f32_e32 v69, v69, v21
	v_mul_f32_e32 v70, v70, v22
	v_mul_f32_e32 v71, v71, v23
	global_store_dwordx4 v251, v[68:71], s[76:77] offset:1024 nt
	v_lshlrev_b32_e32 v72, 16, v44
	v_and_b32_e32 v73, 0xffff0000, v44
	v_lshlrev_b32_e32 v74, 16, v45
	v_and_b32_e32 v75, 0xffff0000, v45
	v_mul_f32_e32 v72, v72, v226
	v_mul_f32_e32 v73, v73, v226
	v_mul_f32_e32 v74, v74, v226
	v_mul_f32_e32 v75, v75, v226
	v_mul_f32_e32 v72, v72, v24
	v_mul_f32_e32 v73, v73, v25
	v_mul_f32_e32 v74, v74, v26
	v_mul_f32_e32 v75, v75, v27
	global_store_dwordx4 v251, v[72:75], s[76:77] offset:2048 nt
	v_lshlrev_b32_e32 v76, 16, v46
	v_and_b32_e32 v77, 0xffff0000, v46
	v_lshlrev_b32_e32 v78, 16, v47
	v_and_b32_e32 v79, 0xffff0000, v47
	v_mul_f32_e32 v76, v76, v226
	v_mul_f32_e32 v77, v77, v226
	v_mul_f32_e32 v78, v78, v226
	v_mul_f32_e32 v79, v79, v226
	v_mul_f32_e32 v76, v76, v28
	v_mul_f32_e32 v77, v77, v29
	v_mul_f32_e32 v78, v78, v30
	v_mul_f32_e32 v79, v79, v31
	global_store_dwordx4 v251, v[76:79], s[76:77] offset:3072 nt
	s_waitcnt vmcnt(8)
	s_add_u32 s76, s46, 0xe000
	s_addc_u32 s77, s47, 0
	v_lshlrev_b32_e32 v64, 16, v48
	v_and_b32_e32 v65, 0xffff0000, v48
	v_lshlrev_b32_e32 v66, 16, v49
	v_and_b32_e32 v67, 0xffff0000, v49
	v_mul_f32_e32 v64, v64, v227
	v_mul_f32_e32 v65, v65, v227
	v_mul_f32_e32 v66, v66, v227
	v_mul_f32_e32 v67, v67, v227
	v_mul_f32_e32 v64, v64, v0
	v_mul_f32_e32 v65, v65, v1
	v_mul_f32_e32 v66, v66, v2
	v_mul_f32_e32 v67, v67, v3
	global_store_dwordx4 v250, v[64:67], s[76:77] offset:0 nt
	v_lshlrev_b32_e32 v68, 16, v50
	v_and_b32_e32 v69, 0xffff0000, v50
	v_lshlrev_b32_e32 v70, 16, v51
	v_and_b32_e32 v71, 0xffff0000, v51
	v_mul_f32_e32 v68, v68, v227
	v_mul_f32_e32 v69, v69, v227
	v_mul_f32_e32 v70, v70, v227
	v_mul_f32_e32 v71, v71, v227
	v_mul_f32_e32 v68, v68, v4
	v_mul_f32_e32 v69, v69, v5
	v_mul_f32_e32 v70, v70, v6
	v_mul_f32_e32 v71, v71, v7
	global_store_dwordx4 v250, v[68:71], s[76:77] offset:1024 nt
	v_lshlrev_b32_e32 v72, 16, v52
	v_and_b32_e32 v73, 0xffff0000, v52
	v_lshlrev_b32_e32 v74, 16, v53
	v_and_b32_e32 v75, 0xffff0000, v53
	v_mul_f32_e32 v72, v72, v227
	v_mul_f32_e32 v73, v73, v227
	v_mul_f32_e32 v74, v74, v227
	v_mul_f32_e32 v75, v75, v227
	v_mul_f32_e32 v72, v72, v8
	v_mul_f32_e32 v73, v73, v9
	v_mul_f32_e32 v74, v74, v10
	v_mul_f32_e32 v75, v75, v11
	global_store_dwordx4 v250, v[72:75], s[76:77] offset:2048 nt
	v_lshlrev_b32_e32 v76, 16, v54
	v_and_b32_e32 v77, 0xffff0000, v54
	v_lshlrev_b32_e32 v78, 16, v55
	v_and_b32_e32 v79, 0xffff0000, v55
	v_mul_f32_e32 v76, v76, v227
	v_mul_f32_e32 v77, v77, v227
	v_mul_f32_e32 v78, v78, v227
	v_mul_f32_e32 v79, v79, v227
	v_mul_f32_e32 v76, v76, v12
	v_mul_f32_e32 v77, v77, v13
	v_mul_f32_e32 v78, v78, v14
	v_mul_f32_e32 v79, v79, v15
	global_store_dwordx4 v250, v[76:79], s[76:77] offset:3072 nt
	v_lshlrev_b32_e32 v64, 16, v56
	v_and_b32_e32 v65, 0xffff0000, v56
	v_lshlrev_b32_e32 v66, 16, v57
	v_and_b32_e32 v67, 0xffff0000, v57
	v_mul_f32_e32 v64, v64, v227
	v_mul_f32_e32 v65, v65, v227
	v_mul_f32_e32 v66, v66, v227
	v_mul_f32_e32 v67, v67, v227
	v_mul_f32_e32 v64, v64, v16
	v_mul_f32_e32 v65, v65, v17
	v_mul_f32_e32 v66, v66, v18
	v_mul_f32_e32 v67, v67, v19
	global_store_dwordx4 v251, v[64:67], s[76:77] offset:0 nt
	v_lshlrev_b32_e32 v68, 16, v58
	v_and_b32_e32 v69, 0xffff0000, v58
	v_lshlrev_b32_e32 v70, 16, v59
	v_and_b32_e32 v71, 0xffff0000, v59
	v_mul_f32_e32 v68, v68, v227
	v_mul_f32_e32 v69, v69, v227
	v_mul_f32_e32 v70, v70, v227
	v_mul_f32_e32 v71, v71, v227
	v_mul_f32_e32 v68, v68, v20
	v_mul_f32_e32 v69, v69, v21
	v_mul_f32_e32 v70, v70, v22
	v_mul_f32_e32 v71, v71, v23
	global_store_dwordx4 v251, v[68:71], s[76:77] offset:1024 nt
	v_lshlrev_b32_e32 v72, 16, v60
	v_and_b32_e32 v73, 0xffff0000, v60
	v_lshlrev_b32_e32 v74, 16, v61
	v_and_b32_e32 v75, 0xffff0000, v61
	v_mul_f32_e32 v72, v72, v227
	v_mul_f32_e32 v73, v73, v227
	v_mul_f32_e32 v74, v74, v227
	v_mul_f32_e32 v75, v75, v227
	v_mul_f32_e32 v72, v72, v24
	v_mul_f32_e32 v73, v73, v25
	v_mul_f32_e32 v74, v74, v26
	v_mul_f32_e32 v75, v75, v27
	global_store_dwordx4 v251, v[72:75], s[76:77] offset:2048 nt
	v_lshlrev_b32_e32 v76, 16, v62
	v_and_b32_e32 v77, 0xffff0000, v62
	v_lshlrev_b32_e32 v78, 16, v63
	v_and_b32_e32 v79, 0xffff0000, v63
	v_mul_f32_e32 v76, v76, v227
	v_mul_f32_e32 v77, v77, v227
	v_mul_f32_e32 v78, v78, v227
	v_mul_f32_e32 v79, v79, v227
	v_mul_f32_e32 v76, v76, v28
	v_mul_f32_e32 v77, v77, v29
	v_mul_f32_e32 v78, v78, v30
	v_mul_f32_e32 v79, v79, v31
	global_store_dwordx4 v251, v[76:79], s[76:77] offset:3072 nt
	s_add_u32 s63, s63, s90
	s_cmpk_lt_i32 s63, 0x800
	s_cbranch_scc1 .LpgL1_group
